# v3 + mid-segment setprio flips removed + final (useless) grid barrier skipped
# baseline (speedup 1.0000x reference)
; template <class Epi, class Sched, bool ALIGN_EPI = false, bool SP2 = false, bool A_TILED = false>
; __device__ __forceinline__ void gemm_phase(PG8_LAS unsigned char* lds, const Gemm g, const Sched& S, const Epi& E, const int wave_s) {
;     ...
;         const bool has_next = Epi::AFTER_DRAIN ? false : S.next(ui + 1, nxt);
;         const char* nA = has_next ? (const char*)g.A + (size_t)nxt.pm * tstepA : cA; const char* nB = has_next ? (const char*)g.Bt + (size_t)nxt.pn * tstep : cB;
;         constexpr bool PEEL = SP2 && !Epi::AFTER_DRAIN;
;         if constexpr (PEEL) {
;             const char* a1 = cA + kstepA; const char* a2 = cA + 2 * kstepA; const char* b2 = cB + 2 * kstep; const char* a3 = a2 + kstepA; const char* b3 = b2 + kstep;
;             PG8_ITER(PG8_MMAZ)
.LBB0_776:
	s_ashr_i32 s73, s72, 31
	ds_read_b128 v[0:3], v149
	ds_read_b128 v[4:7], v149 offset:1024
	ds_read_b128 v[8:11], v149 offset:2048
	ds_read_b128 v[12:15], v149 offset:3072
	ds_read_b128 v[16:19], v150
	ds_read_b128 v[20:23], v150 offset:1024
	ds_read_b128 v[24:27], v150 offset:2048
	ds_read_b128 v[28:31], v150 offset:3072
	s_lshl_b64 s[52:53], s[72:73], 20
	s_add_u32 s74, s7, s52
	s_addc_u32 s75, s8, s53
	s_and_b64 s[52:53], s[0:1], exec
	s_cselect_b32 s51, s75, s83
	s_cselect_b32 s52, s74, s82
	s_ashr_i32 s71, s70, 31
	s_lshl_b64 s[54:55], s[70:71], 20
	s_add_u32 s76, s9, s54
	s_addc_u32 s77, s14, s55
	s_and_b64 s[54:55], s[0:1], exec
	s_cselect_b32 s53, s77, s81
	s_cselect_b32 s54, s76, s80
	s_add_u32 s56, s82, 0x80080
	s_addc_u32 s57, s83, 0
	s_mov_b32 m0, s48
	v_lshl_add_u64 v[64:65], s[56:57], 0, v[134:135]
	ds_read_b128 v[32:35], v151
	ds_read_b128 v[36:39], v151 offset:1024
	ds_read_b128 v[40:43], v151 offset:2048
	ds_read_b128 v[44:47], v151 offset:3072
	ds_read_b128 v[48:51], v151 offset:4096
	ds_read_b128 v[52:55], v151 offset:5120
	ds_read_b128 v[56:59], v151 offset:6144
	ds_read_b128 v[60:63], v151 offset:7168
	global_load_lds_dwordx4 v[64:65], off
	v_lshl_add_u64 v[64:65], s[56:57], 0, v[132:133]
	s_mov_b32 m0, s49
	s_nop 0
	global_load_lds_dwordx4 v[64:65], off
	s_waitcnt vmcnt(8) lgkmcnt(0)
	s_setprio 1
	s_barrier
	v_mfma_f32_16x16x32_bf16 v[88:91], v[0:3], v[56:59], 0
	v_mfma_f32_16x16x32_bf16 v[64:67], v[0:3], v[32:35], 0
	v_mfma_f32_16x16x32_bf16 v[68:71], v[8:11], v[32:35], 0
	v_mfma_f32_16x16x32_bf16 v[72:75], v[0:3], v[40:43], 0
	v_mfma_f32_16x16x32_bf16 v[76:79], v[8:11], v[40:43], 0
	v_mfma_f32_16x16x32_bf16 v[80:83], v[0:3], v[48:51], 0
	v_mfma_f32_16x16x32_bf16 v[84:87], v[8:11], v[48:51], 0
	v_mfma_f32_16x16x32_bf16 v[92:95], v[4:7], v[60:63], v[88:91]
	v_mfma_f32_16x16x32_bf16 v[88:91], v[8:11], v[56:59], 0
	v_mfma_f32_16x16x32_bf16 v[64:67], v[4:7], v[36:39], v[64:67]
	v_mfma_f32_16x16x32_bf16 v[68:71], v[12:15], v[36:39], v[68:71]
	v_mfma_f32_16x16x32_bf16 v[72:75], v[4:7], v[44:47], v[72:75]
	v_mfma_f32_16x16x32_bf16 v[76:79], v[12:15], v[44:47], v[76:79]
	v_mfma_f32_16x16x32_bf16 v[80:83], v[4:7], v[52:55], v[80:83]
	v_mfma_f32_16x16x32_bf16 v[84:87], v[12:15], v[52:55], v[84:87]
	v_mfma_f32_16x16x32_bf16 v[100:103], v[12:15], v[60:63], v[88:91]
	v_mfma_f32_16x16x32_bf16 v[88:91], v[16:19], v[32:35], 0
	v_mfma_f32_16x16x32_bf16 v[32:35], v[24:27], v[32:35], 0
	v_mfma_f32_16x16x32_bf16 v[108:111], v[20:23], v[36:39], v[88:91]
	v_mfma_f32_16x16x32_bf16 v[32:35], v[28:31], v[36:39], v[32:35]
	v_mfma_f32_16x16x32_bf16 v[36:39], v[16:19], v[40:43], 0
	v_mfma_f32_16x16x32_bf16 v[40:43], v[24:27], v[40:43], 0
	v_mfma_f32_16x16x32_bf16 v[36:39], v[20:23], v[44:47], v[36:39]
	v_mfma_f32_16x16x32_bf16 v[40:43], v[28:31], v[44:47], v[40:43]
	v_mfma_f32_16x16x32_bf16 v[44:47], v[16:19], v[48:51], 0
	v_mfma_f32_16x16x32_bf16 v[48:51], v[24:27], v[48:51], 0
	v_mfma_f32_16x16x32_bf16 v[44:47], v[20:23], v[52:55], v[44:47]
	v_mfma_f32_16x16x32_bf16 v[52:55], v[28:31], v[52:55], v[48:51]
	v_mfma_f32_16x16x32_bf16 v[48:51], v[16:19], v[56:59], 0
	v_mfma_f32_16x16x32_bf16 v[152:155], v[20:23], v[60:63], v[48:51]
	v_mfma_f32_16x16x32_bf16 v[48:51], v[24:27], v[56:59], 0
	v_mfma_f32_16x16x32_bf16 v[156:159], v[28:31], v[60:63], v[48:51]
	s_barrier
	s_setprio 0
	s_add_i32 s55, s45, s15
	v_lshl_add_u64 v[146:147], s[80:81], 0, v[128:129]
	s_add_i32 s56, s55, 0x2000
	v_lshl_add_u64 v[120:121], v[146:147], 0, s[68:69]
	s_mov_b32 m0, s55
	v_lshl_add_u64 v[252:253], s[80:81], 0, v[130:131]
	s_add_u32 s58, s80, 0x80100
	ds_read_b128 v[48:51], v151 offset:16384
	ds_read_b128 v[56:59], v151 offset:17408
	ds_read_b128 v[60:63], v151 offset:18432
	ds_read_b128 v[88:91], v151 offset:19456
	ds_read_b128 v[96:99], v151 offset:20480
	ds_read_b128 v[104:107], v151 offset:21504
	ds_read_b128 v[112:115], v151 offset:22528
	ds_read_b128 v[116:119], v151 offset:23552
	global_load_lds_dwordx4 v[120:121], off
	v_lshl_add_u64 v[120:121], v[252:253], 0, s[68:69]
	s_mov_b32 m0, s56
	s_addc_u32 s59, s81, 0
	s_add_i32 s57, s46, s15
	global_load_lds_dwordx4 v[120:121], off
	v_lshl_add_u64 v[120:121], s[58:59], 0, v[128:129]
	s_mov_b32 m0, s57
	v_lshl_add_u64 v[140:141], s[82:83], 0, v[134:135]
	global_load_lds_dwordx4 v[120:121], off
	v_lshl_add_u64 v[120:121], s[58:59], 0, v[130:131]
	s_add_i32 s58, s57, 0x2000
	s_mov_b32 m0, s58
	v_lshl_add_u64 v[142:143], s[82:83], 0, v[132:133]
	global_load_lds_dwordx4 v[120:121], off
	v_lshl_add_u64 v[120:121], v[140:141], 0, s[68:69]
	s_mov_b32 m0, s23
	s_nop 0
	global_load_lds_dwordx4 v[120:121], off
	v_lshl_add_u64 v[120:121], v[142:143], 0, s[68:69]
	s_mov_b32 m0, s36
	s_nop 0
	global_load_lds_dwordx4 v[120:121], off
	s_waitcnt vmcnt(8) lgkmcnt(0)
	s_setprio 1
	s_barrier
	v_mfma_f32_16x16x32_bf16 v[120:123], v[0:3], v[48:51], 0
	v_mfma_f32_16x16x32_bf16 v[160:163], v[4:7], v[56:59], v[120:123]
	v_mfma_f32_16x16x32_bf16 v[120:123], v[8:11], v[48:51], 0
	v_mfma_f32_16x16x32_bf16 v[164:167], v[12:15], v[56:59], v[120:123]
	v_mfma_f32_16x16x32_bf16 v[120:123], v[0:3], v[60:63], 0
	v_mfma_f32_16x16x32_bf16 v[168:171], v[4:7], v[88:91], v[120:123]
	v_mfma_f32_16x16x32_bf16 v[120:123], v[8:11], v[60:63], 0
	v_mfma_f32_16x16x32_bf16 v[172:175], v[12:15], v[88:91], v[120:123]
	v_mfma_f32_16x16x32_bf16 v[120:123], v[0:3], v[96:99], 0
	v_mfma_f32_16x16x32_bf16 v[0:3], v[0:3], v[112:115], 0
	v_mfma_f32_16x16x32_bf16 v[176:179], v[4:7], v[104:107], v[120:123]
	v_mfma_f32_16x16x32_bf16 v[0:3], v[4:7], v[116:119], v[0:3]
	v_mfma_f32_16x16x32_bf16 v[4:7], v[8:11], v[112:115], 0
	v_mfma_f32_16x16x32_bf16 v[120:123], v[8:11], v[96:99], 0
	v_mfma_f32_16x16x32_bf16 v[4:7], v[12:15], v[116:119], v[4:7]
	v_mfma_f32_16x16x32_bf16 v[180:183], v[12:15], v[104:107], v[120:123]
	v_mfma_f32_16x16x32_bf16 v[8:11], v[16:19], v[48:51], 0
	v_mfma_f32_16x16x32_bf16 v[12:15], v[20:23], v[56:59], v[8:11]
	v_mfma_f32_16x16x32_bf16 v[8:11], v[24:27], v[48:51], 0
	v_mfma_f32_16x16x32_bf16 v[184:187], v[28:31], v[56:59], v[8:11]
	v_mfma_f32_16x16x32_bf16 v[8:11], v[16:19], v[60:63], 0
	v_mfma_f32_16x16x32_bf16 v[188:191], v[20:23], v[88:91], v[8:11]
	v_mfma_f32_16x16x32_bf16 v[8:11], v[24:27], v[60:63], 0
	v_mfma_f32_16x16x32_bf16 v[192:195], v[28:31], v[88:91], v[8:11]
	v_mfma_f32_16x16x32_bf16 v[8:11], v[16:19], v[96:99], 0
	v_mfma_f32_16x16x32_bf16 v[196:199], v[20:23], v[104:107], v[8:11]
	v_mfma_f32_16x16x32_bf16 v[8:11], v[24:27], v[96:99], 0
	v_mfma_f32_16x16x32_bf16 v[200:203], v[28:31], v[104:107], v[8:11]
	v_mfma_f32_16x16x32_bf16 v[8:11], v[16:19], v[112:115], 0
	v_mfma_f32_16x16x32_bf16 v[204:207], v[20:23], v[116:119], v[8:11]
	v_mfma_f32_16x16x32_bf16 v[8:11], v[24:27], v[112:115], 0
	v_mfma_f32_16x16x32_bf16 v[208:211], v[28:31], v[116:119], v[8:11]
	s_barrier
	s_setprio 0
	s_add_i32 s59, 0, 0x18000
	s_add_i32 s73, 0, 0x1c000
	v_add_u32_e32 v144, s59, v148
	v_add_u32_e32 v145, s73, v148
	s_nop 0
	ds_read_b128 v[8:11], v144
	ds_read_b128 v[20:23], v144 offset:1024
	ds_read_b128 v[28:31], v144 offset:2048
	ds_read_b128 v[212:215], v144 offset:3072
	ds_read_b128 v[216:219], v145
	ds_read_b128 v[220:223], v145 offset:1024
	ds_read_b128 v[224:227], v145 offset:2048
	ds_read_b128 v[228:231], v145 offset:3072
	s_add_u32 s84, s82, 0x80100
	s_addc_u32 s85, s83, 0
	s_mov_b32 m0, s37
	v_lshl_add_u64 v[48:49], s[84:85], 0, v[134:135]
	ds_read_b128 v[16:19], v151 offset:32768
	ds_read_b128 v[24:27], v151 offset:33792
	ds_read_b128 v[60:63], v151 offset:34816
	ds_read_b128 v[232:235], v151 offset:35840
	ds_read_b128 v[236:239], v151 offset:36864
	ds_read_b128 v[240:243], v151 offset:37888
	ds_read_b128 v[244:247], v151 offset:38912
	ds_read_b128 v[248:251], v151 offset:39936
	global_load_lds_dwordx4 v[48:49], off
	v_lshl_add_u64 v[48:49], s[84:85], 0, v[132:133]
	s_mov_b32 m0, s38
	s_nop 0
	global_load_lds_dwordx4 v[48:49], off
	s_waitcnt vmcnt(8) lgkmcnt(0)
	s_setprio 1
	s_barrier
	v_mfma_f32_16x16x32_bf16 v[48:51], v[8:11], v[16:19], v[64:67]
	v_mfma_f32_16x16x32_bf16 v[120:123], v[20:23], v[24:27], v[48:51]
	v_mfma_f32_16x16x32_bf16 v[48:51], v[28:31], v[16:19], v[68:71]
	v_mfma_f32_16x16x32_bf16 v[112:115], v[212:215], v[24:27], v[48:51]
	v_mfma_f32_16x16x32_bf16 v[48:51], v[8:11], v[60:63], v[72:75]
	v_mfma_f32_16x16x32_bf16 v[104:107], v[20:23], v[232:235], v[48:51]
	v_mfma_f32_16x16x32_bf16 v[48:51], v[28:31], v[60:63], v[76:79]
	v_mfma_f32_16x16x32_bf16 v[96:99], v[212:215], v[232:235], v[48:51]
	v_mfma_f32_16x16x32_bf16 v[48:51], v[8:11], v[236:239], v[80:83]
	v_mfma_f32_16x16x32_bf16 v[88:91], v[20:23], v[240:243], v[48:51]
	v_mfma_f32_16x16x32_bf16 v[48:51], v[28:31], v[236:239], v[84:87]
	v_mfma_f32_16x16x32_bf16 v[80:83], v[212:215], v[240:243], v[48:51]
	v_mfma_f32_16x16x32_bf16 v[48:51], v[8:11], v[244:247], v[92:95]
	v_mfma_f32_16x16x32_bf16 v[56:59], v[20:23], v[248:251], v[48:51]
	v_mfma_f32_16x16x32_bf16 v[48:51], v[28:31], v[244:247], v[100:103]
	v_mfma_f32_16x16x32_bf16 v[48:51], v[212:215], v[248:251], v[48:51]
	v_mfma_f32_16x16x32_bf16 v[64:67], v[216:219], v[16:19], v[108:111]
	v_mfma_f32_16x16x32_bf16 v[16:19], v[224:227], v[16:19], v[32:35]
	v_mfma_f32_16x16x32_bf16 v[116:119], v[228:231], v[24:27], v[16:19]
	v_mfma_f32_16x16x32_bf16 v[16:19], v[216:219], v[60:63], v[36:39]
	v_mfma_f32_16x16x32_bf16 v[108:111], v[220:223], v[232:235], v[16:19]
	v_mfma_f32_16x16x32_bf16 v[16:19], v[224:227], v[60:63], v[40:43]
	v_mfma_f32_16x16x32_bf16 v[100:103], v[228:231], v[232:235], v[16:19]
	v_mfma_f32_16x16x32_bf16 v[16:19], v[216:219], v[236:239], v[44:47]
	v_mfma_f32_16x16x32_bf16 v[92:95], v[220:223], v[240:243], v[16:19]
	v_mfma_f32_16x16x32_bf16 v[16:19], v[224:227], v[236:239], v[52:55]
	v_mfma_f32_16x16x32_bf16 v[84:87], v[228:231], v[240:243], v[16:19]
	v_mfma_f32_16x16x32_bf16 v[16:19], v[216:219], v[244:247], v[152:155]
	v_mfma_f32_16x16x32_bf16 v[60:63], v[220:223], v[248:251], v[16:19]
	v_mfma_f32_16x16x32_bf16 v[16:19], v[224:227], v[244:247], v[156:159]
	v_mfma_f32_16x16x32_bf16 v[124:127], v[220:223], v[24:27], v[64:67]
	v_mfma_f32_16x16x32_bf16 v[52:55], v[228:231], v[248:251], v[16:19]
	s_barrier
; template <class Epi, class Sched, bool ALIGN_EPI = false, bool SP2 = false, bool A_TILED = false>
; __device__ __forceinline__ void gemm_phase(PG8_LAS unsigned char* lds, const Gemm g, const Sched& S, const Epi& E, const int wave_s) {
;     ...
;         for (int t = PEEL ? 2 : 0; t < nt; t += 2) {
;             const bool last = (t == nt - 2);
;             const char* a1 = cA + (size_t)(t + 1) * kstepA;
;             const char* a2 = last ? nA : cA + (size_t)(t + 2) * kstepA; const char* b2 = last ? nB : cB + (size_t)(t + 2) * kstep;
;             const char* a3 = a2 + kstepA; const char* b3 = b2 + kstep;
	s_setprio 0
	s_add_i32 s59, s59, s15
	s_add_i32 s71, s59, 0x2000
	s_nop 1
	v_lshl_add_u64 v[16:17], v[146:147], 0, s[66:67]
	s_mov_b32 m0, s59
	s_add_u32 s84, s80, 0x80180
	ds_read_b128 v[36:39], v151 offset:49152
	ds_read_b128 v[44:47], v151 offset:50176
	ds_read_b128 v[152:155], v151 offset:51200
	ds_read_b128 v[156:159], v151 offset:52224
	ds_read_b128 v[232:235], v151 offset:53248
	ds_read_b128 v[236:239], v151 offset:54272
	ds_read_b128 v[240:243], v151 offset:55296
	ds_read_b128 v[244:247], v151 offset:56320
	global_load_lds_dwordx4 v[16:17], off
	v_lshl_add_u64 v[16:17], v[252:253], 0, s[66:67]
	s_mov_b32 m0, s71
	s_addc_u32 s85, s81, 0
	s_add_i32 s73, s73, s15
	global_load_lds_dwordx4 v[16:17], off
	v_lshl_add_u64 v[16:17], s[84:85], 0, v[128:129]
	s_mov_b32 m0, s73
	s_add_i32 s79, s73, 0x2000
	global_load_lds_dwordx4 v[16:17], off
	v_lshl_add_u64 v[16:17], s[84:85], 0, v[130:131]
	s_mov_b32 m0, s79
	s_nop 0
	global_load_lds_dwordx4 v[16:17], off
	v_lshl_add_u64 v[16:17], v[140:141], 0, s[66:67]
	s_mov_b32 m0, s43
	s_nop 0
	global_load_lds_dwordx4 v[16:17], off
	v_lshl_add_u64 v[16:17], v[142:143], 0, s[66:67]
	s_mov_b32 m0, s44
	s_nop 0
	global_load_lds_dwordx4 v[16:17], off
	s_waitcnt vmcnt(8) lgkmcnt(0)
	s_setprio 1
	s_barrier
	v_mfma_f32_16x16x32_bf16 v[16:19], v[8:11], v[36:39], v[160:163]
	v_mfma_f32_16x16x32_bf16 v[72:75], v[20:23], v[44:47], v[16:19]
	v_mfma_f32_16x16x32_bf16 v[16:19], v[28:31], v[36:39], v[164:167]
	v_mfma_f32_16x16x32_bf16 v[64:67], v[212:215], v[44:47], v[16:19]
	v_mfma_f32_16x16x32_bf16 v[16:19], v[8:11], v[152:155], v[168:171]
	v_mfma_f32_16x16x32_bf16 v[40:43], v[20:23], v[156:159], v[16:19]
	v_mfma_f32_16x16x32_bf16 v[16:19], v[28:31], v[152:155], v[172:175]
	v_mfma_f32_16x16x32_bf16 v[32:35], v[212:215], v[156:159], v[16:19]
	v_mfma_f32_16x16x32_bf16 v[16:19], v[8:11], v[232:235], v[176:179]
	v_mfma_f32_16x16x32_bf16 v[0:3], v[8:11], v[240:243], v[0:3]
	v_mfma_f32_16x16x32_bf16 v[24:27], v[20:23], v[236:239], v[16:19]
	v_mfma_f32_16x16x32_bf16 v[16:19], v[28:31], v[232:235], v[180:183]
	v_mfma_f32_16x16x32_bf16 v[8:11], v[20:23], v[244:247], v[0:3]
	v_mfma_f32_16x16x32_bf16 v[0:3], v[28:31], v[240:243], v[4:7]
	v_mfma_f32_16x16x32_bf16 v[16:19], v[212:215], v[236:239], v[16:19]
	v_mfma_f32_16x16x32_bf16 v[0:3], v[212:215], v[244:247], v[0:3]
	v_mfma_f32_16x16x32_bf16 v[4:7], v[216:219], v[36:39], v[12:15]
	v_mfma_f32_16x16x32_bf16 v[76:79], v[220:223], v[44:47], v[4:7]
	v_mfma_f32_16x16x32_bf16 v[4:7], v[224:227], v[36:39], v[184:187]
	v_mfma_f32_16x16x32_bf16 v[68:71], v[228:231], v[44:47], v[4:7]
	v_mfma_f32_16x16x32_bf16 v[4:7], v[216:219], v[152:155], v[188:191]
	v_mfma_f32_16x16x32_bf16 v[44:47], v[220:223], v[156:159], v[4:7]
	v_mfma_f32_16x16x32_bf16 v[4:7], v[224:227], v[152:155], v[192:195]
	v_mfma_f32_16x16x32_bf16 v[36:39], v[228:231], v[156:159], v[4:7]
	v_mfma_f32_16x16x32_bf16 v[4:7], v[216:219], v[232:235], v[196:199]
	v_mfma_f32_16x16x32_bf16 v[28:31], v[220:223], v[236:239], v[4:7]
	v_mfma_f32_16x16x32_bf16 v[4:7], v[224:227], v[232:235], v[200:203]
	v_mfma_f32_16x16x32_bf16 v[20:23], v[228:231], v[236:239], v[4:7]
	v_mfma_f32_16x16x32_bf16 v[4:7], v[216:219], v[240:243], v[204:207]
	v_mfma_f32_16x16x32_bf16 v[12:15], v[220:223], v[244:247], v[4:7]
	v_mfma_f32_16x16x32_bf16 v[4:7], v[224:227], v[240:243], v[208:211]
	v_mfma_f32_16x16x32_bf16 v[4:7], v[228:231], v[244:247], v[4:7]
	s_barrier
	s_setprio 0
	s_add_u32 s88, s80, 0x200
	s_addc_u32 s89, s81, 0
	s_add_u32 s80, s82, 0x80180
	s_addc_u32 s81, s83, 0
	s_mov_b32 s90, 0
.LBB0_777:
	ds_read_b128 v[152:155], v149
	ds_read_b128 v[156:159], v149 offset:1024
	ds_read_b128 v[160:163], v149 offset:2048
	ds_read_b128 v[164:167], v149 offset:3072
	ds_read_b128 v[168:171], v150
	ds_read_b128 v[172:175], v150 offset:1024
	ds_read_b128 v[176:179], v150 offset:2048
	ds_read_b128 v[180:183], v150 offset:3072
	s_add_u32 s82, s80, 0xfff80080
	s_addc_u32 s83, s81, -1
	s_cmp_eq_u32 s90, 28
	s_cselect_b32 s85, s51, s83
	s_cselect_b32 s84, s52, s82
	s_cselect_b32 s83, s53, s89
	s_cselect_b32 s82, s54, s88
	s_mov_b32 m0, s48
	v_lshl_add_u64 v[140:141], s[80:81], 0, v[138:139]
	ds_read_b128 v[184:187], v151
	ds_read_b128 v[188:191], v151 offset:1024
	ds_read_b128 v[192:195], v151 offset:2048
	ds_read_b128 v[196:199], v151 offset:3072
	ds_read_b128 v[200:203], v151 offset:4096
	ds_read_b128 v[204:207], v151 offset:5120
	ds_read_b128 v[208:211], v151 offset:6144
	ds_read_b128 v[212:215], v151 offset:7168
	global_load_lds_dwordx4 v[140:141], off
	v_lshl_add_u64 v[140:141], s[80:81], 0, v[136:137]
	s_mov_b32 m0, s49
	s_nop 0
	global_load_lds_dwordx4 v[140:141], off
	s_waitcnt vmcnt(8) lgkmcnt(0)
	s_setprio 1
	s_barrier
	v_mfma_f32_16x16x32_bf16 v[120:123], v[152:155], v[184:187], v[120:123]
	v_mfma_f32_16x16x32_bf16 v[112:115], v[160:163], v[184:187], v[112:115]
	v_mfma_f32_16x16x32_bf16 v[104:107], v[152:155], v[192:195], v[104:107]
	v_mfma_f32_16x16x32_bf16 v[96:99], v[160:163], v[192:195], v[96:99]
	v_mfma_f32_16x16x32_bf16 v[88:91], v[152:155], v[200:203], v[88:91]
	v_mfma_f32_16x16x32_bf16 v[80:83], v[160:163], v[200:203], v[80:83]
	v_mfma_f32_16x16x32_bf16 v[56:59], v[152:155], v[208:211], v[56:59]
	v_mfma_f32_16x16x32_bf16 v[48:51], v[160:163], v[208:211], v[48:51]
	v_mfma_f32_16x16x32_bf16 v[120:123], v[156:159], v[188:191], v[120:123]
	v_mfma_f32_16x16x32_bf16 v[112:115], v[164:167], v[188:191], v[112:115]
	v_mfma_f32_16x16x32_bf16 v[104:107], v[156:159], v[196:199], v[104:107]
	v_mfma_f32_16x16x32_bf16 v[96:99], v[164:167], v[196:199], v[96:99]
	v_mfma_f32_16x16x32_bf16 v[88:91], v[156:159], v[204:207], v[88:91]
	v_mfma_f32_16x16x32_bf16 v[80:83], v[164:167], v[204:207], v[80:83]
	v_mfma_f32_16x16x32_bf16 v[56:59], v[156:159], v[212:215], v[56:59]
	v_mfma_f32_16x16x32_bf16 v[48:51], v[164:167], v[212:215], v[48:51]
	v_mfma_f32_16x16x32_bf16 v[124:127], v[168:171], v[184:187], v[124:127]
	v_mfma_f32_16x16x32_bf16 v[116:119], v[176:179], v[184:187], v[116:119]
	v_mfma_f32_16x16x32_bf16 v[108:111], v[168:171], v[192:195], v[108:111]
	v_mfma_f32_16x16x32_bf16 v[100:103], v[176:179], v[192:195], v[100:103]
	v_mfma_f32_16x16x32_bf16 v[92:95], v[168:171], v[200:203], v[92:95]
	v_mfma_f32_16x16x32_bf16 v[84:87], v[176:179], v[200:203], v[84:87]
	v_mfma_f32_16x16x32_bf16 v[60:63], v[168:171], v[208:211], v[60:63]
	v_mfma_f32_16x16x32_bf16 v[52:55], v[176:179], v[208:211], v[52:55]
	v_mfma_f32_16x16x32_bf16 v[124:127], v[172:175], v[188:191], v[124:127]
	v_mfma_f32_16x16x32_bf16 v[116:119], v[180:183], v[188:191], v[116:119]
	v_mfma_f32_16x16x32_bf16 v[108:111], v[172:175], v[196:199], v[108:111]
	v_mfma_f32_16x16x32_bf16 v[100:103], v[180:183], v[196:199], v[100:103]
	v_mfma_f32_16x16x32_bf16 v[92:95], v[172:175], v[204:207], v[92:95]
	v_mfma_f32_16x16x32_bf16 v[84:87], v[180:183], v[204:207], v[84:87]
	v_mfma_f32_16x16x32_bf16 v[60:63], v[172:175], v[212:215], v[60:63]
	v_mfma_f32_16x16x32_bf16 v[52:55], v[180:183], v[212:215], v[52:55]
	s_barrier
	s_setprio 0
	s_mov_b32 m0, s55
	v_lshl_add_u64 v[140:141], s[82:83], 0, v[128:129]
	s_add_u32 s94, s82, 0x80000
	ds_read_b128 v[184:187], v151 offset:16384
	ds_read_b128 v[188:191], v151 offset:17408
	ds_read_b128 v[192:195], v151 offset:18432
	ds_read_b128 v[196:199], v151 offset:19456
	ds_read_b128 v[200:203], v151 offset:20480
	ds_read_b128 v[204:207], v151 offset:21504
	ds_read_b128 v[208:211], v151 offset:22528
	ds_read_b128 v[212:215], v151 offset:23552
	global_load_lds_dwordx4 v[140:141], off
	v_lshl_add_u64 v[142:143], s[82:83], 0, v[130:131]
	s_mov_b32 m0, s56
	s_addc_u32 s95, s83, 0
	global_load_lds_dwordx4 v[142:143], off
	v_lshl_add_u64 v[146:147], s[94:95], 0, v[128:129]
	s_mov_b32 m0, s57
	v_lshl_add_u64 v[216:217], s[84:85], 0, v[132:133]
	global_load_lds_dwordx4 v[146:147], off
	v_lshl_add_u64 v[146:147], s[94:95], 0, v[130:131]
	s_mov_b32 m0, s58
	s_nop 0
	global_load_lds_dwordx4 v[146:147], off
	v_lshl_add_u64 v[146:147], s[84:85], 0, v[134:135]
	s_mov_b32 m0, s23
	s_nop 0
	global_load_lds_dwordx4 v[146:147], off
	s_mov_b32 m0, s36
	s_nop 0
	global_load_lds_dwordx4 v[216:217], off
	s_waitcnt vmcnt(8) lgkmcnt(0)
	s_setprio 1
	s_barrier
	v_mfma_f32_16x16x32_bf16 v[72:75], v[152:155], v[184:187], v[72:75]
	v_mfma_f32_16x16x32_bf16 v[64:67], v[160:163], v[184:187], v[64:67]
	v_mfma_f32_16x16x32_bf16 v[40:43], v[152:155], v[192:195], v[40:43]
	v_mfma_f32_16x16x32_bf16 v[32:35], v[160:163], v[192:195], v[32:35]
	v_mfma_f32_16x16x32_bf16 v[24:27], v[152:155], v[200:203], v[24:27]
	v_mfma_f32_16x16x32_bf16 v[16:19], v[160:163], v[200:203], v[16:19]
	v_mfma_f32_16x16x32_bf16 v[8:11], v[152:155], v[208:211], v[8:11]
	v_mfma_f32_16x16x32_bf16 v[0:3], v[160:163], v[208:211], v[0:3]
	v_mfma_f32_16x16x32_bf16 v[72:75], v[156:159], v[188:191], v[72:75]
	v_mfma_f32_16x16x32_bf16 v[64:67], v[164:167], v[188:191], v[64:67]
	v_mfma_f32_16x16x32_bf16 v[40:43], v[156:159], v[196:199], v[40:43]
	v_mfma_f32_16x16x32_bf16 v[32:35], v[164:167], v[196:199], v[32:35]
	v_mfma_f32_16x16x32_bf16 v[24:27], v[156:159], v[204:207], v[24:27]
	v_mfma_f32_16x16x32_bf16 v[16:19], v[164:167], v[204:207], v[16:19]
	v_mfma_f32_16x16x32_bf16 v[8:11], v[156:159], v[212:215], v[8:11]
	v_mfma_f32_16x16x32_bf16 v[0:3], v[164:167], v[212:215], v[0:3]
	v_mfma_f32_16x16x32_bf16 v[76:79], v[168:171], v[184:187], v[76:79]
	v_mfma_f32_16x16x32_bf16 v[68:71], v[176:179], v[184:187], v[68:71]
	v_mfma_f32_16x16x32_bf16 v[44:47], v[168:171], v[192:195], v[44:47]
	v_mfma_f32_16x16x32_bf16 v[36:39], v[176:179], v[192:195], v[36:39]
	v_mfma_f32_16x16x32_bf16 v[28:31], v[168:171], v[200:203], v[28:31]
	v_mfma_f32_16x16x32_bf16 v[20:23], v[176:179], v[200:203], v[20:23]
	v_mfma_f32_16x16x32_bf16 v[12:15], v[168:171], v[208:211], v[12:15]
	v_mfma_f32_16x16x32_bf16 v[4:7], v[176:179], v[208:211], v[4:7]
	v_mfma_f32_16x16x32_bf16 v[76:79], v[172:175], v[188:191], v[76:79]
	v_mfma_f32_16x16x32_bf16 v[68:71], v[180:183], v[188:191], v[68:71]
	v_mfma_f32_16x16x32_bf16 v[44:47], v[172:175], v[196:199], v[44:47]
	v_mfma_f32_16x16x32_bf16 v[36:39], v[180:183], v[196:199], v[36:39]
	v_mfma_f32_16x16x32_bf16 v[28:31], v[172:175], v[204:207], v[28:31]
	v_mfma_f32_16x16x32_bf16 v[20:23], v[180:183], v[204:207], v[20:23]
	v_mfma_f32_16x16x32_bf16 v[12:15], v[172:175], v[212:215], v[12:15]
	v_mfma_f32_16x16x32_bf16 v[4:7], v[180:183], v[212:215], v[4:7]
	s_barrier
; #define PG8_BAR __builtin_amdgcn_s_barrier()
; template <class Epi, class Sched, bool ALIGN_EPI = false, bool SP2 = false, bool A_TILED = false>
; __device__ __forceinline__ void gemm_phase(PG8_LAS unsigned char* lds, const Gemm g, const Sched& S, const Epi& E, const int wave_s) {
;     ...
;         if constexpr (ALIGN_EPI) { if (wr == 0) PG8_BAR; }
	s_setprio 0
	ds_read_b128 v[152:155], v144
	ds_read_b128 v[156:159], v144 offset:1024
	ds_read_b128 v[160:163], v144 offset:2048
	ds_read_b128 v[164:167], v144 offset:3072
	ds_read_b128 v[168:171], v145
	ds_read_b128 v[172:175], v145 offset:1024
	ds_read_b128 v[176:179], v145 offset:2048
	ds_read_b128 v[180:183], v145 offset:3072
	s_add_u32 s84, s84, 0x80000
	s_addc_u32 s85, s85, 0
	s_mov_b32 m0, s37
	v_lshl_add_u64 v[218:219], s[84:85], 0, v[134:135]
	ds_read_b128 v[184:187], v151 offset:32768
	ds_read_b128 v[188:191], v151 offset:33792
	ds_read_b128 v[192:195], v151 offset:34816
	ds_read_b128 v[196:199], v151 offset:35840
	ds_read_b128 v[200:203], v151 offset:36864
	ds_read_b128 v[204:207], v151 offset:37888
	ds_read_b128 v[208:211], v151 offset:38912
	ds_read_b128 v[212:215], v151 offset:39936
	global_load_lds_dwordx4 v[218:219], off
	v_lshl_add_u64 v[218:219], s[84:85], 0, v[132:133]
	s_mov_b32 m0, s38
	s_nop 0
	global_load_lds_dwordx4 v[218:219], off
	s_waitcnt vmcnt(8) lgkmcnt(0)
	s_setprio 1
	s_barrier
	v_mfma_f32_16x16x32_bf16 v[120:123], v[152:155], v[184:187], v[120:123]
	v_mfma_f32_16x16x32_bf16 v[112:115], v[160:163], v[184:187], v[112:115]
	v_mfma_f32_16x16x32_bf16 v[104:107], v[152:155], v[192:195], v[104:107]
	v_mfma_f32_16x16x32_bf16 v[96:99], v[160:163], v[192:195], v[96:99]
	v_mfma_f32_16x16x32_bf16 v[88:91], v[152:155], v[200:203], v[88:91]
	v_mfma_f32_16x16x32_bf16 v[80:83], v[160:163], v[200:203], v[80:83]
	v_mfma_f32_16x16x32_bf16 v[56:59], v[152:155], v[208:211], v[56:59]
	v_mfma_f32_16x16x32_bf16 v[48:51], v[160:163], v[208:211], v[48:51]
	v_mfma_f32_16x16x32_bf16 v[120:123], v[156:159], v[188:191], v[120:123]
	v_mfma_f32_16x16x32_bf16 v[112:115], v[164:167], v[188:191], v[112:115]
	v_mfma_f32_16x16x32_bf16 v[104:107], v[156:159], v[196:199], v[104:107]
	v_mfma_f32_16x16x32_bf16 v[96:99], v[164:167], v[196:199], v[96:99]
	v_mfma_f32_16x16x32_bf16 v[88:91], v[156:159], v[204:207], v[88:91]
	v_mfma_f32_16x16x32_bf16 v[80:83], v[164:167], v[204:207], v[80:83]
	v_mfma_f32_16x16x32_bf16 v[56:59], v[156:159], v[212:215], v[56:59]
	v_mfma_f32_16x16x32_bf16 v[48:51], v[164:167], v[212:215], v[48:51]
	v_mfma_f32_16x16x32_bf16 v[124:127], v[168:171], v[184:187], v[124:127]
	v_mfma_f32_16x16x32_bf16 v[116:119], v[176:179], v[184:187], v[116:119]
	v_mfma_f32_16x16x32_bf16 v[108:111], v[168:171], v[192:195], v[108:111]
	v_mfma_f32_16x16x32_bf16 v[100:103], v[176:179], v[192:195], v[100:103]
	v_mfma_f32_16x16x32_bf16 v[92:95], v[168:171], v[200:203], v[92:95]
	v_mfma_f32_16x16x32_bf16 v[84:87], v[176:179], v[200:203], v[84:87]
	v_mfma_f32_16x16x32_bf16 v[60:63], v[168:171], v[208:211], v[60:63]
	v_mfma_f32_16x16x32_bf16 v[52:55], v[176:179], v[208:211], v[52:55]
	v_mfma_f32_16x16x32_bf16 v[124:127], v[172:175], v[188:191], v[124:127]
	v_mfma_f32_16x16x32_bf16 v[116:119], v[180:183], v[188:191], v[116:119]
	v_mfma_f32_16x16x32_bf16 v[108:111], v[172:175], v[196:199], v[108:111]
	v_mfma_f32_16x16x32_bf16 v[100:103], v[180:183], v[196:199], v[100:103]
	v_mfma_f32_16x16x32_bf16 v[92:95], v[172:175], v[204:207], v[92:95]
	v_mfma_f32_16x16x32_bf16 v[84:87], v[180:183], v[204:207], v[84:87]
	v_mfma_f32_16x16x32_bf16 v[60:63], v[172:175], v[212:215], v[60:63]
	v_mfma_f32_16x16x32_bf16 v[52:55], v[180:183], v[212:215], v[52:55]
	s_barrier
	s_setprio 0
	s_mov_b32 m0, s59
	v_lshl_add_u64 v[140:141], v[140:141], 0, s[62:63]
	s_add_u32 s82, s82, 0x80080
	ds_read_b128 v[184:187], v151 offset:49152
	ds_read_b128 v[188:191], v151 offset:50176
	ds_read_b128 v[192:195], v151 offset:51200
	ds_read_b128 v[196:199], v151 offset:52224
	ds_read_b128 v[200:203], v151 offset:53248
	ds_read_b128 v[204:207], v151 offset:54272
	ds_read_b128 v[208:211], v151 offset:55296
	ds_read_b128 v[212:215], v151 offset:56320
	global_load_lds_dwordx4 v[140:141], off
	v_lshl_add_u64 v[140:141], v[142:143], 0, s[62:63]
	s_mov_b32 m0, s71
	s_addc_u32 s83, s83, 0
	global_load_lds_dwordx4 v[140:141], off
	v_lshl_add_u64 v[140:141], s[82:83], 0, v[128:129]
	s_mov_b32 m0, s73
	s_nop 0
	global_load_lds_dwordx4 v[140:141], off
	v_lshl_add_u64 v[140:141], s[82:83], 0, v[130:131]
	s_mov_b32 m0, s79
	s_nop 0
	global_load_lds_dwordx4 v[140:141], off
	v_lshl_add_u64 v[140:141], v[146:147], 0, s[62:63]
	s_mov_b32 m0, s43
	s_nop 0
	global_load_lds_dwordx4 v[140:141], off
	v_lshl_add_u64 v[140:141], v[216:217], 0, s[62:63]
	s_mov_b32 m0, s44
	s_nop 0
	global_load_lds_dwordx4 v[140:141], off
	s_waitcnt vmcnt(8) lgkmcnt(0)
	s_setprio 1
	s_barrier
	v_mfma_f32_16x16x32_bf16 v[72:75], v[152:155], v[184:187], v[72:75]
	v_mfma_f32_16x16x32_bf16 v[64:67], v[160:163], v[184:187], v[64:67]
	v_mfma_f32_16x16x32_bf16 v[40:43], v[152:155], v[192:195], v[40:43]
	v_mfma_f32_16x16x32_bf16 v[32:35], v[160:163], v[192:195], v[32:35]
	v_mfma_f32_16x16x32_bf16 v[24:27], v[152:155], v[200:203], v[24:27]
	v_mfma_f32_16x16x32_bf16 v[16:19], v[160:163], v[200:203], v[16:19]
	v_mfma_f32_16x16x32_bf16 v[8:11], v[152:155], v[208:211], v[8:11]
	v_mfma_f32_16x16x32_bf16 v[0:3], v[160:163], v[208:211], v[0:3]
	v_mfma_f32_16x16x32_bf16 v[72:75], v[156:159], v[188:191], v[72:75]
	v_mfma_f32_16x16x32_bf16 v[64:67], v[164:167], v[188:191], v[64:67]
	v_mfma_f32_16x16x32_bf16 v[40:43], v[156:159], v[196:199], v[40:43]
	v_mfma_f32_16x16x32_bf16 v[32:35], v[164:167], v[196:199], v[32:35]
	v_mfma_f32_16x16x32_bf16 v[24:27], v[156:159], v[204:207], v[24:27]
	v_mfma_f32_16x16x32_bf16 v[16:19], v[164:167], v[204:207], v[16:19]
	v_mfma_f32_16x16x32_bf16 v[8:11], v[156:159], v[212:215], v[8:11]
	v_mfma_f32_16x16x32_bf16 v[0:3], v[164:167], v[212:215], v[0:3]
	v_mfma_f32_16x16x32_bf16 v[76:79], v[168:171], v[184:187], v[76:79]
	v_mfma_f32_16x16x32_bf16 v[68:71], v[176:179], v[184:187], v[68:71]
	v_mfma_f32_16x16x32_bf16 v[44:47], v[168:171], v[192:195], v[44:47]
	v_mfma_f32_16x16x32_bf16 v[36:39], v[176:179], v[192:195], v[36:39]
	v_mfma_f32_16x16x32_bf16 v[28:31], v[168:171], v[200:203], v[28:31]
	v_mfma_f32_16x16x32_bf16 v[20:23], v[176:179], v[200:203], v[20:23]
	v_mfma_f32_16x16x32_bf16 v[12:15], v[168:171], v[208:211], v[12:15]
	v_mfma_f32_16x16x32_bf16 v[4:7], v[176:179], v[208:211], v[4:7]
	v_mfma_f32_16x16x32_bf16 v[76:79], v[172:175], v[188:191], v[76:79]
	v_mfma_f32_16x16x32_bf16 v[68:71], v[180:183], v[188:191], v[68:71]
	v_mfma_f32_16x16x32_bf16 v[44:47], v[172:175], v[196:199], v[44:47]
	v_mfma_f32_16x16x32_bf16 v[36:39], v[180:183], v[196:199], v[36:39]
	v_mfma_f32_16x16x32_bf16 v[28:31], v[172:175], v[204:207], v[28:31]
	v_mfma_f32_16x16x32_bf16 v[20:23], v[180:183], v[204:207], v[20:23]
	v_mfma_f32_16x16x32_bf16 v[12:15], v[172:175], v[212:215], v[12:15]
	v_mfma_f32_16x16x32_bf16 v[4:7], v[180:183], v[212:215], v[4:7]
	s_barrier
	s_setprio 0
	s_add_i32 s90, s90, 2
	s_add_u32 s88, s88, 0x100
	s_addc_u32 s89, s89, 0
	s_add_u32 s80, s80, 0x100
	s_addc_u32 s81, s81, 0
	s_cmp_gt_u32 s90, 29
	s_cbranch_scc0 .LBB0_777
	s_and_b64 vcc, exec, s[64:65]
	s_cbranch_vccz .LBB0_780
	s_barrier

; template <class Epi, class Sched, bool ALIGN_EPI = false, bool SP2 = false, bool A_TILED = false>
; __device__ __forceinline__ void gemm_phase(PG8_LAS unsigned char* lds, const Gemm g, const Sched& S, const Epi& E, const int wave_s) {
;     ...
;             const bool last = (t == nt - 2);
;             const char* a1 = cA + (size_t)(t + 1) * kstepA;
;             const char* a2 = last ? nA : cA + (size_t)(t + 2) * kstepA; const char* b2 = last ? nB : cB + (size_t)(t + 2) * kstep;
;             const char* a3 = a2 + kstepA; const char* b3 = b2 + kstep;
.LBB0_1043:
	ds_read_b128 v[146:149], v140
	ds_read_b128 v[150:153], v140 offset:1024
	ds_read_b128 v[154:157], v140 offset:2048
	ds_read_b128 v[158:161], v140 offset:3072
	ds_read_b128 v[162:165], v141
	ds_read_b128 v[166:169], v141 offset:1024
	ds_read_b128 v[170:173], v141 offset:2048
	ds_read_b128 v[174:177], v141 offset:3072
	s_add_u32 s52, s62, s39
	s_addc_u32 s53, s63, s40
	s_add_u32 s54, s62, s37
	s_addc_u32 s55, s63, s38
	s_cmp_eq_u32 s41, 28
	s_cselect_b32 s73, s5, s53
	s_cselect_b32 s72, s4, s52
	s_cselect_b32 s71, s1, s55
	s_cselect_b32 s70, s0, s54
	s_mov_b32 m0, s42
	v_lshl_add_u64 v[210:211], s[62:63], 0, v[138:139]
	ds_read_b128 v[178:181], v142
	ds_read_b128 v[182:185], v142 offset:1024
	ds_read_b128 v[186:189], v142 offset:2048
	ds_read_b128 v[190:193], v142 offset:3072
	ds_read_b128 v[194:197], v142 offset:4096
	ds_read_b128 v[198:201], v142 offset:5120
	ds_read_b128 v[202:205], v142 offset:6144
	ds_read_b128 v[206:209], v142 offset:7168
	global_load_lds_dwordx4 v[210:211], off
	v_lshl_add_u64 v[210:211], s[62:63], 0, v[136:137]
	s_mov_b32 m0, s43
	s_nop 0
	global_load_lds_dwordx4 v[210:211], off
	s_waitcnt vmcnt(8) lgkmcnt(0)
	s_setprio 1
	s_barrier
	v_mfma_f32_16x16x32_bf16 v[8:11], v[146:149], v[178:181], v[8:11]
	v_mfma_f32_16x16x32_bf16 v[12:15], v[154:157], v[178:181], v[12:15]
	v_mfma_f32_16x16x32_bf16 v[36:39], v[146:149], v[186:189], v[36:39]
	v_mfma_f32_16x16x32_bf16 v[32:35], v[154:157], v[186:189], v[32:35]
	v_mfma_f32_16x16x32_bf16 v[60:63], v[146:149], v[194:197], v[60:63]
	v_mfma_f32_16x16x32_bf16 v[56:59], v[154:157], v[194:197], v[56:59]
	v_mfma_f32_16x16x32_bf16 v[80:83], v[146:149], v[202:205], v[80:83]
	v_mfma_f32_16x16x32_bf16 v[72:75], v[154:157], v[202:205], v[72:75]
	v_mfma_f32_16x16x32_bf16 v[8:11], v[150:153], v[182:185], v[8:11]
	v_mfma_f32_16x16x32_bf16 v[12:15], v[158:161], v[182:185], v[12:15]
	v_mfma_f32_16x16x32_bf16 v[36:39], v[150:153], v[190:193], v[36:39]
	v_mfma_f32_16x16x32_bf16 v[32:35], v[158:161], v[190:193], v[32:35]
	v_mfma_f32_16x16x32_bf16 v[60:63], v[150:153], v[198:201], v[60:63]
	v_mfma_f32_16x16x32_bf16 v[56:59], v[158:161], v[198:201], v[56:59]
	v_mfma_f32_16x16x32_bf16 v[80:83], v[150:153], v[206:209], v[80:83]
	v_mfma_f32_16x16x32_bf16 v[72:75], v[158:161], v[206:209], v[72:75]
	v_mfma_f32_16x16x32_bf16 v[44:47], v[162:165], v[178:181], v[44:47]
	v_mfma_f32_16x16x32_bf16 v[40:43], v[170:173], v[178:181], v[40:43]
	v_mfma_f32_16x16x32_bf16 v[52:55], v[162:165], v[186:189], v[52:55]
	v_mfma_f32_16x16x32_bf16 v[48:51], v[170:173], v[186:189], v[48:51]
	v_mfma_f32_16x16x32_bf16 v[68:71], v[162:165], v[194:197], v[68:71]
	v_mfma_f32_16x16x32_bf16 v[64:67], v[170:173], v[194:197], v[64:67]
	v_mfma_f32_16x16x32_bf16 v[100:103], v[162:165], v[202:205], v[100:103]
	v_mfma_f32_16x16x32_bf16 v[96:99], v[170:173], v[202:205], v[96:99]
	v_mfma_f32_16x16x32_bf16 v[44:47], v[166:169], v[182:185], v[44:47]
	v_mfma_f32_16x16x32_bf16 v[40:43], v[174:177], v[182:185], v[40:43]
	v_mfma_f32_16x16x32_bf16 v[52:55], v[166:169], v[190:193], v[52:55]
	v_mfma_f32_16x16x32_bf16 v[48:51], v[174:177], v[190:193], v[48:51]
	v_mfma_f32_16x16x32_bf16 v[68:71], v[166:169], v[198:201], v[68:71]
	v_mfma_f32_16x16x32_bf16 v[64:67], v[174:177], v[198:201], v[64:67]
	v_mfma_f32_16x16x32_bf16 v[100:103], v[166:169], v[206:209], v[100:103]
	v_mfma_f32_16x16x32_bf16 v[96:99], v[174:177], v[206:209], v[96:99]
	s_barrier
	s_setprio 0
	s_mov_b32 m0, s44
	v_lshl_add_u64 v[210:211], s[70:71], 0, v[130:131]
	s_add_u32 s52, s70, 0x80000
	ds_read_b128 v[178:181], v142 offset:16384
	ds_read_b128 v[182:185], v142 offset:17408
	ds_read_b128 v[186:189], v142 offset:18432
	ds_read_b128 v[190:193], v142 offset:19456
	ds_read_b128 v[194:197], v142 offset:20480
	ds_read_b128 v[198:201], v142 offset:21504
	ds_read_b128 v[202:205], v142 offset:22528
	ds_read_b128 v[206:209], v142 offset:23552
	global_load_lds_dwordx4 v[210:211], off
	v_lshl_add_u64 v[212:213], s[70:71], 0, v[134:135]
	s_mov_b32 m0, s45
	s_addc_u32 s53, s71, 0
	global_load_lds_dwordx4 v[212:213], off
	v_lshl_add_u64 v[214:215], s[52:53], 0, v[130:131]
	s_mov_b32 m0, s46
	v_lshl_add_u64 v[216:217], s[72:73], 0, v[132:133]
	global_load_lds_dwordx4 v[214:215], off
	v_lshl_add_u64 v[214:215], s[52:53], 0, v[134:135]
	s_mov_b32 m0, s47
	s_nop 0
	global_load_lds_dwordx4 v[214:215], off
	v_lshl_add_u64 v[214:215], s[72:73], 0, v[128:129]
	s_mov_b32 m0, s14
	s_nop 0
	global_load_lds_dwordx4 v[214:215], off
	s_mov_b32 m0, s15
	s_nop 0
	global_load_lds_dwordx4 v[216:217], off
	s_waitcnt vmcnt(8) lgkmcnt(0)
	s_setprio 1
	s_barrier
	v_mfma_f32_16x16x32_bf16 v[108:111], v[146:149], v[178:181], v[108:111]
	v_mfma_f32_16x16x32_bf16 v[104:107], v[154:157], v[178:181], v[104:107]
	v_mfma_f32_16x16x32_bf16 v[124:127], v[146:149], v[186:189], v[124:127]
	v_mfma_f32_16x16x32_bf16 v[120:123], v[154:157], v[186:189], v[120:123]
	v_mfma_f32_16x16x32_bf16 v[84:87], v[146:149], v[194:197], v[84:87]
	v_mfma_f32_16x16x32_bf16 v[76:79], v[154:157], v[194:197], v[76:79]
	v_mfma_f32_16x16x32_bf16 v[20:23], v[146:149], v[202:205], v[20:23]
	v_mfma_f32_16x16x32_bf16 v[16:19], v[154:157], v[202:205], v[16:19]
	v_mfma_f32_16x16x32_bf16 v[108:111], v[150:153], v[182:185], v[108:111]
	v_mfma_f32_16x16x32_bf16 v[104:107], v[158:161], v[182:185], v[104:107]
	v_mfma_f32_16x16x32_bf16 v[124:127], v[150:153], v[190:193], v[124:127]
	v_mfma_f32_16x16x32_bf16 v[120:123], v[158:161], v[190:193], v[120:123]
	v_mfma_f32_16x16x32_bf16 v[84:87], v[150:153], v[198:201], v[84:87]
	v_mfma_f32_16x16x32_bf16 v[76:79], v[158:161], v[198:201], v[76:79]
	v_mfma_f32_16x16x32_bf16 v[20:23], v[150:153], v[206:209], v[20:23]
	v_mfma_f32_16x16x32_bf16 v[16:19], v[158:161], v[206:209], v[16:19]
	v_mfma_f32_16x16x32_bf16 v[116:119], v[162:165], v[178:181], v[116:119]
	v_mfma_f32_16x16x32_bf16 v[112:115], v[170:173], v[178:181], v[112:115]
	v_mfma_f32_16x16x32_bf16 v[92:95], v[162:165], v[186:189], v[92:95]
	v_mfma_f32_16x16x32_bf16 v[88:91], v[170:173], v[186:189], v[88:91]
	v_mfma_f32_16x16x32_bf16 v[28:31], v[162:165], v[194:197], v[28:31]
	v_mfma_f32_16x16x32_bf16 v[24:27], v[170:173], v[194:197], v[24:27]
	v_mfma_f32_16x16x32_bf16 v[4:7], v[162:165], v[202:205], v[4:7]
	v_mfma_f32_16x16x32_bf16 v[0:3], v[170:173], v[202:205], v[0:3]
	v_mfma_f32_16x16x32_bf16 v[116:119], v[166:169], v[182:185], v[116:119]
	v_mfma_f32_16x16x32_bf16 v[112:115], v[174:177], v[182:185], v[112:115]
	v_mfma_f32_16x16x32_bf16 v[92:95], v[166:169], v[190:193], v[92:95]
	v_mfma_f32_16x16x32_bf16 v[88:91], v[174:177], v[190:193], v[88:91]
	v_mfma_f32_16x16x32_bf16 v[28:31], v[166:169], v[198:201], v[28:31]
	v_mfma_f32_16x16x32_bf16 v[24:27], v[174:177], v[198:201], v[24:27]
	v_mfma_f32_16x16x32_bf16 v[4:7], v[166:169], v[206:209], v[4:7]
	v_mfma_f32_16x16x32_bf16 v[0:3], v[174:177], v[206:209], v[0:3]
	s_barrier
	s_setprio 0
	ds_read_b128 v[146:149], v143
	ds_read_b128 v[150:153], v143 offset:1024
	ds_read_b128 v[154:157], v143 offset:2048
	ds_read_b128 v[158:161], v143 offset:3072
	ds_read_b128 v[162:165], v144
	ds_read_b128 v[166:169], v144 offset:1024
	ds_read_b128 v[170:173], v144 offset:2048
	ds_read_b128 v[174:177], v144 offset:3072
	s_add_u32 s52, s72, 0x80000
	s_addc_u32 s53, s73, 0
	s_mov_b32 m0, s21
	v_lshl_add_u64 v[218:219], s[52:53], 0, v[128:129]
	ds_read_b128 v[178:181], v142 offset:32768
	ds_read_b128 v[182:185], v142 offset:33792
	ds_read_b128 v[186:189], v142 offset:34816
	ds_read_b128 v[190:193], v142 offset:35840
	ds_read_b128 v[194:197], v142 offset:36864
	ds_read_b128 v[198:201], v142 offset:37888
	ds_read_b128 v[202:205], v142 offset:38912
	ds_read_b128 v[206:209], v142 offset:39936
	global_load_lds_dwordx4 v[218:219], off
	v_lshl_add_u64 v[218:219], s[52:53], 0, v[132:133]
	s_mov_b32 m0, s22
	s_nop 0
	global_load_lds_dwordx4 v[218:219], off
	s_waitcnt vmcnt(8) lgkmcnt(0)
	s_setprio 1
	s_barrier
	v_mfma_f32_16x16x32_bf16 v[8:11], v[146:149], v[178:181], v[8:11]
	v_mfma_f32_16x16x32_bf16 v[12:15], v[154:157], v[178:181], v[12:15]
	v_mfma_f32_16x16x32_bf16 v[36:39], v[146:149], v[186:189], v[36:39]
	v_mfma_f32_16x16x32_bf16 v[32:35], v[154:157], v[186:189], v[32:35]
	v_mfma_f32_16x16x32_bf16 v[60:63], v[146:149], v[194:197], v[60:63]
	v_mfma_f32_16x16x32_bf16 v[56:59], v[154:157], v[194:197], v[56:59]
	v_mfma_f32_16x16x32_bf16 v[80:83], v[146:149], v[202:205], v[80:83]
	v_mfma_f32_16x16x32_bf16 v[72:75], v[154:157], v[202:205], v[72:75]
	v_mfma_f32_16x16x32_bf16 v[8:11], v[150:153], v[182:185], v[8:11]
	v_mfma_f32_16x16x32_bf16 v[12:15], v[158:161], v[182:185], v[12:15]
	v_mfma_f32_16x16x32_bf16 v[36:39], v[150:153], v[190:193], v[36:39]
	v_mfma_f32_16x16x32_bf16 v[32:35], v[158:161], v[190:193], v[32:35]
	v_mfma_f32_16x16x32_bf16 v[60:63], v[150:153], v[198:201], v[60:63]
	v_mfma_f32_16x16x32_bf16 v[56:59], v[158:161], v[198:201], v[56:59]
	v_mfma_f32_16x16x32_bf16 v[80:83], v[150:153], v[206:209], v[80:83]
	v_mfma_f32_16x16x32_bf16 v[72:75], v[158:161], v[206:209], v[72:75]
	v_mfma_f32_16x16x32_bf16 v[44:47], v[162:165], v[178:181], v[44:47]
	v_mfma_f32_16x16x32_bf16 v[40:43], v[170:173], v[178:181], v[40:43]
	v_mfma_f32_16x16x32_bf16 v[52:55], v[162:165], v[186:189], v[52:55]
	v_mfma_f32_16x16x32_bf16 v[48:51], v[170:173], v[186:189], v[48:51]
	v_mfma_f32_16x16x32_bf16 v[68:71], v[162:165], v[194:197], v[68:71]
	v_mfma_f32_16x16x32_bf16 v[64:67], v[170:173], v[194:197], v[64:67]
	v_mfma_f32_16x16x32_bf16 v[100:103], v[162:165], v[202:205], v[100:103]
	v_mfma_f32_16x16x32_bf16 v[96:99], v[170:173], v[202:205], v[96:99]
	v_mfma_f32_16x16x32_bf16 v[44:47], v[166:169], v[182:185], v[44:47]
	v_mfma_f32_16x16x32_bf16 v[40:43], v[174:177], v[182:185], v[40:43]
	v_mfma_f32_16x16x32_bf16 v[52:55], v[166:169], v[190:193], v[52:55]
	v_mfma_f32_16x16x32_bf16 v[48:51], v[174:177], v[190:193], v[48:51]
	v_mfma_f32_16x16x32_bf16 v[68:71], v[166:169], v[198:201], v[68:71]
	v_mfma_f32_16x16x32_bf16 v[64:67], v[174:177], v[198:201], v[64:67]
	v_mfma_f32_16x16x32_bf16 v[100:103], v[166:169], v[206:209], v[100:103]
	v_mfma_f32_16x16x32_bf16 v[96:99], v[174:177], v[206:209], v[96:99]
	s_barrier
; #define PG8_WAIT_V(n) asm volatile("s_waitcnt vmcnt(" #n ")" ::: "memory")
; #define PG8_BAR __builtin_amdgcn_s_barrier()
; template <class Epi, class Sched, bool ALIGN_EPI = false, bool SP2 = false, bool A_TILED = false>
; __device__ __forceinline__ void gemm_phase(PG8_LAS unsigned char* lds, const Gemm g, const Sched& S, const Epi& E, const int wave_s) {
;     ...
;     PG8_WAIT_V(0);
;     if constexpr (!ALIGN_EPI) { if (wr == 0) PG8_BAR; }
	s_setprio 0
	s_mov_b32 m0, s48
	v_lshl_add_u64 v[210:211], v[210:211], 0, s[66:67]
	s_add_u32 s52, s70, 0x80080
	ds_read_b128 v[178:181], v142 offset:49152
	ds_read_b128 v[182:185], v142 offset:50176
	ds_read_b128 v[186:189], v142 offset:51200
	ds_read_b128 v[190:193], v142 offset:52224
	ds_read_b128 v[194:197], v142 offset:53248
	ds_read_b128 v[198:201], v142 offset:54272
	ds_read_b128 v[202:205], v142 offset:55296
	ds_read_b128 v[206:209], v142 offset:56320
	global_load_lds_dwordx4 v[210:211], off
	v_lshl_add_u64 v[210:211], v[212:213], 0, s[66:67]
	s_mov_b32 m0, s49
	s_addc_u32 s53, s71, 0
	global_load_lds_dwordx4 v[210:211], off
	v_lshl_add_u64 v[210:211], s[52:53], 0, v[130:131]
	s_mov_b32 m0, s50
	s_nop 0
	global_load_lds_dwordx4 v[210:211], off
	v_lshl_add_u64 v[210:211], s[52:53], 0, v[134:135]
	s_mov_b32 m0, s51
	s_nop 0
	global_load_lds_dwordx4 v[210:211], off
	v_lshl_add_u64 v[210:211], v[214:215], 0, s[66:67]
	s_mov_b32 m0, s23
	s_nop 0
	global_load_lds_dwordx4 v[210:211], off
	v_lshl_add_u64 v[210:211], v[216:217], 0, s[66:67]
	s_mov_b32 m0, s36
	s_nop 0
	global_load_lds_dwordx4 v[210:211], off
	s_waitcnt vmcnt(8) lgkmcnt(0)
	s_setprio 1
	s_barrier
	v_mfma_f32_16x16x32_bf16 v[108:111], v[146:149], v[178:181], v[108:111]
	v_mfma_f32_16x16x32_bf16 v[104:107], v[154:157], v[178:181], v[104:107]
	v_mfma_f32_16x16x32_bf16 v[124:127], v[146:149], v[186:189], v[124:127]
	v_mfma_f32_16x16x32_bf16 v[120:123], v[154:157], v[186:189], v[120:123]
	v_mfma_f32_16x16x32_bf16 v[84:87], v[146:149], v[194:197], v[84:87]
	v_mfma_f32_16x16x32_bf16 v[76:79], v[154:157], v[194:197], v[76:79]
	v_mfma_f32_16x16x32_bf16 v[20:23], v[146:149], v[202:205], v[20:23]
	v_mfma_f32_16x16x32_bf16 v[16:19], v[154:157], v[202:205], v[16:19]
	v_mfma_f32_16x16x32_bf16 v[108:111], v[150:153], v[182:185], v[108:111]
	v_mfma_f32_16x16x32_bf16 v[104:107], v[158:161], v[182:185], v[104:107]
	v_mfma_f32_16x16x32_bf16 v[124:127], v[150:153], v[190:193], v[124:127]
	v_mfma_f32_16x16x32_bf16 v[120:123], v[158:161], v[190:193], v[120:123]
	v_mfma_f32_16x16x32_bf16 v[84:87], v[150:153], v[198:201], v[84:87]
	v_mfma_f32_16x16x32_bf16 v[76:79], v[158:161], v[198:201], v[76:79]
	v_mfma_f32_16x16x32_bf16 v[20:23], v[150:153], v[206:209], v[20:23]
	v_mfma_f32_16x16x32_bf16 v[16:19], v[158:161], v[206:209], v[16:19]
	v_mfma_f32_16x16x32_bf16 v[116:119], v[162:165], v[178:181], v[116:119]
	v_mfma_f32_16x16x32_bf16 v[112:115], v[170:173], v[178:181], v[112:115]
	v_mfma_f32_16x16x32_bf16 v[92:95], v[162:165], v[186:189], v[92:95]
	v_mfma_f32_16x16x32_bf16 v[88:91], v[170:173], v[186:189], v[88:91]
	v_mfma_f32_16x16x32_bf16 v[28:31], v[162:165], v[194:197], v[28:31]
	v_mfma_f32_16x16x32_bf16 v[24:27], v[170:173], v[194:197], v[24:27]
	v_mfma_f32_16x16x32_bf16 v[4:7], v[162:165], v[202:205], v[4:7]
	v_mfma_f32_16x16x32_bf16 v[0:3], v[170:173], v[202:205], v[0:3]
	v_mfma_f32_16x16x32_bf16 v[116:119], v[166:169], v[182:185], v[116:119]
	v_mfma_f32_16x16x32_bf16 v[112:115], v[174:177], v[182:185], v[112:115]
	v_mfma_f32_16x16x32_bf16 v[92:95], v[166:169], v[190:193], v[92:95]
	v_mfma_f32_16x16x32_bf16 v[88:91], v[174:177], v[190:193], v[88:91]
	v_mfma_f32_16x16x32_bf16 v[28:31], v[166:169], v[198:201], v[28:31]
	v_mfma_f32_16x16x32_bf16 v[24:27], v[174:177], v[198:201], v[24:27]
	v_mfma_f32_16x16x32_bf16 v[4:7], v[166:169], v[206:209], v[4:7]
	v_mfma_f32_16x16x32_bf16 v[0:3], v[174:177], v[206:209], v[0:3]
	s_barrier
	s_setprio 0
	s_add_i32 s41, s41, 2
	s_add_u32 s37, s37, 0x100
	s_addc_u32 s38, s38, 0
	s_add_u32 s39, s39, 0x100
	s_addc_u32 s40, s40, 0
	v_lshl_add_u64 v[136:137], v[136:137], 0, s[68:69]
	s_cmp_gt_u32 s41, 29
	v_lshl_add_u64 v[138:139], v[138:139], 0, s[68:69]
	s_cbranch_scc0 .LBB0_1043
	s_waitcnt vmcnt(0)
	s_cmpk_lt_u32 s6, 0x100
	s_cbranch_scc0 .LBB0_1046
	s_barrier

; template <class Epi, class Sched, bool ALIGN_EPI = false, bool SP2 = false, bool A_TILED = false>
; __device__ __forceinline__ void gemm_phase(PG8_LAS unsigned char* lds, const Gemm g, const Sched& S, const Epi& E, const int wave_s) {
;     ...
;         const bool has_next = Epi::AFTER_DRAIN ? false : S.next(ui + 1, nxt);
;         const char* nA = has_next ? (const char*)g.A + (size_t)nxt.pm * tstepA : cA; const char* nB = has_next ? (const char*)g.Bt + (size_t)nxt.pn * tstep : cB;
;         constexpr bool PEEL = SP2 && !Epi::AFTER_DRAIN;
;         if constexpr (PEEL) {
;             const char* a1 = cA + kstepA; const char* a2 = cA + 2 * kstepA; const char* b2 = cB + 2 * kstep; const char* a3 = a2 + kstepA; const char* b3 = b2 + kstep;
;             PG8_ITER(PG8_MMAZ)
.LBB0_1154:
	s_ashr_i32 s69, s68, 31
	s_lshl_b64 s[50:51], s[68:69], 20
	s_add_u32 s70, s7, s50
	ds_read_b128 v[0:3], v145
	ds_read_b128 v[4:7], v145 offset:1024
	ds_read_b128 v[8:11], v145 offset:2048
	ds_read_b128 v[12:15], v145 offset:3072
	ds_read_b128 v[16:19], v146
	ds_read_b128 v[20:23], v146 offset:1024
	ds_read_b128 v[24:27], v146 offset:2048
	ds_read_b128 v[28:31], v146 offset:3072
	s_addc_u32 s71, s8, s51
	s_ashr_i32 s67, s66, 31
	s_lshl_b64 s[50:51], s[66:67], 20
	s_add_u32 s72, s9, s50
	s_addc_u32 s73, s14, s51
	s_and_b64 s[50:51], s[0:1], exec
	s_cselect_b32 s50, s71, s79
	s_cselect_b32 s51, s70, s78
	s_cselect_b32 s52, s73, s77
	s_cselect_b32 s53, s72, s76
	s_add_u32 s56, s78, 0x80080
	s_addc_u32 s57, s79, 0
	s_add_i32 s54, s22, 0xc000
	v_lshl_add_u64 v[64:65], s[56:57], 0, v[134:135]
	s_mov_b32 m0, s54
	s_add_i32 s55, s22, 0xe000
	ds_read_b128 v[32:35], v147
	ds_read_b128 v[36:39], v147 offset:1024
	ds_read_b128 v[40:43], v147 offset:2048
	ds_read_b128 v[44:47], v147 offset:3072
	ds_read_b128 v[48:51], v147 offset:4096
	ds_read_b128 v[52:55], v147 offset:5120
	ds_read_b128 v[56:59], v147 offset:6144
	ds_read_b128 v[60:63], v147 offset:7168
	global_load_lds_dwordx4 v[64:65], off
	v_lshl_add_u64 v[64:65], s[56:57], 0, v[132:133]
	s_mov_b32 m0, s55
	s_nop 0
	global_load_lds_dwordx4 v[64:65], off
	s_waitcnt vmcnt(8) lgkmcnt(0)
	s_setprio 1
	s_barrier
	v_mfma_f32_16x16x32_bf16 v[88:91], v[0:3], v[56:59], 0
	v_mfma_f32_16x16x32_bf16 v[64:67], v[0:3], v[32:35], 0
	v_mfma_f32_16x16x32_bf16 v[68:71], v[8:11], v[32:35], 0
	v_mfma_f32_16x16x32_bf16 v[72:75], v[0:3], v[40:43], 0
	v_mfma_f32_16x16x32_bf16 v[76:79], v[8:11], v[40:43], 0
	v_mfma_f32_16x16x32_bf16 v[80:83], v[0:3], v[48:51], 0
	v_mfma_f32_16x16x32_bf16 v[84:87], v[8:11], v[48:51], 0
	v_mfma_f32_16x16x32_bf16 v[96:99], v[4:7], v[60:63], v[88:91]
	v_mfma_f32_16x16x32_bf16 v[88:91], v[8:11], v[56:59], 0
	v_mfma_f32_16x16x32_bf16 v[64:67], v[4:7], v[36:39], v[64:67]
	v_mfma_f32_16x16x32_bf16 v[68:71], v[12:15], v[36:39], v[68:71]
	v_mfma_f32_16x16x32_bf16 v[72:75], v[4:7], v[44:47], v[72:75]
	v_mfma_f32_16x16x32_bf16 v[76:79], v[12:15], v[44:47], v[76:79]
	v_mfma_f32_16x16x32_bf16 v[80:83], v[4:7], v[52:55], v[80:83]
	v_mfma_f32_16x16x32_bf16 v[84:87], v[12:15], v[52:55], v[84:87]
	v_mfma_f32_16x16x32_bf16 v[100:103], v[12:15], v[60:63], v[88:91]
	v_mfma_f32_16x16x32_bf16 v[88:91], v[16:19], v[32:35], 0
	v_mfma_f32_16x16x32_bf16 v[32:35], v[24:27], v[32:35], 0
	v_mfma_f32_16x16x32_bf16 v[112:115], v[20:23], v[36:39], v[88:91]
	v_mfma_f32_16x16x32_bf16 v[32:35], v[28:31], v[36:39], v[32:35]
	v_mfma_f32_16x16x32_bf16 v[36:39], v[16:19], v[40:43], 0
	v_mfma_f32_16x16x32_bf16 v[40:43], v[24:27], v[40:43], 0
	v_mfma_f32_16x16x32_bf16 v[36:39], v[20:23], v[44:47], v[36:39]
	v_mfma_f32_16x16x32_bf16 v[40:43], v[28:31], v[44:47], v[40:43]
	v_mfma_f32_16x16x32_bf16 v[44:47], v[16:19], v[48:51], 0
	v_mfma_f32_16x16x32_bf16 v[48:51], v[24:27], v[48:51], 0
	v_mfma_f32_16x16x32_bf16 v[44:47], v[20:23], v[52:55], v[44:47]
	v_mfma_f32_16x16x32_bf16 v[48:51], v[28:31], v[52:55], v[48:51]
	v_mfma_f32_16x16x32_bf16 v[52:55], v[16:19], v[56:59], 0
	v_mfma_f32_16x16x32_bf16 v[56:59], v[24:27], v[56:59], 0
	v_mfma_f32_16x16x32_bf16 v[52:55], v[20:23], v[60:63], v[52:55]
	v_mfma_f32_16x16x32_bf16 v[56:59], v[28:31], v[60:63], v[56:59]
	s_barrier
	s_setprio 0
	s_add_i32 s56, s47, s15
	v_lshl_add_u64 v[242:243], s[76:77], 0, v[128:129]
	s_add_i32 s57, s56, 0x2000
	v_lshl_add_u64 v[148:149], v[242:243], 0, s[62:63]
	s_mov_b32 m0, s56
	v_lshl_add_u64 v[244:245], s[76:77], 0, v[130:131]
	s_add_u32 s80, s76, 0x80100
	ds_read_b128 v[60:63], v147 offset:16384
	ds_read_b128 v[88:91], v147 offset:17408
	ds_read_b128 v[92:95], v147 offset:18432
	ds_read_b128 v[104:107], v147 offset:19456
	ds_read_b128 v[108:111], v147 offset:20480
	ds_read_b128 v[116:119], v147 offset:21504
	ds_read_b128 v[120:123], v147 offset:22528
	ds_read_b128 v[124:127], v147 offset:23552
	global_load_lds_dwordx4 v[148:149], off
	v_lshl_add_u64 v[148:149], v[244:245], 0, s[62:63]
	s_mov_b32 m0, s57
	s_addc_u32 s81, s77, 0
	s_add_i32 s58, s48, s15
	global_load_lds_dwordx4 v[148:149], off
	v_lshl_add_u64 v[148:149], s[80:81], 0, v[128:129]
	s_mov_b32 m0, s58
	s_add_i32 s59, s58, 0x2000
	global_load_lds_dwordx4 v[148:149], off
	v_lshl_add_u64 v[148:149], s[80:81], 0, v[130:131]
	s_mov_b32 m0, s59
	v_lshl_add_u64 v[246:247], s[78:79], 0, v[134:135]
	global_load_lds_dwordx4 v[148:149], off
	v_lshl_add_u64 v[148:149], v[246:247], 0, s[62:63]
	s_mov_b32 m0, s22
	v_lshl_add_u64 v[248:249], s[78:79], 0, v[132:133]
	global_load_lds_dwordx4 v[148:149], off
	v_lshl_add_u64 v[148:149], v[248:249], 0, s[62:63]
	s_mov_b32 m0, s23
	s_nop 0
	global_load_lds_dwordx4 v[148:149], off
	s_waitcnt vmcnt(8) lgkmcnt(0)
	s_setprio 1
	s_barrier
	v_mfma_f32_16x16x32_bf16 v[148:151], v[0:3], v[60:63], 0
	v_mfma_f32_16x16x32_bf16 v[158:161], v[0:3], v[92:95], 0
	v_mfma_f32_16x16x32_bf16 v[166:169], v[0:3], v[108:111], 0
	v_mfma_f32_16x16x32_bf16 v[0:3], v[0:3], v[120:123], 0
	v_mfma_f32_16x16x32_bf16 v[150:153], v[4:7], v[88:91], v[148:151]
	v_mfma_f32_16x16x32_bf16 v[158:161], v[4:7], v[104:107], v[158:161]
	v_mfma_f32_16x16x32_bf16 v[166:169], v[4:7], v[116:119], v[166:169]
	v_mfma_f32_16x16x32_bf16 v[0:3], v[4:7], v[124:127], v[0:3]
	v_mfma_f32_16x16x32_bf16 v[4:7], v[8:11], v[120:123], 0
	v_mfma_f32_16x16x32_bf16 v[154:157], v[8:11], v[60:63], 0
	v_mfma_f32_16x16x32_bf16 v[162:165], v[8:11], v[92:95], 0
	v_mfma_f32_16x16x32_bf16 v[170:173], v[8:11], v[108:111], 0
	v_mfma_f32_16x16x32_bf16 v[4:7], v[12:15], v[124:127], v[4:7]
	v_mfma_f32_16x16x32_bf16 v[154:157], v[12:15], v[88:91], v[154:157]
	v_mfma_f32_16x16x32_bf16 v[162:165], v[12:15], v[104:107], v[162:165]
	v_mfma_f32_16x16x32_bf16 v[170:173], v[12:15], v[116:119], v[170:173]
	v_mfma_f32_16x16x32_bf16 v[8:11], v[16:19], v[60:63], 0
	v_mfma_f32_16x16x32_bf16 v[174:177], v[20:23], v[88:91], v[8:11]
	v_mfma_f32_16x16x32_bf16 v[8:11], v[24:27], v[60:63], 0
	v_mfma_f32_16x16x32_bf16 v[60:63], v[28:31], v[88:91], v[8:11]
	v_mfma_f32_16x16x32_bf16 v[8:11], v[16:19], v[92:95], 0
	v_mfma_f32_16x16x32_bf16 v[178:181], v[20:23], v[104:107], v[8:11]
	v_mfma_f32_16x16x32_bf16 v[8:11], v[24:27], v[92:95], 0
	v_mfma_f32_16x16x32_bf16 v[182:185], v[28:31], v[104:107], v[8:11]
	v_mfma_f32_16x16x32_bf16 v[8:11], v[16:19], v[108:111], 0
	v_mfma_f32_16x16x32_bf16 v[186:189], v[20:23], v[116:119], v[8:11]
	v_mfma_f32_16x16x32_bf16 v[8:11], v[24:27], v[108:111], 0
	v_mfma_f32_16x16x32_bf16 v[190:193], v[28:31], v[116:119], v[8:11]
	v_mfma_f32_16x16x32_bf16 v[8:11], v[16:19], v[120:123], 0
	v_mfma_f32_16x16x32_bf16 v[194:197], v[20:23], v[124:127], v[8:11]
	v_mfma_f32_16x16x32_bf16 v[8:11], v[24:27], v[120:123], 0
	v_mfma_f32_16x16x32_bf16 v[198:201], v[28:31], v[124:127], v[8:11]
	s_barrier
	s_setprio 0
	s_add_i32 s67, 0, 0x18000
	s_add_i32 s75, 0, 0x1c000
	v_add_u32_e32 v148, s67, v144
	v_add_u32_e32 v149, s75, v144
	s_nop 0
	ds_read_b128 v[8:11], v148
	ds_read_b128 v[12:15], v148 offset:1024
	ds_read_b128 v[16:19], v148 offset:2048
	ds_read_b128 v[20:23], v148 offset:3072
	ds_read_b128 v[202:205], v149
	ds_read_b128 v[206:209], v149 offset:1024
	ds_read_b128 v[210:213], v149 offset:2048
	ds_read_b128 v[214:217], v149 offset:3072
	s_add_u32 s80, s78, 0x80100
	s_addc_u32 s81, s79, 0
	s_mov_b32 m0, s36
	v_lshl_add_u64 v[88:89], s[80:81], 0, v[134:135]
	ds_read_b128 v[24:27], v147 offset:32768
	ds_read_b128 v[28:31], v147 offset:33792
	ds_read_b128 v[218:221], v147 offset:34816
	ds_read_b128 v[222:225], v147 offset:35840
	ds_read_b128 v[226:229], v147 offset:36864
	ds_read_b128 v[230:233], v147 offset:37888
	ds_read_b128 v[234:237], v147 offset:38912
	ds_read_b128 v[238:241], v147 offset:39936
	global_load_lds_dwordx4 v[88:89], off
	v_lshl_add_u64 v[88:89], s[80:81], 0, v[132:133]
	s_mov_b32 m0, s37
	s_nop 0
	global_load_lds_dwordx4 v[88:89], off
	s_waitcnt vmcnt(8) lgkmcnt(0)
	s_setprio 1
	s_barrier
	v_mfma_f32_16x16x32_bf16 v[64:67], v[8:11], v[24:27], v[64:67]
	v_mfma_f32_16x16x32_bf16 v[120:123], v[12:15], v[28:31], v[64:67]
	v_mfma_f32_16x16x32_bf16 v[64:67], v[16:19], v[24:27], v[68:71]
	v_mfma_f32_16x16x32_bf16 v[124:127], v[20:23], v[28:31], v[64:67]
	v_mfma_f32_16x16x32_bf16 v[64:67], v[8:11], v[218:221], v[72:75]
	v_mfma_f32_16x16x32_bf16 v[104:107], v[12:15], v[222:225], v[64:67]
	v_mfma_f32_16x16x32_bf16 v[64:67], v[16:19], v[218:221], v[76:79]
	v_mfma_f32_16x16x32_bf16 v[108:111], v[20:23], v[222:225], v[64:67]
	v_mfma_f32_16x16x32_bf16 v[64:67], v[8:11], v[226:229], v[80:83]
	v_mfma_f32_16x16x32_bf16 v[88:91], v[12:15], v[230:233], v[64:67]
	v_mfma_f32_16x16x32_bf16 v[64:67], v[16:19], v[226:229], v[84:87]
	v_mfma_f32_16x16x32_bf16 v[92:95], v[20:23], v[230:233], v[64:67]
	v_mfma_f32_16x16x32_bf16 v[64:67], v[8:11], v[234:237], v[96:99]
	v_mfma_f32_16x16x32_bf16 v[68:71], v[16:19], v[234:237], v[100:103]
	v_mfma_f32_16x16x32_bf16 v[64:67], v[12:15], v[238:241], v[64:67]
	v_mfma_f32_16x16x32_bf16 v[68:71], v[20:23], v[238:241], v[68:71]
	v_mfma_f32_16x16x32_bf16 v[72:75], v[202:205], v[24:27], v[112:115]
	v_mfma_f32_16x16x32_bf16 v[24:27], v[210:213], v[24:27], v[32:35]
	v_mfma_f32_16x16x32_bf16 v[116:119], v[214:217], v[28:31], v[24:27]
	v_mfma_f32_16x16x32_bf16 v[24:27], v[202:205], v[218:221], v[36:39]
	v_mfma_f32_16x16x32_bf16 v[96:99], v[206:209], v[222:225], v[24:27]
	v_mfma_f32_16x16x32_bf16 v[24:27], v[210:213], v[218:221], v[40:43]
	v_mfma_f32_16x16x32_bf16 v[100:103], v[214:217], v[222:225], v[24:27]
	v_mfma_f32_16x16x32_bf16 v[24:27], v[202:205], v[226:229], v[44:47]
	v_mfma_f32_16x16x32_bf16 v[80:83], v[206:209], v[230:233], v[24:27]
	v_mfma_f32_16x16x32_bf16 v[24:27], v[210:213], v[226:229], v[48:51]
	v_mfma_f32_16x16x32_bf16 v[84:87], v[214:217], v[230:233], v[24:27]
	v_mfma_f32_16x16x32_bf16 v[24:27], v[202:205], v[234:237], v[52:55]
	v_mfma_f32_16x16x32_bf16 v[48:51], v[206:209], v[238:241], v[24:27]
	v_mfma_f32_16x16x32_bf16 v[24:27], v[210:213], v[234:237], v[56:59]
	v_mfma_f32_16x16x32_bf16 v[112:115], v[206:209], v[28:31], v[72:75]
	v_mfma_f32_16x16x32_bf16 v[52:55], v[214:217], v[238:241], v[24:27]
	s_barrier
; template <class Epi, class Sched, bool ALIGN_EPI = false, bool SP2 = false, bool A_TILED = false>
; __device__ __forceinline__ void gemm_phase(PG8_LAS unsigned char* lds, const Gemm g, const Sched& S, const Epi& E, const int wave_s) {
;     ...
;         for (int t = PEEL ? 2 : 0; t < nt; t += 2) {
;             const bool last = (t == nt - 2);
;             const char* a1 = cA + (size_t)(t + 1) * kstepA;
;             const char* a2 = last ? nA : cA + (size_t)(t + 2) * kstepA; const char* b2 = last ? nB : cB + (size_t)(t + 2) * kstep;
;             const char* a3 = a2 + kstepA; const char* b3 = b2 + kstep;
	s_setprio 0
	s_add_i32 s67, s67, s15
	s_add_i32 s69, s67, 0x2000
	s_nop 1
	v_lshl_add_u64 v[24:25], v[242:243], 0, s[64:65]
	s_mov_b32 m0, s67
	s_add_u32 s80, s76, 0x80180
	ds_read_b128 v[32:35], v147 offset:49152
	ds_read_b128 v[36:39], v147 offset:50176
	ds_read_b128 v[218:221], v147 offset:51200
	ds_read_b128 v[222:225], v147 offset:52224
	ds_read_b128 v[226:229], v147 offset:53248
	ds_read_b128 v[230:233], v147 offset:54272
	ds_read_b128 v[234:237], v147 offset:55296
	ds_read_b128 v[238:241], v147 offset:56320
	global_load_lds_dwordx4 v[24:25], off
	v_lshl_add_u64 v[24:25], v[244:245], 0, s[64:65]
	s_mov_b32 m0, s69
	s_addc_u32 s81, s77, 0
	s_add_i32 s75, s75, s15
	global_load_lds_dwordx4 v[24:25], off
	v_lshl_add_u64 v[24:25], s[80:81], 0, v[128:129]
	s_mov_b32 m0, s75
	s_add_i32 s82, s75, 0x2000
	global_load_lds_dwordx4 v[24:25], off
	v_lshl_add_u64 v[24:25], s[80:81], 0, v[130:131]
	s_mov_b32 m0, s82
	s_nop 0
	global_load_lds_dwordx4 v[24:25], off
	v_lshl_add_u64 v[24:25], v[246:247], 0, s[64:65]
	s_mov_b32 m0, s43
	s_nop 0
	global_load_lds_dwordx4 v[24:25], off
	v_lshl_add_u64 v[24:25], v[248:249], 0, s[64:65]
	s_mov_b32 m0, s44
	s_nop 0
	global_load_lds_dwordx4 v[24:25], off
	s_waitcnt vmcnt(8) lgkmcnt(0)
	s_setprio 1
	s_barrier
	v_mfma_f32_16x16x32_bf16 v[24:27], v[8:11], v[32:35], v[150:153]
	v_mfma_f32_16x16x32_bf16 v[72:75], v[12:15], v[36:39], v[24:27]
	v_mfma_f32_16x16x32_bf16 v[24:27], v[16:19], v[32:35], v[154:157]
	v_mfma_f32_16x16x32_bf16 v[76:79], v[20:23], v[36:39], v[24:27]
	v_mfma_f32_16x16x32_bf16 v[24:27], v[8:11], v[218:221], v[158:161]
	v_mfma_f32_16x16x32_bf16 v[40:43], v[12:15], v[222:225], v[24:27]
	v_mfma_f32_16x16x32_bf16 v[24:27], v[16:19], v[218:221], v[162:165]
	v_mfma_f32_16x16x32_bf16 v[0:3], v[8:11], v[234:237], v[0:3]
	v_mfma_f32_16x16x32_bf16 v[44:47], v[20:23], v[222:225], v[24:27]
	v_mfma_f32_16x16x32_bf16 v[24:27], v[8:11], v[226:229], v[166:169]
	v_mfma_f32_16x16x32_bf16 v[28:31], v[16:19], v[226:229], v[170:173]
	v_mfma_f32_16x16x32_bf16 v[8:11], v[12:15], v[238:241], v[0:3]
	v_mfma_f32_16x16x32_bf16 v[0:3], v[16:19], v[234:237], v[4:7]
	v_mfma_f32_16x16x32_bf16 v[24:27], v[12:15], v[230:233], v[24:27]
	v_mfma_f32_16x16x32_bf16 v[28:31], v[20:23], v[230:233], v[28:31]
	v_mfma_f32_16x16x32_bf16 v[12:15], v[20:23], v[238:241], v[0:3]
	v_mfma_f32_16x16x32_bf16 v[0:3], v[202:205], v[32:35], v[174:177]
	v_mfma_f32_16x16x32_bf16 v[56:59], v[206:209], v[36:39], v[0:3]
	v_mfma_f32_16x16x32_bf16 v[0:3], v[210:213], v[32:35], v[60:63]
	v_mfma_f32_16x16x32_bf16 v[60:63], v[214:217], v[36:39], v[0:3]
	v_mfma_f32_16x16x32_bf16 v[0:3], v[202:205], v[218:221], v[178:181]
	v_mfma_f32_16x16x32_bf16 v[32:35], v[206:209], v[222:225], v[0:3]
	v_mfma_f32_16x16x32_bf16 v[0:3], v[210:213], v[218:221], v[182:185]
	v_mfma_f32_16x16x32_bf16 v[36:39], v[214:217], v[222:225], v[0:3]
	v_mfma_f32_16x16x32_bf16 v[0:3], v[202:205], v[226:229], v[186:189]
	v_mfma_f32_16x16x32_bf16 v[16:19], v[206:209], v[230:233], v[0:3]
	v_mfma_f32_16x16x32_bf16 v[0:3], v[210:213], v[226:229], v[190:193]
	v_mfma_f32_16x16x32_bf16 v[20:23], v[214:217], v[230:233], v[0:3]
	v_mfma_f32_16x16x32_bf16 v[0:3], v[202:205], v[234:237], v[194:197]
	v_mfma_f32_16x16x32_bf16 v[4:7], v[210:213], v[234:237], v[198:201]
	v_mfma_f32_16x16x32_bf16 v[0:3], v[206:209], v[238:241], v[0:3]
	v_mfma_f32_16x16x32_bf16 v[4:7], v[214:217], v[238:241], v[4:7]
	s_barrier
	s_setprio 0
	s_add_u32 s83, s76, 0x200
	s_addc_u32 s84, s77, 0
	s_add_u32 s76, s78, 0x80180
	s_addc_u32 s77, s79, 0
	s_mov_b32 s85, 0
.LBB0_1155:
	ds_read_b128 v[150:153], v145
	ds_read_b128 v[154:157], v145 offset:1024
	ds_read_b128 v[158:161], v145 offset:2048
	ds_read_b128 v[162:165], v145 offset:3072
	ds_read_b128 v[166:169], v146
	ds_read_b128 v[170:173], v146 offset:1024
	ds_read_b128 v[174:177], v146 offset:2048
	ds_read_b128 v[178:181], v146 offset:3072
	s_add_u32 s78, s76, 0xfff80080
	s_addc_u32 s79, s77, -1
	s_cmp_eq_u32 s85, 28
	s_cselect_b32 s81, s50, s79
	s_cselect_b32 s80, s51, s78
	s_cselect_b32 s79, s52, s84
	s_cselect_b32 s78, s53, s83
	s_mov_b32 m0, s54
	v_lshl_add_u64 v[214:215], s[76:77], 0, v[138:139]
	ds_read_b128 v[182:185], v147
	ds_read_b128 v[186:189], v147 offset:1024
	ds_read_b128 v[190:193], v147 offset:2048
	ds_read_b128 v[194:197], v147 offset:3072
	ds_read_b128 v[198:201], v147 offset:4096
	ds_read_b128 v[202:205], v147 offset:5120
	ds_read_b128 v[206:209], v147 offset:6144
	ds_read_b128 v[210:213], v147 offset:7168
	global_load_lds_dwordx4 v[214:215], off
	v_lshl_add_u64 v[214:215], s[76:77], 0, v[136:137]
	s_mov_b32 m0, s55
	s_nop 0
	global_load_lds_dwordx4 v[214:215], off
	s_waitcnt vmcnt(8) lgkmcnt(0)
	s_setprio 1
	s_barrier
	v_mfma_f32_16x16x32_bf16 v[120:123], v[150:153], v[182:185], v[120:123]
	v_mfma_f32_16x16x32_bf16 v[124:127], v[158:161], v[182:185], v[124:127]
	v_mfma_f32_16x16x32_bf16 v[104:107], v[150:153], v[190:193], v[104:107]
	v_mfma_f32_16x16x32_bf16 v[108:111], v[158:161], v[190:193], v[108:111]
	v_mfma_f32_16x16x32_bf16 v[88:91], v[150:153], v[198:201], v[88:91]
	v_mfma_f32_16x16x32_bf16 v[92:95], v[158:161], v[198:201], v[92:95]
	v_mfma_f32_16x16x32_bf16 v[64:67], v[150:153], v[206:209], v[64:67]
	v_mfma_f32_16x16x32_bf16 v[68:71], v[158:161], v[206:209], v[68:71]
	v_mfma_f32_16x16x32_bf16 v[120:123], v[154:157], v[186:189], v[120:123]
	v_mfma_f32_16x16x32_bf16 v[124:127], v[162:165], v[186:189], v[124:127]
	v_mfma_f32_16x16x32_bf16 v[104:107], v[154:157], v[194:197], v[104:107]
	v_mfma_f32_16x16x32_bf16 v[108:111], v[162:165], v[194:197], v[108:111]
	v_mfma_f32_16x16x32_bf16 v[88:91], v[154:157], v[202:205], v[88:91]
	v_mfma_f32_16x16x32_bf16 v[92:95], v[162:165], v[202:205], v[92:95]
	v_mfma_f32_16x16x32_bf16 v[64:67], v[154:157], v[210:213], v[64:67]
	v_mfma_f32_16x16x32_bf16 v[68:71], v[162:165], v[210:213], v[68:71]
	v_mfma_f32_16x16x32_bf16 v[112:115], v[166:169], v[182:185], v[112:115]
	v_mfma_f32_16x16x32_bf16 v[116:119], v[174:177], v[182:185], v[116:119]
	v_mfma_f32_16x16x32_bf16 v[96:99], v[166:169], v[190:193], v[96:99]
	v_mfma_f32_16x16x32_bf16 v[100:103], v[174:177], v[190:193], v[100:103]
	v_mfma_f32_16x16x32_bf16 v[80:83], v[166:169], v[198:201], v[80:83]
	v_mfma_f32_16x16x32_bf16 v[84:87], v[174:177], v[198:201], v[84:87]
	v_mfma_f32_16x16x32_bf16 v[48:51], v[166:169], v[206:209], v[48:51]
	v_mfma_f32_16x16x32_bf16 v[52:55], v[174:177], v[206:209], v[52:55]
	v_mfma_f32_16x16x32_bf16 v[112:115], v[170:173], v[186:189], v[112:115]
	v_mfma_f32_16x16x32_bf16 v[116:119], v[178:181], v[186:189], v[116:119]
	v_mfma_f32_16x16x32_bf16 v[96:99], v[170:173], v[194:197], v[96:99]
	v_mfma_f32_16x16x32_bf16 v[100:103], v[178:181], v[194:197], v[100:103]
	v_mfma_f32_16x16x32_bf16 v[80:83], v[170:173], v[202:205], v[80:83]
	v_mfma_f32_16x16x32_bf16 v[84:87], v[178:181], v[202:205], v[84:87]
	v_mfma_f32_16x16x32_bf16 v[48:51], v[170:173], v[210:213], v[48:51]
	v_mfma_f32_16x16x32_bf16 v[52:55], v[178:181], v[210:213], v[52:55]
	s_barrier
	s_setprio 0
	s_mov_b32 m0, s56
	v_lshl_add_u64 v[214:215], s[78:79], 0, v[128:129]
	s_add_u32 s88, s78, 0x80000
	ds_read_b128 v[182:185], v147 offset:16384
	ds_read_b128 v[186:189], v147 offset:17408
	ds_read_b128 v[190:193], v147 offset:18432
	ds_read_b128 v[194:197], v147 offset:19456
	ds_read_b128 v[198:201], v147 offset:20480
	ds_read_b128 v[202:205], v147 offset:21504
	ds_read_b128 v[206:209], v147 offset:22528
	ds_read_b128 v[210:213], v147 offset:23552
	global_load_lds_dwordx4 v[214:215], off
	v_lshl_add_u64 v[216:217], s[78:79], 0, v[130:131]
	s_mov_b32 m0, s57
	s_addc_u32 s89, s79, 0
	global_load_lds_dwordx4 v[216:217], off
	v_lshl_add_u64 v[218:219], s[88:89], 0, v[128:129]
	s_mov_b32 m0, s58
	v_lshl_add_u64 v[220:221], s[80:81], 0, v[132:133]
	global_load_lds_dwordx4 v[218:219], off
	v_lshl_add_u64 v[218:219], s[88:89], 0, v[130:131]
	s_mov_b32 m0, s59
	s_nop 0
	global_load_lds_dwordx4 v[218:219], off
	v_lshl_add_u64 v[218:219], s[80:81], 0, v[134:135]
	s_mov_b32 m0, s22
	s_nop 0
	global_load_lds_dwordx4 v[218:219], off
	s_mov_b32 m0, s23
	s_nop 0
	global_load_lds_dwordx4 v[220:221], off
	s_waitcnt vmcnt(8) lgkmcnt(0)
	s_setprio 1
	s_barrier
	v_mfma_f32_16x16x32_bf16 v[72:75], v[150:153], v[182:185], v[72:75]
	v_mfma_f32_16x16x32_bf16 v[76:79], v[158:161], v[182:185], v[76:79]
	v_mfma_f32_16x16x32_bf16 v[40:43], v[150:153], v[190:193], v[40:43]
	v_mfma_f32_16x16x32_bf16 v[44:47], v[158:161], v[190:193], v[44:47]
	v_mfma_f32_16x16x32_bf16 v[24:27], v[150:153], v[198:201], v[24:27]
	v_mfma_f32_16x16x32_bf16 v[28:31], v[158:161], v[198:201], v[28:31]
	v_mfma_f32_16x16x32_bf16 v[8:11], v[150:153], v[206:209], v[8:11]
	v_mfma_f32_16x16x32_bf16 v[12:15], v[158:161], v[206:209], v[12:15]
	v_mfma_f32_16x16x32_bf16 v[72:75], v[154:157], v[186:189], v[72:75]
	v_mfma_f32_16x16x32_bf16 v[76:79], v[162:165], v[186:189], v[76:79]
	v_mfma_f32_16x16x32_bf16 v[40:43], v[154:157], v[194:197], v[40:43]
	v_mfma_f32_16x16x32_bf16 v[44:47], v[162:165], v[194:197], v[44:47]
	v_mfma_f32_16x16x32_bf16 v[24:27], v[154:157], v[202:205], v[24:27]
	v_mfma_f32_16x16x32_bf16 v[28:31], v[162:165], v[202:205], v[28:31]
	v_mfma_f32_16x16x32_bf16 v[8:11], v[154:157], v[210:213], v[8:11]
	v_mfma_f32_16x16x32_bf16 v[12:15], v[162:165], v[210:213], v[12:15]
	v_mfma_f32_16x16x32_bf16 v[56:59], v[166:169], v[182:185], v[56:59]
	v_mfma_f32_16x16x32_bf16 v[60:63], v[174:177], v[182:185], v[60:63]
	v_mfma_f32_16x16x32_bf16 v[32:35], v[166:169], v[190:193], v[32:35]
	v_mfma_f32_16x16x32_bf16 v[36:39], v[174:177], v[190:193], v[36:39]
	v_mfma_f32_16x16x32_bf16 v[16:19], v[166:169], v[198:201], v[16:19]
	v_mfma_f32_16x16x32_bf16 v[20:23], v[174:177], v[198:201], v[20:23]
	v_mfma_f32_16x16x32_bf16 v[0:3], v[166:169], v[206:209], v[0:3]
	v_mfma_f32_16x16x32_bf16 v[4:7], v[174:177], v[206:209], v[4:7]
	v_mfma_f32_16x16x32_bf16 v[56:59], v[170:173], v[186:189], v[56:59]
	v_mfma_f32_16x16x32_bf16 v[60:63], v[178:181], v[186:189], v[60:63]
	v_mfma_f32_16x16x32_bf16 v[32:35], v[170:173], v[194:197], v[32:35]
	v_mfma_f32_16x16x32_bf16 v[36:39], v[178:181], v[194:197], v[36:39]
	v_mfma_f32_16x16x32_bf16 v[16:19], v[170:173], v[202:205], v[16:19]
	v_mfma_f32_16x16x32_bf16 v[20:23], v[178:181], v[202:205], v[20:23]
	v_mfma_f32_16x16x32_bf16 v[0:3], v[170:173], v[210:213], v[0:3]
	v_mfma_f32_16x16x32_bf16 v[4:7], v[178:181], v[210:213], v[4:7]
	s_barrier
; #define PG8_BAR __builtin_amdgcn_s_barrier()
; template <class Epi, class Sched, bool ALIGN_EPI = false, bool SP2 = false, bool A_TILED = false>
; __device__ __forceinline__ void gemm_phase(PG8_LAS unsigned char* lds, const Gemm g, const Sched& S, const Epi& E, const int wave_s) {
;     ...
;         if constexpr (ALIGN_EPI) { if (wr == 0) PG8_BAR; }
	s_setprio 0
	ds_read_b128 v[150:153], v148
	ds_read_b128 v[154:157], v148 offset:1024
	ds_read_b128 v[158:161], v148 offset:2048
	ds_read_b128 v[162:165], v148 offset:3072
	ds_read_b128 v[166:169], v149
	ds_read_b128 v[170:173], v149 offset:1024
	ds_read_b128 v[174:177], v149 offset:2048
	ds_read_b128 v[178:181], v149 offset:3072
	s_add_u32 s80, s80, 0x80000
	s_addc_u32 s81, s81, 0
	s_mov_b32 m0, s36
	v_lshl_add_u64 v[222:223], s[80:81], 0, v[134:135]
	ds_read_b128 v[182:185], v147 offset:32768
	ds_read_b128 v[186:189], v147 offset:33792
	ds_read_b128 v[190:193], v147 offset:34816
	ds_read_b128 v[194:197], v147 offset:35840
	ds_read_b128 v[198:201], v147 offset:36864
	ds_read_b128 v[202:205], v147 offset:37888
	ds_read_b128 v[206:209], v147 offset:38912
	ds_read_b128 v[210:213], v147 offset:39936
	global_load_lds_dwordx4 v[222:223], off
	v_lshl_add_u64 v[222:223], s[80:81], 0, v[132:133]
	s_mov_b32 m0, s37
	s_nop 0
	global_load_lds_dwordx4 v[222:223], off
	s_waitcnt vmcnt(8) lgkmcnt(0)
	s_setprio 1
	s_barrier
	v_mfma_f32_16x16x32_bf16 v[120:123], v[150:153], v[182:185], v[120:123]
	v_mfma_f32_16x16x32_bf16 v[124:127], v[158:161], v[182:185], v[124:127]
	v_mfma_f32_16x16x32_bf16 v[104:107], v[150:153], v[190:193], v[104:107]
	v_mfma_f32_16x16x32_bf16 v[108:111], v[158:161], v[190:193], v[108:111]
	v_mfma_f32_16x16x32_bf16 v[88:91], v[150:153], v[198:201], v[88:91]
	v_mfma_f32_16x16x32_bf16 v[92:95], v[158:161], v[198:201], v[92:95]
	v_mfma_f32_16x16x32_bf16 v[64:67], v[150:153], v[206:209], v[64:67]
	v_mfma_f32_16x16x32_bf16 v[68:71], v[158:161], v[206:209], v[68:71]
	v_mfma_f32_16x16x32_bf16 v[120:123], v[154:157], v[186:189], v[120:123]
	v_mfma_f32_16x16x32_bf16 v[124:127], v[162:165], v[186:189], v[124:127]
	v_mfma_f32_16x16x32_bf16 v[104:107], v[154:157], v[194:197], v[104:107]
	v_mfma_f32_16x16x32_bf16 v[108:111], v[162:165], v[194:197], v[108:111]
	v_mfma_f32_16x16x32_bf16 v[88:91], v[154:157], v[202:205], v[88:91]
	v_mfma_f32_16x16x32_bf16 v[92:95], v[162:165], v[202:205], v[92:95]
	v_mfma_f32_16x16x32_bf16 v[64:67], v[154:157], v[210:213], v[64:67]
	v_mfma_f32_16x16x32_bf16 v[68:71], v[162:165], v[210:213], v[68:71]
	v_mfma_f32_16x16x32_bf16 v[112:115], v[166:169], v[182:185], v[112:115]
	v_mfma_f32_16x16x32_bf16 v[116:119], v[174:177], v[182:185], v[116:119]
	v_mfma_f32_16x16x32_bf16 v[96:99], v[166:169], v[190:193], v[96:99]
	v_mfma_f32_16x16x32_bf16 v[100:103], v[174:177], v[190:193], v[100:103]
	v_mfma_f32_16x16x32_bf16 v[80:83], v[166:169], v[198:201], v[80:83]
	v_mfma_f32_16x16x32_bf16 v[84:87], v[174:177], v[198:201], v[84:87]
	v_mfma_f32_16x16x32_bf16 v[48:51], v[166:169], v[206:209], v[48:51]
	v_mfma_f32_16x16x32_bf16 v[52:55], v[174:177], v[206:209], v[52:55]
	v_mfma_f32_16x16x32_bf16 v[112:115], v[170:173], v[186:189], v[112:115]
	v_mfma_f32_16x16x32_bf16 v[116:119], v[178:181], v[186:189], v[116:119]
	v_mfma_f32_16x16x32_bf16 v[96:99], v[170:173], v[194:197], v[96:99]
	v_mfma_f32_16x16x32_bf16 v[100:103], v[178:181], v[194:197], v[100:103]
	v_mfma_f32_16x16x32_bf16 v[80:83], v[170:173], v[202:205], v[80:83]
	v_mfma_f32_16x16x32_bf16 v[84:87], v[178:181], v[202:205], v[84:87]
	v_mfma_f32_16x16x32_bf16 v[48:51], v[170:173], v[210:213], v[48:51]
	v_mfma_f32_16x16x32_bf16 v[52:55], v[178:181], v[210:213], v[52:55]
	s_barrier
	s_setprio 0
	s_mov_b32 m0, s67
	v_lshl_add_u64 v[214:215], v[214:215], 0, s[12:13]
	s_add_u32 s78, s78, 0x80080
	ds_read_b128 v[182:185], v147 offset:49152
	ds_read_b128 v[186:189], v147 offset:50176
	ds_read_b128 v[190:193], v147 offset:51200
	ds_read_b128 v[194:197], v147 offset:52224
	ds_read_b128 v[198:201], v147 offset:53248
	ds_read_b128 v[202:205], v147 offset:54272
	ds_read_b128 v[206:209], v147 offset:55296
	ds_read_b128 v[210:213], v147 offset:56320
	global_load_lds_dwordx4 v[214:215], off
	v_lshl_add_u64 v[214:215], v[216:217], 0, s[12:13]
	s_mov_b32 m0, s69
	s_addc_u32 s79, s79, 0
	global_load_lds_dwordx4 v[214:215], off
	v_lshl_add_u64 v[214:215], s[78:79], 0, v[128:129]
	s_mov_b32 m0, s75
	s_nop 0
	global_load_lds_dwordx4 v[214:215], off
	v_lshl_add_u64 v[214:215], s[78:79], 0, v[130:131]
	s_mov_b32 m0, s82
	s_nop 0
	global_load_lds_dwordx4 v[214:215], off
	v_lshl_add_u64 v[214:215], v[218:219], 0, s[12:13]
	s_mov_b32 m0, s43
	s_nop 0
	global_load_lds_dwordx4 v[214:215], off
	v_lshl_add_u64 v[214:215], v[220:221], 0, s[12:13]
	s_mov_b32 m0, s44
	s_nop 0
	global_load_lds_dwordx4 v[214:215], off
	s_waitcnt vmcnt(8) lgkmcnt(0)
	s_setprio 1
	s_barrier
	v_mfma_f32_16x16x32_bf16 v[72:75], v[150:153], v[182:185], v[72:75]
	v_mfma_f32_16x16x32_bf16 v[76:79], v[158:161], v[182:185], v[76:79]
	v_mfma_f32_16x16x32_bf16 v[40:43], v[150:153], v[190:193], v[40:43]
	v_mfma_f32_16x16x32_bf16 v[44:47], v[158:161], v[190:193], v[44:47]
	v_mfma_f32_16x16x32_bf16 v[24:27], v[150:153], v[198:201], v[24:27]
	v_mfma_f32_16x16x32_bf16 v[28:31], v[158:161], v[198:201], v[28:31]
	v_mfma_f32_16x16x32_bf16 v[8:11], v[150:153], v[206:209], v[8:11]
	v_mfma_f32_16x16x32_bf16 v[12:15], v[158:161], v[206:209], v[12:15]
	v_mfma_f32_16x16x32_bf16 v[72:75], v[154:157], v[186:189], v[72:75]
	v_mfma_f32_16x16x32_bf16 v[76:79], v[162:165], v[186:189], v[76:79]
	v_mfma_f32_16x16x32_bf16 v[40:43], v[154:157], v[194:197], v[40:43]
	v_mfma_f32_16x16x32_bf16 v[44:47], v[162:165], v[194:197], v[44:47]
	v_mfma_f32_16x16x32_bf16 v[24:27], v[154:157], v[202:205], v[24:27]
	v_mfma_f32_16x16x32_bf16 v[28:31], v[162:165], v[202:205], v[28:31]
	v_mfma_f32_16x16x32_bf16 v[8:11], v[154:157], v[210:213], v[8:11]
	v_mfma_f32_16x16x32_bf16 v[12:15], v[162:165], v[210:213], v[12:15]
	v_mfma_f32_16x16x32_bf16 v[56:59], v[166:169], v[182:185], v[56:59]
	v_mfma_f32_16x16x32_bf16 v[60:63], v[174:177], v[182:185], v[60:63]
	v_mfma_f32_16x16x32_bf16 v[32:35], v[166:169], v[190:193], v[32:35]
	v_mfma_f32_16x16x32_bf16 v[36:39], v[174:177], v[190:193], v[36:39]
	v_mfma_f32_16x16x32_bf16 v[16:19], v[166:169], v[198:201], v[16:19]
	v_mfma_f32_16x16x32_bf16 v[20:23], v[174:177], v[198:201], v[20:23]
	v_mfma_f32_16x16x32_bf16 v[0:3], v[166:169], v[206:209], v[0:3]
	v_mfma_f32_16x16x32_bf16 v[4:7], v[174:177], v[206:209], v[4:7]
	v_mfma_f32_16x16x32_bf16 v[56:59], v[170:173], v[186:189], v[56:59]
	v_mfma_f32_16x16x32_bf16 v[60:63], v[178:181], v[186:189], v[60:63]
	v_mfma_f32_16x16x32_bf16 v[32:35], v[170:173], v[194:197], v[32:35]
	v_mfma_f32_16x16x32_bf16 v[36:39], v[178:181], v[194:197], v[36:39]
	v_mfma_f32_16x16x32_bf16 v[16:19], v[170:173], v[202:205], v[16:19]
	v_mfma_f32_16x16x32_bf16 v[20:23], v[178:181], v[202:205], v[20:23]
	v_mfma_f32_16x16x32_bf16 v[0:3], v[170:173], v[210:213], v[0:3]
	v_mfma_f32_16x16x32_bf16 v[4:7], v[178:181], v[210:213], v[4:7]
	s_barrier
	s_setprio 0
	s_add_i32 s85, s85, 2
	s_add_u32 s83, s83, 0x100
	s_addc_u32 s84, s84, 0
	s_add_u32 s76, s76, 0x100
	s_addc_u32 s77, s77, 0
	s_cmp_gt_u32 s85, 29
	s_cbranch_scc0 .LBB0_1155
	s_and_b64 vcc, exec, s[60:61]
	s_cbranch_vccz .LBB0_1158
	s_barrier

; template <class Epi, class Sched, bool ALIGN_EPI = false, bool SP2 = false, bool A_TILED = false>
; __device__ __forceinline__ void gemm_phase(PG8_LAS unsigned char* lds, const Gemm g, const Sched& S, const Epi& E, const int wave_s) {
;     ...
;             const bool last = (t == nt - 2);
;             const char* a1 = cA + (size_t)(t + 1) * kstepA;
;             const char* a2 = last ? nA : cA + (size_t)(t + 2) * kstepA; const char* b2 = last ? nB : cB + (size_t)(t + 2) * kstep;
;             const char* a3 = a2 + kstepA; const char* b3 = b2 + kstep;
.LBB0_1228:
	ds_read_b128 v[146:149], v140
	ds_read_b128 v[150:153], v140 offset:1024
	ds_read_b128 v[154:157], v140 offset:2048
	ds_read_b128 v[158:161], v140 offset:3072
	ds_read_b128 v[162:165], v141
	ds_read_b128 v[166:169], v141 offset:1024
	ds_read_b128 v[170:173], v141 offset:2048
	ds_read_b128 v[174:177], v141 offset:3072
	s_add_u32 s52, s12, s39
	s_addc_u32 s53, s13, s40
	s_add_u32 s54, s12, s37
	s_addc_u32 s55, s13, s38
	s_cmpk_eq_i32 s41, 0x7c
	s_cselect_b32 s72, s4, s52
	s_cselect_b32 s73, s5, s53
	s_cselect_b32 s70, s0, s54
	s_cselect_b32 s71, s1, s55
	s_add_u32 s68, s72, 0x8000
	s_addc_u32 s69, s73, 0
	s_mov_b32 m0, s42
	v_lshl_add_u64 v[210:211], s[12:13], 0, v[138:139]
	ds_read_b128 v[178:181], v142
	ds_read_b128 v[182:185], v142 offset:1024
	ds_read_b128 v[186:189], v142 offset:2048
	ds_read_b128 v[190:193], v142 offset:3072
	ds_read_b128 v[194:197], v142 offset:4096
	ds_read_b128 v[198:201], v142 offset:5120
	ds_read_b128 v[202:205], v142 offset:6144
	ds_read_b128 v[206:209], v142 offset:7168
	global_load_lds_dwordx4 v[210:211], off
	v_lshl_add_u64 v[210:211], s[12:13], 0, v[136:137]
	s_mov_b32 m0, s43
	s_nop 0
	global_load_lds_dwordx4 v[210:211], off
	s_waitcnt vmcnt(8) lgkmcnt(0)
	s_setprio 1
	s_barrier
	v_mfma_f32_16x16x32_bf16 v[8:11], v[146:149], v[178:181], v[8:11]
	v_mfma_f32_16x16x32_bf16 v[12:15], v[154:157], v[178:181], v[12:15]
	v_mfma_f32_16x16x32_bf16 v[60:63], v[146:149], v[186:189], v[60:63]
	v_mfma_f32_16x16x32_bf16 v[20:23], v[154:157], v[186:189], v[20:23]
	v_mfma_f32_16x16x32_bf16 v[76:79], v[146:149], v[194:197], v[76:79]
	v_mfma_f32_16x16x32_bf16 v[52:55], v[154:157], v[194:197], v[52:55]
	v_mfma_f32_16x16x32_bf16 v[128:131], v[146:149], v[202:205], v[128:131]
	v_mfma_f32_16x16x32_bf16 v[68:71], v[154:157], v[202:205], v[68:71]
	v_mfma_f32_16x16x32_bf16 v[8:11], v[150:153], v[182:185], v[8:11]
	v_mfma_f32_16x16x32_bf16 v[12:15], v[158:161], v[182:185], v[12:15]
	v_mfma_f32_16x16x32_bf16 v[60:63], v[150:153], v[190:193], v[60:63]
	v_mfma_f32_16x16x32_bf16 v[20:23], v[158:161], v[190:193], v[20:23]
	v_mfma_f32_16x16x32_bf16 v[76:79], v[150:153], v[198:201], v[76:79]
	v_mfma_f32_16x16x32_bf16 v[52:55], v[158:161], v[198:201], v[52:55]
	v_mfma_f32_16x16x32_bf16 v[128:131], v[150:153], v[206:209], v[128:131]
	v_mfma_f32_16x16x32_bf16 v[68:71], v[158:161], v[206:209], v[68:71]
	v_mfma_f32_16x16x32_bf16 v[28:31], v[162:165], v[178:181], v[28:31]
	v_mfma_f32_16x16x32_bf16 v[16:19], v[170:173], v[178:181], v[16:19]
	v_mfma_f32_16x16x32_bf16 v[56:59], v[162:165], v[186:189], v[56:59]
	v_mfma_f32_16x16x32_bf16 v[48:51], v[170:173], v[186:189], v[48:51]
	v_mfma_f32_16x16x32_bf16 v[72:75], v[162:165], v[194:197], v[72:75]
	v_mfma_f32_16x16x32_bf16 v[64:67], v[170:173], v[194:197], v[64:67]
	v_mfma_f32_16x16x32_bf16 v[108:111], v[162:165], v[202:205], v[108:111]
	v_mfma_f32_16x16x32_bf16 v[96:99], v[170:173], v[202:205], v[96:99]
	v_mfma_f32_16x16x32_bf16 v[28:31], v[166:169], v[182:185], v[28:31]
	v_mfma_f32_16x16x32_bf16 v[16:19], v[174:177], v[182:185], v[16:19]
	v_mfma_f32_16x16x32_bf16 v[56:59], v[166:169], v[190:193], v[56:59]
	v_mfma_f32_16x16x32_bf16 v[48:51], v[174:177], v[190:193], v[48:51]
	v_mfma_f32_16x16x32_bf16 v[72:75], v[166:169], v[198:201], v[72:75]
	v_mfma_f32_16x16x32_bf16 v[64:67], v[174:177], v[198:201], v[64:67]
	v_mfma_f32_16x16x32_bf16 v[108:111], v[166:169], v[206:209], v[108:111]
	v_mfma_f32_16x16x32_bf16 v[96:99], v[174:177], v[206:209], v[96:99]
	s_barrier
	s_setprio 0
	s_mov_b32 m0, s44
	v_lshl_add_u64 v[210:211], s[70:71], 0, v[34:35]
	s_add_u32 s52, s70, 0x200000
	ds_read_b128 v[178:181], v142 offset:16384
	ds_read_b128 v[182:185], v142 offset:17408
	ds_read_b128 v[186:189], v142 offset:18432
	ds_read_b128 v[190:193], v142 offset:19456
	ds_read_b128 v[194:197], v142 offset:20480
	ds_read_b128 v[198:201], v142 offset:21504
	ds_read_b128 v[202:205], v142 offset:22528
	ds_read_b128 v[206:209], v142 offset:23552
	global_load_lds_dwordx4 v[210:211], off
	v_lshl_add_u64 v[212:213], s[70:71], 0, v[134:135]
	s_mov_b32 m0, s45
	s_addc_u32 s53, s71, 0
	global_load_lds_dwordx4 v[212:213], off
	v_lshl_add_u64 v[214:215], s[52:53], 0, v[34:35]
	s_mov_b32 m0, s46
	s_nop 0
	global_load_lds_dwordx4 v[214:215], off
	v_lshl_add_u64 v[214:215], s[52:53], 0, v[134:135]
	s_mov_b32 m0, s47
	s_nop 0
	global_load_lds_dwordx4 v[214:215], off
	v_lshl_add_u64 v[214:215], s[72:73], 0, v[32:33]
	s_mov_b32 m0, s14
	s_nop 0
	global_load_lds_dwordx4 v[214:215], off
	v_lshl_add_u64 v[214:215], s[72:73], 0, v[132:133]
	s_mov_b32 m0, s15
	s_nop 0
	global_load_lds_dwordx4 v[214:215], off
	s_waitcnt vmcnt(8) lgkmcnt(0)
	s_setprio 1
	s_barrier
	v_mfma_f32_16x16x32_bf16 v[100:103], v[146:149], v[178:181], v[100:103]
	v_mfma_f32_16x16x32_bf16 v[104:107], v[154:157], v[178:181], v[104:107]
	v_mfma_f32_16x16x32_bf16 v[116:119], v[146:149], v[186:189], v[116:119]
	v_mfma_f32_16x16x32_bf16 v[120:123], v[154:157], v[186:189], v[120:123]
	v_mfma_f32_16x16x32_bf16 v[84:87], v[146:149], v[194:197], v[84:87]
	v_mfma_f32_16x16x32_bf16 v[80:83], v[154:157], v[194:197], v[80:83]
	v_mfma_f32_16x16x32_bf16 v[36:39], v[146:149], v[202:205], v[36:39]
	v_mfma_f32_16x16x32_bf16 v[24:27], v[154:157], v[202:205], v[24:27]
	v_mfma_f32_16x16x32_bf16 v[100:103], v[150:153], v[182:185], v[100:103]
	v_mfma_f32_16x16x32_bf16 v[104:107], v[158:161], v[182:185], v[104:107]
	v_mfma_f32_16x16x32_bf16 v[116:119], v[150:153], v[190:193], v[116:119]
	v_mfma_f32_16x16x32_bf16 v[120:123], v[158:161], v[190:193], v[120:123]
	v_mfma_f32_16x16x32_bf16 v[84:87], v[150:153], v[198:201], v[84:87]
	v_mfma_f32_16x16x32_bf16 v[80:83], v[158:161], v[198:201], v[80:83]
	v_mfma_f32_16x16x32_bf16 v[36:39], v[150:153], v[206:209], v[36:39]
	v_mfma_f32_16x16x32_bf16 v[24:27], v[158:161], v[206:209], v[24:27]
	v_mfma_f32_16x16x32_bf16 v[124:127], v[162:165], v[178:181], v[124:127]
	v_mfma_f32_16x16x32_bf16 v[112:115], v[170:173], v[178:181], v[112:115]
	v_mfma_f32_16x16x32_bf16 v[92:95], v[162:165], v[186:189], v[92:95]
	v_mfma_f32_16x16x32_bf16 v[88:91], v[170:173], v[186:189], v[88:91]
	v_mfma_f32_16x16x32_bf16 v[44:47], v[162:165], v[194:197], v[44:47]
	v_mfma_f32_16x16x32_bf16 v[40:43], v[170:173], v[194:197], v[40:43]
	v_mfma_f32_16x16x32_bf16 v[4:7], v[162:165], v[202:205], v[4:7]
	v_mfma_f32_16x16x32_bf16 v[0:3], v[170:173], v[202:205], v[0:3]
	v_mfma_f32_16x16x32_bf16 v[124:127], v[166:169], v[182:185], v[124:127]
	v_mfma_f32_16x16x32_bf16 v[112:115], v[174:177], v[182:185], v[112:115]
	v_mfma_f32_16x16x32_bf16 v[92:95], v[166:169], v[190:193], v[92:95]
	v_mfma_f32_16x16x32_bf16 v[88:91], v[174:177], v[190:193], v[88:91]
	v_mfma_f32_16x16x32_bf16 v[44:47], v[166:169], v[198:201], v[44:47]
	v_mfma_f32_16x16x32_bf16 v[40:43], v[174:177], v[198:201], v[40:43]
	v_mfma_f32_16x16x32_bf16 v[4:7], v[166:169], v[206:209], v[4:7]
	v_mfma_f32_16x16x32_bf16 v[0:3], v[174:177], v[206:209], v[0:3]
	s_barrier
	s_setprio 0
	ds_read_b128 v[146:149], v143
	ds_read_b128 v[150:153], v143 offset:1024
	ds_read_b128 v[154:157], v143 offset:2048
	ds_read_b128 v[158:161], v143 offset:3072
	ds_read_b128 v[162:165], v144
	ds_read_b128 v[166:169], v144 offset:1024
	ds_read_b128 v[170:173], v144 offset:2048
	ds_read_b128 v[174:177], v144 offset:3072
	s_add_u32 s52, s72, 0x4000
	s_addc_u32 s53, s73, 0
	s_mov_b32 m0, s21
	v_lshl_add_u64 v[214:215], s[52:53], 0, v[32:33]
	ds_read_b128 v[178:181], v142 offset:32768
	ds_read_b128 v[182:185], v142 offset:33792
	ds_read_b128 v[186:189], v142 offset:34816
	ds_read_b128 v[190:193], v142 offset:35840
	ds_read_b128 v[194:197], v142 offset:36864
	ds_read_b128 v[198:201], v142 offset:37888
	ds_read_b128 v[202:205], v142 offset:38912
	ds_read_b128 v[206:209], v142 offset:39936
	global_load_lds_dwordx4 v[214:215], off
	v_lshl_add_u64 v[214:215], s[52:53], 0, v[132:133]
	s_mov_b32 m0, s22
	s_nop 0
	global_load_lds_dwordx4 v[214:215], off
	s_waitcnt vmcnt(8) lgkmcnt(0)
	s_setprio 1
	s_barrier
	v_mfma_f32_16x16x32_bf16 v[8:11], v[146:149], v[178:181], v[8:11]
	v_mfma_f32_16x16x32_bf16 v[12:15], v[154:157], v[178:181], v[12:15]
	v_mfma_f32_16x16x32_bf16 v[60:63], v[146:149], v[186:189], v[60:63]
	v_mfma_f32_16x16x32_bf16 v[20:23], v[154:157], v[186:189], v[20:23]
	v_mfma_f32_16x16x32_bf16 v[76:79], v[146:149], v[194:197], v[76:79]
	v_mfma_f32_16x16x32_bf16 v[52:55], v[154:157], v[194:197], v[52:55]
	v_mfma_f32_16x16x32_bf16 v[128:131], v[146:149], v[202:205], v[128:131]
	v_mfma_f32_16x16x32_bf16 v[68:71], v[154:157], v[202:205], v[68:71]
	v_mfma_f32_16x16x32_bf16 v[8:11], v[150:153], v[182:185], v[8:11]
	v_mfma_f32_16x16x32_bf16 v[12:15], v[158:161], v[182:185], v[12:15]
	v_mfma_f32_16x16x32_bf16 v[60:63], v[150:153], v[190:193], v[60:63]
	v_mfma_f32_16x16x32_bf16 v[20:23], v[158:161], v[190:193], v[20:23]
	v_mfma_f32_16x16x32_bf16 v[76:79], v[150:153], v[198:201], v[76:79]
	v_mfma_f32_16x16x32_bf16 v[52:55], v[158:161], v[198:201], v[52:55]
	v_mfma_f32_16x16x32_bf16 v[128:131], v[150:153], v[206:209], v[128:131]
	v_mfma_f32_16x16x32_bf16 v[68:71], v[158:161], v[206:209], v[68:71]
	v_mfma_f32_16x16x32_bf16 v[28:31], v[162:165], v[178:181], v[28:31]
	v_mfma_f32_16x16x32_bf16 v[16:19], v[170:173], v[178:181], v[16:19]
	v_mfma_f32_16x16x32_bf16 v[56:59], v[162:165], v[186:189], v[56:59]
	v_mfma_f32_16x16x32_bf16 v[48:51], v[170:173], v[186:189], v[48:51]
	v_mfma_f32_16x16x32_bf16 v[72:75], v[162:165], v[194:197], v[72:75]
	v_mfma_f32_16x16x32_bf16 v[64:67], v[170:173], v[194:197], v[64:67]
	v_mfma_f32_16x16x32_bf16 v[108:111], v[162:165], v[202:205], v[108:111]
	v_mfma_f32_16x16x32_bf16 v[96:99], v[170:173], v[202:205], v[96:99]
	v_mfma_f32_16x16x32_bf16 v[28:31], v[166:169], v[182:185], v[28:31]
	v_mfma_f32_16x16x32_bf16 v[16:19], v[174:177], v[182:185], v[16:19]
	v_mfma_f32_16x16x32_bf16 v[56:59], v[166:169], v[190:193], v[56:59]
	v_mfma_f32_16x16x32_bf16 v[48:51], v[174:177], v[190:193], v[48:51]
	v_mfma_f32_16x16x32_bf16 v[72:75], v[166:169], v[198:201], v[72:75]
	v_mfma_f32_16x16x32_bf16 v[64:67], v[174:177], v[198:201], v[64:67]
	v_mfma_f32_16x16x32_bf16 v[108:111], v[166:169], v[206:209], v[108:111]
	v_mfma_f32_16x16x32_bf16 v[96:99], v[174:177], v[206:209], v[96:99]
	s_barrier
; #define PG8_WAIT_V(n) asm volatile("s_waitcnt vmcnt(" #n ")" ::: "memory")
; #define PG8_BAR __builtin_amdgcn_s_barrier()
; template <class Epi, class Sched, bool ALIGN_EPI = false, bool SP2 = false, bool A_TILED = false>
; __device__ __forceinline__ void gemm_phase(PG8_LAS unsigned char* lds, const Gemm g, const Sched& S, const Epi& E, const int wave_s) {
;     ...
;     PG8_WAIT_V(0);
;     if constexpr (!ALIGN_EPI) { if (wr == 0) PG8_BAR; }
	s_setprio 0
	s_mov_b32 m0, s48
	v_lshl_add_u64 v[210:211], v[210:211], 0, s[64:65]
	s_add_u32 s52, s70, 0x200080
	ds_read_b128 v[178:181], v142 offset:49152
	ds_read_b128 v[182:185], v142 offset:50176
	ds_read_b128 v[186:189], v142 offset:51200
	ds_read_b128 v[190:193], v142 offset:52224
	ds_read_b128 v[194:197], v142 offset:53248
	ds_read_b128 v[198:201], v142 offset:54272
	ds_read_b128 v[202:205], v142 offset:55296
	ds_read_b128 v[206:209], v142 offset:56320
	global_load_lds_dwordx4 v[210:211], off
	v_lshl_add_u64 v[210:211], v[212:213], 0, s[64:65]
	s_mov_b32 m0, s49
	s_addc_u32 s53, s71, 0
	global_load_lds_dwordx4 v[210:211], off
	v_lshl_add_u64 v[210:211], s[52:53], 0, v[34:35]
	s_mov_b32 m0, s50
	s_nop 0
	global_load_lds_dwordx4 v[210:211], off
	v_lshl_add_u64 v[210:211], s[52:53], 0, v[134:135]
	s_mov_b32 m0, s51
	s_nop 0
	global_load_lds_dwordx4 v[210:211], off
	v_lshl_add_u64 v[210:211], s[68:69], 0, v[32:33]
	s_mov_b32 m0, s23
	s_nop 0
	global_load_lds_dwordx4 v[210:211], off
	v_lshl_add_u64 v[210:211], s[68:69], 0, v[132:133]
	s_mov_b32 m0, s36
	s_nop 0
	global_load_lds_dwordx4 v[210:211], off
	s_waitcnt vmcnt(8) lgkmcnt(0)
	s_setprio 1
	s_barrier
	v_mfma_f32_16x16x32_bf16 v[100:103], v[146:149], v[178:181], v[100:103]
	v_mfma_f32_16x16x32_bf16 v[104:107], v[154:157], v[178:181], v[104:107]
	v_mfma_f32_16x16x32_bf16 v[116:119], v[146:149], v[186:189], v[116:119]
	v_mfma_f32_16x16x32_bf16 v[120:123], v[154:157], v[186:189], v[120:123]
	v_mfma_f32_16x16x32_bf16 v[84:87], v[146:149], v[194:197], v[84:87]
	v_mfma_f32_16x16x32_bf16 v[80:83], v[154:157], v[194:197], v[80:83]
	v_mfma_f32_16x16x32_bf16 v[36:39], v[146:149], v[202:205], v[36:39]
	v_mfma_f32_16x16x32_bf16 v[24:27], v[154:157], v[202:205], v[24:27]
	v_mfma_f32_16x16x32_bf16 v[100:103], v[150:153], v[182:185], v[100:103]
	v_mfma_f32_16x16x32_bf16 v[104:107], v[158:161], v[182:185], v[104:107]
	v_mfma_f32_16x16x32_bf16 v[116:119], v[150:153], v[190:193], v[116:119]
	v_mfma_f32_16x16x32_bf16 v[120:123], v[158:161], v[190:193], v[120:123]
	v_mfma_f32_16x16x32_bf16 v[84:87], v[150:153], v[198:201], v[84:87]
	v_mfma_f32_16x16x32_bf16 v[80:83], v[158:161], v[198:201], v[80:83]
	v_mfma_f32_16x16x32_bf16 v[36:39], v[150:153], v[206:209], v[36:39]
	v_mfma_f32_16x16x32_bf16 v[24:27], v[158:161], v[206:209], v[24:27]
	v_mfma_f32_16x16x32_bf16 v[124:127], v[162:165], v[178:181], v[124:127]
	v_mfma_f32_16x16x32_bf16 v[112:115], v[170:173], v[178:181], v[112:115]
	v_mfma_f32_16x16x32_bf16 v[92:95], v[162:165], v[186:189], v[92:95]
	v_mfma_f32_16x16x32_bf16 v[88:91], v[170:173], v[186:189], v[88:91]
	v_mfma_f32_16x16x32_bf16 v[44:47], v[162:165], v[194:197], v[44:47]
	v_mfma_f32_16x16x32_bf16 v[40:43], v[170:173], v[194:197], v[40:43]
	v_mfma_f32_16x16x32_bf16 v[4:7], v[162:165], v[202:205], v[4:7]
	v_mfma_f32_16x16x32_bf16 v[0:3], v[170:173], v[202:205], v[0:3]
	v_mfma_f32_16x16x32_bf16 v[124:127], v[166:169], v[182:185], v[124:127]
	v_mfma_f32_16x16x32_bf16 v[112:115], v[174:177], v[182:185], v[112:115]
	v_mfma_f32_16x16x32_bf16 v[92:95], v[166:169], v[190:193], v[92:95]
	v_mfma_f32_16x16x32_bf16 v[88:91], v[174:177], v[190:193], v[88:91]
	v_mfma_f32_16x16x32_bf16 v[44:47], v[166:169], v[198:201], v[44:47]
	v_mfma_f32_16x16x32_bf16 v[40:43], v[174:177], v[198:201], v[40:43]
	v_mfma_f32_16x16x32_bf16 v[4:7], v[166:169], v[206:209], v[4:7]
	v_mfma_f32_16x16x32_bf16 v[0:3], v[174:177], v[206:209], v[0:3]
	s_barrier
	s_setprio 0
	s_add_i32 s41, s41, 2
	s_add_u32 s37, s37, 0x100
	s_addc_u32 s38, s38, 0
	s_add_u32 s39, s39, 0x10000
	s_addc_u32 s40, s40, 0
	v_lshl_add_u64 v[136:137], v[136:137], 0, s[66:67]
	s_cmpk_gt_u32 s41, 0x7d
	v_lshl_add_u64 v[138:139], v[138:139], 0, s[66:67]
	s_cbranch_scc0 .LBB0_1228
	s_waitcnt vmcnt(0)
	s_cmpk_lt_u32 s8, 0x100
	s_cbranch_scc0 .LBB0_1231
	s_barrier

; template <class Epi, class Sched, bool ALIGN_EPI = false, bool SP2 = false, bool A_TILED = false>
; __device__ __forceinline__ void gemm_phase(PG8_LAS unsigned char* lds, const Gemm g, const Sched& S, const Epi& E, const int wave_s) {
;     ...
;         const bool has_next = Epi::AFTER_DRAIN ? false : S.next(ui + 1, nxt);
;         const char* nA = has_next ? (const char*)g.A + (size_t)nxt.pm * tstepA : cA; const char* nB = has_next ? (const char*)g.Bt + (size_t)nxt.pn * tstep : cB;
;         constexpr bool PEEL = SP2 && !Epi::AFTER_DRAIN;
;         if constexpr (PEEL) {
;             const char* a1 = cA + kstepA; const char* a2 = cA + 2 * kstepA; const char* b2 = cB + 2 * kstep; const char* a3 = a2 + kstepA; const char* b3 = b2 + kstep;
;             PG8_ITER(PG8_MMAZ)
.LBB0_1618:
	s_ashr_i32 s71, s70, 31
	s_lshl_b64 s[52:53], s[70:71], 20
	s_add_u32 s72, s1, s52
	ds_read_b128 v[0:3], v149
	ds_read_b128 v[4:7], v149 offset:1024
	ds_read_b128 v[8:11], v149 offset:2048
	ds_read_b128 v[12:15], v149 offset:3072
	ds_read_b128 v[16:19], v150
	ds_read_b128 v[20:23], v150 offset:1024
	ds_read_b128 v[24:27], v150 offset:2048
	ds_read_b128 v[28:31], v150 offset:3072
	s_addc_u32 s73, s8, s53
	s_ashr_i32 s69, s68, 31
	s_lshl_b64 s[52:53], s[68:69], 20
	s_add_u32 s74, s9, s52
	s_addc_u32 s75, s14, s53
	s_and_b64 s[52:53], s[2:3], exec
	s_cselect_b32 s51, s73, s81
	s_cselect_b32 s52, s72, s80
	s_cselect_b32 s53, s75, s79
	s_cselect_b32 s54, s74, s78
	s_add_u32 s56, s80, 0x80080
	s_addc_u32 s57, s81, 0
	s_add_i32 s55, s23, 0xc000
	v_lshl_add_u64 v[64:65], s[56:57], 0, v[134:135]
	s_mov_b32 m0, s55
	ds_read_b128 v[32:35], v151
	ds_read_b128 v[36:39], v151 offset:1024
	ds_read_b128 v[40:43], v151 offset:2048
	ds_read_b128 v[44:47], v151 offset:3072
	ds_read_b128 v[48:51], v151 offset:4096
	ds_read_b128 v[52:55], v151 offset:5120
	ds_read_b128 v[56:59], v151 offset:6144
	ds_read_b128 v[60:63], v151 offset:7168
	global_load_lds_dwordx4 v[64:65], off
	v_lshl_add_u64 v[64:65], s[56:57], 0, v[132:133]
	s_add_i32 s56, s23, 0xe000
	s_mov_b32 m0, s56
	s_nop 0
	global_load_lds_dwordx4 v[64:65], off
	s_waitcnt vmcnt(8) lgkmcnt(0)
	s_setprio 1
	s_barrier
	v_mfma_f32_16x16x32_bf16 v[88:91], v[0:3], v[56:59], 0
	v_mfma_f32_16x16x32_bf16 v[64:67], v[0:3], v[32:35], 0
	v_mfma_f32_16x16x32_bf16 v[68:71], v[8:11], v[32:35], 0
	v_mfma_f32_16x16x32_bf16 v[72:75], v[0:3], v[40:43], 0
	v_mfma_f32_16x16x32_bf16 v[76:79], v[8:11], v[40:43], 0
	v_mfma_f32_16x16x32_bf16 v[80:83], v[0:3], v[48:51], 0
	v_mfma_f32_16x16x32_bf16 v[84:87], v[8:11], v[48:51], 0
	v_mfma_f32_16x16x32_bf16 v[96:99], v[4:7], v[60:63], v[88:91]
	v_mfma_f32_16x16x32_bf16 v[88:91], v[8:11], v[56:59], 0
	v_mfma_f32_16x16x32_bf16 v[64:67], v[4:7], v[36:39], v[64:67]
	v_mfma_f32_16x16x32_bf16 v[68:71], v[12:15], v[36:39], v[68:71]
	v_mfma_f32_16x16x32_bf16 v[72:75], v[4:7], v[44:47], v[72:75]
	v_mfma_f32_16x16x32_bf16 v[76:79], v[12:15], v[44:47], v[76:79]
	v_mfma_f32_16x16x32_bf16 v[80:83], v[4:7], v[52:55], v[80:83]
	v_mfma_f32_16x16x32_bf16 v[84:87], v[12:15], v[52:55], v[84:87]
	v_mfma_f32_16x16x32_bf16 v[100:103], v[12:15], v[60:63], v[88:91]
	v_mfma_f32_16x16x32_bf16 v[88:91], v[16:19], v[32:35], 0
	v_mfma_f32_16x16x32_bf16 v[32:35], v[24:27], v[32:35], 0
	v_mfma_f32_16x16x32_bf16 v[112:115], v[20:23], v[36:39], v[88:91]
	v_mfma_f32_16x16x32_bf16 v[32:35], v[28:31], v[36:39], v[32:35]
	v_mfma_f32_16x16x32_bf16 v[36:39], v[16:19], v[40:43], 0
	v_mfma_f32_16x16x32_bf16 v[40:43], v[24:27], v[40:43], 0
	v_mfma_f32_16x16x32_bf16 v[36:39], v[20:23], v[44:47], v[36:39]
	v_mfma_f32_16x16x32_bf16 v[40:43], v[28:31], v[44:47], v[40:43]
	v_mfma_f32_16x16x32_bf16 v[44:47], v[16:19], v[48:51], 0
	v_mfma_f32_16x16x32_bf16 v[48:51], v[24:27], v[48:51], 0
	v_mfma_f32_16x16x32_bf16 v[44:47], v[20:23], v[52:55], v[44:47]
	v_mfma_f32_16x16x32_bf16 v[48:51], v[28:31], v[52:55], v[48:51]
	v_mfma_f32_16x16x32_bf16 v[52:55], v[16:19], v[56:59], 0
	v_mfma_f32_16x16x32_bf16 v[56:59], v[24:27], v[56:59], 0
	v_mfma_f32_16x16x32_bf16 v[52:55], v[20:23], v[60:63], v[52:55]
	v_mfma_f32_16x16x32_bf16 v[56:59], v[28:31], v[60:63], v[56:59]
	s_barrier
	s_setprio 0
	s_add_i32 s57, s46, s15
	v_lshl_add_u64 v[250:251], s[78:79], 0, v[128:129]
	s_add_i32 s58, s57, 0x2000
	v_lshl_add_u64 v[144:145], v[250:251], 0, s[64:65]
	s_mov_b32 m0, s57
	v_lshl_add_u64 v[252:253], s[78:79], 0, v[130:131]
	s_add_u32 s82, s78, 0x80100
	ds_read_b128 v[60:63], v151 offset:16384
	ds_read_b128 v[88:91], v151 offset:17408
	ds_read_b128 v[92:95], v151 offset:18432
	ds_read_b128 v[104:107], v151 offset:19456
	ds_read_b128 v[108:111], v151 offset:20480
	ds_read_b128 v[116:119], v151 offset:21504
	ds_read_b128 v[120:123], v151 offset:22528
	ds_read_b128 v[124:127], v151 offset:23552
	global_load_lds_dwordx4 v[144:145], off
	v_lshl_add_u64 v[144:145], v[252:253], 0, s[64:65]
	s_mov_b32 m0, s58
	s_addc_u32 s83, s79, 0
	s_add_i32 s59, s47, s15
	global_load_lds_dwordx4 v[144:145], off
	v_lshl_add_u64 v[144:145], s[82:83], 0, v[128:129]
	s_mov_b32 m0, s59
	s_add_i32 s69, s59, 0x2000
	global_load_lds_dwordx4 v[144:145], off
	v_lshl_add_u64 v[144:145], s[82:83], 0, v[130:131]
	s_mov_b32 m0, s69
	v_lshl_add_u64 v[140:141], s[80:81], 0, v[134:135]
	global_load_lds_dwordx4 v[144:145], off
	v_lshl_add_u64 v[144:145], v[140:141], 0, s[64:65]
	s_mov_b32 m0, s23
	v_lshl_add_u64 v[142:143], s[80:81], 0, v[132:133]
	global_load_lds_dwordx4 v[144:145], off
	v_lshl_add_u64 v[144:145], v[142:143], 0, s[64:65]
	s_mov_b32 m0, s36
	s_nop 0
	global_load_lds_dwordx4 v[144:145], off
	s_waitcnt vmcnt(8) lgkmcnt(0)
	s_setprio 1
	s_barrier
	v_mfma_f32_16x16x32_bf16 v[144:147], v[0:3], v[60:63], 0
	v_mfma_f32_16x16x32_bf16 v[154:157], v[4:7], v[88:91], v[144:147]
	v_mfma_f32_16x16x32_bf16 v[144:147], v[8:11], v[60:63], 0
	v_mfma_f32_16x16x32_bf16 v[158:161], v[12:15], v[88:91], v[144:147]
	v_mfma_f32_16x16x32_bf16 v[144:147], v[0:3], v[92:95], 0
	v_mfma_f32_16x16x32_bf16 v[162:165], v[4:7], v[104:107], v[144:147]
	v_mfma_f32_16x16x32_bf16 v[144:147], v[8:11], v[92:95], 0
	v_mfma_f32_16x16x32_bf16 v[166:169], v[12:15], v[104:107], v[144:147]
	v_mfma_f32_16x16x32_bf16 v[144:147], v[0:3], v[108:111], 0
	v_mfma_f32_16x16x32_bf16 v[0:3], v[0:3], v[120:123], 0
	v_mfma_f32_16x16x32_bf16 v[170:173], v[4:7], v[116:119], v[144:147]
	v_mfma_f32_16x16x32_bf16 v[0:3], v[4:7], v[124:127], v[0:3]
	v_mfma_f32_16x16x32_bf16 v[4:7], v[8:11], v[120:123], 0
	v_mfma_f32_16x16x32_bf16 v[144:147], v[8:11], v[108:111], 0
	v_mfma_f32_16x16x32_bf16 v[4:7], v[12:15], v[124:127], v[4:7]
	v_mfma_f32_16x16x32_bf16 v[174:177], v[12:15], v[116:119], v[144:147]
	v_mfma_f32_16x16x32_bf16 v[8:11], v[16:19], v[60:63], 0
	v_mfma_f32_16x16x32_bf16 v[178:181], v[20:23], v[88:91], v[8:11]
	v_mfma_f32_16x16x32_bf16 v[8:11], v[24:27], v[60:63], 0
	v_mfma_f32_16x16x32_bf16 v[182:185], v[28:31], v[88:91], v[8:11]
	v_mfma_f32_16x16x32_bf16 v[8:11], v[16:19], v[92:95], 0
	v_mfma_f32_16x16x32_bf16 v[186:189], v[20:23], v[104:107], v[8:11]
	v_mfma_f32_16x16x32_bf16 v[8:11], v[24:27], v[92:95], 0
	v_mfma_f32_16x16x32_bf16 v[190:193], v[28:31], v[104:107], v[8:11]
	v_mfma_f32_16x16x32_bf16 v[8:11], v[16:19], v[108:111], 0
	v_mfma_f32_16x16x32_bf16 v[194:197], v[20:23], v[116:119], v[8:11]
	v_mfma_f32_16x16x32_bf16 v[8:11], v[24:27], v[108:111], 0
	v_mfma_f32_16x16x32_bf16 v[198:201], v[28:31], v[116:119], v[8:11]
	v_mfma_f32_16x16x32_bf16 v[8:11], v[16:19], v[120:123], 0
	v_mfma_f32_16x16x32_bf16 v[202:205], v[20:23], v[124:127], v[8:11]
	v_mfma_f32_16x16x32_bf16 v[8:11], v[24:27], v[120:123], 0
	v_mfma_f32_16x16x32_bf16 v[206:209], v[28:31], v[124:127], v[8:11]
	s_barrier
	s_setprio 0
	s_add_i32 s71, 0, 0x18000
	s_add_i32 s88, 0, 0x1c000
	v_add_u32_e32 v144, s71, v148
	v_add_u32_e32 v145, s88, v148
	s_nop 0
	ds_read_b128 v[8:11], v144
	ds_read_b128 v[12:15], v144 offset:1024
	ds_read_b128 v[16:19], v144 offset:2048
	ds_read_b128 v[20:23], v144 offset:3072
	ds_read_b128 v[210:213], v145
	ds_read_b128 v[214:217], v145 offset:1024
	ds_read_b128 v[218:221], v145 offset:2048
	ds_read_b128 v[222:225], v145 offset:3072
	s_add_u32 s82, s80, 0x80100
	s_addc_u32 s83, s81, 0
	s_mov_b32 m0, s37
	v_lshl_add_u64 v[88:89], s[82:83], 0, v[134:135]
	ds_read_b128 v[24:27], v151 offset:32768
	ds_read_b128 v[28:31], v151 offset:33792
	ds_read_b128 v[60:63], v151 offset:34816
	ds_read_b128 v[226:229], v151 offset:35840
	ds_read_b128 v[230:233], v151 offset:36864
	ds_read_b128 v[234:237], v151 offset:37888
	ds_read_b128 v[238:241], v151 offset:38912
	ds_read_b128 v[242:245], v151 offset:39936
	global_load_lds_dwordx4 v[88:89], off
	v_lshl_add_u64 v[88:89], s[82:83], 0, v[132:133]
	s_mov_b32 m0, s38
	s_nop 0
	global_load_lds_dwordx4 v[88:89], off
	s_waitcnt vmcnt(8) lgkmcnt(0)
	s_setprio 1
	s_barrier
	v_mfma_f32_16x16x32_bf16 v[64:67], v[8:11], v[24:27], v[64:67]
	v_mfma_f32_16x16x32_bf16 v[124:127], v[12:15], v[28:31], v[64:67]
	v_mfma_f32_16x16x32_bf16 v[64:67], v[16:19], v[24:27], v[68:71]
	v_mfma_f32_16x16x32_bf16 v[120:123], v[20:23], v[28:31], v[64:67]
	v_mfma_f32_16x16x32_bf16 v[64:67], v[8:11], v[60:63], v[72:75]
	v_mfma_f32_16x16x32_bf16 v[108:111], v[12:15], v[226:229], v[64:67]
	v_mfma_f32_16x16x32_bf16 v[64:67], v[16:19], v[60:63], v[76:79]
	v_mfma_f32_16x16x32_bf16 v[104:107], v[20:23], v[226:229], v[64:67]
	v_mfma_f32_16x16x32_bf16 v[64:67], v[8:11], v[230:233], v[80:83]
	v_mfma_f32_16x16x32_bf16 v[92:95], v[12:15], v[234:237], v[64:67]
	v_mfma_f32_16x16x32_bf16 v[64:67], v[16:19], v[230:233], v[84:87]
	v_mfma_f32_16x16x32_bf16 v[88:91], v[20:23], v[234:237], v[64:67]
	v_mfma_f32_16x16x32_bf16 v[64:67], v[8:11], v[238:241], v[96:99]
	v_mfma_f32_16x16x32_bf16 v[76:79], v[12:15], v[242:245], v[64:67]
	v_mfma_f32_16x16x32_bf16 v[64:67], v[16:19], v[238:241], v[100:103]
	v_mfma_f32_16x16x32_bf16 v[72:75], v[20:23], v[242:245], v[64:67]
	v_mfma_f32_16x16x32_bf16 v[64:67], v[210:213], v[24:27], v[112:115]
	v_mfma_f32_16x16x32_bf16 v[24:27], v[218:221], v[24:27], v[32:35]
	v_mfma_f32_16x16x32_bf16 v[112:115], v[222:225], v[28:31], v[24:27]
	v_mfma_f32_16x16x32_bf16 v[24:27], v[210:213], v[60:63], v[36:39]
	v_mfma_f32_16x16x32_bf16 v[100:103], v[214:217], v[226:229], v[24:27]
	v_mfma_f32_16x16x32_bf16 v[24:27], v[218:221], v[60:63], v[40:43]
	v_mfma_f32_16x16x32_bf16 v[96:99], v[222:225], v[226:229], v[24:27]
	v_mfma_f32_16x16x32_bf16 v[24:27], v[210:213], v[230:233], v[44:47]
	v_mfma_f32_16x16x32_bf16 v[84:87], v[214:217], v[234:237], v[24:27]
	v_mfma_f32_16x16x32_bf16 v[24:27], v[218:221], v[230:233], v[48:51]
	v_mfma_f32_16x16x32_bf16 v[80:83], v[222:225], v[234:237], v[24:27]
	v_mfma_f32_16x16x32_bf16 v[24:27], v[210:213], v[238:241], v[52:55]
	v_mfma_f32_16x16x32_bf16 v[68:71], v[214:217], v[242:245], v[24:27]
	v_mfma_f32_16x16x32_bf16 v[24:27], v[218:221], v[238:241], v[56:59]
	v_mfma_f32_16x16x32_bf16 v[116:119], v[214:217], v[28:31], v[64:67]
	v_mfma_f32_16x16x32_bf16 v[64:67], v[222:225], v[242:245], v[24:27]
	s_barrier
; template <class Epi, class Sched, bool ALIGN_EPI = false, bool SP2 = false, bool A_TILED = false>
; __device__ __forceinline__ void gemm_phase(PG8_LAS unsigned char* lds, const Gemm g, const Sched& S, const Epi& E, const int wave_s) {
;     ...
;         for (int t = PEEL ? 2 : 0; t < nt; t += 2) {
;             const bool last = (t == nt - 2);
;             const char* a1 = cA + (size_t)(t + 1) * kstepA;
;             const char* a2 = last ? nA : cA + (size_t)(t + 2) * kstepA; const char* b2 = last ? nB : cB + (size_t)(t + 2) * kstep;
;             const char* a3 = a2 + kstepA; const char* b3 = b2 + kstep;
;             if (last && has_next) S.a_ready(nxt);
	s_setprio 0
	s_add_i32 s71, s71, s15
	s_add_i32 s77, s71, 0x2000
	s_nop 1
	v_lshl_add_u64 v[24:25], v[250:251], 0, s[66:67]
	s_mov_b32 m0, s71
	s_add_u32 s82, s78, 0x80180
	ds_read_b128 v[32:35], v151 offset:49152
	ds_read_b128 v[36:39], v151 offset:50176
	ds_read_b128 v[226:229], v151 offset:51200
	ds_read_b128 v[230:233], v151 offset:52224
	ds_read_b128 v[234:237], v151 offset:53248
	ds_read_b128 v[238:241], v151 offset:54272
	ds_read_b128 v[242:245], v151 offset:55296
	ds_read_b128 v[246:249], v151 offset:56320
	global_load_lds_dwordx4 v[24:25], off
	v_lshl_add_u64 v[24:25], v[252:253], 0, s[66:67]
	s_mov_b32 m0, s77
	s_addc_u32 s83, s79, 0
	s_add_i32 s88, s88, s15
	global_load_lds_dwordx4 v[24:25], off
	v_lshl_add_u64 v[24:25], s[82:83], 0, v[128:129]
	s_mov_b32 m0, s88
	s_add_i32 s89, s88, 0x2000
	global_load_lds_dwordx4 v[24:25], off
	v_lshl_add_u64 v[24:25], s[82:83], 0, v[130:131]
	s_mov_b32 m0, s89
	s_nop 0
	global_load_lds_dwordx4 v[24:25], off
	v_lshl_add_u64 v[24:25], v[140:141], 0, s[66:67]
	s_mov_b32 m0, s43
	s_nop 0
	global_load_lds_dwordx4 v[24:25], off
	v_lshl_add_u64 v[24:25], v[142:143], 0, s[66:67]
	s_mov_b32 m0, s44
	s_nop 0
	global_load_lds_dwordx4 v[24:25], off
	s_waitcnt vmcnt(8) lgkmcnt(0)
	s_setprio 1
	s_barrier
	v_mfma_f32_16x16x32_bf16 v[24:27], v[8:11], v[32:35], v[154:157]
	v_mfma_f32_16x16x32_bf16 v[60:63], v[12:15], v[36:39], v[24:27]
	v_mfma_f32_16x16x32_bf16 v[24:27], v[16:19], v[32:35], v[158:161]
	v_mfma_f32_16x16x32_bf16 v[56:59], v[20:23], v[36:39], v[24:27]
	v_mfma_f32_16x16x32_bf16 v[24:27], v[8:11], v[226:229], v[162:165]
	v_mfma_f32_16x16x32_bf16 v[44:47], v[12:15], v[230:233], v[24:27]
	v_mfma_f32_16x16x32_bf16 v[24:27], v[16:19], v[226:229], v[166:169]
	v_mfma_f32_16x16x32_bf16 v[40:43], v[20:23], v[230:233], v[24:27]
	v_mfma_f32_16x16x32_bf16 v[24:27], v[8:11], v[234:237], v[170:173]
	v_mfma_f32_16x16x32_bf16 v[0:3], v[8:11], v[242:245], v[0:3]
	v_mfma_f32_16x16x32_bf16 v[28:31], v[12:15], v[238:241], v[24:27]
	v_mfma_f32_16x16x32_bf16 v[24:27], v[16:19], v[234:237], v[174:177]
	v_mfma_f32_16x16x32_bf16 v[12:15], v[12:15], v[246:249], v[0:3]
	v_mfma_f32_16x16x32_bf16 v[0:3], v[16:19], v[242:245], v[4:7]
	v_mfma_f32_16x16x32_bf16 v[24:27], v[20:23], v[238:241], v[24:27]
	v_mfma_f32_16x16x32_bf16 v[8:11], v[20:23], v[246:249], v[0:3]
	v_mfma_f32_16x16x32_bf16 v[0:3], v[210:213], v[32:35], v[178:181]
	v_mfma_f32_16x16x32_bf16 v[52:55], v[214:217], v[36:39], v[0:3]
	v_mfma_f32_16x16x32_bf16 v[0:3], v[218:221], v[32:35], v[182:185]
	v_mfma_f32_16x16x32_bf16 v[48:51], v[222:225], v[36:39], v[0:3]
	v_mfma_f32_16x16x32_bf16 v[0:3], v[210:213], v[226:229], v[186:189]
	v_mfma_f32_16x16x32_bf16 v[36:39], v[214:217], v[230:233], v[0:3]
	v_mfma_f32_16x16x32_bf16 v[0:3], v[218:221], v[226:229], v[190:193]
	v_mfma_f32_16x16x32_bf16 v[32:35], v[222:225], v[230:233], v[0:3]
	v_mfma_f32_16x16x32_bf16 v[0:3], v[210:213], v[234:237], v[194:197]
	v_mfma_f32_16x16x32_bf16 v[20:23], v[214:217], v[238:241], v[0:3]
	v_mfma_f32_16x16x32_bf16 v[0:3], v[218:221], v[234:237], v[198:201]
	v_mfma_f32_16x16x32_bf16 v[16:19], v[222:225], v[238:241], v[0:3]
	v_mfma_f32_16x16x32_bf16 v[0:3], v[210:213], v[242:245], v[202:205]
	v_mfma_f32_16x16x32_bf16 v[4:7], v[214:217], v[246:249], v[0:3]
	v_mfma_f32_16x16x32_bf16 v[0:3], v[218:221], v[242:245], v[206:209]
	v_mfma_f32_16x16x32_bf16 v[0:3], v[222:225], v[246:249], v[0:3]
	s_barrier
	s_setprio 0
	s_add_u32 s90, s78, 0x200
	s_addc_u32 s85, s79, 0
	s_add_u32 s78, s80, 0x80180
	s_addc_u32 s79, s81, 0
	s_mov_b32 s91, 0
.LBB0_1619:
	ds_read_b128 v[154:157], v149
	ds_read_b128 v[158:161], v149 offset:1024
	ds_read_b128 v[162:165], v149 offset:2048
	ds_read_b128 v[166:169], v149 offset:3072
	ds_read_b128 v[170:173], v150
	ds_read_b128 v[174:177], v150 offset:1024
	ds_read_b128 v[178:181], v150 offset:2048
	ds_read_b128 v[182:185], v150 offset:3072
	s_add_u32 s80, s78, 0xfff80080
	s_addc_u32 s81, s79, -1
	s_cmp_eq_u32 s91, 28
	s_cselect_b32 s83, s51, s81
	s_cselect_b32 s82, s52, s80
	s_cselect_b32 s81, s53, s85
	s_cselect_b32 s80, s54, s90
	s_mov_b32 m0, s55
	v_lshl_add_u64 v[140:141], s[78:79], 0, v[138:139]
	ds_read_b128 v[186:189], v151
	ds_read_b128 v[190:193], v151 offset:1024
	ds_read_b128 v[194:197], v151 offset:2048
	ds_read_b128 v[198:201], v151 offset:3072
	ds_read_b128 v[202:205], v151 offset:4096
	ds_read_b128 v[206:209], v151 offset:5120
	ds_read_b128 v[210:213], v151 offset:6144
	ds_read_b128 v[214:217], v151 offset:7168
	global_load_lds_dwordx4 v[140:141], off
	v_lshl_add_u64 v[140:141], s[78:79], 0, v[136:137]
	s_mov_b32 m0, s56
	s_nop 0
	global_load_lds_dwordx4 v[140:141], off
	s_waitcnt vmcnt(8) lgkmcnt(0)
	s_setprio 1
	s_barrier
	v_mfma_f32_16x16x32_bf16 v[124:127], v[154:157], v[186:189], v[124:127]
	v_mfma_f32_16x16x32_bf16 v[120:123], v[162:165], v[186:189], v[120:123]
	v_mfma_f32_16x16x32_bf16 v[108:111], v[154:157], v[194:197], v[108:111]
	v_mfma_f32_16x16x32_bf16 v[104:107], v[162:165], v[194:197], v[104:107]
	v_mfma_f32_16x16x32_bf16 v[92:95], v[154:157], v[202:205], v[92:95]
	v_mfma_f32_16x16x32_bf16 v[88:91], v[162:165], v[202:205], v[88:91]
	v_mfma_f32_16x16x32_bf16 v[76:79], v[154:157], v[210:213], v[76:79]
	v_mfma_f32_16x16x32_bf16 v[72:75], v[162:165], v[210:213], v[72:75]
	v_mfma_f32_16x16x32_bf16 v[124:127], v[158:161], v[190:193], v[124:127]
	v_mfma_f32_16x16x32_bf16 v[120:123], v[166:169], v[190:193], v[120:123]
	v_mfma_f32_16x16x32_bf16 v[108:111], v[158:161], v[198:201], v[108:111]
	v_mfma_f32_16x16x32_bf16 v[104:107], v[166:169], v[198:201], v[104:107]
	v_mfma_f32_16x16x32_bf16 v[92:95], v[158:161], v[206:209], v[92:95]
	v_mfma_f32_16x16x32_bf16 v[88:91], v[166:169], v[206:209], v[88:91]
	v_mfma_f32_16x16x32_bf16 v[76:79], v[158:161], v[214:217], v[76:79]
	v_mfma_f32_16x16x32_bf16 v[72:75], v[166:169], v[214:217], v[72:75]
	v_mfma_f32_16x16x32_bf16 v[116:119], v[170:173], v[186:189], v[116:119]
	v_mfma_f32_16x16x32_bf16 v[112:115], v[178:181], v[186:189], v[112:115]
	v_mfma_f32_16x16x32_bf16 v[100:103], v[170:173], v[194:197], v[100:103]
	v_mfma_f32_16x16x32_bf16 v[96:99], v[178:181], v[194:197], v[96:99]
	v_mfma_f32_16x16x32_bf16 v[84:87], v[170:173], v[202:205], v[84:87]
	v_mfma_f32_16x16x32_bf16 v[80:83], v[178:181], v[202:205], v[80:83]
	v_mfma_f32_16x16x32_bf16 v[68:71], v[170:173], v[210:213], v[68:71]
	v_mfma_f32_16x16x32_bf16 v[64:67], v[178:181], v[210:213], v[64:67]
	v_mfma_f32_16x16x32_bf16 v[116:119], v[174:177], v[190:193], v[116:119]
	v_mfma_f32_16x16x32_bf16 v[112:115], v[182:185], v[190:193], v[112:115]
	v_mfma_f32_16x16x32_bf16 v[100:103], v[174:177], v[198:201], v[100:103]
	v_mfma_f32_16x16x32_bf16 v[96:99], v[182:185], v[198:201], v[96:99]
	v_mfma_f32_16x16x32_bf16 v[84:87], v[174:177], v[206:209], v[84:87]
	v_mfma_f32_16x16x32_bf16 v[80:83], v[182:185], v[206:209], v[80:83]
	v_mfma_f32_16x16x32_bf16 v[68:71], v[174:177], v[214:217], v[68:71]
	v_mfma_f32_16x16x32_bf16 v[64:67], v[182:185], v[214:217], v[64:67]
	s_barrier
	s_setprio 0
	s_mov_b32 m0, s57
	v_lshl_add_u64 v[140:141], s[80:81], 0, v[128:129]
	s_add_u32 s94, s80, 0x80000
	ds_read_b128 v[186:189], v151 offset:16384
	ds_read_b128 v[190:193], v151 offset:17408
	ds_read_b128 v[194:197], v151 offset:18432
	ds_read_b128 v[198:201], v151 offset:19456
	ds_read_b128 v[202:205], v151 offset:20480
	ds_read_b128 v[206:209], v151 offset:21504
	ds_read_b128 v[210:213], v151 offset:22528
	ds_read_b128 v[214:217], v151 offset:23552
	global_load_lds_dwordx4 v[140:141], off
	v_lshl_add_u64 v[142:143], s[80:81], 0, v[130:131]
	s_mov_b32 m0, s58
	s_addc_u32 s95, s81, 0
	global_load_lds_dwordx4 v[142:143], off
	v_lshl_add_u64 v[146:147], s[94:95], 0, v[128:129]
	s_mov_b32 m0, s59
	v_lshl_add_u64 v[218:219], s[82:83], 0, v[132:133]
	global_load_lds_dwordx4 v[146:147], off
	v_lshl_add_u64 v[146:147], s[94:95], 0, v[130:131]
	s_mov_b32 m0, s69
	s_nop 0
	global_load_lds_dwordx4 v[146:147], off
	v_lshl_add_u64 v[146:147], s[82:83], 0, v[134:135]
	s_mov_b32 m0, s23
	s_nop 0
	global_load_lds_dwordx4 v[146:147], off
	s_mov_b32 m0, s36
	s_nop 0
	global_load_lds_dwordx4 v[218:219], off
	s_waitcnt vmcnt(8) lgkmcnt(0)
	s_setprio 1
	s_barrier
	v_mfma_f32_16x16x32_bf16 v[60:63], v[154:157], v[186:189], v[60:63]
	v_mfma_f32_16x16x32_bf16 v[56:59], v[162:165], v[186:189], v[56:59]
	v_mfma_f32_16x16x32_bf16 v[44:47], v[154:157], v[194:197], v[44:47]
	v_mfma_f32_16x16x32_bf16 v[40:43], v[162:165], v[194:197], v[40:43]
	v_mfma_f32_16x16x32_bf16 v[28:31], v[154:157], v[202:205], v[28:31]
	v_mfma_f32_16x16x32_bf16 v[24:27], v[162:165], v[202:205], v[24:27]
	v_mfma_f32_16x16x32_bf16 v[12:15], v[154:157], v[210:213], v[12:15]
	v_mfma_f32_16x16x32_bf16 v[8:11], v[162:165], v[210:213], v[8:11]
	v_mfma_f32_16x16x32_bf16 v[60:63], v[158:161], v[190:193], v[60:63]
	v_mfma_f32_16x16x32_bf16 v[56:59], v[166:169], v[190:193], v[56:59]
	v_mfma_f32_16x16x32_bf16 v[44:47], v[158:161], v[198:201], v[44:47]
	v_mfma_f32_16x16x32_bf16 v[40:43], v[166:169], v[198:201], v[40:43]
	v_mfma_f32_16x16x32_bf16 v[28:31], v[158:161], v[206:209], v[28:31]
	v_mfma_f32_16x16x32_bf16 v[24:27], v[166:169], v[206:209], v[24:27]
	v_mfma_f32_16x16x32_bf16 v[12:15], v[158:161], v[214:217], v[12:15]
	v_mfma_f32_16x16x32_bf16 v[8:11], v[166:169], v[214:217], v[8:11]
	v_mfma_f32_16x16x32_bf16 v[52:55], v[170:173], v[186:189], v[52:55]
	v_mfma_f32_16x16x32_bf16 v[48:51], v[178:181], v[186:189], v[48:51]
	v_mfma_f32_16x16x32_bf16 v[36:39], v[170:173], v[194:197], v[36:39]
	v_mfma_f32_16x16x32_bf16 v[32:35], v[178:181], v[194:197], v[32:35]
	v_mfma_f32_16x16x32_bf16 v[20:23], v[170:173], v[202:205], v[20:23]
	v_mfma_f32_16x16x32_bf16 v[16:19], v[178:181], v[202:205], v[16:19]
	v_mfma_f32_16x16x32_bf16 v[4:7], v[170:173], v[210:213], v[4:7]
	v_mfma_f32_16x16x32_bf16 v[0:3], v[178:181], v[210:213], v[0:3]
	v_mfma_f32_16x16x32_bf16 v[52:55], v[174:177], v[190:193], v[52:55]
	v_mfma_f32_16x16x32_bf16 v[48:51], v[182:185], v[190:193], v[48:51]
	v_mfma_f32_16x16x32_bf16 v[36:39], v[174:177], v[198:201], v[36:39]
	v_mfma_f32_16x16x32_bf16 v[32:35], v[182:185], v[198:201], v[32:35]
	v_mfma_f32_16x16x32_bf16 v[20:23], v[174:177], v[206:209], v[20:23]
	v_mfma_f32_16x16x32_bf16 v[16:19], v[182:185], v[206:209], v[16:19]
	v_mfma_f32_16x16x32_bf16 v[4:7], v[174:177], v[214:217], v[4:7]
	v_mfma_f32_16x16x32_bf16 v[0:3], v[182:185], v[214:217], v[0:3]
	s_barrier
; #define PG8_STAGE(bufoff, gbase, voff) do { _Pragma("unroll") for (int _i = 0; _i < 2; ++_i) \
;         __builtin_amdgcn_global_load_lds((const unsigned*)((const char*)(gbase) + (voff)[_i]), (PG8_LAS unsigned*)(lds + (bufoff) + ldsw + _i * 8192), 16, 0, 0); } while (0)
; #define PG8_BAR __builtin_amdgcn_s_barrier()
; template <class Epi, class Sched, bool ALIGN_EPI = false, bool SP2 = false, bool A_TILED = false>
; __device__ __forceinline__ void gemm_phase(PG8_LAS unsigned char* lds, const Gemm g, const Sched& S, const Epi& E, const int wave_s) {
;     ...
;         for (int t = PEEL ? 2 : 0; t < nt; t += 2) {
;             const bool last = (t == nt - 2);
;             const char* a1 = cA + (size_t)(t + 1) * kstepA;
;             const char* a2 = last ? nA : cA + (size_t)(t + 2) * kstepA; const char* b2 = last ? nB : cB + (size_t)(t + 2) * kstep;
;             const char* a3 = a2 + kstepA; const char* b3 = b2 + kstep;
;             if (last && has_next) S.a_ready(nxt);
;             if constexpr (SP2) {
;             PG8_ITER(PG8_MMA)
;             } else {
;             PG8_LDB(B0, 0, 0); PG8_SCHED; PG8_LDA(At, 0, 0); PG8_STAGE(PG8_SA(1, 1), a1 + hstepA, voffA);
;             PG8_WAIT_L(8); PG8_BAR; PG8_WAIT_L(0); PG8_MMA(0, 0, At, B0); PG8_BAR; PG8_SCHED;
;             PG8_LDB(B1, 0, 1); PG8_STAGE(PG8_SB(0, 0), b2, voffB);
;             PG8_BAR; PG8_WAIT_L(0); PG8_MMA(0, 1, At, B1); PG8_BAR;
;             PG8_LDA(At, 0, 1); PG8_STAGE(PG8_SA(0, 0), a2, voffA);
;             PG8_BAR; PG8_WAIT_L(0); PG8_MMA(1, 0, At, B0); PG8_BAR; PG8_SCHED;
;             PG8_STAGE(PG8_SB(0, 1), b2 + hstep, voffB);
;             PG8_WAIT_V(6); PG8_BAR; PG8_MMA(1, 1, At, B1); PG8_BAR;
;             PG8_LDB(B0, 1, 0); PG8_SCHED; PG8_LDA(At, 1, 0); PG8_STAGE(PG8_SA(0, 1), a2 + hstepA, voffA);
;             PG8_WAIT_L(8); PG8_BAR; PG8_WAIT_L(0); PG8_MMA(0, 0, At, B0); PG8_BAR; PG8_SCHED;
;             PG8_LDB(B1, 1, 1); PG8_STAGE(PG8_SB(1, 0), b3, voffB);
;             PG8_BAR; PG8_WAIT_L(0); PG8_MMA(0, 1, At, B1); PG8_BAR;
;             PG8_LDA(At, 1, 1); PG8_STAGE(PG8_SA(1, 0), a3, voffA);
;             PG8_BAR; PG8_WAIT_L(0); PG8_MMA(1, 0, At, B0); PG8_BAR; PG8_SCHED;
;             PG8_STAGE(PG8_SB(1, 1), b3 + hstep, voffB);
;             PG8_WAIT_V(6); PG8_BAR; PG8_MMA(1, 1, At, B1); PG8_BAR;
;             }
;         }
;         if constexpr (ALIGN_EPI) { if (wr == 0) PG8_BAR; }
	s_setprio 0
	ds_read_b128 v[154:157], v144
	ds_read_b128 v[158:161], v144 offset:1024
	ds_read_b128 v[162:165], v144 offset:2048
	ds_read_b128 v[166:169], v144 offset:3072
	ds_read_b128 v[170:173], v145
	ds_read_b128 v[174:177], v145 offset:1024
	ds_read_b128 v[178:181], v145 offset:2048
	ds_read_b128 v[182:185], v145 offset:3072
	s_add_u32 s82, s82, 0x80000
	s_addc_u32 s83, s83, 0
	s_mov_b32 m0, s37
	v_lshl_add_u64 v[220:221], s[82:83], 0, v[134:135]
	ds_read_b128 v[186:189], v151 offset:32768
	ds_read_b128 v[190:193], v151 offset:33792
	ds_read_b128 v[194:197], v151 offset:34816
	ds_read_b128 v[198:201], v151 offset:35840
	ds_read_b128 v[202:205], v151 offset:36864
	ds_read_b128 v[206:209], v151 offset:37888
	ds_read_b128 v[210:213], v151 offset:38912
	ds_read_b128 v[214:217], v151 offset:39936
	global_load_lds_dwordx4 v[220:221], off
	v_lshl_add_u64 v[220:221], s[82:83], 0, v[132:133]
	s_mov_b32 m0, s38
	s_nop 0
	global_load_lds_dwordx4 v[220:221], off
	s_waitcnt vmcnt(8) lgkmcnt(0)
	s_setprio 1
	s_barrier
	v_mfma_f32_16x16x32_bf16 v[124:127], v[154:157], v[186:189], v[124:127]
	v_mfma_f32_16x16x32_bf16 v[120:123], v[162:165], v[186:189], v[120:123]
	v_mfma_f32_16x16x32_bf16 v[108:111], v[154:157], v[194:197], v[108:111]
	v_mfma_f32_16x16x32_bf16 v[104:107], v[162:165], v[194:197], v[104:107]
	v_mfma_f32_16x16x32_bf16 v[92:95], v[154:157], v[202:205], v[92:95]
	v_mfma_f32_16x16x32_bf16 v[88:91], v[162:165], v[202:205], v[88:91]
	v_mfma_f32_16x16x32_bf16 v[76:79], v[154:157], v[210:213], v[76:79]
	v_mfma_f32_16x16x32_bf16 v[72:75], v[162:165], v[210:213], v[72:75]
	v_mfma_f32_16x16x32_bf16 v[124:127], v[158:161], v[190:193], v[124:127]
	v_mfma_f32_16x16x32_bf16 v[120:123], v[166:169], v[190:193], v[120:123]
	v_mfma_f32_16x16x32_bf16 v[108:111], v[158:161], v[198:201], v[108:111]
	v_mfma_f32_16x16x32_bf16 v[104:107], v[166:169], v[198:201], v[104:107]
	v_mfma_f32_16x16x32_bf16 v[92:95], v[158:161], v[206:209], v[92:95]
	v_mfma_f32_16x16x32_bf16 v[88:91], v[166:169], v[206:209], v[88:91]
	v_mfma_f32_16x16x32_bf16 v[76:79], v[158:161], v[214:217], v[76:79]
	v_mfma_f32_16x16x32_bf16 v[72:75], v[166:169], v[214:217], v[72:75]
	v_mfma_f32_16x16x32_bf16 v[116:119], v[170:173], v[186:189], v[116:119]
	v_mfma_f32_16x16x32_bf16 v[112:115], v[178:181], v[186:189], v[112:115]
	v_mfma_f32_16x16x32_bf16 v[100:103], v[170:173], v[194:197], v[100:103]
	v_mfma_f32_16x16x32_bf16 v[96:99], v[178:181], v[194:197], v[96:99]
	v_mfma_f32_16x16x32_bf16 v[84:87], v[170:173], v[202:205], v[84:87]
	v_mfma_f32_16x16x32_bf16 v[80:83], v[178:181], v[202:205], v[80:83]
	v_mfma_f32_16x16x32_bf16 v[68:71], v[170:173], v[210:213], v[68:71]
	v_mfma_f32_16x16x32_bf16 v[64:67], v[178:181], v[210:213], v[64:67]
	v_mfma_f32_16x16x32_bf16 v[116:119], v[174:177], v[190:193], v[116:119]
	v_mfma_f32_16x16x32_bf16 v[112:115], v[182:185], v[190:193], v[112:115]
	v_mfma_f32_16x16x32_bf16 v[100:103], v[174:177], v[198:201], v[100:103]
	v_mfma_f32_16x16x32_bf16 v[96:99], v[182:185], v[198:201], v[96:99]
	v_mfma_f32_16x16x32_bf16 v[84:87], v[174:177], v[206:209], v[84:87]
	v_mfma_f32_16x16x32_bf16 v[80:83], v[182:185], v[206:209], v[80:83]
	v_mfma_f32_16x16x32_bf16 v[68:71], v[174:177], v[214:217], v[68:71]
	v_mfma_f32_16x16x32_bf16 v[64:67], v[182:185], v[214:217], v[64:67]
	s_barrier
	s_setprio 0
	s_mov_b32 m0, s71
	v_lshl_add_u64 v[140:141], v[140:141], 0, s[60:61]
	s_add_u32 s80, s80, 0x80080
	ds_read_b128 v[186:189], v151 offset:49152
	ds_read_b128 v[190:193], v151 offset:50176
	ds_read_b128 v[194:197], v151 offset:51200
	ds_read_b128 v[198:201], v151 offset:52224
	ds_read_b128 v[202:205], v151 offset:53248
	ds_read_b128 v[206:209], v151 offset:54272
	ds_read_b128 v[210:213], v151 offset:55296
	ds_read_b128 v[214:217], v151 offset:56320
	global_load_lds_dwordx4 v[140:141], off
	v_lshl_add_u64 v[140:141], v[142:143], 0, s[60:61]
	s_mov_b32 m0, s77
	s_addc_u32 s81, s81, 0
	global_load_lds_dwordx4 v[140:141], off
	v_lshl_add_u64 v[140:141], s[80:81], 0, v[128:129]
	s_mov_b32 m0, s88
	s_nop 0
	global_load_lds_dwordx4 v[140:141], off
	v_lshl_add_u64 v[140:141], s[80:81], 0, v[130:131]
	s_mov_b32 m0, s89
	s_nop 0
	global_load_lds_dwordx4 v[140:141], off
	v_lshl_add_u64 v[140:141], v[146:147], 0, s[60:61]
	s_mov_b32 m0, s43
	s_nop 0
	global_load_lds_dwordx4 v[140:141], off
	v_lshl_add_u64 v[140:141], v[218:219], 0, s[60:61]
	s_mov_b32 m0, s44
	s_nop 0
	global_load_lds_dwordx4 v[140:141], off
	s_waitcnt vmcnt(8) lgkmcnt(0)
	s_setprio 1
	s_barrier
	v_mfma_f32_16x16x32_bf16 v[60:63], v[154:157], v[186:189], v[60:63]
	v_mfma_f32_16x16x32_bf16 v[56:59], v[162:165], v[186:189], v[56:59]
	v_mfma_f32_16x16x32_bf16 v[44:47], v[154:157], v[194:197], v[44:47]
	v_mfma_f32_16x16x32_bf16 v[40:43], v[162:165], v[194:197], v[40:43]
	v_mfma_f32_16x16x32_bf16 v[28:31], v[154:157], v[202:205], v[28:31]
	v_mfma_f32_16x16x32_bf16 v[24:27], v[162:165], v[202:205], v[24:27]
	v_mfma_f32_16x16x32_bf16 v[12:15], v[154:157], v[210:213], v[12:15]
	v_mfma_f32_16x16x32_bf16 v[8:11], v[162:165], v[210:213], v[8:11]
	v_mfma_f32_16x16x32_bf16 v[60:63], v[158:161], v[190:193], v[60:63]
	v_mfma_f32_16x16x32_bf16 v[56:59], v[166:169], v[190:193], v[56:59]
	v_mfma_f32_16x16x32_bf16 v[44:47], v[158:161], v[198:201], v[44:47]
	v_mfma_f32_16x16x32_bf16 v[40:43], v[166:169], v[198:201], v[40:43]
	v_mfma_f32_16x16x32_bf16 v[28:31], v[158:161], v[206:209], v[28:31]
	v_mfma_f32_16x16x32_bf16 v[24:27], v[166:169], v[206:209], v[24:27]
	v_mfma_f32_16x16x32_bf16 v[12:15], v[158:161], v[214:217], v[12:15]
	v_mfma_f32_16x16x32_bf16 v[8:11], v[166:169], v[214:217], v[8:11]
	v_mfma_f32_16x16x32_bf16 v[52:55], v[170:173], v[186:189], v[52:55]
	v_mfma_f32_16x16x32_bf16 v[48:51], v[178:181], v[186:189], v[48:51]
	v_mfma_f32_16x16x32_bf16 v[36:39], v[170:173], v[194:197], v[36:39]
	v_mfma_f32_16x16x32_bf16 v[32:35], v[178:181], v[194:197], v[32:35]
	v_mfma_f32_16x16x32_bf16 v[20:23], v[170:173], v[202:205], v[20:23]
	v_mfma_f32_16x16x32_bf16 v[16:19], v[178:181], v[202:205], v[16:19]
	v_mfma_f32_16x16x32_bf16 v[4:7], v[170:173], v[210:213], v[4:7]
	v_mfma_f32_16x16x32_bf16 v[0:3], v[178:181], v[210:213], v[0:3]
	v_mfma_f32_16x16x32_bf16 v[52:55], v[174:177], v[190:193], v[52:55]
	v_mfma_f32_16x16x32_bf16 v[48:51], v[182:185], v[190:193], v[48:51]
	v_mfma_f32_16x16x32_bf16 v[36:39], v[174:177], v[198:201], v[36:39]
	v_mfma_f32_16x16x32_bf16 v[32:35], v[182:185], v[198:201], v[32:35]
	v_mfma_f32_16x16x32_bf16 v[20:23], v[174:177], v[206:209], v[20:23]
	v_mfma_f32_16x16x32_bf16 v[16:19], v[182:185], v[206:209], v[16:19]
	v_mfma_f32_16x16x32_bf16 v[4:7], v[174:177], v[214:217], v[4:7]
	v_mfma_f32_16x16x32_bf16 v[0:3], v[182:185], v[214:217], v[0:3]
	s_barrier
	s_setprio 0
	s_add_i32 s91, s91, 2
	s_add_u32 s90, s90, 0x100
	s_addc_u32 s85, s85, 0
	s_add_u32 s78, s78, 0x100
	s_addc_u32 s79, s79, 0
	s_cmp_gt_u32 s91, 29
	s_cbranch_scc0 .LBB0_1619
	s_and_b64 vcc, exec, s[62:63]
	s_cbranch_vccz .LBB0_1622
	s_barrier

; template <class Epi, class Sched, bool ALIGN_EPI = false, bool SP2 = false, bool A_TILED = false>
; __device__ __forceinline__ void gemm_phase(PG8_LAS unsigned char* lds, const Gemm g, const Sched& S, const Epi& E, const int wave_s) {
;     ...
;         for (int t = PEEL ? 2 : 0; t < nt; t += 2) {
;             const bool last = (t == nt - 2);
;             const char* a1 = cA + (size_t)(t + 1) * kstepA;
;             const char* a2 = last ? nA : cA + (size_t)(t + 2) * kstepA; const char* b2 = last ? nB : cB + (size_t)(t + 2) * kstep;
;             const char* a3 = a2 + kstepA; const char* b3 = b2 + kstep;
;             if (last && has_next) S.a_ready(nxt);
.LBB0_1841:
	ds_read_b128 v[146:149], v140
	ds_read_b128 v[150:153], v140 offset:1024
	ds_read_b128 v[154:157], v140 offset:2048
	ds_read_b128 v[158:161], v140 offset:3072
	ds_read_b128 v[162:165], v141
	ds_read_b128 v[166:169], v141 offset:1024
	ds_read_b128 v[170:173], v141 offset:2048
	ds_read_b128 v[174:177], v141 offset:3072
	s_add_u32 s52, s60, s39
	s_addc_u32 s53, s61, s40
	s_add_u32 s54, s60, s37
	s_addc_u32 s55, s61, s38
	s_cmp_eq_u32 s41, 28
	s_cselect_b32 s71, s7, s53
	s_cselect_b32 s70, s6, s52
	s_cselect_b32 s69, s3, s55
	s_cselect_b32 s68, s2, s54
	s_mov_b32 m0, s42
	v_lshl_add_u64 v[210:211], s[60:61], 0, v[138:139]
	ds_read_b128 v[178:181], v142
	ds_read_b128 v[182:185], v142 offset:1024
	ds_read_b128 v[186:189], v142 offset:2048
	ds_read_b128 v[190:193], v142 offset:3072
	ds_read_b128 v[194:197], v142 offset:4096
	ds_read_b128 v[198:201], v142 offset:5120
	ds_read_b128 v[202:205], v142 offset:6144
	ds_read_b128 v[206:209], v142 offset:7168
	global_load_lds_dwordx4 v[210:211], off
	v_lshl_add_u64 v[210:211], s[60:61], 0, v[136:137]
	s_mov_b32 m0, s43
	s_nop 0
	global_load_lds_dwordx4 v[210:211], off
	s_waitcnt vmcnt(8) lgkmcnt(0)
	s_setprio 1
	s_barrier
	v_mfma_f32_16x16x32_bf16 v[8:11], v[146:149], v[178:181], v[8:11]
	v_mfma_f32_16x16x32_bf16 v[12:15], v[154:157], v[178:181], v[12:15]
	v_mfma_f32_16x16x32_bf16 v[60:63], v[146:149], v[186:189], v[60:63]
	v_mfma_f32_16x16x32_bf16 v[20:23], v[154:157], v[186:189], v[20:23]
	v_mfma_f32_16x16x32_bf16 v[76:79], v[146:149], v[194:197], v[76:79]
	v_mfma_f32_16x16x32_bf16 v[52:55], v[154:157], v[194:197], v[52:55]
	v_mfma_f32_16x16x32_bf16 v[128:131], v[146:149], v[202:205], v[128:131]
	v_mfma_f32_16x16x32_bf16 v[68:71], v[154:157], v[202:205], v[68:71]
	v_mfma_f32_16x16x32_bf16 v[8:11], v[150:153], v[182:185], v[8:11]
	v_mfma_f32_16x16x32_bf16 v[12:15], v[158:161], v[182:185], v[12:15]
	v_mfma_f32_16x16x32_bf16 v[60:63], v[150:153], v[190:193], v[60:63]
	v_mfma_f32_16x16x32_bf16 v[20:23], v[158:161], v[190:193], v[20:23]
	v_mfma_f32_16x16x32_bf16 v[76:79], v[150:153], v[198:201], v[76:79]
	v_mfma_f32_16x16x32_bf16 v[52:55], v[158:161], v[198:201], v[52:55]
	v_mfma_f32_16x16x32_bf16 v[128:131], v[150:153], v[206:209], v[128:131]
	v_mfma_f32_16x16x32_bf16 v[68:71], v[158:161], v[206:209], v[68:71]
	v_mfma_f32_16x16x32_bf16 v[24:27], v[162:165], v[178:181], v[24:27]
	v_mfma_f32_16x16x32_bf16 v[16:19], v[170:173], v[178:181], v[16:19]
	v_mfma_f32_16x16x32_bf16 v[56:59], v[162:165], v[186:189], v[56:59]
	v_mfma_f32_16x16x32_bf16 v[48:51], v[170:173], v[186:189], v[48:51]
	v_mfma_f32_16x16x32_bf16 v[72:75], v[162:165], v[194:197], v[72:75]
	v_mfma_f32_16x16x32_bf16 v[64:67], v[170:173], v[194:197], v[64:67]
	v_mfma_f32_16x16x32_bf16 v[108:111], v[162:165], v[202:205], v[108:111]
	v_mfma_f32_16x16x32_bf16 v[96:99], v[170:173], v[202:205], v[96:99]
	v_mfma_f32_16x16x32_bf16 v[24:27], v[166:169], v[182:185], v[24:27]
	v_mfma_f32_16x16x32_bf16 v[16:19], v[174:177], v[182:185], v[16:19]
	v_mfma_f32_16x16x32_bf16 v[56:59], v[166:169], v[190:193], v[56:59]
	v_mfma_f32_16x16x32_bf16 v[48:51], v[174:177], v[190:193], v[48:51]
	v_mfma_f32_16x16x32_bf16 v[72:75], v[166:169], v[198:201], v[72:75]
	v_mfma_f32_16x16x32_bf16 v[64:67], v[174:177], v[198:201], v[64:67]
	v_mfma_f32_16x16x32_bf16 v[108:111], v[166:169], v[206:209], v[108:111]
	v_mfma_f32_16x16x32_bf16 v[96:99], v[174:177], v[206:209], v[96:99]
	s_barrier
	s_setprio 0
	s_mov_b32 m0, s44
	v_lshl_add_u64 v[210:211], s[68:69], 0, v[34:35]
	s_add_u32 s52, s68, 0x80000
	ds_read_b128 v[178:181], v142 offset:16384
	ds_read_b128 v[182:185], v142 offset:17408
	ds_read_b128 v[186:189], v142 offset:18432
	ds_read_b128 v[190:193], v142 offset:19456
	ds_read_b128 v[194:197], v142 offset:20480
	ds_read_b128 v[198:201], v142 offset:21504
	ds_read_b128 v[202:205], v142 offset:22528
	ds_read_b128 v[206:209], v142 offset:23552
	global_load_lds_dwordx4 v[210:211], off
	v_lshl_add_u64 v[212:213], s[68:69], 0, v[134:135]
	s_mov_b32 m0, s45
	s_addc_u32 s53, s69, 0
	global_load_lds_dwordx4 v[212:213], off
	v_lshl_add_u64 v[214:215], s[52:53], 0, v[34:35]
	s_mov_b32 m0, s46
	v_lshl_add_u64 v[216:217], s[70:71], 0, v[132:133]
	global_load_lds_dwordx4 v[214:215], off
	v_lshl_add_u64 v[214:215], s[52:53], 0, v[134:135]
	s_mov_b32 m0, s47
	s_nop 0
	global_load_lds_dwordx4 v[214:215], off
	v_lshl_add_u64 v[214:215], s[70:71], 0, v[32:33]
	s_mov_b32 m0, s14
	s_nop 0
	global_load_lds_dwordx4 v[214:215], off
	s_mov_b32 m0, s15
	s_nop 0
	global_load_lds_dwordx4 v[216:217], off
	s_waitcnt vmcnt(8) lgkmcnt(0)
	s_setprio 1
	s_barrier
	v_mfma_f32_16x16x32_bf16 v[100:103], v[146:149], v[178:181], v[100:103]
	v_mfma_f32_16x16x32_bf16 v[104:107], v[154:157], v[178:181], v[104:107]
	v_mfma_f32_16x16x32_bf16 v[116:119], v[146:149], v[186:189], v[116:119]
	v_mfma_f32_16x16x32_bf16 v[120:123], v[154:157], v[186:189], v[120:123]
	v_mfma_f32_16x16x32_bf16 v[84:87], v[146:149], v[194:197], v[84:87]
	v_mfma_f32_16x16x32_bf16 v[80:83], v[154:157], v[194:197], v[80:83]
	v_mfma_f32_16x16x32_bf16 v[36:39], v[146:149], v[202:205], v[36:39]
	v_mfma_f32_16x16x32_bf16 v[28:31], v[154:157], v[202:205], v[28:31]
	v_mfma_f32_16x16x32_bf16 v[100:103], v[150:153], v[182:185], v[100:103]
	v_mfma_f32_16x16x32_bf16 v[104:107], v[158:161], v[182:185], v[104:107]
	v_mfma_f32_16x16x32_bf16 v[116:119], v[150:153], v[190:193], v[116:119]
	v_mfma_f32_16x16x32_bf16 v[120:123], v[158:161], v[190:193], v[120:123]
	v_mfma_f32_16x16x32_bf16 v[84:87], v[150:153], v[198:201], v[84:87]
	v_mfma_f32_16x16x32_bf16 v[80:83], v[158:161], v[198:201], v[80:83]
	v_mfma_f32_16x16x32_bf16 v[36:39], v[150:153], v[206:209], v[36:39]
	v_mfma_f32_16x16x32_bf16 v[28:31], v[158:161], v[206:209], v[28:31]
	v_mfma_f32_16x16x32_bf16 v[124:127], v[162:165], v[178:181], v[124:127]
	v_mfma_f32_16x16x32_bf16 v[112:115], v[170:173], v[178:181], v[112:115]
	v_mfma_f32_16x16x32_bf16 v[92:95], v[162:165], v[186:189], v[92:95]
	v_mfma_f32_16x16x32_bf16 v[88:91], v[170:173], v[186:189], v[88:91]
	v_mfma_f32_16x16x32_bf16 v[44:47], v[162:165], v[194:197], v[44:47]
	v_mfma_f32_16x16x32_bf16 v[40:43], v[170:173], v[194:197], v[40:43]
	v_mfma_f32_16x16x32_bf16 v[4:7], v[162:165], v[202:205], v[4:7]
	v_mfma_f32_16x16x32_bf16 v[0:3], v[170:173], v[202:205], v[0:3]
	v_mfma_f32_16x16x32_bf16 v[124:127], v[166:169], v[182:185], v[124:127]
	v_mfma_f32_16x16x32_bf16 v[112:115], v[174:177], v[182:185], v[112:115]
	v_mfma_f32_16x16x32_bf16 v[92:95], v[166:169], v[190:193], v[92:95]
	v_mfma_f32_16x16x32_bf16 v[88:91], v[174:177], v[190:193], v[88:91]
	v_mfma_f32_16x16x32_bf16 v[44:47], v[166:169], v[198:201], v[44:47]
	v_mfma_f32_16x16x32_bf16 v[40:43], v[174:177], v[198:201], v[40:43]
	v_mfma_f32_16x16x32_bf16 v[4:7], v[166:169], v[206:209], v[4:7]
	v_mfma_f32_16x16x32_bf16 v[0:3], v[174:177], v[206:209], v[0:3]
	s_barrier
	s_setprio 0
	ds_read_b128 v[146:149], v143
	ds_read_b128 v[150:153], v143 offset:1024
	ds_read_b128 v[154:157], v143 offset:2048
	ds_read_b128 v[158:161], v143 offset:3072
	ds_read_b128 v[162:165], v144
	ds_read_b128 v[166:169], v144 offset:1024
	ds_read_b128 v[170:173], v144 offset:2048
	ds_read_b128 v[174:177], v144 offset:3072
	s_add_u32 s52, s70, 0x80000
	s_addc_u32 s53, s71, 0
	s_mov_b32 m0, s21
	v_lshl_add_u64 v[218:219], s[52:53], 0, v[32:33]
	ds_read_b128 v[178:181], v142 offset:32768
	ds_read_b128 v[182:185], v142 offset:33792
	ds_read_b128 v[186:189], v142 offset:34816
	ds_read_b128 v[190:193], v142 offset:35840
	ds_read_b128 v[194:197], v142 offset:36864
	ds_read_b128 v[198:201], v142 offset:37888
	ds_read_b128 v[202:205], v142 offset:38912
	ds_read_b128 v[206:209], v142 offset:39936
	global_load_lds_dwordx4 v[218:219], off
	v_lshl_add_u64 v[218:219], s[52:53], 0, v[132:133]
	s_mov_b32 m0, s22
	s_nop 0
	global_load_lds_dwordx4 v[218:219], off
	s_waitcnt vmcnt(8) lgkmcnt(0)
	s_setprio 1
	s_barrier
	v_mfma_f32_16x16x32_bf16 v[8:11], v[146:149], v[178:181], v[8:11]
	v_mfma_f32_16x16x32_bf16 v[12:15], v[154:157], v[178:181], v[12:15]
	v_mfma_f32_16x16x32_bf16 v[60:63], v[146:149], v[186:189], v[60:63]
	v_mfma_f32_16x16x32_bf16 v[20:23], v[154:157], v[186:189], v[20:23]
	v_mfma_f32_16x16x32_bf16 v[76:79], v[146:149], v[194:197], v[76:79]
	v_mfma_f32_16x16x32_bf16 v[52:55], v[154:157], v[194:197], v[52:55]
	v_mfma_f32_16x16x32_bf16 v[128:131], v[146:149], v[202:205], v[128:131]
	v_mfma_f32_16x16x32_bf16 v[68:71], v[154:157], v[202:205], v[68:71]
	v_mfma_f32_16x16x32_bf16 v[8:11], v[150:153], v[182:185], v[8:11]
	v_mfma_f32_16x16x32_bf16 v[12:15], v[158:161], v[182:185], v[12:15]
	v_mfma_f32_16x16x32_bf16 v[60:63], v[150:153], v[190:193], v[60:63]
	v_mfma_f32_16x16x32_bf16 v[20:23], v[158:161], v[190:193], v[20:23]
	v_mfma_f32_16x16x32_bf16 v[76:79], v[150:153], v[198:201], v[76:79]
	v_mfma_f32_16x16x32_bf16 v[52:55], v[158:161], v[198:201], v[52:55]
	v_mfma_f32_16x16x32_bf16 v[128:131], v[150:153], v[206:209], v[128:131]
	v_mfma_f32_16x16x32_bf16 v[68:71], v[158:161], v[206:209], v[68:71]
	v_mfma_f32_16x16x32_bf16 v[24:27], v[162:165], v[178:181], v[24:27]
	v_mfma_f32_16x16x32_bf16 v[16:19], v[170:173], v[178:181], v[16:19]
	v_mfma_f32_16x16x32_bf16 v[56:59], v[162:165], v[186:189], v[56:59]
	v_mfma_f32_16x16x32_bf16 v[48:51], v[170:173], v[186:189], v[48:51]
	v_mfma_f32_16x16x32_bf16 v[72:75], v[162:165], v[194:197], v[72:75]
	v_mfma_f32_16x16x32_bf16 v[64:67], v[170:173], v[194:197], v[64:67]
	v_mfma_f32_16x16x32_bf16 v[108:111], v[162:165], v[202:205], v[108:111]
	v_mfma_f32_16x16x32_bf16 v[96:99], v[170:173], v[202:205], v[96:99]
	v_mfma_f32_16x16x32_bf16 v[24:27], v[166:169], v[182:185], v[24:27]
	v_mfma_f32_16x16x32_bf16 v[16:19], v[174:177], v[182:185], v[16:19]
	v_mfma_f32_16x16x32_bf16 v[56:59], v[166:169], v[190:193], v[56:59]
	v_mfma_f32_16x16x32_bf16 v[48:51], v[174:177], v[190:193], v[48:51]
	v_mfma_f32_16x16x32_bf16 v[72:75], v[166:169], v[198:201], v[72:75]
	v_mfma_f32_16x16x32_bf16 v[64:67], v[174:177], v[198:201], v[64:67]
	v_mfma_f32_16x16x32_bf16 v[108:111], v[166:169], v[206:209], v[108:111]
	v_mfma_f32_16x16x32_bf16 v[96:99], v[174:177], v[206:209], v[96:99]
	s_barrier
; #define PG8_WAIT_V(n) asm volatile("s_waitcnt vmcnt(" #n ")" ::: "memory")
; #define PG8_BAR __builtin_amdgcn_s_barrier()
; template <class Epi, class Sched, bool ALIGN_EPI = false, bool SP2 = false, bool A_TILED = false>
; __device__ __forceinline__ void gemm_phase(PG8_LAS unsigned char* lds, const Gemm g, const Sched& S, const Epi& E, const int wave_s) {
;     ...
;     PG8_WAIT_V(0);
;     if constexpr (!ALIGN_EPI) { if (wr == 0) PG8_BAR; }
	s_setprio 0
	s_mov_b32 m0, s48
	v_lshl_add_u64 v[210:211], v[210:211], 0, s[64:65]
	s_add_u32 s52, s68, 0x80080
	ds_read_b128 v[178:181], v142 offset:49152
	ds_read_b128 v[182:185], v142 offset:50176
	ds_read_b128 v[186:189], v142 offset:51200
	ds_read_b128 v[190:193], v142 offset:52224
	ds_read_b128 v[194:197], v142 offset:53248
	ds_read_b128 v[198:201], v142 offset:54272
	ds_read_b128 v[202:205], v142 offset:55296
	ds_read_b128 v[206:209], v142 offset:56320
	global_load_lds_dwordx4 v[210:211], off
	v_lshl_add_u64 v[210:211], v[212:213], 0, s[64:65]
	s_mov_b32 m0, s49
	s_addc_u32 s53, s69, 0
	global_load_lds_dwordx4 v[210:211], off
	v_lshl_add_u64 v[210:211], s[52:53], 0, v[34:35]
	s_mov_b32 m0, s50
	s_nop 0
	global_load_lds_dwordx4 v[210:211], off
	v_lshl_add_u64 v[210:211], s[52:53], 0, v[134:135]
	s_mov_b32 m0, s51
	s_nop 0
	global_load_lds_dwordx4 v[210:211], off
	v_lshl_add_u64 v[210:211], v[214:215], 0, s[64:65]
	s_mov_b32 m0, s23
	s_nop 0
	global_load_lds_dwordx4 v[210:211], off
	v_lshl_add_u64 v[210:211], v[216:217], 0, s[64:65]
	s_mov_b32 m0, s36
	s_nop 0
	global_load_lds_dwordx4 v[210:211], off
	s_waitcnt vmcnt(8) lgkmcnt(0)
	s_setprio 1
	s_barrier
	v_mfma_f32_16x16x32_bf16 v[100:103], v[146:149], v[178:181], v[100:103]
	v_mfma_f32_16x16x32_bf16 v[104:107], v[154:157], v[178:181], v[104:107]
	v_mfma_f32_16x16x32_bf16 v[116:119], v[146:149], v[186:189], v[116:119]
	v_mfma_f32_16x16x32_bf16 v[120:123], v[154:157], v[186:189], v[120:123]
	v_mfma_f32_16x16x32_bf16 v[84:87], v[146:149], v[194:197], v[84:87]
	v_mfma_f32_16x16x32_bf16 v[80:83], v[154:157], v[194:197], v[80:83]
	v_mfma_f32_16x16x32_bf16 v[36:39], v[146:149], v[202:205], v[36:39]
	v_mfma_f32_16x16x32_bf16 v[28:31], v[154:157], v[202:205], v[28:31]
	v_mfma_f32_16x16x32_bf16 v[100:103], v[150:153], v[182:185], v[100:103]
	v_mfma_f32_16x16x32_bf16 v[104:107], v[158:161], v[182:185], v[104:107]
	v_mfma_f32_16x16x32_bf16 v[116:119], v[150:153], v[190:193], v[116:119]
	v_mfma_f32_16x16x32_bf16 v[120:123], v[158:161], v[190:193], v[120:123]
	v_mfma_f32_16x16x32_bf16 v[84:87], v[150:153], v[198:201], v[84:87]
	v_mfma_f32_16x16x32_bf16 v[80:83], v[158:161], v[198:201], v[80:83]
	v_mfma_f32_16x16x32_bf16 v[36:39], v[150:153], v[206:209], v[36:39]
	v_mfma_f32_16x16x32_bf16 v[28:31], v[158:161], v[206:209], v[28:31]
	v_mfma_f32_16x16x32_bf16 v[124:127], v[162:165], v[178:181], v[124:127]
	v_mfma_f32_16x16x32_bf16 v[112:115], v[170:173], v[178:181], v[112:115]
	v_mfma_f32_16x16x32_bf16 v[92:95], v[162:165], v[186:189], v[92:95]
	v_mfma_f32_16x16x32_bf16 v[88:91], v[170:173], v[186:189], v[88:91]
	v_mfma_f32_16x16x32_bf16 v[44:47], v[162:165], v[194:197], v[44:47]
	v_mfma_f32_16x16x32_bf16 v[40:43], v[170:173], v[194:197], v[40:43]
	v_mfma_f32_16x16x32_bf16 v[4:7], v[162:165], v[202:205], v[4:7]
	v_mfma_f32_16x16x32_bf16 v[0:3], v[170:173], v[202:205], v[0:3]
	v_mfma_f32_16x16x32_bf16 v[124:127], v[166:169], v[182:185], v[124:127]
	v_mfma_f32_16x16x32_bf16 v[112:115], v[174:177], v[182:185], v[112:115]
	v_mfma_f32_16x16x32_bf16 v[92:95], v[166:169], v[190:193], v[92:95]
	v_mfma_f32_16x16x32_bf16 v[88:91], v[174:177], v[190:193], v[88:91]
	v_mfma_f32_16x16x32_bf16 v[44:47], v[166:169], v[198:201], v[44:47]
	v_mfma_f32_16x16x32_bf16 v[40:43], v[174:177], v[198:201], v[40:43]
	v_mfma_f32_16x16x32_bf16 v[4:7], v[166:169], v[206:209], v[4:7]
	v_mfma_f32_16x16x32_bf16 v[0:3], v[174:177], v[206:209], v[0:3]
	s_barrier
	s_setprio 0
	s_add_i32 s41, s41, 2
	s_add_u32 s37, s37, 0x100
	s_addc_u32 s38, s38, 0
	s_add_u32 s39, s39, 0x100
	s_addc_u32 s40, s40, 0
	v_lshl_add_u64 v[136:137], v[136:137], 0, s[66:67]
	s_cmp_gt_u32 s41, 29
	v_lshl_add_u64 v[138:139], v[138:139], 0, s[66:67]
	s_cbranch_scc0 .LBB0_1841
	s_waitcnt vmcnt(0)
	s_cmpk_lt_u32 s0, 0x100
	s_cbranch_scc0 .LBB0_1844
	s_barrier

; template <class Epi, class Sched, bool ALIGN_EPI = false, bool SP2 = false, bool A_TILED = false>
; __device__ __forceinline__ void gemm_phase(PG8_LAS unsigned char* lds, const Gemm g, const Sched& S, const Epi& E, const int wave_s) {
;     ...
;         const bool has_next = Epi::AFTER_DRAIN ? false : S.next(ui + 1, nxt);
;         const char* nA = has_next ? (const char*)g.A + (size_t)nxt.pm * tstepA : cA; const char* nB = has_next ? (const char*)g.Bt + (size_t)nxt.pn * tstep : cB;
;         constexpr bool PEEL = SP2 && !Epi::AFTER_DRAIN;
;         if constexpr (PEEL) {
;             const char* a1 = cA + kstepA; const char* a2 = cA + 2 * kstepA; const char* b2 = cB + 2 * kstep; const char* a3 = a2 + kstepA; const char* b3 = b2 + kstep;
;             PG8_ITER(PG8_MMAZ)
.LBB0_1952:
	s_ashr_i32 s69, s68, 31
	s_lshl_b64 s[50:51], s[68:69], 20
	s_add_u32 s70, s1, s50
	ds_read_b128 v[0:3], v145
	ds_read_b128 v[4:7], v145 offset:1024
	ds_read_b128 v[8:11], v145 offset:2048
	ds_read_b128 v[12:15], v145 offset:3072
	ds_read_b128 v[16:19], v146
	ds_read_b128 v[20:23], v146 offset:1024
	ds_read_b128 v[24:27], v146 offset:2048
	ds_read_b128 v[28:31], v146 offset:3072
	s_addc_u32 s71, s8, s51
	s_ashr_i32 s67, s66, 31
	s_lshl_b64 s[50:51], s[66:67], 20
	s_add_u32 s72, s9, s50
	s_addc_u32 s73, s14, s51
	s_and_b64 s[50:51], s[2:3], exec
	s_cselect_b32 s50, s71, s79
	s_cselect_b32 s51, s70, s78
	s_cselect_b32 s52, s73, s77
	s_cselect_b32 s53, s72, s76
	s_add_u32 s56, s78, 0x80080
	s_addc_u32 s57, s79, 0
	s_add_i32 s54, s22, 0xc000
	v_lshl_add_u64 v[64:65], s[56:57], 0, v[134:135]
	s_mov_b32 m0, s54
	s_add_i32 s55, s22, 0xe000
	ds_read_b128 v[32:35], v147
	ds_read_b128 v[36:39], v147 offset:1024
	ds_read_b128 v[40:43], v147 offset:2048
	ds_read_b128 v[44:47], v147 offset:3072
	ds_read_b128 v[48:51], v147 offset:4096
	ds_read_b128 v[52:55], v147 offset:5120
	ds_read_b128 v[56:59], v147 offset:6144
	ds_read_b128 v[60:63], v147 offset:7168
	global_load_lds_dwordx4 v[64:65], off
	v_lshl_add_u64 v[64:65], s[56:57], 0, v[132:133]
	s_mov_b32 m0, s55
	s_nop 0
	global_load_lds_dwordx4 v[64:65], off
	s_waitcnt vmcnt(8) lgkmcnt(0)
	s_setprio 1
	s_barrier
	v_mfma_f32_16x16x32_bf16 v[88:91], v[0:3], v[56:59], 0
	v_mfma_f32_16x16x32_bf16 v[64:67], v[0:3], v[32:35], 0
	v_mfma_f32_16x16x32_bf16 v[68:71], v[8:11], v[32:35], 0
	v_mfma_f32_16x16x32_bf16 v[72:75], v[0:3], v[40:43], 0
	v_mfma_f32_16x16x32_bf16 v[76:79], v[8:11], v[40:43], 0
	v_mfma_f32_16x16x32_bf16 v[80:83], v[0:3], v[48:51], 0
	v_mfma_f32_16x16x32_bf16 v[84:87], v[8:11], v[48:51], 0
	v_mfma_f32_16x16x32_bf16 v[96:99], v[4:7], v[60:63], v[88:91]
	v_mfma_f32_16x16x32_bf16 v[88:91], v[8:11], v[56:59], 0
	v_mfma_f32_16x16x32_bf16 v[64:67], v[4:7], v[36:39], v[64:67]
	v_mfma_f32_16x16x32_bf16 v[68:71], v[12:15], v[36:39], v[68:71]
	v_mfma_f32_16x16x32_bf16 v[72:75], v[4:7], v[44:47], v[72:75]
	v_mfma_f32_16x16x32_bf16 v[76:79], v[12:15], v[44:47], v[76:79]
	v_mfma_f32_16x16x32_bf16 v[80:83], v[4:7], v[52:55], v[80:83]
	v_mfma_f32_16x16x32_bf16 v[84:87], v[12:15], v[52:55], v[84:87]
	v_mfma_f32_16x16x32_bf16 v[100:103], v[12:15], v[60:63], v[88:91]
	v_mfma_f32_16x16x32_bf16 v[88:91], v[16:19], v[32:35], 0
	v_mfma_f32_16x16x32_bf16 v[32:35], v[24:27], v[32:35], 0
	v_mfma_f32_16x16x32_bf16 v[112:115], v[20:23], v[36:39], v[88:91]
	v_mfma_f32_16x16x32_bf16 v[32:35], v[28:31], v[36:39], v[32:35]
	v_mfma_f32_16x16x32_bf16 v[36:39], v[16:19], v[40:43], 0
	v_mfma_f32_16x16x32_bf16 v[40:43], v[24:27], v[40:43], 0
	v_mfma_f32_16x16x32_bf16 v[36:39], v[20:23], v[44:47], v[36:39]
	v_mfma_f32_16x16x32_bf16 v[40:43], v[28:31], v[44:47], v[40:43]
	v_mfma_f32_16x16x32_bf16 v[44:47], v[16:19], v[48:51], 0
	v_mfma_f32_16x16x32_bf16 v[48:51], v[24:27], v[48:51], 0
	v_mfma_f32_16x16x32_bf16 v[44:47], v[20:23], v[52:55], v[44:47]
	v_mfma_f32_16x16x32_bf16 v[48:51], v[28:31], v[52:55], v[48:51]
	v_mfma_f32_16x16x32_bf16 v[52:55], v[16:19], v[56:59], 0
	v_mfma_f32_16x16x32_bf16 v[56:59], v[24:27], v[56:59], 0
	v_mfma_f32_16x16x32_bf16 v[52:55], v[20:23], v[60:63], v[52:55]
	v_mfma_f32_16x16x32_bf16 v[56:59], v[28:31], v[60:63], v[56:59]
	s_barrier
	s_setprio 0
	s_add_i32 s56, s47, s15
	v_lshl_add_u64 v[242:243], s[76:77], 0, v[128:129]
	s_add_i32 s57, s56, 0x2000
	v_lshl_add_u64 v[148:149], v[242:243], 0, s[62:63]
	s_mov_b32 m0, s56
	v_lshl_add_u64 v[244:245], s[76:77], 0, v[130:131]
	s_add_u32 s80, s76, 0x80100
	ds_read_b128 v[60:63], v147 offset:16384
	ds_read_b128 v[88:91], v147 offset:17408
	ds_read_b128 v[92:95], v147 offset:18432
	ds_read_b128 v[104:107], v147 offset:19456
	ds_read_b128 v[108:111], v147 offset:20480
	ds_read_b128 v[116:119], v147 offset:21504
	ds_read_b128 v[120:123], v147 offset:22528
	ds_read_b128 v[124:127], v147 offset:23552
	global_load_lds_dwordx4 v[148:149], off
	v_lshl_add_u64 v[148:149], v[244:245], 0, s[62:63]
	s_mov_b32 m0, s57
	s_addc_u32 s81, s77, 0
	s_add_i32 s58, s48, s15
	global_load_lds_dwordx4 v[148:149], off
	v_lshl_add_u64 v[148:149], s[80:81], 0, v[128:129]
	s_mov_b32 m0, s58
	s_add_i32 s59, s58, 0x2000
	global_load_lds_dwordx4 v[148:149], off
	v_lshl_add_u64 v[148:149], s[80:81], 0, v[130:131]
	s_mov_b32 m0, s59
	v_lshl_add_u64 v[246:247], s[78:79], 0, v[134:135]
	global_load_lds_dwordx4 v[148:149], off
	v_lshl_add_u64 v[148:149], v[246:247], 0, s[62:63]
	s_mov_b32 m0, s22
	v_lshl_add_u64 v[248:249], s[78:79], 0, v[132:133]
	global_load_lds_dwordx4 v[148:149], off
	v_lshl_add_u64 v[148:149], v[248:249], 0, s[62:63]
	s_mov_b32 m0, s23
	s_nop 0
	global_load_lds_dwordx4 v[148:149], off
	s_waitcnt vmcnt(8) lgkmcnt(0)
	s_setprio 1
	s_barrier
	v_mfma_f32_16x16x32_bf16 v[148:151], v[0:3], v[60:63], 0
	v_mfma_f32_16x16x32_bf16 v[158:161], v[0:3], v[92:95], 0
	v_mfma_f32_16x16x32_bf16 v[166:169], v[0:3], v[108:111], 0
	v_mfma_f32_16x16x32_bf16 v[0:3], v[0:3], v[120:123], 0
	v_mfma_f32_16x16x32_bf16 v[150:153], v[4:7], v[88:91], v[148:151]
	v_mfma_f32_16x16x32_bf16 v[158:161], v[4:7], v[104:107], v[158:161]
	v_mfma_f32_16x16x32_bf16 v[166:169], v[4:7], v[116:119], v[166:169]
	v_mfma_f32_16x16x32_bf16 v[0:3], v[4:7], v[124:127], v[0:3]
	v_mfma_f32_16x16x32_bf16 v[4:7], v[8:11], v[120:123], 0
	v_mfma_f32_16x16x32_bf16 v[154:157], v[8:11], v[60:63], 0
	v_mfma_f32_16x16x32_bf16 v[162:165], v[8:11], v[92:95], 0
	v_mfma_f32_16x16x32_bf16 v[170:173], v[8:11], v[108:111], 0
	v_mfma_f32_16x16x32_bf16 v[4:7], v[12:15], v[124:127], v[4:7]
	v_mfma_f32_16x16x32_bf16 v[154:157], v[12:15], v[88:91], v[154:157]
	v_mfma_f32_16x16x32_bf16 v[162:165], v[12:15], v[104:107], v[162:165]
	v_mfma_f32_16x16x32_bf16 v[170:173], v[12:15], v[116:119], v[170:173]
	v_mfma_f32_16x16x32_bf16 v[8:11], v[16:19], v[60:63], 0
	v_mfma_f32_16x16x32_bf16 v[174:177], v[20:23], v[88:91], v[8:11]
	v_mfma_f32_16x16x32_bf16 v[8:11], v[24:27], v[60:63], 0
	v_mfma_f32_16x16x32_bf16 v[60:63], v[28:31], v[88:91], v[8:11]
	v_mfma_f32_16x16x32_bf16 v[8:11], v[16:19], v[92:95], 0
	v_mfma_f32_16x16x32_bf16 v[178:181], v[20:23], v[104:107], v[8:11]
	v_mfma_f32_16x16x32_bf16 v[8:11], v[24:27], v[92:95], 0
	v_mfma_f32_16x16x32_bf16 v[182:185], v[28:31], v[104:107], v[8:11]
	v_mfma_f32_16x16x32_bf16 v[8:11], v[16:19], v[108:111], 0
	v_mfma_f32_16x16x32_bf16 v[186:189], v[20:23], v[116:119], v[8:11]
	v_mfma_f32_16x16x32_bf16 v[8:11], v[24:27], v[108:111], 0
	v_mfma_f32_16x16x32_bf16 v[190:193], v[28:31], v[116:119], v[8:11]
	v_mfma_f32_16x16x32_bf16 v[8:11], v[16:19], v[120:123], 0
	v_mfma_f32_16x16x32_bf16 v[194:197], v[20:23], v[124:127], v[8:11]
	v_mfma_f32_16x16x32_bf16 v[8:11], v[24:27], v[120:123], 0
	v_mfma_f32_16x16x32_bf16 v[198:201], v[28:31], v[124:127], v[8:11]
	s_barrier
	s_setprio 0
	s_add_i32 s67, 0, 0x18000
	s_add_i32 s75, 0, 0x1c000
	v_add_u32_e32 v148, s67, v144
	v_add_u32_e32 v149, s75, v144
	s_nop 0
	ds_read_b128 v[8:11], v148
	ds_read_b128 v[12:15], v148 offset:1024
	ds_read_b128 v[16:19], v148 offset:2048
	ds_read_b128 v[20:23], v148 offset:3072
	ds_read_b128 v[202:205], v149
	ds_read_b128 v[206:209], v149 offset:1024
	ds_read_b128 v[210:213], v149 offset:2048
	ds_read_b128 v[214:217], v149 offset:3072
	s_add_u32 s80, s78, 0x80100
	s_addc_u32 s81, s79, 0
	s_mov_b32 m0, s36
	v_lshl_add_u64 v[88:89], s[80:81], 0, v[134:135]
	ds_read_b128 v[24:27], v147 offset:32768
	ds_read_b128 v[28:31], v147 offset:33792
	ds_read_b128 v[218:221], v147 offset:34816
	ds_read_b128 v[222:225], v147 offset:35840
	ds_read_b128 v[226:229], v147 offset:36864
	ds_read_b128 v[230:233], v147 offset:37888
	ds_read_b128 v[234:237], v147 offset:38912
	ds_read_b128 v[238:241], v147 offset:39936
	global_load_lds_dwordx4 v[88:89], off
	v_lshl_add_u64 v[88:89], s[80:81], 0, v[132:133]
	s_mov_b32 m0, s37
	s_nop 0
	global_load_lds_dwordx4 v[88:89], off
	s_waitcnt vmcnt(8) lgkmcnt(0)
	s_setprio 1
	s_barrier
	v_mfma_f32_16x16x32_bf16 v[64:67], v[8:11], v[24:27], v[64:67]
	v_mfma_f32_16x16x32_bf16 v[120:123], v[12:15], v[28:31], v[64:67]
	v_mfma_f32_16x16x32_bf16 v[64:67], v[16:19], v[24:27], v[68:71]
	v_mfma_f32_16x16x32_bf16 v[124:127], v[20:23], v[28:31], v[64:67]
	v_mfma_f32_16x16x32_bf16 v[64:67], v[8:11], v[218:221], v[72:75]
	v_mfma_f32_16x16x32_bf16 v[104:107], v[12:15], v[222:225], v[64:67]
	v_mfma_f32_16x16x32_bf16 v[64:67], v[16:19], v[218:221], v[76:79]
	v_mfma_f32_16x16x32_bf16 v[108:111], v[20:23], v[222:225], v[64:67]
	v_mfma_f32_16x16x32_bf16 v[64:67], v[8:11], v[226:229], v[80:83]
	v_mfma_f32_16x16x32_bf16 v[88:91], v[12:15], v[230:233], v[64:67]
	v_mfma_f32_16x16x32_bf16 v[64:67], v[16:19], v[226:229], v[84:87]
	v_mfma_f32_16x16x32_bf16 v[92:95], v[20:23], v[230:233], v[64:67]
	v_mfma_f32_16x16x32_bf16 v[64:67], v[8:11], v[234:237], v[96:99]
	v_mfma_f32_16x16x32_bf16 v[68:71], v[16:19], v[234:237], v[100:103]
	v_mfma_f32_16x16x32_bf16 v[64:67], v[12:15], v[238:241], v[64:67]
	v_mfma_f32_16x16x32_bf16 v[68:71], v[20:23], v[238:241], v[68:71]
	v_mfma_f32_16x16x32_bf16 v[72:75], v[202:205], v[24:27], v[112:115]
	v_mfma_f32_16x16x32_bf16 v[24:27], v[210:213], v[24:27], v[32:35]
	v_mfma_f32_16x16x32_bf16 v[116:119], v[214:217], v[28:31], v[24:27]
	v_mfma_f32_16x16x32_bf16 v[24:27], v[202:205], v[218:221], v[36:39]
	v_mfma_f32_16x16x32_bf16 v[96:99], v[206:209], v[222:225], v[24:27]
	v_mfma_f32_16x16x32_bf16 v[24:27], v[210:213], v[218:221], v[40:43]
	v_mfma_f32_16x16x32_bf16 v[100:103], v[214:217], v[222:225], v[24:27]
	v_mfma_f32_16x16x32_bf16 v[24:27], v[202:205], v[226:229], v[44:47]
	v_mfma_f32_16x16x32_bf16 v[80:83], v[206:209], v[230:233], v[24:27]
	v_mfma_f32_16x16x32_bf16 v[24:27], v[210:213], v[226:229], v[48:51]
	v_mfma_f32_16x16x32_bf16 v[84:87], v[214:217], v[230:233], v[24:27]
	v_mfma_f32_16x16x32_bf16 v[24:27], v[202:205], v[234:237], v[52:55]
	v_mfma_f32_16x16x32_bf16 v[48:51], v[206:209], v[238:241], v[24:27]
	v_mfma_f32_16x16x32_bf16 v[24:27], v[210:213], v[234:237], v[56:59]
	v_mfma_f32_16x16x32_bf16 v[112:115], v[206:209], v[28:31], v[72:75]
	v_mfma_f32_16x16x32_bf16 v[52:55], v[214:217], v[238:241], v[24:27]
	s_barrier
; template <class Epi, class Sched, bool ALIGN_EPI = false, bool SP2 = false, bool A_TILED = false>
; __device__ __forceinline__ void gemm_phase(PG8_LAS unsigned char* lds, const Gemm g, const Sched& S, const Epi& E, const int wave_s) {
;     ...
;         for (int t = PEEL ? 2 : 0; t < nt; t += 2) {
;             const bool last = (t == nt - 2);
;             const char* a1 = cA + (size_t)(t + 1) * kstepA;
;             const char* a2 = last ? nA : cA + (size_t)(t + 2) * kstepA; const char* b2 = last ? nB : cB + (size_t)(t + 2) * kstep;
;             const char* a3 = a2 + kstepA; const char* b3 = b2 + kstep;
;             if (last && has_next) S.a_ready(nxt);
	s_setprio 0
	s_add_i32 s67, s67, s15
	s_add_i32 s69, s67, 0x2000
	s_nop 1
	v_lshl_add_u64 v[24:25], v[242:243], 0, s[64:65]
	s_mov_b32 m0, s67
	s_add_u32 s80, s76, 0x80180
	ds_read_b128 v[32:35], v147 offset:49152
	ds_read_b128 v[36:39], v147 offset:50176
	ds_read_b128 v[218:221], v147 offset:51200
	ds_read_b128 v[222:225], v147 offset:52224
	ds_read_b128 v[226:229], v147 offset:53248
	ds_read_b128 v[230:233], v147 offset:54272
	ds_read_b128 v[234:237], v147 offset:55296
	ds_read_b128 v[238:241], v147 offset:56320
	global_load_lds_dwordx4 v[24:25], off
	v_lshl_add_u64 v[24:25], v[244:245], 0, s[64:65]
	s_mov_b32 m0, s69
	s_addc_u32 s81, s77, 0
	s_add_i32 s75, s75, s15
	global_load_lds_dwordx4 v[24:25], off
	v_lshl_add_u64 v[24:25], s[80:81], 0, v[128:129]
	s_mov_b32 m0, s75
	s_add_i32 s82, s75, 0x2000
	global_load_lds_dwordx4 v[24:25], off
	v_lshl_add_u64 v[24:25], s[80:81], 0, v[130:131]
	s_mov_b32 m0, s82
	s_nop 0
	global_load_lds_dwordx4 v[24:25], off
	v_lshl_add_u64 v[24:25], v[246:247], 0, s[64:65]
	s_mov_b32 m0, s43
	s_nop 0
	global_load_lds_dwordx4 v[24:25], off
	v_lshl_add_u64 v[24:25], v[248:249], 0, s[64:65]
	s_mov_b32 m0, s44
	s_nop 0
	global_load_lds_dwordx4 v[24:25], off
	s_waitcnt vmcnt(8) lgkmcnt(0)
	s_setprio 1
	s_barrier
	v_mfma_f32_16x16x32_bf16 v[24:27], v[8:11], v[32:35], v[150:153]
	v_mfma_f32_16x16x32_bf16 v[72:75], v[12:15], v[36:39], v[24:27]
	v_mfma_f32_16x16x32_bf16 v[24:27], v[16:19], v[32:35], v[154:157]
	v_mfma_f32_16x16x32_bf16 v[76:79], v[20:23], v[36:39], v[24:27]
	v_mfma_f32_16x16x32_bf16 v[24:27], v[8:11], v[218:221], v[158:161]
	v_mfma_f32_16x16x32_bf16 v[40:43], v[12:15], v[222:225], v[24:27]
	v_mfma_f32_16x16x32_bf16 v[24:27], v[16:19], v[218:221], v[162:165]
	v_mfma_f32_16x16x32_bf16 v[0:3], v[8:11], v[234:237], v[0:3]
	v_mfma_f32_16x16x32_bf16 v[44:47], v[20:23], v[222:225], v[24:27]
	v_mfma_f32_16x16x32_bf16 v[24:27], v[8:11], v[226:229], v[166:169]
	v_mfma_f32_16x16x32_bf16 v[28:31], v[16:19], v[226:229], v[170:173]
	v_mfma_f32_16x16x32_bf16 v[8:11], v[12:15], v[238:241], v[0:3]
	v_mfma_f32_16x16x32_bf16 v[0:3], v[16:19], v[234:237], v[4:7]
	v_mfma_f32_16x16x32_bf16 v[24:27], v[12:15], v[230:233], v[24:27]
	v_mfma_f32_16x16x32_bf16 v[28:31], v[20:23], v[230:233], v[28:31]
	v_mfma_f32_16x16x32_bf16 v[12:15], v[20:23], v[238:241], v[0:3]
	v_mfma_f32_16x16x32_bf16 v[0:3], v[202:205], v[32:35], v[174:177]
	v_mfma_f32_16x16x32_bf16 v[56:59], v[206:209], v[36:39], v[0:3]
	v_mfma_f32_16x16x32_bf16 v[0:3], v[210:213], v[32:35], v[60:63]
	v_mfma_f32_16x16x32_bf16 v[60:63], v[214:217], v[36:39], v[0:3]
	v_mfma_f32_16x16x32_bf16 v[0:3], v[202:205], v[218:221], v[178:181]
	v_mfma_f32_16x16x32_bf16 v[32:35], v[206:209], v[222:225], v[0:3]
	v_mfma_f32_16x16x32_bf16 v[0:3], v[210:213], v[218:221], v[182:185]
	v_mfma_f32_16x16x32_bf16 v[36:39], v[214:217], v[222:225], v[0:3]
	v_mfma_f32_16x16x32_bf16 v[0:3], v[202:205], v[226:229], v[186:189]
	v_mfma_f32_16x16x32_bf16 v[16:19], v[206:209], v[230:233], v[0:3]
	v_mfma_f32_16x16x32_bf16 v[0:3], v[210:213], v[226:229], v[190:193]
	v_mfma_f32_16x16x32_bf16 v[20:23], v[214:217], v[230:233], v[0:3]
	v_mfma_f32_16x16x32_bf16 v[0:3], v[202:205], v[234:237], v[194:197]
	v_mfma_f32_16x16x32_bf16 v[4:7], v[210:213], v[234:237], v[198:201]
	v_mfma_f32_16x16x32_bf16 v[0:3], v[206:209], v[238:241], v[0:3]
	v_mfma_f32_16x16x32_bf16 v[4:7], v[214:217], v[238:241], v[4:7]
	s_barrier
	s_setprio 0
	s_add_u32 s83, s76, 0x200
	s_addc_u32 s85, s77, 0
	s_add_u32 s76, s78, 0x80180
	s_addc_u32 s77, s79, 0
	s_mov_b32 s88, 0
.LBB0_1953:
	ds_read_b128 v[150:153], v145
	ds_read_b128 v[154:157], v145 offset:1024
	ds_read_b128 v[158:161], v145 offset:2048
	ds_read_b128 v[162:165], v145 offset:3072
	ds_read_b128 v[166:169], v146
	ds_read_b128 v[170:173], v146 offset:1024
	ds_read_b128 v[174:177], v146 offset:2048
	ds_read_b128 v[178:181], v146 offset:3072
	s_add_u32 s78, s76, 0xfff80080
	s_addc_u32 s79, s77, -1
	s_cmp_eq_u32 s88, 28
	s_cselect_b32 s81, s50, s79
	s_cselect_b32 s80, s51, s78
	s_cselect_b32 s79, s52, s85
	s_cselect_b32 s78, s53, s83
	s_mov_b32 m0, s54
	v_lshl_add_u64 v[214:215], s[76:77], 0, v[138:139]
	ds_read_b128 v[182:185], v147
	ds_read_b128 v[186:189], v147 offset:1024
	ds_read_b128 v[190:193], v147 offset:2048
	ds_read_b128 v[194:197], v147 offset:3072
	ds_read_b128 v[198:201], v147 offset:4096
	ds_read_b128 v[202:205], v147 offset:5120
	ds_read_b128 v[206:209], v147 offset:6144
	ds_read_b128 v[210:213], v147 offset:7168
	global_load_lds_dwordx4 v[214:215], off
	v_lshl_add_u64 v[214:215], s[76:77], 0, v[136:137]
	s_mov_b32 m0, s55
	s_nop 0
	global_load_lds_dwordx4 v[214:215], off
	s_waitcnt vmcnt(8) lgkmcnt(0)
	s_setprio 1
	s_barrier
	v_mfma_f32_16x16x32_bf16 v[120:123], v[150:153], v[182:185], v[120:123]
	v_mfma_f32_16x16x32_bf16 v[124:127], v[158:161], v[182:185], v[124:127]
	v_mfma_f32_16x16x32_bf16 v[104:107], v[150:153], v[190:193], v[104:107]
	v_mfma_f32_16x16x32_bf16 v[108:111], v[158:161], v[190:193], v[108:111]
	v_mfma_f32_16x16x32_bf16 v[88:91], v[150:153], v[198:201], v[88:91]
	v_mfma_f32_16x16x32_bf16 v[92:95], v[158:161], v[198:201], v[92:95]
	v_mfma_f32_16x16x32_bf16 v[64:67], v[150:153], v[206:209], v[64:67]
	v_mfma_f32_16x16x32_bf16 v[68:71], v[158:161], v[206:209], v[68:71]
	v_mfma_f32_16x16x32_bf16 v[120:123], v[154:157], v[186:189], v[120:123]
	v_mfma_f32_16x16x32_bf16 v[124:127], v[162:165], v[186:189], v[124:127]
	v_mfma_f32_16x16x32_bf16 v[104:107], v[154:157], v[194:197], v[104:107]
	v_mfma_f32_16x16x32_bf16 v[108:111], v[162:165], v[194:197], v[108:111]
	v_mfma_f32_16x16x32_bf16 v[88:91], v[154:157], v[202:205], v[88:91]
	v_mfma_f32_16x16x32_bf16 v[92:95], v[162:165], v[202:205], v[92:95]
	v_mfma_f32_16x16x32_bf16 v[64:67], v[154:157], v[210:213], v[64:67]
	v_mfma_f32_16x16x32_bf16 v[68:71], v[162:165], v[210:213], v[68:71]
	v_mfma_f32_16x16x32_bf16 v[112:115], v[166:169], v[182:185], v[112:115]
	v_mfma_f32_16x16x32_bf16 v[116:119], v[174:177], v[182:185], v[116:119]
	v_mfma_f32_16x16x32_bf16 v[96:99], v[166:169], v[190:193], v[96:99]
	v_mfma_f32_16x16x32_bf16 v[100:103], v[174:177], v[190:193], v[100:103]
	v_mfma_f32_16x16x32_bf16 v[80:83], v[166:169], v[198:201], v[80:83]
	v_mfma_f32_16x16x32_bf16 v[84:87], v[174:177], v[198:201], v[84:87]
	v_mfma_f32_16x16x32_bf16 v[48:51], v[166:169], v[206:209], v[48:51]
	v_mfma_f32_16x16x32_bf16 v[52:55], v[174:177], v[206:209], v[52:55]
	v_mfma_f32_16x16x32_bf16 v[112:115], v[170:173], v[186:189], v[112:115]
	v_mfma_f32_16x16x32_bf16 v[116:119], v[178:181], v[186:189], v[116:119]
	v_mfma_f32_16x16x32_bf16 v[96:99], v[170:173], v[194:197], v[96:99]
	v_mfma_f32_16x16x32_bf16 v[100:103], v[178:181], v[194:197], v[100:103]
	v_mfma_f32_16x16x32_bf16 v[80:83], v[170:173], v[202:205], v[80:83]
	v_mfma_f32_16x16x32_bf16 v[84:87], v[178:181], v[202:205], v[84:87]
	v_mfma_f32_16x16x32_bf16 v[48:51], v[170:173], v[210:213], v[48:51]
	v_mfma_f32_16x16x32_bf16 v[52:55], v[178:181], v[210:213], v[52:55]
	s_barrier
	s_setprio 0
	s_mov_b32 m0, s56
	v_lshl_add_u64 v[214:215], s[78:79], 0, v[128:129]
	s_add_u32 s90, s78, 0x80000
	ds_read_b128 v[182:185], v147 offset:16384
	ds_read_b128 v[186:189], v147 offset:17408
	ds_read_b128 v[190:193], v147 offset:18432
	ds_read_b128 v[194:197], v147 offset:19456
	ds_read_b128 v[198:201], v147 offset:20480
	ds_read_b128 v[202:205], v147 offset:21504
	ds_read_b128 v[206:209], v147 offset:22528
	ds_read_b128 v[210:213], v147 offset:23552
	global_load_lds_dwordx4 v[214:215], off
	v_lshl_add_u64 v[216:217], s[78:79], 0, v[130:131]
	s_mov_b32 m0, s57
	s_addc_u32 s91, s79, 0
	global_load_lds_dwordx4 v[216:217], off
	v_lshl_add_u64 v[218:219], s[90:91], 0, v[128:129]
	s_mov_b32 m0, s58
	v_lshl_add_u64 v[220:221], s[80:81], 0, v[132:133]
	global_load_lds_dwordx4 v[218:219], off
	v_lshl_add_u64 v[218:219], s[90:91], 0, v[130:131]
	s_mov_b32 m0, s59
	s_nop 0
	global_load_lds_dwordx4 v[218:219], off
	v_lshl_add_u64 v[218:219], s[80:81], 0, v[134:135]
	s_mov_b32 m0, s22
	s_nop 0
	global_load_lds_dwordx4 v[218:219], off
	s_mov_b32 m0, s23
	s_nop 0
	global_load_lds_dwordx4 v[220:221], off
	s_waitcnt vmcnt(8) lgkmcnt(0)
	s_setprio 1
	s_barrier
	v_mfma_f32_16x16x32_bf16 v[72:75], v[150:153], v[182:185], v[72:75]
	v_mfma_f32_16x16x32_bf16 v[76:79], v[158:161], v[182:185], v[76:79]
	v_mfma_f32_16x16x32_bf16 v[40:43], v[150:153], v[190:193], v[40:43]
	v_mfma_f32_16x16x32_bf16 v[44:47], v[158:161], v[190:193], v[44:47]
	v_mfma_f32_16x16x32_bf16 v[24:27], v[150:153], v[198:201], v[24:27]
	v_mfma_f32_16x16x32_bf16 v[28:31], v[158:161], v[198:201], v[28:31]
	v_mfma_f32_16x16x32_bf16 v[8:11], v[150:153], v[206:209], v[8:11]
	v_mfma_f32_16x16x32_bf16 v[12:15], v[158:161], v[206:209], v[12:15]
	v_mfma_f32_16x16x32_bf16 v[72:75], v[154:157], v[186:189], v[72:75]
	v_mfma_f32_16x16x32_bf16 v[76:79], v[162:165], v[186:189], v[76:79]
	v_mfma_f32_16x16x32_bf16 v[40:43], v[154:157], v[194:197], v[40:43]
	v_mfma_f32_16x16x32_bf16 v[44:47], v[162:165], v[194:197], v[44:47]
	v_mfma_f32_16x16x32_bf16 v[24:27], v[154:157], v[202:205], v[24:27]
	v_mfma_f32_16x16x32_bf16 v[28:31], v[162:165], v[202:205], v[28:31]
	v_mfma_f32_16x16x32_bf16 v[8:11], v[154:157], v[210:213], v[8:11]
	v_mfma_f32_16x16x32_bf16 v[12:15], v[162:165], v[210:213], v[12:15]
	v_mfma_f32_16x16x32_bf16 v[56:59], v[166:169], v[182:185], v[56:59]
	v_mfma_f32_16x16x32_bf16 v[60:63], v[174:177], v[182:185], v[60:63]
	v_mfma_f32_16x16x32_bf16 v[32:35], v[166:169], v[190:193], v[32:35]
	v_mfma_f32_16x16x32_bf16 v[36:39], v[174:177], v[190:193], v[36:39]
	v_mfma_f32_16x16x32_bf16 v[16:19], v[166:169], v[198:201], v[16:19]
	v_mfma_f32_16x16x32_bf16 v[20:23], v[174:177], v[198:201], v[20:23]
	v_mfma_f32_16x16x32_bf16 v[0:3], v[166:169], v[206:209], v[0:3]
	v_mfma_f32_16x16x32_bf16 v[4:7], v[174:177], v[206:209], v[4:7]
	v_mfma_f32_16x16x32_bf16 v[56:59], v[170:173], v[186:189], v[56:59]
	v_mfma_f32_16x16x32_bf16 v[60:63], v[178:181], v[186:189], v[60:63]
	v_mfma_f32_16x16x32_bf16 v[32:35], v[170:173], v[194:197], v[32:35]
	v_mfma_f32_16x16x32_bf16 v[36:39], v[178:181], v[194:197], v[36:39]
	v_mfma_f32_16x16x32_bf16 v[16:19], v[170:173], v[202:205], v[16:19]
	v_mfma_f32_16x16x32_bf16 v[20:23], v[178:181], v[202:205], v[20:23]
	v_mfma_f32_16x16x32_bf16 v[0:3], v[170:173], v[210:213], v[0:3]
	v_mfma_f32_16x16x32_bf16 v[4:7], v[178:181], v[210:213], v[4:7]
	s_barrier
; #define PG8_STAGE(bufoff, gbase, voff) do { _Pragma("unroll") for (int _i = 0; _i < 2; ++_i) \
;         __builtin_amdgcn_global_load_lds((const unsigned*)((const char*)(gbase) + (voff)[_i]), (PG8_LAS unsigned*)(lds + (bufoff) + ldsw + _i * 8192), 16, 0, 0); } while (0)
; #define PG8_BAR __builtin_amdgcn_s_barrier()
; template <class Epi, class Sched, bool ALIGN_EPI = false, bool SP2 = false, bool A_TILED = false>
; __device__ __forceinline__ void gemm_phase(PG8_LAS unsigned char* lds, const Gemm g, const Sched& S, const Epi& E, const int wave_s) {
;     ...
;         for (int t = PEEL ? 2 : 0; t < nt; t += 2) {
;             const bool last = (t == nt - 2);
;             const char* a1 = cA + (size_t)(t + 1) * kstepA;
;             const char* a2 = last ? nA : cA + (size_t)(t + 2) * kstepA; const char* b2 = last ? nB : cB + (size_t)(t + 2) * kstep;
;             const char* a3 = a2 + kstepA; const char* b3 = b2 + kstep;
;             if (last && has_next) S.a_ready(nxt);
;             if constexpr (SP2) {
;             PG8_ITER(PG8_MMA)
;             } else {
;             PG8_LDB(B0, 0, 0); PG8_SCHED; PG8_LDA(At, 0, 0); PG8_STAGE(PG8_SA(1, 1), a1 + hstepA, voffA);
;             PG8_WAIT_L(8); PG8_BAR; PG8_WAIT_L(0); PG8_MMA(0, 0, At, B0); PG8_BAR; PG8_SCHED;
;             PG8_LDB(B1, 0, 1); PG8_STAGE(PG8_SB(0, 0), b2, voffB);
;             PG8_BAR; PG8_WAIT_L(0); PG8_MMA(0, 1, At, B1); PG8_BAR;
;             PG8_LDA(At, 0, 1); PG8_STAGE(PG8_SA(0, 0), a2, voffA);
;             PG8_BAR; PG8_WAIT_L(0); PG8_MMA(1, 0, At, B0); PG8_BAR; PG8_SCHED;
;             PG8_STAGE(PG8_SB(0, 1), b2 + hstep, voffB);
;             PG8_WAIT_V(6); PG8_BAR; PG8_MMA(1, 1, At, B1); PG8_BAR;
;             PG8_LDB(B0, 1, 0); PG8_SCHED; PG8_LDA(At, 1, 0); PG8_STAGE(PG8_SA(0, 1), a2 + hstepA, voffA);
;             PG8_WAIT_L(8); PG8_BAR; PG8_WAIT_L(0); PG8_MMA(0, 0, At, B0); PG8_BAR; PG8_SCHED;
;             PG8_LDB(B1, 1, 1); PG8_STAGE(PG8_SB(1, 0), b3, voffB);
;             PG8_BAR; PG8_WAIT_L(0); PG8_MMA(0, 1, At, B1); PG8_BAR;
;             PG8_LDA(At, 1, 1); PG8_STAGE(PG8_SA(1, 0), a3, voffA);
;             PG8_BAR; PG8_WAIT_L(0); PG8_MMA(1, 0, At, B0); PG8_BAR; PG8_SCHED;
;             PG8_STAGE(PG8_SB(1, 1), b3 + hstep, voffB);
;             PG8_WAIT_V(6); PG8_BAR; PG8_MMA(1, 1, At, B1); PG8_BAR;
;             }
;         }
;         if constexpr (ALIGN_EPI) { if (wr == 0) PG8_BAR; }
	s_setprio 0
	ds_read_b128 v[150:153], v148
	ds_read_b128 v[154:157], v148 offset:1024
	ds_read_b128 v[158:161], v148 offset:2048
	ds_read_b128 v[162:165], v148 offset:3072
	ds_read_b128 v[166:169], v149
	ds_read_b128 v[170:173], v149 offset:1024
	ds_read_b128 v[174:177], v149 offset:2048
	ds_read_b128 v[178:181], v149 offset:3072
	s_add_u32 s80, s80, 0x80000
	s_addc_u32 s81, s81, 0
	s_mov_b32 m0, s36
	v_lshl_add_u64 v[222:223], s[80:81], 0, v[134:135]
	ds_read_b128 v[182:185], v147 offset:32768
	ds_read_b128 v[186:189], v147 offset:33792
	ds_read_b128 v[190:193], v147 offset:34816
	ds_read_b128 v[194:197], v147 offset:35840
	ds_read_b128 v[198:201], v147 offset:36864
	ds_read_b128 v[202:205], v147 offset:37888
	ds_read_b128 v[206:209], v147 offset:38912
	ds_read_b128 v[210:213], v147 offset:39936
	global_load_lds_dwordx4 v[222:223], off
	v_lshl_add_u64 v[222:223], s[80:81], 0, v[132:133]
	s_mov_b32 m0, s37
	s_nop 0
	global_load_lds_dwordx4 v[222:223], off
	s_waitcnt vmcnt(8) lgkmcnt(0)
	s_setprio 1
	s_barrier
	v_mfma_f32_16x16x32_bf16 v[120:123], v[150:153], v[182:185], v[120:123]
	v_mfma_f32_16x16x32_bf16 v[124:127], v[158:161], v[182:185], v[124:127]
	v_mfma_f32_16x16x32_bf16 v[104:107], v[150:153], v[190:193], v[104:107]
	v_mfma_f32_16x16x32_bf16 v[108:111], v[158:161], v[190:193], v[108:111]
	v_mfma_f32_16x16x32_bf16 v[88:91], v[150:153], v[198:201], v[88:91]
	v_mfma_f32_16x16x32_bf16 v[92:95], v[158:161], v[198:201], v[92:95]
	v_mfma_f32_16x16x32_bf16 v[64:67], v[150:153], v[206:209], v[64:67]
	v_mfma_f32_16x16x32_bf16 v[68:71], v[158:161], v[206:209], v[68:71]
	v_mfma_f32_16x16x32_bf16 v[120:123], v[154:157], v[186:189], v[120:123]
	v_mfma_f32_16x16x32_bf16 v[124:127], v[162:165], v[186:189], v[124:127]
	v_mfma_f32_16x16x32_bf16 v[104:107], v[154:157], v[194:197], v[104:107]
	v_mfma_f32_16x16x32_bf16 v[108:111], v[162:165], v[194:197], v[108:111]
	v_mfma_f32_16x16x32_bf16 v[88:91], v[154:157], v[202:205], v[88:91]
	v_mfma_f32_16x16x32_bf16 v[92:95], v[162:165], v[202:205], v[92:95]
	v_mfma_f32_16x16x32_bf16 v[64:67], v[154:157], v[210:213], v[64:67]
	v_mfma_f32_16x16x32_bf16 v[68:71], v[162:165], v[210:213], v[68:71]
	v_mfma_f32_16x16x32_bf16 v[112:115], v[166:169], v[182:185], v[112:115]
	v_mfma_f32_16x16x32_bf16 v[116:119], v[174:177], v[182:185], v[116:119]
	v_mfma_f32_16x16x32_bf16 v[96:99], v[166:169], v[190:193], v[96:99]
	v_mfma_f32_16x16x32_bf16 v[100:103], v[174:177], v[190:193], v[100:103]
	v_mfma_f32_16x16x32_bf16 v[80:83], v[166:169], v[198:201], v[80:83]
	v_mfma_f32_16x16x32_bf16 v[84:87], v[174:177], v[198:201], v[84:87]
	v_mfma_f32_16x16x32_bf16 v[48:51], v[166:169], v[206:209], v[48:51]
	v_mfma_f32_16x16x32_bf16 v[52:55], v[174:177], v[206:209], v[52:55]
	v_mfma_f32_16x16x32_bf16 v[112:115], v[170:173], v[186:189], v[112:115]
	v_mfma_f32_16x16x32_bf16 v[116:119], v[178:181], v[186:189], v[116:119]
	v_mfma_f32_16x16x32_bf16 v[96:99], v[170:173], v[194:197], v[96:99]
	v_mfma_f32_16x16x32_bf16 v[100:103], v[178:181], v[194:197], v[100:103]
	v_mfma_f32_16x16x32_bf16 v[80:83], v[170:173], v[202:205], v[80:83]
	v_mfma_f32_16x16x32_bf16 v[84:87], v[178:181], v[202:205], v[84:87]
	v_mfma_f32_16x16x32_bf16 v[48:51], v[170:173], v[210:213], v[48:51]
	v_mfma_f32_16x16x32_bf16 v[52:55], v[178:181], v[210:213], v[52:55]
	s_barrier
	s_setprio 0
	s_mov_b32 m0, s67
	v_lshl_add_u64 v[214:215], v[214:215], 0, s[12:13]
	s_add_u32 s78, s78, 0x80080
	ds_read_b128 v[182:185], v147 offset:49152
	ds_read_b128 v[186:189], v147 offset:50176
	ds_read_b128 v[190:193], v147 offset:51200
	ds_read_b128 v[194:197], v147 offset:52224
	ds_read_b128 v[198:201], v147 offset:53248
	ds_read_b128 v[202:205], v147 offset:54272
	ds_read_b128 v[206:209], v147 offset:55296
	ds_read_b128 v[210:213], v147 offset:56320
	global_load_lds_dwordx4 v[214:215], off
	v_lshl_add_u64 v[214:215], v[216:217], 0, s[12:13]
	s_mov_b32 m0, s69
	s_addc_u32 s79, s79, 0
	global_load_lds_dwordx4 v[214:215], off
	v_lshl_add_u64 v[214:215], s[78:79], 0, v[128:129]
	s_mov_b32 m0, s75
	s_nop 0
	global_load_lds_dwordx4 v[214:215], off
	v_lshl_add_u64 v[214:215], s[78:79], 0, v[130:131]
	s_mov_b32 m0, s82
	s_nop 0
	global_load_lds_dwordx4 v[214:215], off
	v_lshl_add_u64 v[214:215], v[218:219], 0, s[12:13]
	s_mov_b32 m0, s43
	s_nop 0
	global_load_lds_dwordx4 v[214:215], off
	v_lshl_add_u64 v[214:215], v[220:221], 0, s[12:13]
	s_mov_b32 m0, s44
	s_nop 0
	global_load_lds_dwordx4 v[214:215], off
	s_waitcnt vmcnt(8) lgkmcnt(0)
	s_setprio 1
	s_barrier
	v_mfma_f32_16x16x32_bf16 v[72:75], v[150:153], v[182:185], v[72:75]
	v_mfma_f32_16x16x32_bf16 v[76:79], v[158:161], v[182:185], v[76:79]
	v_mfma_f32_16x16x32_bf16 v[40:43], v[150:153], v[190:193], v[40:43]
	v_mfma_f32_16x16x32_bf16 v[44:47], v[158:161], v[190:193], v[44:47]
	v_mfma_f32_16x16x32_bf16 v[24:27], v[150:153], v[198:201], v[24:27]
	v_mfma_f32_16x16x32_bf16 v[28:31], v[158:161], v[198:201], v[28:31]
	v_mfma_f32_16x16x32_bf16 v[8:11], v[150:153], v[206:209], v[8:11]
	v_mfma_f32_16x16x32_bf16 v[12:15], v[158:161], v[206:209], v[12:15]
	v_mfma_f32_16x16x32_bf16 v[72:75], v[154:157], v[186:189], v[72:75]
	v_mfma_f32_16x16x32_bf16 v[76:79], v[162:165], v[186:189], v[76:79]
	v_mfma_f32_16x16x32_bf16 v[40:43], v[154:157], v[194:197], v[40:43]
	v_mfma_f32_16x16x32_bf16 v[44:47], v[162:165], v[194:197], v[44:47]
	v_mfma_f32_16x16x32_bf16 v[24:27], v[154:157], v[202:205], v[24:27]
	v_mfma_f32_16x16x32_bf16 v[28:31], v[162:165], v[202:205], v[28:31]
	v_mfma_f32_16x16x32_bf16 v[8:11], v[154:157], v[210:213], v[8:11]
	v_mfma_f32_16x16x32_bf16 v[12:15], v[162:165], v[210:213], v[12:15]
	v_mfma_f32_16x16x32_bf16 v[56:59], v[166:169], v[182:185], v[56:59]
	v_mfma_f32_16x16x32_bf16 v[60:63], v[174:177], v[182:185], v[60:63]
	v_mfma_f32_16x16x32_bf16 v[32:35], v[166:169], v[190:193], v[32:35]
	v_mfma_f32_16x16x32_bf16 v[36:39], v[174:177], v[190:193], v[36:39]
	v_mfma_f32_16x16x32_bf16 v[16:19], v[166:169], v[198:201], v[16:19]
	v_mfma_f32_16x16x32_bf16 v[20:23], v[174:177], v[198:201], v[20:23]
	v_mfma_f32_16x16x32_bf16 v[0:3], v[166:169], v[206:209], v[0:3]
	v_mfma_f32_16x16x32_bf16 v[4:7], v[174:177], v[206:209], v[4:7]
	v_mfma_f32_16x16x32_bf16 v[56:59], v[170:173], v[186:189], v[56:59]
	v_mfma_f32_16x16x32_bf16 v[60:63], v[178:181], v[186:189], v[60:63]
	v_mfma_f32_16x16x32_bf16 v[32:35], v[170:173], v[194:197], v[32:35]
	v_mfma_f32_16x16x32_bf16 v[36:39], v[178:181], v[194:197], v[36:39]
	v_mfma_f32_16x16x32_bf16 v[16:19], v[170:173], v[202:205], v[16:19]
	v_mfma_f32_16x16x32_bf16 v[20:23], v[178:181], v[202:205], v[20:23]
	v_mfma_f32_16x16x32_bf16 v[0:3], v[170:173], v[210:213], v[0:3]
	v_mfma_f32_16x16x32_bf16 v[4:7], v[178:181], v[210:213], v[4:7]
	s_barrier
	s_setprio 0
	s_add_i32 s88, s88, 2
	s_add_u32 s83, s83, 0x100
	s_addc_u32 s85, s85, 0
	s_add_u32 s76, s76, 0x100
	s_addc_u32 s77, s77, 0
	s_cmp_gt_u32 s88, 29
	s_cbranch_scc0 .LBB0_1953
	s_and_b64 vcc, exec, s[60:61]
	s_cbranch_vccz .LBB0_1956
	s_barrier

; template <class Epi, class Sched, bool ALIGN_EPI = false, bool SP2 = false, bool A_TILED = false>
; __device__ __forceinline__ void gemm_phase(PG8_LAS unsigned char* lds, const Gemm g, const Sched& S, const Epi& E, const int wave_s) {
;     ...
;         for (int t = PEEL ? 2 : 0; t < nt; t += 2) {
;             const bool last = (t == nt - 2);
;             const char* a1 = cA + (size_t)(t + 1) * kstepA;
;             const char* a2 = last ? nA : cA + (size_t)(t + 2) * kstepA; const char* b2 = last ? nB : cB + (size_t)(t + 2) * kstep;
;             const char* a3 = a2 + kstepA; const char* b3 = b2 + kstep;
;             if (last && has_next) S.a_ready(nxt);
.LBB0_2026:
	ds_read_b128 v[146:149], v140
	ds_read_b128 v[150:153], v140 offset:1024
	ds_read_b128 v[154:157], v140 offset:2048
	ds_read_b128 v[158:161], v140 offset:3072
	ds_read_b128 v[162:165], v141
	ds_read_b128 v[166:169], v141 offset:1024
	ds_read_b128 v[170:173], v141 offset:2048
	ds_read_b128 v[174:177], v141 offset:3072
	s_add_u32 s52, s60, s39
	s_addc_u32 s53, s61, s40
	s_add_u32 s54, s60, s37
	s_addc_u32 s55, s61, s38
	s_cmpk_eq_i32 s41, 0x7c
	s_cselect_b32 s72, s6, s52
	s_cselect_b32 s73, s7, s53
	s_cselect_b32 s70, s2, s54
	s_cselect_b32 s71, s3, s55
	s_add_u32 s68, s72, 0x8000
	s_addc_u32 s69, s73, 0
	s_mov_b32 m0, s42
	v_lshl_add_u64 v[210:211], s[60:61], 0, v[138:139]
	ds_read_b128 v[178:181], v142
	ds_read_b128 v[182:185], v142 offset:1024
	ds_read_b128 v[186:189], v142 offset:2048
	ds_read_b128 v[190:193], v142 offset:3072
	ds_read_b128 v[194:197], v142 offset:4096
	ds_read_b128 v[198:201], v142 offset:5120
	ds_read_b128 v[202:205], v142 offset:6144
	ds_read_b128 v[206:209], v142 offset:7168
	global_load_lds_dwordx4 v[210:211], off
	v_lshl_add_u64 v[210:211], s[60:61], 0, v[136:137]
	s_mov_b32 m0, s43
	s_nop 0
	global_load_lds_dwordx4 v[210:211], off
	s_waitcnt vmcnt(8) lgkmcnt(0)
	s_setprio 1
	s_barrier
	v_mfma_f32_16x16x32_bf16 v[8:11], v[146:149], v[178:181], v[8:11]
	v_mfma_f32_16x16x32_bf16 v[12:15], v[154:157], v[178:181], v[12:15]
	v_mfma_f32_16x16x32_bf16 v[60:63], v[146:149], v[186:189], v[60:63]
	v_mfma_f32_16x16x32_bf16 v[20:23], v[154:157], v[186:189], v[20:23]
	v_mfma_f32_16x16x32_bf16 v[76:79], v[146:149], v[194:197], v[76:79]
	v_mfma_f32_16x16x32_bf16 v[52:55], v[154:157], v[194:197], v[52:55]
	v_mfma_f32_16x16x32_bf16 v[128:131], v[146:149], v[202:205], v[128:131]
	v_mfma_f32_16x16x32_bf16 v[68:71], v[154:157], v[202:205], v[68:71]
	v_mfma_f32_16x16x32_bf16 v[8:11], v[150:153], v[182:185], v[8:11]
	v_mfma_f32_16x16x32_bf16 v[12:15], v[158:161], v[182:185], v[12:15]
	v_mfma_f32_16x16x32_bf16 v[60:63], v[150:153], v[190:193], v[60:63]
	v_mfma_f32_16x16x32_bf16 v[20:23], v[158:161], v[190:193], v[20:23]
	v_mfma_f32_16x16x32_bf16 v[76:79], v[150:153], v[198:201], v[76:79]
	v_mfma_f32_16x16x32_bf16 v[52:55], v[158:161], v[198:201], v[52:55]
	v_mfma_f32_16x16x32_bf16 v[128:131], v[150:153], v[206:209], v[128:131]
	v_mfma_f32_16x16x32_bf16 v[68:71], v[158:161], v[206:209], v[68:71]
	v_mfma_f32_16x16x32_bf16 v[28:31], v[162:165], v[178:181], v[28:31]
	v_mfma_f32_16x16x32_bf16 v[16:19], v[170:173], v[178:181], v[16:19]
	v_mfma_f32_16x16x32_bf16 v[56:59], v[162:165], v[186:189], v[56:59]
	v_mfma_f32_16x16x32_bf16 v[48:51], v[170:173], v[186:189], v[48:51]
	v_mfma_f32_16x16x32_bf16 v[72:75], v[162:165], v[194:197], v[72:75]
	v_mfma_f32_16x16x32_bf16 v[64:67], v[170:173], v[194:197], v[64:67]
	v_mfma_f32_16x16x32_bf16 v[108:111], v[162:165], v[202:205], v[108:111]
	v_mfma_f32_16x16x32_bf16 v[96:99], v[170:173], v[202:205], v[96:99]
	v_mfma_f32_16x16x32_bf16 v[28:31], v[166:169], v[182:185], v[28:31]
	v_mfma_f32_16x16x32_bf16 v[16:19], v[174:177], v[182:185], v[16:19]
	v_mfma_f32_16x16x32_bf16 v[56:59], v[166:169], v[190:193], v[56:59]
	v_mfma_f32_16x16x32_bf16 v[48:51], v[174:177], v[190:193], v[48:51]
	v_mfma_f32_16x16x32_bf16 v[72:75], v[166:169], v[198:201], v[72:75]
	v_mfma_f32_16x16x32_bf16 v[64:67], v[174:177], v[198:201], v[64:67]
	v_mfma_f32_16x16x32_bf16 v[108:111], v[166:169], v[206:209], v[108:111]
	v_mfma_f32_16x16x32_bf16 v[96:99], v[174:177], v[206:209], v[96:99]
	s_barrier
	s_setprio 0
	s_mov_b32 m0, s44
	v_lshl_add_u64 v[210:211], s[70:71], 0, v[34:35]
	s_add_u32 s52, s70, 0x200000
	ds_read_b128 v[178:181], v142 offset:16384
	ds_read_b128 v[182:185], v142 offset:17408
	ds_read_b128 v[186:189], v142 offset:18432
	ds_read_b128 v[190:193], v142 offset:19456
	ds_read_b128 v[194:197], v142 offset:20480
	ds_read_b128 v[198:201], v142 offset:21504
	ds_read_b128 v[202:205], v142 offset:22528
	ds_read_b128 v[206:209], v142 offset:23552
	global_load_lds_dwordx4 v[210:211], off
	v_lshl_add_u64 v[212:213], s[70:71], 0, v[134:135]
	s_mov_b32 m0, s45
	s_addc_u32 s53, s71, 0
	global_load_lds_dwordx4 v[212:213], off
	v_lshl_add_u64 v[214:215], s[52:53], 0, v[34:35]
	s_mov_b32 m0, s46
	s_nop 0
	global_load_lds_dwordx4 v[214:215], off
	v_lshl_add_u64 v[214:215], s[52:53], 0, v[134:135]
	s_mov_b32 m0, s47
	s_nop 0
	global_load_lds_dwordx4 v[214:215], off
	v_lshl_add_u64 v[214:215], s[72:73], 0, v[32:33]
	s_mov_b32 m0, s14
	s_nop 0
	global_load_lds_dwordx4 v[214:215], off
	v_lshl_add_u64 v[214:215], s[72:73], 0, v[132:133]
	s_mov_b32 m0, s15
	s_nop 0
	global_load_lds_dwordx4 v[214:215], off
	s_waitcnt vmcnt(8) lgkmcnt(0)
	s_setprio 1
	s_barrier
	v_mfma_f32_16x16x32_bf16 v[100:103], v[146:149], v[178:181], v[100:103]
	v_mfma_f32_16x16x32_bf16 v[104:107], v[154:157], v[178:181], v[104:107]
	v_mfma_f32_16x16x32_bf16 v[116:119], v[146:149], v[186:189], v[116:119]
	v_mfma_f32_16x16x32_bf16 v[120:123], v[154:157], v[186:189], v[120:123]
	v_mfma_f32_16x16x32_bf16 v[84:87], v[146:149], v[194:197], v[84:87]
	v_mfma_f32_16x16x32_bf16 v[80:83], v[154:157], v[194:197], v[80:83]
	v_mfma_f32_16x16x32_bf16 v[36:39], v[146:149], v[202:205], v[36:39]
	v_mfma_f32_16x16x32_bf16 v[24:27], v[154:157], v[202:205], v[24:27]
	v_mfma_f32_16x16x32_bf16 v[100:103], v[150:153], v[182:185], v[100:103]
	v_mfma_f32_16x16x32_bf16 v[104:107], v[158:161], v[182:185], v[104:107]
	v_mfma_f32_16x16x32_bf16 v[116:119], v[150:153], v[190:193], v[116:119]
	v_mfma_f32_16x16x32_bf16 v[120:123], v[158:161], v[190:193], v[120:123]
	v_mfma_f32_16x16x32_bf16 v[84:87], v[150:153], v[198:201], v[84:87]
	v_mfma_f32_16x16x32_bf16 v[80:83], v[158:161], v[198:201], v[80:83]
	v_mfma_f32_16x16x32_bf16 v[36:39], v[150:153], v[206:209], v[36:39]
	v_mfma_f32_16x16x32_bf16 v[24:27], v[158:161], v[206:209], v[24:27]
	v_mfma_f32_16x16x32_bf16 v[124:127], v[162:165], v[178:181], v[124:127]
	v_mfma_f32_16x16x32_bf16 v[112:115], v[170:173], v[178:181], v[112:115]
	v_mfma_f32_16x16x32_bf16 v[92:95], v[162:165], v[186:189], v[92:95]
	v_mfma_f32_16x16x32_bf16 v[88:91], v[170:173], v[186:189], v[88:91]
	v_mfma_f32_16x16x32_bf16 v[44:47], v[162:165], v[194:197], v[44:47]
	v_mfma_f32_16x16x32_bf16 v[40:43], v[170:173], v[194:197], v[40:43]
	v_mfma_f32_16x16x32_bf16 v[4:7], v[162:165], v[202:205], v[4:7]
	v_mfma_f32_16x16x32_bf16 v[0:3], v[170:173], v[202:205], v[0:3]
	v_mfma_f32_16x16x32_bf16 v[124:127], v[166:169], v[182:185], v[124:127]
	v_mfma_f32_16x16x32_bf16 v[112:115], v[174:177], v[182:185], v[112:115]
	v_mfma_f32_16x16x32_bf16 v[92:95], v[166:169], v[190:193], v[92:95]
	v_mfma_f32_16x16x32_bf16 v[88:91], v[174:177], v[190:193], v[88:91]
	v_mfma_f32_16x16x32_bf16 v[44:47], v[166:169], v[198:201], v[44:47]
	v_mfma_f32_16x16x32_bf16 v[40:43], v[174:177], v[198:201], v[40:43]
	v_mfma_f32_16x16x32_bf16 v[4:7], v[166:169], v[206:209], v[4:7]
	v_mfma_f32_16x16x32_bf16 v[0:3], v[174:177], v[206:209], v[0:3]
	s_barrier
	s_setprio 0
	ds_read_b128 v[146:149], v143
	ds_read_b128 v[150:153], v143 offset:1024
	ds_read_b128 v[154:157], v143 offset:2048
	ds_read_b128 v[158:161], v143 offset:3072
	ds_read_b128 v[162:165], v144
	ds_read_b128 v[166:169], v144 offset:1024
	ds_read_b128 v[170:173], v144 offset:2048
	ds_read_b128 v[174:177], v144 offset:3072
	s_add_u32 s52, s72, 0x4000
	s_addc_u32 s53, s73, 0
	s_mov_b32 m0, s21
	v_lshl_add_u64 v[214:215], s[52:53], 0, v[32:33]
	ds_read_b128 v[178:181], v142 offset:32768
	ds_read_b128 v[182:185], v142 offset:33792
	ds_read_b128 v[186:189], v142 offset:34816
	ds_read_b128 v[190:193], v142 offset:35840
	ds_read_b128 v[194:197], v142 offset:36864
	ds_read_b128 v[198:201], v142 offset:37888
	ds_read_b128 v[202:205], v142 offset:38912
	ds_read_b128 v[206:209], v142 offset:39936
	global_load_lds_dwordx4 v[214:215], off
	v_lshl_add_u64 v[214:215], s[52:53], 0, v[132:133]
	s_mov_b32 m0, s22
	s_nop 0
	global_load_lds_dwordx4 v[214:215], off
	s_waitcnt vmcnt(8) lgkmcnt(0)
	s_setprio 1
	s_barrier
	v_mfma_f32_16x16x32_bf16 v[8:11], v[146:149], v[178:181], v[8:11]
	v_mfma_f32_16x16x32_bf16 v[12:15], v[154:157], v[178:181], v[12:15]
	v_mfma_f32_16x16x32_bf16 v[60:63], v[146:149], v[186:189], v[60:63]
	v_mfma_f32_16x16x32_bf16 v[20:23], v[154:157], v[186:189], v[20:23]
	v_mfma_f32_16x16x32_bf16 v[76:79], v[146:149], v[194:197], v[76:79]
	v_mfma_f32_16x16x32_bf16 v[52:55], v[154:157], v[194:197], v[52:55]
	v_mfma_f32_16x16x32_bf16 v[128:131], v[146:149], v[202:205], v[128:131]
	v_mfma_f32_16x16x32_bf16 v[68:71], v[154:157], v[202:205], v[68:71]
	v_mfma_f32_16x16x32_bf16 v[8:11], v[150:153], v[182:185], v[8:11]
	v_mfma_f32_16x16x32_bf16 v[12:15], v[158:161], v[182:185], v[12:15]
	v_mfma_f32_16x16x32_bf16 v[60:63], v[150:153], v[190:193], v[60:63]
	v_mfma_f32_16x16x32_bf16 v[20:23], v[158:161], v[190:193], v[20:23]
	v_mfma_f32_16x16x32_bf16 v[76:79], v[150:153], v[198:201], v[76:79]
	v_mfma_f32_16x16x32_bf16 v[52:55], v[158:161], v[198:201], v[52:55]
	v_mfma_f32_16x16x32_bf16 v[128:131], v[150:153], v[206:209], v[128:131]
	v_mfma_f32_16x16x32_bf16 v[68:71], v[158:161], v[206:209], v[68:71]
	v_mfma_f32_16x16x32_bf16 v[28:31], v[162:165], v[178:181], v[28:31]
	v_mfma_f32_16x16x32_bf16 v[16:19], v[170:173], v[178:181], v[16:19]
	v_mfma_f32_16x16x32_bf16 v[56:59], v[162:165], v[186:189], v[56:59]
	v_mfma_f32_16x16x32_bf16 v[48:51], v[170:173], v[186:189], v[48:51]
	v_mfma_f32_16x16x32_bf16 v[72:75], v[162:165], v[194:197], v[72:75]
	v_mfma_f32_16x16x32_bf16 v[64:67], v[170:173], v[194:197], v[64:67]
	v_mfma_f32_16x16x32_bf16 v[108:111], v[162:165], v[202:205], v[108:111]
	v_mfma_f32_16x16x32_bf16 v[96:99], v[170:173], v[202:205], v[96:99]
	v_mfma_f32_16x16x32_bf16 v[28:31], v[166:169], v[182:185], v[28:31]
	v_mfma_f32_16x16x32_bf16 v[16:19], v[174:177], v[182:185], v[16:19]
	v_mfma_f32_16x16x32_bf16 v[56:59], v[166:169], v[190:193], v[56:59]
	v_mfma_f32_16x16x32_bf16 v[48:51], v[174:177], v[190:193], v[48:51]
	v_mfma_f32_16x16x32_bf16 v[72:75], v[166:169], v[198:201], v[72:75]
	v_mfma_f32_16x16x32_bf16 v[64:67], v[174:177], v[198:201], v[64:67]
	v_mfma_f32_16x16x32_bf16 v[108:111], v[166:169], v[206:209], v[108:111]
	v_mfma_f32_16x16x32_bf16 v[96:99], v[174:177], v[206:209], v[96:99]
	s_barrier
; #define PG8_WAIT_V(n) asm volatile("s_waitcnt vmcnt(" #n ")" ::: "memory")
; #define PG8_BAR __builtin_amdgcn_s_barrier()
; template <class Epi, class Sched, bool ALIGN_EPI = false, bool SP2 = false, bool A_TILED = false>
; __device__ __forceinline__ void gemm_phase(PG8_LAS unsigned char* lds, const Gemm g, const Sched& S, const Epi& E, const int wave_s) {
;     ...
;     PG8_WAIT_V(0);
;     if constexpr (!ALIGN_EPI) { if (wr == 0) PG8_BAR; }
	s_setprio 0
	s_mov_b32 m0, s48
	v_lshl_add_u64 v[210:211], v[210:211], 0, s[64:65]
	s_add_u32 s52, s70, 0x200080
	ds_read_b128 v[178:181], v142 offset:49152
	ds_read_b128 v[182:185], v142 offset:50176
	ds_read_b128 v[186:189], v142 offset:51200
	ds_read_b128 v[190:193], v142 offset:52224
	ds_read_b128 v[194:197], v142 offset:53248
	ds_read_b128 v[198:201], v142 offset:54272
	ds_read_b128 v[202:205], v142 offset:55296
	ds_read_b128 v[206:209], v142 offset:56320
	global_load_lds_dwordx4 v[210:211], off
	v_lshl_add_u64 v[210:211], v[212:213], 0, s[64:65]
	s_mov_b32 m0, s49
	s_addc_u32 s53, s71, 0
	global_load_lds_dwordx4 v[210:211], off
	v_lshl_add_u64 v[210:211], s[52:53], 0, v[34:35]
	s_mov_b32 m0, s50
	s_nop 0
	global_load_lds_dwordx4 v[210:211], off
	v_lshl_add_u64 v[210:211], s[52:53], 0, v[134:135]
	s_mov_b32 m0, s51
	s_nop 0
	global_load_lds_dwordx4 v[210:211], off
	v_lshl_add_u64 v[210:211], s[68:69], 0, v[32:33]
	s_mov_b32 m0, s23
	s_nop 0
	global_load_lds_dwordx4 v[210:211], off
	v_lshl_add_u64 v[210:211], s[68:69], 0, v[132:133]
	s_mov_b32 m0, s36
	s_nop 0
	global_load_lds_dwordx4 v[210:211], off
	s_waitcnt vmcnt(8) lgkmcnt(0)
	s_setprio 1
	s_barrier
	v_mfma_f32_16x16x32_bf16 v[100:103], v[146:149], v[178:181], v[100:103]
	v_mfma_f32_16x16x32_bf16 v[104:107], v[154:157], v[178:181], v[104:107]
	v_mfma_f32_16x16x32_bf16 v[116:119], v[146:149], v[186:189], v[116:119]
	v_mfma_f32_16x16x32_bf16 v[120:123], v[154:157], v[186:189], v[120:123]
	v_mfma_f32_16x16x32_bf16 v[84:87], v[146:149], v[194:197], v[84:87]
	v_mfma_f32_16x16x32_bf16 v[80:83], v[154:157], v[194:197], v[80:83]
	v_mfma_f32_16x16x32_bf16 v[36:39], v[146:149], v[202:205], v[36:39]
	v_mfma_f32_16x16x32_bf16 v[24:27], v[154:157], v[202:205], v[24:27]
	v_mfma_f32_16x16x32_bf16 v[100:103], v[150:153], v[182:185], v[100:103]
	v_mfma_f32_16x16x32_bf16 v[104:107], v[158:161], v[182:185], v[104:107]
	v_mfma_f32_16x16x32_bf16 v[116:119], v[150:153], v[190:193], v[116:119]
	v_mfma_f32_16x16x32_bf16 v[120:123], v[158:161], v[190:193], v[120:123]
	v_mfma_f32_16x16x32_bf16 v[84:87], v[150:153], v[198:201], v[84:87]
	v_mfma_f32_16x16x32_bf16 v[80:83], v[158:161], v[198:201], v[80:83]
	v_mfma_f32_16x16x32_bf16 v[36:39], v[150:153], v[206:209], v[36:39]
	v_mfma_f32_16x16x32_bf16 v[24:27], v[158:161], v[206:209], v[24:27]
	v_mfma_f32_16x16x32_bf16 v[124:127], v[162:165], v[178:181], v[124:127]
	v_mfma_f32_16x16x32_bf16 v[112:115], v[170:173], v[178:181], v[112:115]
	v_mfma_f32_16x16x32_bf16 v[92:95], v[162:165], v[186:189], v[92:95]
	v_mfma_f32_16x16x32_bf16 v[88:91], v[170:173], v[186:189], v[88:91]
	v_mfma_f32_16x16x32_bf16 v[44:47], v[162:165], v[194:197], v[44:47]
	v_mfma_f32_16x16x32_bf16 v[40:43], v[170:173], v[194:197], v[40:43]
	v_mfma_f32_16x16x32_bf16 v[4:7], v[162:165], v[202:205], v[4:7]
	v_mfma_f32_16x16x32_bf16 v[0:3], v[170:173], v[202:205], v[0:3]
	v_mfma_f32_16x16x32_bf16 v[124:127], v[166:169], v[182:185], v[124:127]
	v_mfma_f32_16x16x32_bf16 v[112:115], v[174:177], v[182:185], v[112:115]
	v_mfma_f32_16x16x32_bf16 v[92:95], v[166:169], v[190:193], v[92:95]
	v_mfma_f32_16x16x32_bf16 v[88:91], v[174:177], v[190:193], v[88:91]
	v_mfma_f32_16x16x32_bf16 v[44:47], v[166:169], v[198:201], v[44:47]
	v_mfma_f32_16x16x32_bf16 v[40:43], v[174:177], v[198:201], v[40:43]
	v_mfma_f32_16x16x32_bf16 v[4:7], v[166:169], v[206:209], v[4:7]
	v_mfma_f32_16x16x32_bf16 v[0:3], v[174:177], v[206:209], v[0:3]
	s_barrier
	s_setprio 0
	s_add_i32 s41, s41, 2
	s_add_u32 s37, s37, 0x100
	s_addc_u32 s38, s38, 0
	s_add_u32 s39, s39, 0x10000
	s_addc_u32 s40, s40, 0
	v_lshl_add_u64 v[136:137], v[136:137], 0, s[66:67]
	s_cmpk_gt_u32 s41, 0x7d
	v_lshl_add_u64 v[138:139], v[138:139], 0, s[66:67]
	s_cbranch_scc0 .LBB0_2026
	s_waitcnt vmcnt(0)
	s_cmpk_lt_u32 s0, 0x100
	s_cbranch_scc0 .LBB0_2029
	s_barrier

; template <class Epi, class Sched, bool ALIGN_EPI = false, bool SP2 = false, bool A_TILED = false>
; __device__ __forceinline__ void gemm_phase(PG8_LAS unsigned char* lds, const Gemm g, const Sched& S, const Epi& E, const int wave_s) {
;     ...
;         const bool has_next = Epi::AFTER_DRAIN ? false : S.next(ui + 1, nxt);
;         const char* nA = has_next ? (const char*)g.A + (size_t)nxt.pm * tstepA : cA; const char* nB = has_next ? (const char*)g.Bt + (size_t)nxt.pn * tstep : cB;
;         constexpr bool PEEL = SP2 && !Epi::AFTER_DRAIN;
;         if constexpr (PEEL) {
;             const char* a1 = cA + kstepA; const char* a2 = cA + 2 * kstepA; const char* b2 = cB + 2 * kstep; const char* a3 = a2 + kstepA; const char* b3 = b2 + kstep;
;             PG8_ITER(PG8_MMAZ)
.LBB0_2416:
	s_ashr_i32 s73, s72, 31
	s_lshl_b64 s[50:51], s[72:73], 20
	s_add_u32 s74, s1, s50
	ds_read_b128 v[0:3], v141
	ds_read_b128 v[4:7], v141 offset:1024
	ds_read_b128 v[8:11], v141 offset:2048
	ds_read_b128 v[12:15], v141 offset:3072
	ds_read_b128 v[16:19], v142
	ds_read_b128 v[20:23], v142 offset:1024
	ds_read_b128 v[24:27], v142 offset:2048
	ds_read_b128 v[28:31], v142 offset:3072
	s_addc_u32 s75, s8, s51
	s_ashr_i32 s71, s70, 31
	s_lshl_b64 s[50:51], s[70:71], 20
	s_add_u32 s76, s9, s50
	s_addc_u32 s77, s14, s51
	s_and_b64 s[50:51], s[2:3], exec
	s_cselect_b32 s50, s75, s81
	s_cselect_b32 s51, s74, s80
	s_cselect_b32 s52, s77, s79
	s_cselect_b32 s53, s76, s78
	s_add_u32 s54, s80, 0x80080
	s_addc_u32 s55, s81, 0
	s_mov_b32 m0, s48
	v_lshl_add_u64 v[64:65], s[54:55], 0, v[128:129]
	ds_read_b128 v[32:35], v143
	ds_read_b128 v[36:39], v143 offset:1024
	ds_read_b128 v[40:43], v143 offset:2048
	ds_read_b128 v[44:47], v143 offset:3072
	ds_read_b128 v[48:51], v143 offset:4096
	ds_read_b128 v[52:55], v143 offset:5120
	ds_read_b128 v[56:59], v143 offset:6144
	ds_read_b128 v[60:63], v143 offset:7168
	global_load_lds_dwordx4 v[64:65], off
	v_lshl_add_u64 v[64:65], s[54:55], 0, v[130:131]
	s_mov_b32 m0, s49
	s_nop 0
	global_load_lds_dwordx4 v[64:65], off
	s_waitcnt vmcnt(8) lgkmcnt(0)
	s_setprio 1
	s_barrier
	v_mfma_f32_16x16x32_bf16 v[64:67], v[0:3], v[32:35], 0
	v_mfma_f32_16x16x32_bf16 v[68:71], v[8:11], v[32:35], 0
	v_mfma_f32_16x16x32_bf16 v[72:75], v[0:3], v[40:43], 0
	v_mfma_f32_16x16x32_bf16 v[76:79], v[8:11], v[40:43], 0
	v_mfma_f32_16x16x32_bf16 v[80:83], v[0:3], v[48:51], 0
	v_mfma_f32_16x16x32_bf16 v[84:87], v[8:11], v[48:51], 0
	v_mfma_f32_16x16x32_bf16 v[88:91], v[0:3], v[56:59], 0
	v_mfma_f32_16x16x32_bf16 v[92:95], v[8:11], v[56:59], 0
	v_mfma_f32_16x16x32_bf16 v[64:67], v[4:7], v[36:39], v[64:67]
	v_mfma_f32_16x16x32_bf16 v[68:71], v[12:15], v[36:39], v[68:71]
	v_mfma_f32_16x16x32_bf16 v[72:75], v[4:7], v[44:47], v[72:75]
	v_mfma_f32_16x16x32_bf16 v[76:79], v[12:15], v[44:47], v[76:79]
	v_mfma_f32_16x16x32_bf16 v[80:83], v[4:7], v[52:55], v[80:83]
	v_mfma_f32_16x16x32_bf16 v[84:87], v[12:15], v[52:55], v[84:87]
	v_mfma_f32_16x16x32_bf16 v[88:91], v[4:7], v[60:63], v[88:91]
	v_mfma_f32_16x16x32_bf16 v[92:95], v[12:15], v[60:63], v[92:95]
	v_mfma_f32_16x16x32_bf16 v[96:99], v[16:19], v[32:35], 0
	v_mfma_f32_16x16x32_bf16 v[32:35], v[24:27], v[32:35], 0
	v_mfma_f32_16x16x32_bf16 v[96:99], v[20:23], v[36:39], v[96:99]
	v_mfma_f32_16x16x32_bf16 v[32:35], v[28:31], v[36:39], v[32:35]
	v_mfma_f32_16x16x32_bf16 v[36:39], v[16:19], v[40:43], 0
	v_mfma_f32_16x16x32_bf16 v[40:43], v[24:27], v[40:43], 0
	v_mfma_f32_16x16x32_bf16 v[36:39], v[20:23], v[44:47], v[36:39]
	v_mfma_f32_16x16x32_bf16 v[40:43], v[28:31], v[44:47], v[40:43]
	v_mfma_f32_16x16x32_bf16 v[44:47], v[16:19], v[48:51], 0
	v_mfma_f32_16x16x32_bf16 v[48:51], v[24:27], v[48:51], 0
	v_mfma_f32_16x16x32_bf16 v[100:103], v[28:31], v[52:55], v[48:51]
	v_mfma_f32_16x16x32_bf16 v[48:51], v[16:19], v[56:59], 0
	v_mfma_f32_16x16x32_bf16 v[104:107], v[20:23], v[60:63], v[48:51]
	v_mfma_f32_16x16x32_bf16 v[48:51], v[24:27], v[56:59], 0
	v_mfma_f32_16x16x32_bf16 v[44:47], v[20:23], v[52:55], v[44:47]
	v_mfma_f32_16x16x32_bf16 v[108:111], v[28:31], v[60:63], v[48:51]
	s_barrier
	s_setprio 0
	s_add_i32 s54, s45, s15
	v_lshl_add_u64 v[250:251], s[78:79], 0, v[128:129]
	s_add_i32 s55, s54, 0x2000
	v_lshl_add_u64 v[144:145], v[250:251], 0, s[66:67]
	s_mov_b32 m0, s54
	v_lshl_add_u64 v[252:253], s[78:79], 0, v[130:131]
	s_add_u32 s58, s78, 0x80100
	ds_read_b128 v[48:51], v143 offset:16384
	ds_read_b128 v[52:55], v143 offset:17408
	ds_read_b128 v[56:59], v143 offset:18432
	ds_read_b128 v[60:63], v143 offset:19456
	ds_read_b128 v[112:115], v143 offset:20480
	ds_read_b128 v[116:119], v143 offset:21504
	ds_read_b128 v[120:123], v143 offset:22528
	ds_read_b128 v[124:127], v143 offset:23552
	global_load_lds_dwordx4 v[144:145], off
	v_lshl_add_u64 v[144:145], v[252:253], 0, s[66:67]
	s_mov_b32 m0, s55
	s_addc_u32 s59, s79, 0
	s_add_i32 s56, s46, s15
	global_load_lds_dwordx4 v[144:145], off
	v_lshl_add_u64 v[144:145], s[58:59], 0, v[128:129]
	s_mov_b32 m0, s56
	s_add_i32 s57, s56, 0x2000
	global_load_lds_dwordx4 v[144:145], off
	v_lshl_add_u64 v[144:145], s[58:59], 0, v[130:131]
	s_mov_b32 m0, s57
	v_lshl_add_u64 v[136:137], s[80:81], 0, v[128:129]
	global_load_lds_dwordx4 v[144:145], off
	v_lshl_add_u64 v[144:145], v[136:137], 0, s[66:67]
	s_mov_b32 m0, s22
	v_lshl_add_u64 v[138:139], s[80:81], 0, v[130:131]
	global_load_lds_dwordx4 v[144:145], off
	v_lshl_add_u64 v[144:145], v[138:139], 0, s[66:67]
	s_mov_b32 m0, s23
	s_nop 0
	global_load_lds_dwordx4 v[144:145], off
	s_waitcnt vmcnt(8) lgkmcnt(0)
	s_setprio 1
	s_barrier
	v_mfma_f32_16x16x32_bf16 v[144:147], v[0:3], v[48:51], 0
	v_mfma_f32_16x16x32_bf16 v[154:157], v[0:3], v[56:59], 0
	v_mfma_f32_16x16x32_bf16 v[162:165], v[0:3], v[112:115], 0
	v_mfma_f32_16x16x32_bf16 v[0:3], v[0:3], v[120:123], 0
	v_mfma_f32_16x16x32_bf16 v[150:153], v[8:11], v[48:51], 0
	v_mfma_f32_16x16x32_bf16 v[158:161], v[8:11], v[56:59], 0
	v_mfma_f32_16x16x32_bf16 v[166:169], v[8:11], v[112:115], 0
	v_mfma_f32_16x16x32_bf16 v[170:173], v[4:7], v[124:127], v[0:3]
	v_mfma_f32_16x16x32_bf16 v[0:3], v[8:11], v[120:123], 0
	v_mfma_f32_16x16x32_bf16 v[146:149], v[4:7], v[52:55], v[144:147]
	v_mfma_f32_16x16x32_bf16 v[150:153], v[12:15], v[52:55], v[150:153]
	v_mfma_f32_16x16x32_bf16 v[154:157], v[4:7], v[60:63], v[154:157]
	v_mfma_f32_16x16x32_bf16 v[158:161], v[12:15], v[60:63], v[158:161]
	v_mfma_f32_16x16x32_bf16 v[162:165], v[4:7], v[116:119], v[162:165]
	v_mfma_f32_16x16x32_bf16 v[166:169], v[12:15], v[116:119], v[166:169]
	v_mfma_f32_16x16x32_bf16 v[174:177], v[12:15], v[124:127], v[0:3]
	v_mfma_f32_16x16x32_bf16 v[0:3], v[16:19], v[48:51], 0
	v_mfma_f32_16x16x32_bf16 v[178:181], v[20:23], v[52:55], v[0:3]
	v_mfma_f32_16x16x32_bf16 v[0:3], v[24:27], v[48:51], 0
	v_mfma_f32_16x16x32_bf16 v[182:185], v[28:31], v[52:55], v[0:3]
	v_mfma_f32_16x16x32_bf16 v[0:3], v[16:19], v[56:59], 0
	v_mfma_f32_16x16x32_bf16 v[186:189], v[20:23], v[60:63], v[0:3]
	v_mfma_f32_16x16x32_bf16 v[0:3], v[24:27], v[56:59], 0
	v_mfma_f32_16x16x32_bf16 v[190:193], v[28:31], v[60:63], v[0:3]
	v_mfma_f32_16x16x32_bf16 v[0:3], v[16:19], v[112:115], 0
	v_mfma_f32_16x16x32_bf16 v[194:197], v[20:23], v[116:119], v[0:3]
	v_mfma_f32_16x16x32_bf16 v[0:3], v[24:27], v[112:115], 0
	v_mfma_f32_16x16x32_bf16 v[198:201], v[28:31], v[116:119], v[0:3]
	v_mfma_f32_16x16x32_bf16 v[0:3], v[16:19], v[120:123], 0
	v_mfma_f32_16x16x32_bf16 v[202:205], v[20:23], v[124:127], v[0:3]
	v_mfma_f32_16x16x32_bf16 v[0:3], v[24:27], v[120:123], 0
	v_mfma_f32_16x16x32_bf16 v[206:209], v[28:31], v[124:127], v[0:3]
	s_barrier
	s_setprio 0
	s_add_i32 s61, 0, 0x18000
	s_add_i32 s71, 0, 0x1c000
	v_add_u32_e32 v144, s61, v140
	v_add_u32_e32 v145, s71, v140
	ds_read_b128 v[112:115], v144
	ds_read_b128 v[116:119], v144 offset:1024
	ds_read_b128 v[120:123], v144 offset:2048
	ds_read_b128 v[124:127], v144 offset:3072
	ds_read_b128 v[210:213], v145
	ds_read_b128 v[214:217], v145 offset:1024
	ds_read_b128 v[218:221], v145 offset:2048
	ds_read_b128 v[222:225], v145 offset:3072
	s_add_u32 s58, s80, 0x80100
	s_addc_u32 s59, s81, 0
	s_mov_b32 m0, s36
	v_lshl_add_u64 v[0:1], s[58:59], 0, v[128:129]
	ds_read_b128 v[48:51], v143 offset:32768
	ds_read_b128 v[52:55], v143 offset:33792
	ds_read_b128 v[226:229], v143 offset:34816
	ds_read_b128 v[230:233], v143 offset:35840
	ds_read_b128 v[234:237], v143 offset:36864
	ds_read_b128 v[238:241], v143 offset:37888
	ds_read_b128 v[242:245], v143 offset:38912
	ds_read_b128 v[246:249], v143 offset:39936
	global_load_lds_dwordx4 v[0:1], off
	v_lshl_add_u64 v[0:1], s[58:59], 0, v[130:131]
	s_mov_b32 m0, s37
	s_nop 0
	global_load_lds_dwordx4 v[0:1], off
	s_waitcnt vmcnt(8) lgkmcnt(0)
	s_setprio 1
	s_barrier
	v_mfma_f32_16x16x32_bf16 v[0:3], v[112:115], v[48:51], v[64:67]
	v_mfma_f32_16x16x32_bf16 v[24:27], v[116:119], v[52:55], v[0:3]
	v_mfma_f32_16x16x32_bf16 v[0:3], v[120:123], v[48:51], v[68:71]
	v_mfma_f32_16x16x32_bf16 v[28:31], v[124:127], v[52:55], v[0:3]
	v_mfma_f32_16x16x32_bf16 v[0:3], v[112:115], v[226:229], v[72:75]
	v_mfma_f32_16x16x32_bf16 v[16:19], v[116:119], v[230:233], v[0:3]
	v_mfma_f32_16x16x32_bf16 v[0:3], v[120:123], v[226:229], v[76:79]
	v_mfma_f32_16x16x32_bf16 v[20:23], v[124:127], v[230:233], v[0:3]
	v_mfma_f32_16x16x32_bf16 v[0:3], v[112:115], v[234:237], v[80:83]
	v_mfma_f32_16x16x32_bf16 v[8:11], v[116:119], v[238:241], v[0:3]
	v_mfma_f32_16x16x32_bf16 v[0:3], v[120:123], v[234:237], v[84:87]
	v_mfma_f32_16x16x32_bf16 v[12:15], v[124:127], v[238:241], v[0:3]
	v_mfma_f32_16x16x32_bf16 v[0:3], v[112:115], v[242:245], v[88:91]
	v_mfma_f32_16x16x32_bf16 v[4:7], v[120:123], v[242:245], v[92:95]
	v_mfma_f32_16x16x32_bf16 v[0:3], v[116:119], v[246:249], v[0:3]
	v_mfma_f32_16x16x32_bf16 v[4:7], v[124:127], v[246:249], v[4:7]
	v_mfma_f32_16x16x32_bf16 v[32:35], v[218:221], v[48:51], v[32:35]
	v_mfma_f32_16x16x32_bf16 v[60:63], v[222:225], v[52:55], v[32:35]
	v_mfma_f32_16x16x32_bf16 v[32:35], v[210:213], v[226:229], v[36:39]
	v_mfma_f32_16x16x32_bf16 v[56:59], v[210:213], v[48:51], v[96:99]
	v_mfma_f32_16x16x32_bf16 v[48:51], v[214:217], v[230:233], v[32:35]
	v_mfma_f32_16x16x32_bf16 v[32:35], v[218:221], v[226:229], v[40:43]
	v_mfma_f32_16x16x32_bf16 v[56:59], v[214:217], v[52:55], v[56:59]
	v_mfma_f32_16x16x32_bf16 v[52:55], v[222:225], v[230:233], v[32:35]
	v_mfma_f32_16x16x32_bf16 v[32:35], v[210:213], v[234:237], v[44:47]
	v_mfma_f32_16x16x32_bf16 v[40:43], v[214:217], v[238:241], v[32:35]
	v_mfma_f32_16x16x32_bf16 v[32:35], v[218:221], v[234:237], v[100:103]
	v_mfma_f32_16x16x32_bf16 v[44:47], v[222:225], v[238:241], v[32:35]
	v_mfma_f32_16x16x32_bf16 v[32:35], v[210:213], v[242:245], v[104:107]
	v_mfma_f32_16x16x32_bf16 v[36:39], v[218:221], v[242:245], v[108:111]
	v_mfma_f32_16x16x32_bf16 v[32:35], v[214:217], v[246:249], v[32:35]
	v_mfma_f32_16x16x32_bf16 v[36:39], v[222:225], v[246:249], v[36:39]
	s_barrier
; template <class Epi, class Sched, bool ALIGN_EPI = false, bool SP2 = false, bool A_TILED = false>
; __device__ __forceinline__ void gemm_phase(PG8_LAS unsigned char* lds, const Gemm g, const Sched& S, const Epi& E, const int wave_s) {
;     ...
;         for (int t = PEEL ? 2 : 0; t < nt; t += 2) {
;             const bool last = (t == nt - 2);
;             const char* a1 = cA + (size_t)(t + 1) * kstepA;
;             const char* a2 = last ? nA : cA + (size_t)(t + 2) * kstepA; const char* b2 = last ? nB : cB + (size_t)(t + 2) * kstep;
;             const char* a3 = a2 + kstepA; const char* b3 = b2 + kstep;
;             if (last && has_next) S.a_ready(nxt);
	s_setprio 0
	s_add_i32 s58, s61, s15
	s_add_i32 s59, s58, 0x2000
	v_lshl_add_u64 v[64:65], v[250:251], 0, s[68:69]
	s_mov_b32 m0, s58
	s_add_u32 s82, s78, 0x80180
	ds_read_b128 v[96:99], v143 offset:49152
	ds_read_b128 v[100:103], v143 offset:50176
	ds_read_b128 v[104:107], v143 offset:51200
	ds_read_b128 v[108:111], v143 offset:52224
	ds_read_b128 v[226:229], v143 offset:53248
	ds_read_b128 v[230:233], v143 offset:54272
	ds_read_b128 v[234:237], v143 offset:55296
	ds_read_b128 v[238:241], v143 offset:56320
	global_load_lds_dwordx4 v[64:65], off
	v_lshl_add_u64 v[64:65], v[252:253], 0, s[68:69]
	s_mov_b32 m0, s59
	s_addc_u32 s83, s79, 0
	s_add_i32 s61, s71, s15
	global_load_lds_dwordx4 v[64:65], off
	v_lshl_add_u64 v[64:65], s[82:83], 0, v[128:129]
	s_mov_b32 m0, s61
	s_add_i32 s71, s61, 0x2000
	global_load_lds_dwordx4 v[64:65], off
	v_lshl_add_u64 v[64:65], s[82:83], 0, v[130:131]
	s_mov_b32 m0, s71
	s_nop 0
	global_load_lds_dwordx4 v[64:65], off
	v_lshl_add_u64 v[64:65], v[136:137], 0, s[68:69]
	s_mov_b32 m0, s42
	s_nop 0
	global_load_lds_dwordx4 v[64:65], off
	v_lshl_add_u64 v[64:65], v[138:139], 0, s[68:69]
	s_mov_b32 m0, s43
	s_nop 0
	global_load_lds_dwordx4 v[64:65], off
	s_waitcnt vmcnt(8) lgkmcnt(0)
	s_setprio 1
	s_barrier
	v_mfma_f32_16x16x32_bf16 v[64:67], v[112:115], v[96:99], v[146:149]
	v_mfma_f32_16x16x32_bf16 v[88:91], v[116:119], v[100:103], v[64:67]
	v_mfma_f32_16x16x32_bf16 v[64:67], v[120:123], v[96:99], v[150:153]
	v_mfma_f32_16x16x32_bf16 v[92:95], v[124:127], v[100:103], v[64:67]
	v_mfma_f32_16x16x32_bf16 v[64:67], v[112:115], v[104:107], v[154:157]
	v_mfma_f32_16x16x32_bf16 v[80:83], v[116:119], v[108:111], v[64:67]
	v_mfma_f32_16x16x32_bf16 v[64:67], v[120:123], v[104:107], v[158:161]
	v_mfma_f32_16x16x32_bf16 v[84:87], v[124:127], v[108:111], v[64:67]
	v_mfma_f32_16x16x32_bf16 v[64:67], v[112:115], v[226:229], v[162:165]
	v_mfma_f32_16x16x32_bf16 v[72:75], v[116:119], v[230:233], v[64:67]
	v_mfma_f32_16x16x32_bf16 v[64:67], v[120:123], v[226:229], v[166:169]
	v_mfma_f32_16x16x32_bf16 v[76:79], v[124:127], v[230:233], v[64:67]
	v_mfma_f32_16x16x32_bf16 v[64:67], v[112:115], v[234:237], v[170:173]
	v_mfma_f32_16x16x32_bf16 v[68:71], v[120:123], v[234:237], v[174:177]
	v_mfma_f32_16x16x32_bf16 v[64:67], v[116:119], v[238:241], v[64:67]
	v_mfma_f32_16x16x32_bf16 v[68:71], v[124:127], v[238:241], v[68:71]
	v_mfma_f32_16x16x32_bf16 v[112:115], v[210:213], v[96:99], v[178:181]
	v_mfma_f32_16x16x32_bf16 v[96:99], v[218:221], v[96:99], v[182:185]
	v_mfma_f32_16x16x32_bf16 v[124:127], v[222:225], v[100:103], v[96:99]
	v_mfma_f32_16x16x32_bf16 v[96:99], v[210:213], v[104:107], v[186:189]
	v_mfma_f32_16x16x32_bf16 v[120:123], v[214:217], v[100:103], v[112:115]
	v_mfma_f32_16x16x32_bf16 v[112:115], v[214:217], v[108:111], v[96:99]
	v_mfma_f32_16x16x32_bf16 v[96:99], v[218:221], v[104:107], v[190:193]
	v_mfma_f32_16x16x32_bf16 v[116:119], v[222:225], v[108:111], v[96:99]
	v_mfma_f32_16x16x32_bf16 v[96:99], v[210:213], v[226:229], v[194:197]
	v_mfma_f32_16x16x32_bf16 v[104:107], v[214:217], v[230:233], v[96:99]
	v_mfma_f32_16x16x32_bf16 v[96:99], v[218:221], v[226:229], v[198:201]
	v_mfma_f32_16x16x32_bf16 v[108:111], v[222:225], v[230:233], v[96:99]
	v_mfma_f32_16x16x32_bf16 v[96:99], v[210:213], v[234:237], v[202:205]
	v_mfma_f32_16x16x32_bf16 v[100:103], v[218:221], v[234:237], v[206:209]
	v_mfma_f32_16x16x32_bf16 v[96:99], v[214:217], v[238:241], v[96:99]
	v_mfma_f32_16x16x32_bf16 v[100:103], v[222:225], v[238:241], v[100:103]
	s_barrier
	s_setprio 0
	s_add_u32 s73, s78, 0x200
	s_addc_u32 s85, s79, 0
	s_add_u32 s78, s80, 0x80180
	s_addc_u32 s79, s81, 0
	s_mov_b32 s88, 0
.LBB0_2417:
	ds_read_b128 v[146:149], v141
	ds_read_b128 v[150:153], v141 offset:1024
	ds_read_b128 v[154:157], v141 offset:2048
	ds_read_b128 v[158:161], v141 offset:3072
	ds_read_b128 v[162:165], v142
	ds_read_b128 v[166:169], v142 offset:1024
	ds_read_b128 v[170:173], v142 offset:2048
	ds_read_b128 v[174:177], v142 offset:3072
	s_add_u32 s80, s78, 0xfff80080
	s_addc_u32 s81, s79, -1
	s_cmp_eq_u32 s88, 28
	s_cselect_b32 s83, s50, s81
	s_cselect_b32 s82, s51, s80
	s_cselect_b32 s81, s52, s85
	s_cselect_b32 s80, s53, s73
	s_mov_b32 m0, s48
	v_lshl_add_u64 v[136:137], s[78:79], 0, v[134:135]
	ds_read_b128 v[178:181], v143
	ds_read_b128 v[182:185], v143 offset:1024
	ds_read_b128 v[186:189], v143 offset:2048
	ds_read_b128 v[190:193], v143 offset:3072
	ds_read_b128 v[194:197], v143 offset:4096
	ds_read_b128 v[198:201], v143 offset:5120
	ds_read_b128 v[202:205], v143 offset:6144
	ds_read_b128 v[206:209], v143 offset:7168
	global_load_lds_dwordx4 v[136:137], off
	v_lshl_add_u64 v[136:137], s[78:79], 0, v[132:133]
	s_mov_b32 m0, s49
	s_nop 0
	global_load_lds_dwordx4 v[136:137], off
	s_waitcnt vmcnt(8) lgkmcnt(0)
	s_setprio 1
	s_barrier
	v_mfma_f32_16x16x32_bf16 v[24:27], v[146:149], v[178:181], v[24:27]
	v_mfma_f32_16x16x32_bf16 v[28:31], v[154:157], v[178:181], v[28:31]
	v_mfma_f32_16x16x32_bf16 v[16:19], v[146:149], v[186:189], v[16:19]
	v_mfma_f32_16x16x32_bf16 v[20:23], v[154:157], v[186:189], v[20:23]
	v_mfma_f32_16x16x32_bf16 v[8:11], v[146:149], v[194:197], v[8:11]
	v_mfma_f32_16x16x32_bf16 v[12:15], v[154:157], v[194:197], v[12:15]
	v_mfma_f32_16x16x32_bf16 v[0:3], v[146:149], v[202:205], v[0:3]
	v_mfma_f32_16x16x32_bf16 v[4:7], v[154:157], v[202:205], v[4:7]
	v_mfma_f32_16x16x32_bf16 v[24:27], v[150:153], v[182:185], v[24:27]
	v_mfma_f32_16x16x32_bf16 v[28:31], v[158:161], v[182:185], v[28:31]
	v_mfma_f32_16x16x32_bf16 v[16:19], v[150:153], v[190:193], v[16:19]
	v_mfma_f32_16x16x32_bf16 v[20:23], v[158:161], v[190:193], v[20:23]
	v_mfma_f32_16x16x32_bf16 v[8:11], v[150:153], v[198:201], v[8:11]
	v_mfma_f32_16x16x32_bf16 v[12:15], v[158:161], v[198:201], v[12:15]
	v_mfma_f32_16x16x32_bf16 v[0:3], v[150:153], v[206:209], v[0:3]
	v_mfma_f32_16x16x32_bf16 v[4:7], v[158:161], v[206:209], v[4:7]
	v_mfma_f32_16x16x32_bf16 v[56:59], v[162:165], v[178:181], v[56:59]
	v_mfma_f32_16x16x32_bf16 v[60:63], v[170:173], v[178:181], v[60:63]
	v_mfma_f32_16x16x32_bf16 v[48:51], v[162:165], v[186:189], v[48:51]
	v_mfma_f32_16x16x32_bf16 v[52:55], v[170:173], v[186:189], v[52:55]
	v_mfma_f32_16x16x32_bf16 v[40:43], v[162:165], v[194:197], v[40:43]
	v_mfma_f32_16x16x32_bf16 v[44:47], v[170:173], v[194:197], v[44:47]
	v_mfma_f32_16x16x32_bf16 v[32:35], v[162:165], v[202:205], v[32:35]
	v_mfma_f32_16x16x32_bf16 v[36:39], v[170:173], v[202:205], v[36:39]
	v_mfma_f32_16x16x32_bf16 v[56:59], v[166:169], v[182:185], v[56:59]
	v_mfma_f32_16x16x32_bf16 v[60:63], v[174:177], v[182:185], v[60:63]
	v_mfma_f32_16x16x32_bf16 v[48:51], v[166:169], v[190:193], v[48:51]
	v_mfma_f32_16x16x32_bf16 v[52:55], v[174:177], v[190:193], v[52:55]
	v_mfma_f32_16x16x32_bf16 v[40:43], v[166:169], v[198:201], v[40:43]
	v_mfma_f32_16x16x32_bf16 v[44:47], v[174:177], v[198:201], v[44:47]
	v_mfma_f32_16x16x32_bf16 v[32:35], v[166:169], v[206:209], v[32:35]
	v_mfma_f32_16x16x32_bf16 v[36:39], v[174:177], v[206:209], v[36:39]
	s_barrier
	s_setprio 0
	s_mov_b32 m0, s54
	v_lshl_add_u64 v[136:137], s[80:81], 0, v[128:129]
	s_add_u32 s90, s80, 0x80000
	ds_read_b128 v[178:181], v143 offset:16384
	ds_read_b128 v[182:185], v143 offset:17408
	ds_read_b128 v[186:189], v143 offset:18432
	ds_read_b128 v[190:193], v143 offset:19456
	ds_read_b128 v[194:197], v143 offset:20480
	ds_read_b128 v[198:201], v143 offset:21504
	ds_read_b128 v[202:205], v143 offset:22528
	ds_read_b128 v[206:209], v143 offset:23552
	global_load_lds_dwordx4 v[136:137], off
	v_lshl_add_u64 v[138:139], s[80:81], 0, v[130:131]
	s_mov_b32 m0, s55
	s_addc_u32 s91, s81, 0
	global_load_lds_dwordx4 v[138:139], off
	v_lshl_add_u64 v[210:211], s[90:91], 0, v[128:129]
	s_mov_b32 m0, s56
	v_lshl_add_u64 v[212:213], s[82:83], 0, v[130:131]
	global_load_lds_dwordx4 v[210:211], off
	v_lshl_add_u64 v[210:211], s[90:91], 0, v[130:131]
	s_mov_b32 m0, s57
	s_nop 0
	global_load_lds_dwordx4 v[210:211], off
	v_lshl_add_u64 v[210:211], s[82:83], 0, v[128:129]
	s_mov_b32 m0, s22
	s_nop 0
	global_load_lds_dwordx4 v[210:211], off
	s_mov_b32 m0, s23
	s_nop 0
	global_load_lds_dwordx4 v[212:213], off
	s_waitcnt vmcnt(8) lgkmcnt(0)
	s_setprio 1
	s_barrier
	v_mfma_f32_16x16x32_bf16 v[88:91], v[146:149], v[178:181], v[88:91]
	v_mfma_f32_16x16x32_bf16 v[92:95], v[154:157], v[178:181], v[92:95]
	v_mfma_f32_16x16x32_bf16 v[80:83], v[146:149], v[186:189], v[80:83]
	v_mfma_f32_16x16x32_bf16 v[84:87], v[154:157], v[186:189], v[84:87]
	v_mfma_f32_16x16x32_bf16 v[72:75], v[146:149], v[194:197], v[72:75]
	v_mfma_f32_16x16x32_bf16 v[76:79], v[154:157], v[194:197], v[76:79]
	v_mfma_f32_16x16x32_bf16 v[64:67], v[146:149], v[202:205], v[64:67]
	v_mfma_f32_16x16x32_bf16 v[68:71], v[154:157], v[202:205], v[68:71]
	v_mfma_f32_16x16x32_bf16 v[88:91], v[150:153], v[182:185], v[88:91]
	v_mfma_f32_16x16x32_bf16 v[92:95], v[158:161], v[182:185], v[92:95]
	v_mfma_f32_16x16x32_bf16 v[80:83], v[150:153], v[190:193], v[80:83]
	v_mfma_f32_16x16x32_bf16 v[84:87], v[158:161], v[190:193], v[84:87]
	v_mfma_f32_16x16x32_bf16 v[72:75], v[150:153], v[198:201], v[72:75]
	v_mfma_f32_16x16x32_bf16 v[76:79], v[158:161], v[198:201], v[76:79]
	v_mfma_f32_16x16x32_bf16 v[64:67], v[150:153], v[206:209], v[64:67]
	v_mfma_f32_16x16x32_bf16 v[68:71], v[158:161], v[206:209], v[68:71]
	v_mfma_f32_16x16x32_bf16 v[120:123], v[162:165], v[178:181], v[120:123]
	v_mfma_f32_16x16x32_bf16 v[124:127], v[170:173], v[178:181], v[124:127]
	v_mfma_f32_16x16x32_bf16 v[112:115], v[162:165], v[186:189], v[112:115]
	v_mfma_f32_16x16x32_bf16 v[116:119], v[170:173], v[186:189], v[116:119]
	v_mfma_f32_16x16x32_bf16 v[104:107], v[162:165], v[194:197], v[104:107]
	v_mfma_f32_16x16x32_bf16 v[108:111], v[170:173], v[194:197], v[108:111]
	v_mfma_f32_16x16x32_bf16 v[96:99], v[162:165], v[202:205], v[96:99]
	v_mfma_f32_16x16x32_bf16 v[100:103], v[170:173], v[202:205], v[100:103]
	v_mfma_f32_16x16x32_bf16 v[120:123], v[166:169], v[182:185], v[120:123]
	v_mfma_f32_16x16x32_bf16 v[124:127], v[174:177], v[182:185], v[124:127]
	v_mfma_f32_16x16x32_bf16 v[112:115], v[166:169], v[190:193], v[112:115]
	v_mfma_f32_16x16x32_bf16 v[116:119], v[174:177], v[190:193], v[116:119]
	v_mfma_f32_16x16x32_bf16 v[104:107], v[166:169], v[198:201], v[104:107]
	v_mfma_f32_16x16x32_bf16 v[108:111], v[174:177], v[198:201], v[108:111]
	v_mfma_f32_16x16x32_bf16 v[96:99], v[166:169], v[206:209], v[96:99]
	v_mfma_f32_16x16x32_bf16 v[100:103], v[174:177], v[206:209], v[100:103]
	s_barrier
; #define PG8_STAGE(bufoff, gbase, voff) do { _Pragma("unroll") for (int _i = 0; _i < 2; ++_i) \
;         __builtin_amdgcn_global_load_lds((const unsigned*)((const char*)(gbase) + (voff)[_i]), (PG8_LAS unsigned*)(lds + (bufoff) + ldsw + _i * 8192), 16, 0, 0); } while (0)
; #define PG8_BAR __builtin_amdgcn_s_barrier()
; template <class Epi, class Sched, bool ALIGN_EPI = false, bool SP2 = false, bool A_TILED = false>
; __device__ __forceinline__ void gemm_phase(PG8_LAS unsigned char* lds, const Gemm g, const Sched& S, const Epi& E, const int wave_s) {
;     ...
;         for (int t = PEEL ? 2 : 0; t < nt; t += 2) {
;             const bool last = (t == nt - 2);
;             const char* a1 = cA + (size_t)(t + 1) * kstepA;
;             const char* a2 = last ? nA : cA + (size_t)(t + 2) * kstepA; const char* b2 = last ? nB : cB + (size_t)(t + 2) * kstep;
;             const char* a3 = a2 + kstepA; const char* b3 = b2 + kstep;
;             if (last && has_next) S.a_ready(nxt);
;             if constexpr (SP2) {
;             PG8_ITER(PG8_MMA)
;             } else {
;             PG8_LDB(B0, 0, 0); PG8_SCHED; PG8_LDA(At, 0, 0); PG8_STAGE(PG8_SA(1, 1), a1 + hstepA, voffA);
;             PG8_WAIT_L(8); PG8_BAR; PG8_WAIT_L(0); PG8_MMA(0, 0, At, B0); PG8_BAR; PG8_SCHED;
;             PG8_LDB(B1, 0, 1); PG8_STAGE(PG8_SB(0, 0), b2, voffB);
;             PG8_BAR; PG8_WAIT_L(0); PG8_MMA(0, 1, At, B1); PG8_BAR;
;             PG8_LDA(At, 0, 1); PG8_STAGE(PG8_SA(0, 0), a2, voffA);
;             PG8_BAR; PG8_WAIT_L(0); PG8_MMA(1, 0, At, B0); PG8_BAR; PG8_SCHED;
;             PG8_STAGE(PG8_SB(0, 1), b2 + hstep, voffB);
;             PG8_WAIT_V(6); PG8_BAR; PG8_MMA(1, 1, At, B1); PG8_BAR;
;             PG8_LDB(B0, 1, 0); PG8_SCHED; PG8_LDA(At, 1, 0); PG8_STAGE(PG8_SA(0, 1), a2 + hstepA, voffA);
;             PG8_WAIT_L(8); PG8_BAR; PG8_WAIT_L(0); PG8_MMA(0, 0, At, B0); PG8_BAR; PG8_SCHED;
;             PG8_LDB(B1, 1, 1); PG8_STAGE(PG8_SB(1, 0), b3, voffB);
;             PG8_BAR; PG8_WAIT_L(0); PG8_MMA(0, 1, At, B1); PG8_BAR;
;             PG8_LDA(At, 1, 1); PG8_STAGE(PG8_SA(1, 0), a3, voffA);
;             PG8_BAR; PG8_WAIT_L(0); PG8_MMA(1, 0, At, B0); PG8_BAR; PG8_SCHED;
;             PG8_STAGE(PG8_SB(1, 1), b3 + hstep, voffB);
;             PG8_WAIT_V(6); PG8_BAR; PG8_MMA(1, 1, At, B1); PG8_BAR;
;             }
;         }
;         if constexpr (ALIGN_EPI) { if (wr == 0) PG8_BAR; }
	s_setprio 0
	ds_read_b128 v[146:149], v144
	ds_read_b128 v[150:153], v144 offset:1024
	ds_read_b128 v[154:157], v144 offset:2048
	ds_read_b128 v[158:161], v144 offset:3072
	ds_read_b128 v[162:165], v145
	ds_read_b128 v[166:169], v145 offset:1024
	ds_read_b128 v[170:173], v145 offset:2048
	ds_read_b128 v[174:177], v145 offset:3072
	s_add_u32 s82, s82, 0x80000
	s_addc_u32 s83, s83, 0
	s_mov_b32 m0, s36
	v_lshl_add_u64 v[214:215], s[82:83], 0, v[128:129]
	ds_read_b128 v[178:181], v143 offset:32768
	ds_read_b128 v[182:185], v143 offset:33792
	ds_read_b128 v[186:189], v143 offset:34816
	ds_read_b128 v[190:193], v143 offset:35840
	ds_read_b128 v[194:197], v143 offset:36864
	ds_read_b128 v[198:201], v143 offset:37888
	ds_read_b128 v[202:205], v143 offset:38912
	ds_read_b128 v[206:209], v143 offset:39936
	global_load_lds_dwordx4 v[214:215], off
	v_lshl_add_u64 v[214:215], s[82:83], 0, v[130:131]
	s_mov_b32 m0, s37
	s_nop 0
	global_load_lds_dwordx4 v[214:215], off
	s_waitcnt vmcnt(8) lgkmcnt(0)
	s_setprio 1
	s_barrier
	v_mfma_f32_16x16x32_bf16 v[24:27], v[146:149], v[178:181], v[24:27]
	v_mfma_f32_16x16x32_bf16 v[28:31], v[154:157], v[178:181], v[28:31]
	v_mfma_f32_16x16x32_bf16 v[16:19], v[146:149], v[186:189], v[16:19]
	v_mfma_f32_16x16x32_bf16 v[20:23], v[154:157], v[186:189], v[20:23]
	v_mfma_f32_16x16x32_bf16 v[8:11], v[146:149], v[194:197], v[8:11]
	v_mfma_f32_16x16x32_bf16 v[12:15], v[154:157], v[194:197], v[12:15]
	v_mfma_f32_16x16x32_bf16 v[0:3], v[146:149], v[202:205], v[0:3]
	v_mfma_f32_16x16x32_bf16 v[4:7], v[154:157], v[202:205], v[4:7]
	v_mfma_f32_16x16x32_bf16 v[24:27], v[150:153], v[182:185], v[24:27]
	v_mfma_f32_16x16x32_bf16 v[28:31], v[158:161], v[182:185], v[28:31]
	v_mfma_f32_16x16x32_bf16 v[16:19], v[150:153], v[190:193], v[16:19]
	v_mfma_f32_16x16x32_bf16 v[20:23], v[158:161], v[190:193], v[20:23]
	v_mfma_f32_16x16x32_bf16 v[8:11], v[150:153], v[198:201], v[8:11]
	v_mfma_f32_16x16x32_bf16 v[12:15], v[158:161], v[198:201], v[12:15]
	v_mfma_f32_16x16x32_bf16 v[0:3], v[150:153], v[206:209], v[0:3]
	v_mfma_f32_16x16x32_bf16 v[4:7], v[158:161], v[206:209], v[4:7]
	v_mfma_f32_16x16x32_bf16 v[56:59], v[162:165], v[178:181], v[56:59]
	v_mfma_f32_16x16x32_bf16 v[60:63], v[170:173], v[178:181], v[60:63]
	v_mfma_f32_16x16x32_bf16 v[48:51], v[162:165], v[186:189], v[48:51]
	v_mfma_f32_16x16x32_bf16 v[52:55], v[170:173], v[186:189], v[52:55]
	v_mfma_f32_16x16x32_bf16 v[40:43], v[162:165], v[194:197], v[40:43]
	v_mfma_f32_16x16x32_bf16 v[44:47], v[170:173], v[194:197], v[44:47]
	v_mfma_f32_16x16x32_bf16 v[32:35], v[162:165], v[202:205], v[32:35]
	v_mfma_f32_16x16x32_bf16 v[36:39], v[170:173], v[202:205], v[36:39]
	v_mfma_f32_16x16x32_bf16 v[56:59], v[166:169], v[182:185], v[56:59]
	v_mfma_f32_16x16x32_bf16 v[60:63], v[174:177], v[182:185], v[60:63]
	v_mfma_f32_16x16x32_bf16 v[48:51], v[166:169], v[190:193], v[48:51]
	v_mfma_f32_16x16x32_bf16 v[52:55], v[174:177], v[190:193], v[52:55]
	v_mfma_f32_16x16x32_bf16 v[40:43], v[166:169], v[198:201], v[40:43]
	v_mfma_f32_16x16x32_bf16 v[44:47], v[174:177], v[198:201], v[44:47]
	v_mfma_f32_16x16x32_bf16 v[32:35], v[166:169], v[206:209], v[32:35]
	v_mfma_f32_16x16x32_bf16 v[36:39], v[174:177], v[206:209], v[36:39]
	s_barrier
	s_setprio 0
	s_mov_b32 m0, s58
	v_lshl_add_u64 v[136:137], v[136:137], 0, s[62:63]
	s_add_u32 s80, s80, 0x80080
	ds_read_b128 v[178:181], v143 offset:49152
	ds_read_b128 v[182:185], v143 offset:50176
	ds_read_b128 v[186:189], v143 offset:51200
	ds_read_b128 v[190:193], v143 offset:52224
	ds_read_b128 v[194:197], v143 offset:53248
	ds_read_b128 v[198:201], v143 offset:54272
	ds_read_b128 v[202:205], v143 offset:55296
	ds_read_b128 v[206:209], v143 offset:56320
	global_load_lds_dwordx4 v[136:137], off
	v_lshl_add_u64 v[136:137], v[138:139], 0, s[62:63]
	s_mov_b32 m0, s59
	s_addc_u32 s81, s81, 0
	global_load_lds_dwordx4 v[136:137], off
	v_lshl_add_u64 v[136:137], s[80:81], 0, v[128:129]
	s_mov_b32 m0, s61
	s_nop 0
	global_load_lds_dwordx4 v[136:137], off
	v_lshl_add_u64 v[136:137], s[80:81], 0, v[130:131]
	s_mov_b32 m0, s71
	s_nop 0
	global_load_lds_dwordx4 v[136:137], off
	v_lshl_add_u64 v[136:137], v[210:211], 0, s[62:63]
	s_mov_b32 m0, s42
	s_nop 0
	global_load_lds_dwordx4 v[136:137], off
	v_lshl_add_u64 v[136:137], v[212:213], 0, s[62:63]
	s_mov_b32 m0, s43
	s_nop 0
	global_load_lds_dwordx4 v[136:137], off
	s_waitcnt vmcnt(8) lgkmcnt(0)
	s_setprio 1
	s_barrier
	v_mfma_f32_16x16x32_bf16 v[88:91], v[146:149], v[178:181], v[88:91]
	v_mfma_f32_16x16x32_bf16 v[92:95], v[154:157], v[178:181], v[92:95]
	v_mfma_f32_16x16x32_bf16 v[80:83], v[146:149], v[186:189], v[80:83]
	v_mfma_f32_16x16x32_bf16 v[84:87], v[154:157], v[186:189], v[84:87]
	v_mfma_f32_16x16x32_bf16 v[72:75], v[146:149], v[194:197], v[72:75]
	v_mfma_f32_16x16x32_bf16 v[76:79], v[154:157], v[194:197], v[76:79]
	v_mfma_f32_16x16x32_bf16 v[64:67], v[146:149], v[202:205], v[64:67]
	v_mfma_f32_16x16x32_bf16 v[68:71], v[154:157], v[202:205], v[68:71]
	v_mfma_f32_16x16x32_bf16 v[88:91], v[150:153], v[182:185], v[88:91]
	v_mfma_f32_16x16x32_bf16 v[92:95], v[158:161], v[182:185], v[92:95]
	v_mfma_f32_16x16x32_bf16 v[80:83], v[150:153], v[190:193], v[80:83]
	v_mfma_f32_16x16x32_bf16 v[84:87], v[158:161], v[190:193], v[84:87]
	v_mfma_f32_16x16x32_bf16 v[72:75], v[150:153], v[198:201], v[72:75]
	v_mfma_f32_16x16x32_bf16 v[76:79], v[158:161], v[198:201], v[76:79]
	v_mfma_f32_16x16x32_bf16 v[64:67], v[150:153], v[206:209], v[64:67]
	v_mfma_f32_16x16x32_bf16 v[68:71], v[158:161], v[206:209], v[68:71]
	v_mfma_f32_16x16x32_bf16 v[120:123], v[162:165], v[178:181], v[120:123]
	v_mfma_f32_16x16x32_bf16 v[124:127], v[170:173], v[178:181], v[124:127]
	v_mfma_f32_16x16x32_bf16 v[112:115], v[162:165], v[186:189], v[112:115]
	v_mfma_f32_16x16x32_bf16 v[116:119], v[170:173], v[186:189], v[116:119]
	v_mfma_f32_16x16x32_bf16 v[104:107], v[162:165], v[194:197], v[104:107]
	v_mfma_f32_16x16x32_bf16 v[108:111], v[170:173], v[194:197], v[108:111]
	v_mfma_f32_16x16x32_bf16 v[96:99], v[162:165], v[202:205], v[96:99]
	v_mfma_f32_16x16x32_bf16 v[100:103], v[170:173], v[202:205], v[100:103]
	v_mfma_f32_16x16x32_bf16 v[120:123], v[166:169], v[182:185], v[120:123]
	v_mfma_f32_16x16x32_bf16 v[124:127], v[174:177], v[182:185], v[124:127]
	v_mfma_f32_16x16x32_bf16 v[112:115], v[166:169], v[190:193], v[112:115]
	v_mfma_f32_16x16x32_bf16 v[116:119], v[174:177], v[190:193], v[116:119]
	v_mfma_f32_16x16x32_bf16 v[104:107], v[166:169], v[198:201], v[104:107]
	v_mfma_f32_16x16x32_bf16 v[108:111], v[174:177], v[198:201], v[108:111]
	v_mfma_f32_16x16x32_bf16 v[96:99], v[166:169], v[206:209], v[96:99]
	v_mfma_f32_16x16x32_bf16 v[100:103], v[174:177], v[206:209], v[100:103]
	s_barrier
	s_setprio 0
	s_add_i32 s88, s88, 2
	s_add_u32 s73, s73, 0x100
	s_addc_u32 s85, s85, 0
	s_add_u32 s78, s78, 0x100
	s_addc_u32 s79, s79, 0
	s_cmp_gt_u32 s88, 29
	s_cbranch_scc0 .LBB0_2417
	s_and_b64 vcc, exec, s[64:65]
	s_cbranch_vccz .LBB0_2420
	s_barrier

; template <class Epi, class Sched, bool ALIGN_EPI = false, bool SP2 = false, bool A_TILED = false>
; __device__ __forceinline__ void gemm_phase(PG8_LAS unsigned char* lds, const Gemm g, const Sched& S, const Epi& E, const int wave_s) {
;     ...
;         const bool has_next = Epi::AFTER_DRAIN ? false : S.next(ui + 1, nxt);
;         const char* nA = has_next ? (const char*)g.A + (size_t)nxt.pm * tstepA : cA; const char* nB = has_next ? (const char*)g.Bt + (size_t)nxt.pn * tstep : cB;
;         constexpr bool PEEL = SP2 && !Epi::AFTER_DRAIN;
;         if constexpr (PEEL) {
;             const char* a1 = cA + kstepA; const char* a2 = cA + 2 * kstepA; const char* b2 = cB + 2 * kstep; const char* a3 = a2 + kstepA; const char* b3 = b2 + kstep;
;             PG8_ITER(PG8_MMAZ)
.LBB0_2545:
	s_ashr_i32 s73, s72, 31
	s_lshl_b64 s[58:59], s[72:73], 18
	s_add_u32 s74, s14, s58
	ds_read_b128 v[0:3], v149
	ds_read_b128 v[4:7], v149 offset:1024
	ds_read_b128 v[8:11], v149 offset:2048
	ds_read_b128 v[12:15], v149 offset:3072
	ds_read_b128 v[16:19], v150
	ds_read_b128 v[20:23], v150 offset:1024
	ds_read_b128 v[24:27], v150 offset:2048
	ds_read_b128 v[28:31], v150 offset:3072
	s_addc_u32 s75, s15, s59
	s_ashr_i32 s71, s70, 31
	s_lshl_b64 s[58:59], s[70:71], 18
	s_add_u32 s76, s23, s58
	s_addc_u32 s77, s36, s59
	s_and_b64 s[58:59], s[2:3], exec
	s_cselect_b32 s58, s75, s81
	s_cselect_b32 s59, s74, s80
	s_cselect_b32 s71, s77, s79
	s_cselect_b32 s73, s76, s78
	s_add_u32 s82, s80, 0x20080
	s_addc_u32 s83, s81, 0
	s_add_i32 s88, s38, 0xc000
	v_lshl_add_u64 v[64:65], s[82:83], 0, v[134:135]
	s_mov_b32 m0, s88
	s_add_i32 s89, s38, 0xe000
	ds_read_b128 v[32:35], v151
	ds_read_b128 v[36:39], v151 offset:1024
	ds_read_b128 v[40:43], v151 offset:2048
	ds_read_b128 v[44:47], v151 offset:3072
	ds_read_b128 v[48:51], v151 offset:4096
	ds_read_b128 v[52:55], v151 offset:5120
	ds_read_b128 v[56:59], v151 offset:6144
	ds_read_b128 v[60:63], v151 offset:7168
	global_load_lds_dwordx4 v[64:65], off
	v_lshl_add_u64 v[64:65], s[82:83], 0, v[132:133]
	s_mov_b32 m0, s89
	s_nop 0
	global_load_lds_dwordx4 v[64:65], off
	s_waitcnt vmcnt(8) lgkmcnt(0)
	s_setprio 1
	s_barrier
	v_mfma_f32_16x16x32_bf16 v[88:91], v[0:3], v[56:59], 0
	v_mfma_f32_16x16x32_bf16 v[64:67], v[0:3], v[32:35], 0
	v_mfma_f32_16x16x32_bf16 v[68:71], v[8:11], v[32:35], 0
	v_mfma_f32_16x16x32_bf16 v[72:75], v[0:3], v[40:43], 0
	v_mfma_f32_16x16x32_bf16 v[76:79], v[8:11], v[40:43], 0
	v_mfma_f32_16x16x32_bf16 v[80:83], v[0:3], v[48:51], 0
	v_mfma_f32_16x16x32_bf16 v[84:87], v[8:11], v[48:51], 0
	v_mfma_f32_16x16x32_bf16 v[96:99], v[4:7], v[60:63], v[88:91]
	v_mfma_f32_16x16x32_bf16 v[88:91], v[8:11], v[56:59], 0
	v_mfma_f32_16x16x32_bf16 v[64:67], v[4:7], v[36:39], v[64:67]
	v_mfma_f32_16x16x32_bf16 v[68:71], v[12:15], v[36:39], v[68:71]
	v_mfma_f32_16x16x32_bf16 v[72:75], v[4:7], v[44:47], v[72:75]
	v_mfma_f32_16x16x32_bf16 v[76:79], v[12:15], v[44:47], v[76:79]
	v_mfma_f32_16x16x32_bf16 v[80:83], v[4:7], v[52:55], v[80:83]
	v_mfma_f32_16x16x32_bf16 v[84:87], v[12:15], v[52:55], v[84:87]
	v_mfma_f32_16x16x32_bf16 v[100:103], v[12:15], v[60:63], v[88:91]
	v_mfma_f32_16x16x32_bf16 v[88:91], v[16:19], v[32:35], 0
	v_mfma_f32_16x16x32_bf16 v[32:35], v[24:27], v[32:35], 0
	v_mfma_f32_16x16x32_bf16 v[112:115], v[20:23], v[36:39], v[88:91]
	v_mfma_f32_16x16x32_bf16 v[32:35], v[28:31], v[36:39], v[32:35]
	v_mfma_f32_16x16x32_bf16 v[36:39], v[16:19], v[40:43], 0
	v_mfma_f32_16x16x32_bf16 v[40:43], v[24:27], v[40:43], 0
	v_mfma_f32_16x16x32_bf16 v[36:39], v[20:23], v[44:47], v[36:39]
	v_mfma_f32_16x16x32_bf16 v[40:43], v[28:31], v[44:47], v[40:43]
	v_mfma_f32_16x16x32_bf16 v[44:47], v[16:19], v[48:51], 0
	v_mfma_f32_16x16x32_bf16 v[48:51], v[24:27], v[48:51], 0
	v_mfma_f32_16x16x32_bf16 v[44:47], v[20:23], v[52:55], v[44:47]
	v_mfma_f32_16x16x32_bf16 v[48:51], v[28:31], v[52:55], v[48:51]
	v_mfma_f32_16x16x32_bf16 v[52:55], v[16:19], v[56:59], 0
	v_mfma_f32_16x16x32_bf16 v[56:59], v[24:27], v[56:59], 0
	v_mfma_f32_16x16x32_bf16 v[52:55], v[20:23], v[60:63], v[52:55]
	v_mfma_f32_16x16x32_bf16 v[56:59], v[28:31], v[60:63], v[56:59]
	s_barrier
	s_setprio 0
	s_add_i32 s90, s53, s37
	v_lshl_add_u64 v[250:251], s[78:79], 0, v[128:129]
	s_add_i32 s91, s90, 0x2000
	v_lshl_add_u64 v[144:145], v[250:251], 0, s[66:67]
	s_mov_b32 m0, s90
	v_lshl_add_u64 v[252:253], s[78:79], 0, v[130:131]
	s_add_u32 s82, s78, 0x20100
	ds_read_b128 v[60:63], v151 offset:16384
	ds_read_b128 v[88:91], v151 offset:17408
	ds_read_b128 v[92:95], v151 offset:18432
	ds_read_b128 v[104:107], v151 offset:19456
	ds_read_b128 v[108:111], v151 offset:20480
	ds_read_b128 v[116:119], v151 offset:21504
	ds_read_b128 v[120:123], v151 offset:22528
	ds_read_b128 v[124:127], v151 offset:23552
	global_load_lds_dwordx4 v[144:145], off
	v_lshl_add_u64 v[144:145], v[252:253], 0, s[66:67]
	s_mov_b32 m0, s91
	s_addc_u32 s83, s79, 0
	s_add_i32 s93, s54, s37
	global_load_lds_dwordx4 v[144:145], off
	v_lshl_add_u64 v[144:145], s[82:83], 0, v[128:129]
	s_mov_b32 m0, s93
	s_add_i32 s95, s93, 0x2000
	global_load_lds_dwordx4 v[144:145], off
	v_lshl_add_u64 v[144:145], s[82:83], 0, v[130:131]
	s_mov_b32 m0, s95
	v_lshl_add_u64 v[140:141], s[80:81], 0, v[134:135]
	global_load_lds_dwordx4 v[144:145], off
	v_lshl_add_u64 v[144:145], v[140:141], 0, s[66:67]
	s_mov_b32 m0, s38
	v_lshl_add_u64 v[142:143], s[80:81], 0, v[132:133]
	global_load_lds_dwordx4 v[144:145], off
	v_lshl_add_u64 v[144:145], v[142:143], 0, s[66:67]
	s_mov_b32 m0, s39
	s_nop 0
	global_load_lds_dwordx4 v[144:145], off
	s_waitcnt vmcnt(8) lgkmcnt(0)
	s_setprio 1
	s_barrier
	v_mfma_f32_16x16x32_bf16 v[144:147], v[0:3], v[60:63], 0
	v_mfma_f32_16x16x32_bf16 v[154:157], v[4:7], v[88:91], v[144:147]
	v_mfma_f32_16x16x32_bf16 v[144:147], v[8:11], v[60:63], 0
	v_mfma_f32_16x16x32_bf16 v[158:161], v[12:15], v[88:91], v[144:147]
	v_mfma_f32_16x16x32_bf16 v[144:147], v[0:3], v[92:95], 0
	v_mfma_f32_16x16x32_bf16 v[162:165], v[4:7], v[104:107], v[144:147]
	v_mfma_f32_16x16x32_bf16 v[144:147], v[8:11], v[92:95], 0
	v_mfma_f32_16x16x32_bf16 v[166:169], v[12:15], v[104:107], v[144:147]
	v_mfma_f32_16x16x32_bf16 v[144:147], v[0:3], v[108:111], 0
	v_mfma_f32_16x16x32_bf16 v[0:3], v[0:3], v[120:123], 0
	v_mfma_f32_16x16x32_bf16 v[170:173], v[4:7], v[116:119], v[144:147]
	v_mfma_f32_16x16x32_bf16 v[0:3], v[4:7], v[124:127], v[0:3]
	v_mfma_f32_16x16x32_bf16 v[4:7], v[8:11], v[120:123], 0
	v_mfma_f32_16x16x32_bf16 v[144:147], v[8:11], v[108:111], 0
	v_mfma_f32_16x16x32_bf16 v[4:7], v[12:15], v[124:127], v[4:7]
	v_mfma_f32_16x16x32_bf16 v[174:177], v[12:15], v[116:119], v[144:147]
	v_mfma_f32_16x16x32_bf16 v[8:11], v[16:19], v[60:63], 0
	v_mfma_f32_16x16x32_bf16 v[178:181], v[20:23], v[88:91], v[8:11]
	v_mfma_f32_16x16x32_bf16 v[8:11], v[24:27], v[60:63], 0
	v_mfma_f32_16x16x32_bf16 v[182:185], v[28:31], v[88:91], v[8:11]
	v_mfma_f32_16x16x32_bf16 v[8:11], v[16:19], v[92:95], 0
	v_mfma_f32_16x16x32_bf16 v[186:189], v[20:23], v[104:107], v[8:11]
	v_mfma_f32_16x16x32_bf16 v[8:11], v[24:27], v[92:95], 0
	v_mfma_f32_16x16x32_bf16 v[190:193], v[28:31], v[104:107], v[8:11]
	v_mfma_f32_16x16x32_bf16 v[8:11], v[16:19], v[108:111], 0
	v_mfma_f32_16x16x32_bf16 v[194:197], v[20:23], v[116:119], v[8:11]
	v_mfma_f32_16x16x32_bf16 v[8:11], v[24:27], v[108:111], 0
	v_mfma_f32_16x16x32_bf16 v[198:201], v[28:31], v[116:119], v[8:11]
	v_mfma_f32_16x16x32_bf16 v[8:11], v[16:19], v[120:123], 0
	v_mfma_f32_16x16x32_bf16 v[202:205], v[20:23], v[124:127], v[8:11]
	v_mfma_f32_16x16x32_bf16 v[8:11], v[24:27], v[120:123], 0
	v_mfma_f32_16x16x32_bf16 v[206:209], v[28:31], v[124:127], v[8:11]
	s_barrier
	s_setprio 0
	s_add_i32 s96, 0, 0x18000
	s_add_i32 vcc_lo, 0, 0x1c000
	v_add_u32_e32 v144, s96, v148
	v_add_u32_e32 v145, vcc_lo, v148
	s_nop 0
	ds_read_b128 v[8:11], v144
	ds_read_b128 v[12:15], v144 offset:1024
	ds_read_b128 v[16:19], v144 offset:2048
	ds_read_b128 v[20:23], v144 offset:3072
	ds_read_b128 v[210:213], v145
	ds_read_b128 v[214:217], v145 offset:1024
	ds_read_b128 v[218:221], v145 offset:2048
	ds_read_b128 v[222:225], v145 offset:3072
	s_add_u32 s82, s80, 0x20100
	s_addc_u32 s83, s81, 0
	s_mov_b32 m0, s40
	v_lshl_add_u64 v[88:89], s[82:83], 0, v[134:135]
	ds_read_b128 v[24:27], v151 offset:32768
	ds_read_b128 v[28:31], v151 offset:33792
	ds_read_b128 v[60:63], v151 offset:34816
	ds_read_b128 v[226:229], v151 offset:35840
	ds_read_b128 v[230:233], v151 offset:36864
	ds_read_b128 v[234:237], v151 offset:37888
	ds_read_b128 v[238:241], v151 offset:38912
	ds_read_b128 v[242:245], v151 offset:39936
	global_load_lds_dwordx4 v[88:89], off
	v_lshl_add_u64 v[88:89], s[82:83], 0, v[132:133]
	s_mov_b32 m0, s41
	s_nop 0
	global_load_lds_dwordx4 v[88:89], off
	s_waitcnt vmcnt(8) lgkmcnt(0)
	s_setprio 1
	s_barrier
	v_mfma_f32_16x16x32_bf16 v[64:67], v[8:11], v[24:27], v[64:67]
	v_mfma_f32_16x16x32_bf16 v[124:127], v[12:15], v[28:31], v[64:67]
	v_mfma_f32_16x16x32_bf16 v[64:67], v[16:19], v[24:27], v[68:71]
	v_mfma_f32_16x16x32_bf16 v[120:123], v[20:23], v[28:31], v[64:67]
	v_mfma_f32_16x16x32_bf16 v[64:67], v[8:11], v[60:63], v[72:75]
	v_mfma_f32_16x16x32_bf16 v[108:111], v[12:15], v[226:229], v[64:67]
	v_mfma_f32_16x16x32_bf16 v[64:67], v[16:19], v[60:63], v[76:79]
	v_mfma_f32_16x16x32_bf16 v[104:107], v[20:23], v[226:229], v[64:67]
	v_mfma_f32_16x16x32_bf16 v[64:67], v[8:11], v[230:233], v[80:83]
	v_mfma_f32_16x16x32_bf16 v[92:95], v[12:15], v[234:237], v[64:67]
	v_mfma_f32_16x16x32_bf16 v[64:67], v[16:19], v[230:233], v[84:87]
	v_mfma_f32_16x16x32_bf16 v[88:91], v[20:23], v[234:237], v[64:67]
	v_mfma_f32_16x16x32_bf16 v[64:67], v[8:11], v[238:241], v[96:99]
	v_mfma_f32_16x16x32_bf16 v[76:79], v[12:15], v[242:245], v[64:67]
	v_mfma_f32_16x16x32_bf16 v[64:67], v[16:19], v[238:241], v[100:103]
	v_mfma_f32_16x16x32_bf16 v[72:75], v[20:23], v[242:245], v[64:67]
	v_mfma_f32_16x16x32_bf16 v[64:67], v[210:213], v[24:27], v[112:115]
	v_mfma_f32_16x16x32_bf16 v[24:27], v[218:221], v[24:27], v[32:35]
	v_mfma_f32_16x16x32_bf16 v[112:115], v[222:225], v[28:31], v[24:27]
	v_mfma_f32_16x16x32_bf16 v[24:27], v[210:213], v[60:63], v[36:39]
	v_mfma_f32_16x16x32_bf16 v[100:103], v[214:217], v[226:229], v[24:27]
	v_mfma_f32_16x16x32_bf16 v[24:27], v[218:221], v[60:63], v[40:43]
	v_mfma_f32_16x16x32_bf16 v[96:99], v[222:225], v[226:229], v[24:27]
	v_mfma_f32_16x16x32_bf16 v[24:27], v[210:213], v[230:233], v[44:47]
	v_mfma_f32_16x16x32_bf16 v[84:87], v[214:217], v[234:237], v[24:27]
	v_mfma_f32_16x16x32_bf16 v[24:27], v[218:221], v[230:233], v[48:51]
	v_mfma_f32_16x16x32_bf16 v[80:83], v[222:225], v[234:237], v[24:27]
	v_mfma_f32_16x16x32_bf16 v[24:27], v[210:213], v[238:241], v[52:55]
	v_mfma_f32_16x16x32_bf16 v[68:71], v[214:217], v[242:245], v[24:27]
	v_mfma_f32_16x16x32_bf16 v[24:27], v[218:221], v[238:241], v[56:59]
	v_mfma_f32_16x16x32_bf16 v[116:119], v[214:217], v[28:31], v[64:67]
	v_mfma_f32_16x16x32_bf16 v[64:67], v[222:225], v[242:245], v[24:27]
	s_barrier
; template <class Epi, class Sched, bool ALIGN_EPI = false, bool SP2 = false, bool A_TILED = false>
; __device__ __forceinline__ void gemm_phase(PG8_LAS unsigned char* lds, const Gemm g, const Sched& S, const Epi& E, const int wave_s) {
;     ...
;         for (int t = PEEL ? 2 : 0; t < nt; t += 2) {
;             const bool last = (t == nt - 2);
;             const char* a1 = cA + (size_t)(t + 1) * kstepA;
;             const char* a2 = last ? nA : cA + (size_t)(t + 2) * kstepA; const char* b2 = last ? nB : cB + (size_t)(t + 2) * kstep;
;             const char* a3 = a2 + kstepA; const char* b3 = b2 + kstep;
;             if (last && has_next) S.a_ready(nxt);
	s_setprio 0
	s_add_i32 s96, s96, s37
	s_add_i32 s97, s96, 0x2000
	s_nop 1
	v_lshl_add_u64 v[24:25], v[250:251], 0, s[68:69]
	s_mov_b32 m0, s96
	s_add_u32 s82, s78, 0x20180
	ds_read_b128 v[32:35], v151 offset:49152
	ds_read_b128 v[36:39], v151 offset:50176
	ds_read_b128 v[226:229], v151 offset:51200
	ds_read_b128 v[230:233], v151 offset:52224
	ds_read_b128 v[234:237], v151 offset:53248
	ds_read_b128 v[238:241], v151 offset:54272
	ds_read_b128 v[242:245], v151 offset:55296
	ds_read_b128 v[246:249], v151 offset:56320
	global_load_lds_dwordx4 v[24:25], off
	v_lshl_add_u64 v[24:25], v[252:253], 0, s[68:69]
	s_mov_b32 m0, s97
	s_addc_u32 s83, s79, 0
	s_add_i32 vcc_lo, vcc_lo, s37
	global_load_lds_dwordx4 v[24:25], off
	v_lshl_add_u64 v[24:25], s[82:83], 0, v[128:129]
	s_mov_b32 m0, vcc_lo
	s_add_i32 vcc_hi, vcc_lo, 0x2000
	global_load_lds_dwordx4 v[24:25], off
	v_lshl_add_u64 v[24:25], s[82:83], 0, v[130:131]
	s_mov_b32 m0, vcc_hi
	s_nop 0
	global_load_lds_dwordx4 v[24:25], off
	v_lshl_add_u64 v[24:25], v[140:141], 0, s[68:69]
	s_mov_b32 m0, s51
	s_nop 0
	global_load_lds_dwordx4 v[24:25], off
	v_lshl_add_u64 v[24:25], v[142:143], 0, s[68:69]
	s_mov_b32 m0, s52
	s_nop 0
	global_load_lds_dwordx4 v[24:25], off
	s_waitcnt vmcnt(8) lgkmcnt(0)
	s_setprio 1
	s_barrier
	v_mfma_f32_16x16x32_bf16 v[24:27], v[8:11], v[32:35], v[154:157]
	v_mfma_f32_16x16x32_bf16 v[60:63], v[12:15], v[36:39], v[24:27]
	v_mfma_f32_16x16x32_bf16 v[24:27], v[16:19], v[32:35], v[158:161]
	v_mfma_f32_16x16x32_bf16 v[56:59], v[20:23], v[36:39], v[24:27]
	v_mfma_f32_16x16x32_bf16 v[24:27], v[8:11], v[226:229], v[162:165]
	v_mfma_f32_16x16x32_bf16 v[44:47], v[12:15], v[230:233], v[24:27]
	v_mfma_f32_16x16x32_bf16 v[24:27], v[16:19], v[226:229], v[166:169]
	v_mfma_f32_16x16x32_bf16 v[40:43], v[20:23], v[230:233], v[24:27]
	v_mfma_f32_16x16x32_bf16 v[24:27], v[8:11], v[234:237], v[170:173]
	v_mfma_f32_16x16x32_bf16 v[0:3], v[8:11], v[242:245], v[0:3]
	v_mfma_f32_16x16x32_bf16 v[28:31], v[12:15], v[238:241], v[24:27]
	v_mfma_f32_16x16x32_bf16 v[24:27], v[16:19], v[234:237], v[174:177]
	v_mfma_f32_16x16x32_bf16 v[12:15], v[12:15], v[246:249], v[0:3]
	v_mfma_f32_16x16x32_bf16 v[0:3], v[16:19], v[242:245], v[4:7]
	v_mfma_f32_16x16x32_bf16 v[24:27], v[20:23], v[238:241], v[24:27]
	v_mfma_f32_16x16x32_bf16 v[8:11], v[20:23], v[246:249], v[0:3]
	v_mfma_f32_16x16x32_bf16 v[0:3], v[210:213], v[32:35], v[178:181]
	v_mfma_f32_16x16x32_bf16 v[52:55], v[214:217], v[36:39], v[0:3]
	v_mfma_f32_16x16x32_bf16 v[0:3], v[218:221], v[32:35], v[182:185]
	v_mfma_f32_16x16x32_bf16 v[48:51], v[222:225], v[36:39], v[0:3]
	v_mfma_f32_16x16x32_bf16 v[0:3], v[210:213], v[226:229], v[186:189]
	v_mfma_f32_16x16x32_bf16 v[36:39], v[214:217], v[230:233], v[0:3]
	v_mfma_f32_16x16x32_bf16 v[0:3], v[218:221], v[226:229], v[190:193]
	v_mfma_f32_16x16x32_bf16 v[32:35], v[222:225], v[230:233], v[0:3]
	v_mfma_f32_16x16x32_bf16 v[0:3], v[210:213], v[234:237], v[194:197]
	v_mfma_f32_16x16x32_bf16 v[20:23], v[214:217], v[238:241], v[0:3]
	v_mfma_f32_16x16x32_bf16 v[0:3], v[218:221], v[234:237], v[198:201]
	v_mfma_f32_16x16x32_bf16 v[16:19], v[222:225], v[238:241], v[0:3]
	v_mfma_f32_16x16x32_bf16 v[0:3], v[210:213], v[242:245], v[202:205]
	v_mfma_f32_16x16x32_bf16 v[4:7], v[214:217], v[246:249], v[0:3]
	v_mfma_f32_16x16x32_bf16 v[0:3], v[218:221], v[242:245], v[206:209]
	v_mfma_f32_16x16x32_bf16 v[0:3], v[222:225], v[246:249], v[0:3]
	s_barrier
	s_setprio 0
	s_add_u32 s85, s78, 0x200
	s_addc_u32 s8, s79, 0
	s_add_u32 s78, s80, 0x20180
	s_addc_u32 s79, s81, 0
	s_mov_b32 s94, 0
.LBB0_2546:
	ds_read_b128 v[154:157], v149
	ds_read_b128 v[158:161], v149 offset:1024
	ds_read_b128 v[162:165], v149 offset:2048
	ds_read_b128 v[166:169], v149 offset:3072
	ds_read_b128 v[170:173], v150
	ds_read_b128 v[174:177], v150 offset:1024
	ds_read_b128 v[178:181], v150 offset:2048
	ds_read_b128 v[182:185], v150 offset:3072
	s_add_u32 s44, s78, 0xfffe0080
	s_addc_u32 s45, s79, -1
	s_cmp_eq_u32 s94, 4
	s_cselect_b32 s83, s58, s45
	s_cselect_b32 s82, s59, s44
	s_cselect_b32 s81, s71, s8
	s_cselect_b32 s80, s73, s85
	s_mov_b32 m0, s88
	v_lshl_add_u64 v[140:141], s[78:79], 0, v[138:139]
	ds_read_b128 v[186:189], v151
	ds_read_b128 v[190:193], v151 offset:1024
	ds_read_b128 v[194:197], v151 offset:2048
	ds_read_b128 v[198:201], v151 offset:3072
	ds_read_b128 v[202:205], v151 offset:4096
	ds_read_b128 v[206:209], v151 offset:5120
	ds_read_b128 v[210:213], v151 offset:6144
	ds_read_b128 v[214:217], v151 offset:7168
	global_load_lds_dwordx4 v[140:141], off
	v_lshl_add_u64 v[140:141], s[78:79], 0, v[136:137]
	s_mov_b32 m0, s89
	s_nop 0
	global_load_lds_dwordx4 v[140:141], off
	s_waitcnt vmcnt(8) lgkmcnt(0)
	s_setprio 1
	s_barrier
	v_mfma_f32_16x16x32_bf16 v[124:127], v[154:157], v[186:189], v[124:127]
	v_mfma_f32_16x16x32_bf16 v[120:123], v[162:165], v[186:189], v[120:123]
	v_mfma_f32_16x16x32_bf16 v[108:111], v[154:157], v[194:197], v[108:111]
	v_mfma_f32_16x16x32_bf16 v[104:107], v[162:165], v[194:197], v[104:107]
	v_mfma_f32_16x16x32_bf16 v[92:95], v[154:157], v[202:205], v[92:95]
	v_mfma_f32_16x16x32_bf16 v[88:91], v[162:165], v[202:205], v[88:91]
	v_mfma_f32_16x16x32_bf16 v[76:79], v[154:157], v[210:213], v[76:79]
	v_mfma_f32_16x16x32_bf16 v[72:75], v[162:165], v[210:213], v[72:75]
	v_mfma_f32_16x16x32_bf16 v[124:127], v[158:161], v[190:193], v[124:127]
	v_mfma_f32_16x16x32_bf16 v[120:123], v[166:169], v[190:193], v[120:123]
	v_mfma_f32_16x16x32_bf16 v[108:111], v[158:161], v[198:201], v[108:111]
	v_mfma_f32_16x16x32_bf16 v[104:107], v[166:169], v[198:201], v[104:107]
	v_mfma_f32_16x16x32_bf16 v[92:95], v[158:161], v[206:209], v[92:95]
	v_mfma_f32_16x16x32_bf16 v[88:91], v[166:169], v[206:209], v[88:91]
	v_mfma_f32_16x16x32_bf16 v[76:79], v[158:161], v[214:217], v[76:79]
	v_mfma_f32_16x16x32_bf16 v[72:75], v[166:169], v[214:217], v[72:75]
	v_mfma_f32_16x16x32_bf16 v[116:119], v[170:173], v[186:189], v[116:119]
	v_mfma_f32_16x16x32_bf16 v[112:115], v[178:181], v[186:189], v[112:115]
	v_mfma_f32_16x16x32_bf16 v[100:103], v[170:173], v[194:197], v[100:103]
	v_mfma_f32_16x16x32_bf16 v[96:99], v[178:181], v[194:197], v[96:99]
	v_mfma_f32_16x16x32_bf16 v[84:87], v[170:173], v[202:205], v[84:87]
	v_mfma_f32_16x16x32_bf16 v[80:83], v[178:181], v[202:205], v[80:83]
	v_mfma_f32_16x16x32_bf16 v[68:71], v[170:173], v[210:213], v[68:71]
	v_mfma_f32_16x16x32_bf16 v[64:67], v[178:181], v[210:213], v[64:67]
	v_mfma_f32_16x16x32_bf16 v[116:119], v[174:177], v[190:193], v[116:119]
	v_mfma_f32_16x16x32_bf16 v[112:115], v[182:185], v[190:193], v[112:115]
	v_mfma_f32_16x16x32_bf16 v[100:103], v[174:177], v[198:201], v[100:103]
	v_mfma_f32_16x16x32_bf16 v[96:99], v[182:185], v[198:201], v[96:99]
	v_mfma_f32_16x16x32_bf16 v[84:87], v[174:177], v[206:209], v[84:87]
	v_mfma_f32_16x16x32_bf16 v[80:83], v[182:185], v[206:209], v[80:83]
	v_mfma_f32_16x16x32_bf16 v[68:71], v[174:177], v[214:217], v[68:71]
	v_mfma_f32_16x16x32_bf16 v[64:67], v[182:185], v[214:217], v[64:67]
	s_barrier
	s_setprio 0
	s_mov_b32 m0, s90
	v_lshl_add_u64 v[140:141], s[80:81], 0, v[128:129]
	s_add_u32 s44, s80, 0x20000
	ds_read_b128 v[186:189], v151 offset:16384
	ds_read_b128 v[190:193], v151 offset:17408
	ds_read_b128 v[194:197], v151 offset:18432
	ds_read_b128 v[198:201], v151 offset:19456
	ds_read_b128 v[202:205], v151 offset:20480
	ds_read_b128 v[206:209], v151 offset:21504
	ds_read_b128 v[210:213], v151 offset:22528
	ds_read_b128 v[214:217], v151 offset:23552
	global_load_lds_dwordx4 v[140:141], off
	v_lshl_add_u64 v[142:143], s[80:81], 0, v[130:131]
	s_mov_b32 m0, s91
	s_addc_u32 s45, s81, 0
	global_load_lds_dwordx4 v[142:143], off
	v_lshl_add_u64 v[146:147], s[44:45], 0, v[128:129]
	s_mov_b32 m0, s93
	v_lshl_add_u64 v[218:219], s[82:83], 0, v[132:133]
	global_load_lds_dwordx4 v[146:147], off
	v_lshl_add_u64 v[146:147], s[44:45], 0, v[130:131]
	s_mov_b32 m0, s95
	s_nop 0
	global_load_lds_dwordx4 v[146:147], off
	v_lshl_add_u64 v[146:147], s[82:83], 0, v[134:135]
	s_mov_b32 m0, s38
	s_nop 0
	global_load_lds_dwordx4 v[146:147], off
	s_mov_b32 m0, s39
	s_nop 0
	global_load_lds_dwordx4 v[218:219], off
	s_waitcnt vmcnt(8) lgkmcnt(0)
	s_setprio 1
	s_barrier
	v_mfma_f32_16x16x32_bf16 v[60:63], v[154:157], v[186:189], v[60:63]
	v_mfma_f32_16x16x32_bf16 v[56:59], v[162:165], v[186:189], v[56:59]
	v_mfma_f32_16x16x32_bf16 v[44:47], v[154:157], v[194:197], v[44:47]
	v_mfma_f32_16x16x32_bf16 v[40:43], v[162:165], v[194:197], v[40:43]
	v_mfma_f32_16x16x32_bf16 v[28:31], v[154:157], v[202:205], v[28:31]
	v_mfma_f32_16x16x32_bf16 v[24:27], v[162:165], v[202:205], v[24:27]
	v_mfma_f32_16x16x32_bf16 v[12:15], v[154:157], v[210:213], v[12:15]
	v_mfma_f32_16x16x32_bf16 v[8:11], v[162:165], v[210:213], v[8:11]
	v_mfma_f32_16x16x32_bf16 v[60:63], v[158:161], v[190:193], v[60:63]
	v_mfma_f32_16x16x32_bf16 v[56:59], v[166:169], v[190:193], v[56:59]
	v_mfma_f32_16x16x32_bf16 v[44:47], v[158:161], v[198:201], v[44:47]
	v_mfma_f32_16x16x32_bf16 v[40:43], v[166:169], v[198:201], v[40:43]
	v_mfma_f32_16x16x32_bf16 v[28:31], v[158:161], v[206:209], v[28:31]
	v_mfma_f32_16x16x32_bf16 v[24:27], v[166:169], v[206:209], v[24:27]
	v_mfma_f32_16x16x32_bf16 v[12:15], v[158:161], v[214:217], v[12:15]
	v_mfma_f32_16x16x32_bf16 v[8:11], v[166:169], v[214:217], v[8:11]
	v_mfma_f32_16x16x32_bf16 v[52:55], v[170:173], v[186:189], v[52:55]
	v_mfma_f32_16x16x32_bf16 v[48:51], v[178:181], v[186:189], v[48:51]
	v_mfma_f32_16x16x32_bf16 v[36:39], v[170:173], v[194:197], v[36:39]
	v_mfma_f32_16x16x32_bf16 v[32:35], v[178:181], v[194:197], v[32:35]
	v_mfma_f32_16x16x32_bf16 v[20:23], v[170:173], v[202:205], v[20:23]
	v_mfma_f32_16x16x32_bf16 v[16:19], v[178:181], v[202:205], v[16:19]
	v_mfma_f32_16x16x32_bf16 v[4:7], v[170:173], v[210:213], v[4:7]
	v_mfma_f32_16x16x32_bf16 v[0:3], v[178:181], v[210:213], v[0:3]
	v_mfma_f32_16x16x32_bf16 v[52:55], v[174:177], v[190:193], v[52:55]
	v_mfma_f32_16x16x32_bf16 v[48:51], v[182:185], v[190:193], v[48:51]
	v_mfma_f32_16x16x32_bf16 v[36:39], v[174:177], v[198:201], v[36:39]
	v_mfma_f32_16x16x32_bf16 v[32:35], v[182:185], v[198:201], v[32:35]
	v_mfma_f32_16x16x32_bf16 v[20:23], v[174:177], v[206:209], v[20:23]
	v_mfma_f32_16x16x32_bf16 v[16:19], v[182:185], v[206:209], v[16:19]
	v_mfma_f32_16x16x32_bf16 v[4:7], v[174:177], v[214:217], v[4:7]
	v_mfma_f32_16x16x32_bf16 v[0:3], v[182:185], v[214:217], v[0:3]
	s_barrier
	s_setprio 0
	ds_read_b128 v[154:157], v144
	ds_read_b128 v[158:161], v144 offset:1024
	ds_read_b128 v[162:165], v144 offset:2048
	ds_read_b128 v[166:169], v144 offset:3072
	ds_read_b128 v[170:173], v145
	ds_read_b128 v[174:177], v145 offset:1024
	ds_read_b128 v[178:181], v145 offset:2048
	ds_read_b128 v[182:185], v145 offset:3072
	s_add_u32 s44, s82, 0x20000
	s_addc_u32 s45, s83, 0
	s_mov_b32 m0, s40
	v_lshl_add_u64 v[220:221], s[44:45], 0, v[134:135]
	ds_read_b128 v[186:189], v151 offset:32768
	ds_read_b128 v[190:193], v151 offset:33792
	ds_read_b128 v[194:197], v151 offset:34816
	ds_read_b128 v[198:201], v151 offset:35840
	ds_read_b128 v[202:205], v151 offset:36864
	ds_read_b128 v[206:209], v151 offset:37888
	ds_read_b128 v[210:213], v151 offset:38912
	ds_read_b128 v[214:217], v151 offset:39936
	global_load_lds_dwordx4 v[220:221], off
	v_lshl_add_u64 v[220:221], s[44:45], 0, v[132:133]
	s_mov_b32 m0, s41
	s_nop 0
	global_load_lds_dwordx4 v[220:221], off
	s_waitcnt vmcnt(8) lgkmcnt(0)
	s_setprio 1
	s_barrier
	v_mfma_f32_16x16x32_bf16 v[124:127], v[154:157], v[186:189], v[124:127]
	v_mfma_f32_16x16x32_bf16 v[120:123], v[162:165], v[186:189], v[120:123]
	v_mfma_f32_16x16x32_bf16 v[108:111], v[154:157], v[194:197], v[108:111]
	v_mfma_f32_16x16x32_bf16 v[104:107], v[162:165], v[194:197], v[104:107]
	v_mfma_f32_16x16x32_bf16 v[92:95], v[154:157], v[202:205], v[92:95]
	v_mfma_f32_16x16x32_bf16 v[88:91], v[162:165], v[202:205], v[88:91]
	v_mfma_f32_16x16x32_bf16 v[76:79], v[154:157], v[210:213], v[76:79]
	v_mfma_f32_16x16x32_bf16 v[72:75], v[162:165], v[210:213], v[72:75]
	v_mfma_f32_16x16x32_bf16 v[124:127], v[158:161], v[190:193], v[124:127]
	v_mfma_f32_16x16x32_bf16 v[120:123], v[166:169], v[190:193], v[120:123]
	v_mfma_f32_16x16x32_bf16 v[108:111], v[158:161], v[198:201], v[108:111]
	v_mfma_f32_16x16x32_bf16 v[104:107], v[166:169], v[198:201], v[104:107]
	v_mfma_f32_16x16x32_bf16 v[92:95], v[158:161], v[206:209], v[92:95]
	v_mfma_f32_16x16x32_bf16 v[88:91], v[166:169], v[206:209], v[88:91]
	v_mfma_f32_16x16x32_bf16 v[76:79], v[158:161], v[214:217], v[76:79]
	v_mfma_f32_16x16x32_bf16 v[72:75], v[166:169], v[214:217], v[72:75]
	v_mfma_f32_16x16x32_bf16 v[116:119], v[170:173], v[186:189], v[116:119]
	v_mfma_f32_16x16x32_bf16 v[112:115], v[178:181], v[186:189], v[112:115]
	v_mfma_f32_16x16x32_bf16 v[100:103], v[170:173], v[194:197], v[100:103]
	v_mfma_f32_16x16x32_bf16 v[96:99], v[178:181], v[194:197], v[96:99]
	v_mfma_f32_16x16x32_bf16 v[84:87], v[170:173], v[202:205], v[84:87]
	v_mfma_f32_16x16x32_bf16 v[80:83], v[178:181], v[202:205], v[80:83]
	v_mfma_f32_16x16x32_bf16 v[68:71], v[170:173], v[210:213], v[68:71]
	v_mfma_f32_16x16x32_bf16 v[64:67], v[178:181], v[210:213], v[64:67]
	v_mfma_f32_16x16x32_bf16 v[116:119], v[174:177], v[190:193], v[116:119]
	v_mfma_f32_16x16x32_bf16 v[112:115], v[182:185], v[190:193], v[112:115]
	v_mfma_f32_16x16x32_bf16 v[100:103], v[174:177], v[198:201], v[100:103]
	v_mfma_f32_16x16x32_bf16 v[96:99], v[182:185], v[198:201], v[96:99]
	v_mfma_f32_16x16x32_bf16 v[84:87], v[174:177], v[206:209], v[84:87]
	v_mfma_f32_16x16x32_bf16 v[80:83], v[182:185], v[206:209], v[80:83]
	v_mfma_f32_16x16x32_bf16 v[68:71], v[174:177], v[214:217], v[68:71]
	v_mfma_f32_16x16x32_bf16 v[64:67], v[182:185], v[214:217], v[64:67]
	s_barrier
	s_setprio 0
	s_mov_b32 m0, s96
	v_lshl_add_u64 v[140:141], v[140:141], 0, s[62:63]
	s_add_u32 s44, s80, 0x20080
	ds_read_b128 v[186:189], v151 offset:49152
	ds_read_b128 v[190:193], v151 offset:50176
	ds_read_b128 v[194:197], v151 offset:51200
	ds_read_b128 v[198:201], v151 offset:52224
	ds_read_b128 v[202:205], v151 offset:53248
	ds_read_b128 v[206:209], v151 offset:54272
	ds_read_b128 v[210:213], v151 offset:55296
	ds_read_b128 v[214:217], v151 offset:56320
	global_load_lds_dwordx4 v[140:141], off
	v_lshl_add_u64 v[140:141], v[142:143], 0, s[62:63]
	s_mov_b32 m0, s97
	s_addc_u32 s45, s81, 0
	global_load_lds_dwordx4 v[140:141], off
	v_lshl_add_u64 v[140:141], s[44:45], 0, v[128:129]
	s_mov_b32 m0, vcc_lo
	s_nop 0
	global_load_lds_dwordx4 v[140:141], off
	v_lshl_add_u64 v[140:141], s[44:45], 0, v[130:131]
	s_mov_b32 m0, vcc_hi
	s_nop 0
	global_load_lds_dwordx4 v[140:141], off
	v_lshl_add_u64 v[140:141], v[146:147], 0, s[62:63]
	s_mov_b32 m0, s51
	s_nop 0
	global_load_lds_dwordx4 v[140:141], off
	v_lshl_add_u64 v[140:141], v[218:219], 0, s[62:63]
	s_mov_b32 m0, s52
	s_nop 0
	global_load_lds_dwordx4 v[140:141], off
	s_waitcnt vmcnt(8) lgkmcnt(0)
	s_setprio 1
	s_barrier
	v_mfma_f32_16x16x32_bf16 v[60:63], v[154:157], v[186:189], v[60:63]
	v_mfma_f32_16x16x32_bf16 v[56:59], v[162:165], v[186:189], v[56:59]
	v_mfma_f32_16x16x32_bf16 v[44:47], v[154:157], v[194:197], v[44:47]
	v_mfma_f32_16x16x32_bf16 v[40:43], v[162:165], v[194:197], v[40:43]
	v_mfma_f32_16x16x32_bf16 v[28:31], v[154:157], v[202:205], v[28:31]
	v_mfma_f32_16x16x32_bf16 v[24:27], v[162:165], v[202:205], v[24:27]
	v_mfma_f32_16x16x32_bf16 v[12:15], v[154:157], v[210:213], v[12:15]
	v_mfma_f32_16x16x32_bf16 v[8:11], v[162:165], v[210:213], v[8:11]
	v_mfma_f32_16x16x32_bf16 v[60:63], v[158:161], v[190:193], v[60:63]
	v_mfma_f32_16x16x32_bf16 v[56:59], v[166:169], v[190:193], v[56:59]
	v_mfma_f32_16x16x32_bf16 v[44:47], v[158:161], v[198:201], v[44:47]
	v_mfma_f32_16x16x32_bf16 v[40:43], v[166:169], v[198:201], v[40:43]
	v_mfma_f32_16x16x32_bf16 v[28:31], v[158:161], v[206:209], v[28:31]
	v_mfma_f32_16x16x32_bf16 v[24:27], v[166:169], v[206:209], v[24:27]
	v_mfma_f32_16x16x32_bf16 v[12:15], v[158:161], v[214:217], v[12:15]
	v_mfma_f32_16x16x32_bf16 v[8:11], v[166:169], v[214:217], v[8:11]
	v_mfma_f32_16x16x32_bf16 v[52:55], v[170:173], v[186:189], v[52:55]
	v_mfma_f32_16x16x32_bf16 v[48:51], v[178:181], v[186:189], v[48:51]
	v_mfma_f32_16x16x32_bf16 v[36:39], v[170:173], v[194:197], v[36:39]
	v_mfma_f32_16x16x32_bf16 v[32:35], v[178:181], v[194:197], v[32:35]
	v_mfma_f32_16x16x32_bf16 v[20:23], v[170:173], v[202:205], v[20:23]
	v_mfma_f32_16x16x32_bf16 v[16:19], v[178:181], v[202:205], v[16:19]
	v_mfma_f32_16x16x32_bf16 v[4:7], v[170:173], v[210:213], v[4:7]
	v_mfma_f32_16x16x32_bf16 v[0:3], v[178:181], v[210:213], v[0:3]
	v_mfma_f32_16x16x32_bf16 v[52:55], v[174:177], v[190:193], v[52:55]
	v_mfma_f32_16x16x32_bf16 v[48:51], v[182:185], v[190:193], v[48:51]
	v_mfma_f32_16x16x32_bf16 v[36:39], v[174:177], v[198:201], v[36:39]
	v_mfma_f32_16x16x32_bf16 v[32:35], v[182:185], v[198:201], v[32:35]
	v_mfma_f32_16x16x32_bf16 v[20:23], v[174:177], v[206:209], v[20:23]
	v_mfma_f32_16x16x32_bf16 v[16:19], v[182:185], v[206:209], v[16:19]
	v_mfma_f32_16x16x32_bf16 v[4:7], v[174:177], v[214:217], v[4:7]
	v_mfma_f32_16x16x32_bf16 v[0:3], v[182:185], v[214:217], v[0:3]
	s_barrier
	s_setprio 0
	s_add_i32 s94, s94, 2
	s_add_u32 s85, s85, 0x100
	s_addc_u32 s8, s8, 0
	s_add_u32 s78, s78, 0x100
	s_addc_u32 s79, s79, 0
	s_cmp_gt_u32 s94, 5
	s_cbranch_scc0 .LBB0_2546
	s_and_b64 vcc, exec, s[64:65]
	s_cbranch_vccz .LBB0_2549
	s_barrier

; template <class Epi, class Sched, bool ALIGN_EPI = false, bool SP2 = false, bool A_TILED = false>
; __device__ __forceinline__ void gemm_phase(PG8_LAS unsigned char* lds, const Gemm g, const Sched& S, const Epi& E, const int wave_s) {
;     ...
;             const char* a1 = cA + kstepA; const char* a2 = cA + 2 * kstepA; const char* b2 = cB + 2 * kstep; const char* a3 = a2 + kstepA; const char* b3 = b2 + kstep;
;             PG8_ITER(PG8_MMAZ)
.LBB0_2565:
	s_ashr_i32 s67, s66, 31
	ds_read_b128 v[0:3], v147
	ds_read_b128 v[4:7], v147 offset:1024
	ds_read_b128 v[8:11], v147 offset:2048
	ds_read_b128 v[12:15], v147 offset:3072
	ds_read_b128 v[16:19], v148
	ds_read_b128 v[20:23], v148 offset:1024
	ds_read_b128 v[24:27], v148 offset:2048
	ds_read_b128 v[28:31], v148 offset:3072
	s_lshl_b64 s[52:53], s[66:67], 18
	s_add_u32 s68, s8, s52
	s_addc_u32 s69, s14, s53
	s_and_b64 s[52:53], s[2:3], exec
	s_cselect_b32 s51, s69, s77
	s_cselect_b32 s52, s68, s76
	s_ashr_i32 s65, s64, 31
	s_lshl_b64 s[54:55], s[64:65], 18
	s_add_u32 s72, s15, s54
	s_addc_u32 s73, s23, s55
	s_and_b64 s[54:55], s[2:3], exec
	s_cselect_b32 s53, s73, s75
	s_cselect_b32 s54, s72, s74
	s_add_u32 s56, s76, 0x20080
	s_addc_u32 s57, s77, 0
	s_add_i32 s55, s0, 0xc000
	v_lshl_add_u64 v[64:65], s[56:57], 0, v[134:135]
	s_mov_b32 m0, s55
	ds_read_b128 v[32:35], v149
	ds_read_b128 v[36:39], v149 offset:1024
	ds_read_b128 v[40:43], v149 offset:2048
	ds_read_b128 v[44:47], v149 offset:3072
	ds_read_b128 v[48:51], v149 offset:4096
	ds_read_b128 v[52:55], v149 offset:5120
	ds_read_b128 v[56:59], v149 offset:6144
	ds_read_b128 v[60:63], v149 offset:7168
	global_load_lds_dwordx4 v[64:65], off
	v_lshl_add_u64 v[64:65], s[56:57], 0, v[132:133]
	s_add_i32 s56, s0, 0xe000
	s_mov_b32 m0, s56
	s_nop 0
	global_load_lds_dwordx4 v[64:65], off
	s_waitcnt vmcnt(8) lgkmcnt(0)
	s_setprio 1
	s_barrier
	v_mfma_f32_16x16x32_bf16 v[88:91], v[0:3], v[56:59], 0
	v_mfma_f32_16x16x32_bf16 v[64:67], v[0:3], v[32:35], 0
	v_mfma_f32_16x16x32_bf16 v[68:71], v[8:11], v[32:35], 0
	v_mfma_f32_16x16x32_bf16 v[72:75], v[0:3], v[40:43], 0
	v_mfma_f32_16x16x32_bf16 v[76:79], v[8:11], v[40:43], 0
	v_mfma_f32_16x16x32_bf16 v[80:83], v[0:3], v[48:51], 0
	v_mfma_f32_16x16x32_bf16 v[84:87], v[8:11], v[48:51], 0
	v_mfma_f32_16x16x32_bf16 v[92:95], v[4:7], v[60:63], v[88:91]
	v_mfma_f32_16x16x32_bf16 v[88:91], v[8:11], v[56:59], 0
	v_mfma_f32_16x16x32_bf16 v[64:67], v[4:7], v[36:39], v[64:67]
	v_mfma_f32_16x16x32_bf16 v[68:71], v[12:15], v[36:39], v[68:71]
	v_mfma_f32_16x16x32_bf16 v[72:75], v[4:7], v[44:47], v[72:75]
	v_mfma_f32_16x16x32_bf16 v[76:79], v[12:15], v[44:47], v[76:79]
	v_mfma_f32_16x16x32_bf16 v[80:83], v[4:7], v[52:55], v[80:83]
	v_mfma_f32_16x16x32_bf16 v[84:87], v[12:15], v[52:55], v[84:87]
	v_mfma_f32_16x16x32_bf16 v[100:103], v[12:15], v[60:63], v[88:91]
	v_mfma_f32_16x16x32_bf16 v[88:91], v[16:19], v[32:35], 0
	v_mfma_f32_16x16x32_bf16 v[32:35], v[24:27], v[32:35], 0
	v_mfma_f32_16x16x32_bf16 v[108:111], v[20:23], v[36:39], v[88:91]
	v_mfma_f32_16x16x32_bf16 v[32:35], v[28:31], v[36:39], v[32:35]
	v_mfma_f32_16x16x32_bf16 v[36:39], v[16:19], v[40:43], 0
	v_mfma_f32_16x16x32_bf16 v[40:43], v[24:27], v[40:43], 0
	v_mfma_f32_16x16x32_bf16 v[36:39], v[20:23], v[44:47], v[36:39]
	v_mfma_f32_16x16x32_bf16 v[40:43], v[28:31], v[44:47], v[40:43]
	v_mfma_f32_16x16x32_bf16 v[44:47], v[16:19], v[48:51], 0
	v_mfma_f32_16x16x32_bf16 v[48:51], v[24:27], v[48:51], 0
	v_mfma_f32_16x16x32_bf16 v[44:47], v[20:23], v[52:55], v[44:47]
	v_mfma_f32_16x16x32_bf16 v[52:55], v[28:31], v[52:55], v[48:51]
	v_mfma_f32_16x16x32_bf16 v[48:51], v[16:19], v[56:59], 0
	v_mfma_f32_16x16x32_bf16 v[150:153], v[20:23], v[60:63], v[48:51]
	v_mfma_f32_16x16x32_bf16 v[48:51], v[24:27], v[56:59], 0
	v_mfma_f32_16x16x32_bf16 v[154:157], v[28:31], v[60:63], v[48:51]
	s_barrier
	s_setprio 0
	s_add_i32 s57, s48, s36
	v_lshl_add_u64 v[250:251], s[74:75], 0, v[128:129]
	s_add_i32 s58, s57, 0x2000
	v_lshl_add_u64 v[120:121], v[250:251], 0, s[60:61]
	s_mov_b32 m0, s57
	v_lshl_add_u64 v[252:253], s[74:75], 0, v[130:131]
	s_add_u32 s78, s74, 0x20100
	ds_read_b128 v[48:51], v149 offset:16384
	ds_read_b128 v[56:59], v149 offset:17408
	ds_read_b128 v[60:63], v149 offset:18432
	ds_read_b128 v[88:91], v149 offset:19456
	ds_read_b128 v[96:99], v149 offset:20480
	ds_read_b128 v[104:107], v149 offset:21504
	ds_read_b128 v[112:115], v149 offset:22528
	ds_read_b128 v[116:119], v149 offset:23552
	global_load_lds_dwordx4 v[120:121], off
	v_lshl_add_u64 v[120:121], v[252:253], 0, s[60:61]
	s_mov_b32 m0, s58
	s_addc_u32 s79, s75, 0
	s_add_i32 s59, s49, s36
	global_load_lds_dwordx4 v[120:121], off
	v_lshl_add_u64 v[120:121], s[78:79], 0, v[128:129]
	s_mov_b32 m0, s59
	s_add_i32 s65, s59, 0x2000
	global_load_lds_dwordx4 v[120:121], off
	v_lshl_add_u64 v[120:121], s[78:79], 0, v[130:131]
	s_mov_b32 m0, s65
	v_lshl_add_u64 v[140:141], s[76:77], 0, v[134:135]
	global_load_lds_dwordx4 v[120:121], off
	v_lshl_add_u64 v[120:121], v[140:141], 0, s[60:61]
	s_mov_b32 m0, s0
	v_lshl_add_u64 v[142:143], s[76:77], 0, v[132:133]
	global_load_lds_dwordx4 v[120:121], off
	v_lshl_add_u64 v[120:121], v[142:143], 0, s[60:61]
	s_mov_b32 m0, s1
	s_nop 0
	global_load_lds_dwordx4 v[120:121], off
	s_waitcnt vmcnt(8) lgkmcnt(0)
	s_setprio 1
	s_barrier
	v_mfma_f32_16x16x32_bf16 v[120:123], v[0:3], v[48:51], 0
	v_mfma_f32_16x16x32_bf16 v[158:161], v[4:7], v[56:59], v[120:123]
	v_mfma_f32_16x16x32_bf16 v[120:123], v[8:11], v[48:51], 0
	v_mfma_f32_16x16x32_bf16 v[162:165], v[12:15], v[56:59], v[120:123]
	v_mfma_f32_16x16x32_bf16 v[120:123], v[0:3], v[60:63], 0
	v_mfma_f32_16x16x32_bf16 v[166:169], v[4:7], v[88:91], v[120:123]
	v_mfma_f32_16x16x32_bf16 v[120:123], v[8:11], v[60:63], 0
	v_mfma_f32_16x16x32_bf16 v[170:173], v[12:15], v[88:91], v[120:123]
	v_mfma_f32_16x16x32_bf16 v[120:123], v[0:3], v[96:99], 0
	v_mfma_f32_16x16x32_bf16 v[0:3], v[0:3], v[112:115], 0
	v_mfma_f32_16x16x32_bf16 v[174:177], v[4:7], v[104:107], v[120:123]
	v_mfma_f32_16x16x32_bf16 v[0:3], v[4:7], v[116:119], v[0:3]
	v_mfma_f32_16x16x32_bf16 v[4:7], v[8:11], v[112:115], 0
	v_mfma_f32_16x16x32_bf16 v[120:123], v[8:11], v[96:99], 0
	v_mfma_f32_16x16x32_bf16 v[4:7], v[12:15], v[116:119], v[4:7]
	v_mfma_f32_16x16x32_bf16 v[178:181], v[12:15], v[104:107], v[120:123]
	v_mfma_f32_16x16x32_bf16 v[8:11], v[16:19], v[48:51], 0
	v_mfma_f32_16x16x32_bf16 v[182:185], v[20:23], v[56:59], v[8:11]
	v_mfma_f32_16x16x32_bf16 v[8:11], v[24:27], v[48:51], 0
	v_mfma_f32_16x16x32_bf16 v[186:189], v[28:31], v[56:59], v[8:11]
	v_mfma_f32_16x16x32_bf16 v[8:11], v[16:19], v[60:63], 0
	v_mfma_f32_16x16x32_bf16 v[190:193], v[20:23], v[88:91], v[8:11]
	v_mfma_f32_16x16x32_bf16 v[8:11], v[24:27], v[60:63], 0
	v_mfma_f32_16x16x32_bf16 v[194:197], v[28:31], v[88:91], v[8:11]
	v_mfma_f32_16x16x32_bf16 v[8:11], v[16:19], v[96:99], 0
	v_mfma_f32_16x16x32_bf16 v[198:201], v[20:23], v[104:107], v[8:11]
	v_mfma_f32_16x16x32_bf16 v[8:11], v[24:27], v[96:99], 0
	v_mfma_f32_16x16x32_bf16 v[202:205], v[28:31], v[104:107], v[8:11]
	v_mfma_f32_16x16x32_bf16 v[8:11], v[16:19], v[112:115], 0
	v_mfma_f32_16x16x32_bf16 v[206:209], v[20:23], v[116:119], v[8:11]
	v_mfma_f32_16x16x32_bf16 v[8:11], v[24:27], v[112:115], 0
	v_mfma_f32_16x16x32_bf16 v[210:213], v[28:31], v[116:119], v[8:11]
	s_barrier
	s_setprio 0
	s_add_i32 s67, 0, 0x18000
	s_add_i32 s80, 0, 0x1c000
	v_add_u32_e32 v144, s67, v146
	v_add_u32_e32 v145, s80, v146
	s_nop 0
	ds_read_b128 v[8:11], v144
	ds_read_b128 v[12:15], v144 offset:1024
	ds_read_b128 v[16:19], v144 offset:2048
	ds_read_b128 v[20:23], v144 offset:3072
	ds_read_b128 v[214:217], v145
	ds_read_b128 v[218:221], v145 offset:1024
	ds_read_b128 v[222:225], v145 offset:2048
	ds_read_b128 v[226:229], v145 offset:3072
	s_add_u32 s78, s76, 0x20100
	s_addc_u32 s79, s77, 0
	s_mov_b32 m0, s37
	v_lshl_add_u64 v[48:49], s[78:79], 0, v[134:135]
	ds_read_b128 v[24:27], v149 offset:32768
	ds_read_b128 v[28:31], v149 offset:33792
	ds_read_b128 v[60:63], v149 offset:34816
	ds_read_b128 v[230:233], v149 offset:35840
	ds_read_b128 v[234:237], v149 offset:36864
	ds_read_b128 v[238:241], v149 offset:37888
	ds_read_b128 v[242:245], v149 offset:38912
	ds_read_b128 v[246:249], v149 offset:39936
	global_load_lds_dwordx4 v[48:49], off
	v_lshl_add_u64 v[48:49], s[78:79], 0, v[132:133]
	s_mov_b32 m0, s38
	s_nop 0
	global_load_lds_dwordx4 v[48:49], off
	s_waitcnt vmcnt(8) lgkmcnt(0)
	s_setprio 1
	s_barrier
	v_mfma_f32_16x16x32_bf16 v[48:51], v[8:11], v[24:27], v[64:67]
	v_mfma_f32_16x16x32_bf16 v[120:123], v[12:15], v[28:31], v[48:51]
	v_mfma_f32_16x16x32_bf16 v[48:51], v[16:19], v[24:27], v[68:71]
	v_mfma_f32_16x16x32_bf16 v[112:115], v[20:23], v[28:31], v[48:51]
	v_mfma_f32_16x16x32_bf16 v[48:51], v[8:11], v[60:63], v[72:75]
	v_mfma_f32_16x16x32_bf16 v[104:107], v[12:15], v[230:233], v[48:51]
	v_mfma_f32_16x16x32_bf16 v[48:51], v[16:19], v[60:63], v[76:79]
	v_mfma_f32_16x16x32_bf16 v[96:99], v[20:23], v[230:233], v[48:51]
	v_mfma_f32_16x16x32_bf16 v[48:51], v[8:11], v[234:237], v[80:83]
	v_mfma_f32_16x16x32_bf16 v[88:91], v[12:15], v[238:241], v[48:51]
	v_mfma_f32_16x16x32_bf16 v[48:51], v[16:19], v[234:237], v[84:87]
	v_mfma_f32_16x16x32_bf16 v[80:83], v[20:23], v[238:241], v[48:51]
	v_mfma_f32_16x16x32_bf16 v[48:51], v[8:11], v[242:245], v[92:95]
	v_mfma_f32_16x16x32_bf16 v[56:59], v[12:15], v[246:249], v[48:51]
	v_mfma_f32_16x16x32_bf16 v[48:51], v[16:19], v[242:245], v[100:103]
	v_mfma_f32_16x16x32_bf16 v[48:51], v[20:23], v[246:249], v[48:51]
	v_mfma_f32_16x16x32_bf16 v[64:67], v[214:217], v[24:27], v[108:111]
	v_mfma_f32_16x16x32_bf16 v[24:27], v[222:225], v[24:27], v[32:35]
	v_mfma_f32_16x16x32_bf16 v[116:119], v[226:229], v[28:31], v[24:27]
	v_mfma_f32_16x16x32_bf16 v[24:27], v[214:217], v[60:63], v[36:39]
	v_mfma_f32_16x16x32_bf16 v[108:111], v[218:221], v[230:233], v[24:27]
	v_mfma_f32_16x16x32_bf16 v[24:27], v[222:225], v[60:63], v[40:43]
	v_mfma_f32_16x16x32_bf16 v[100:103], v[226:229], v[230:233], v[24:27]
	v_mfma_f32_16x16x32_bf16 v[24:27], v[214:217], v[234:237], v[44:47]
	v_mfma_f32_16x16x32_bf16 v[92:95], v[218:221], v[238:241], v[24:27]
	v_mfma_f32_16x16x32_bf16 v[24:27], v[222:225], v[234:237], v[52:55]
	v_mfma_f32_16x16x32_bf16 v[84:87], v[226:229], v[238:241], v[24:27]
	v_mfma_f32_16x16x32_bf16 v[24:27], v[214:217], v[242:245], v[150:153]
	v_mfma_f32_16x16x32_bf16 v[60:63], v[218:221], v[246:249], v[24:27]
	v_mfma_f32_16x16x32_bf16 v[24:27], v[222:225], v[242:245], v[154:157]
	v_mfma_f32_16x16x32_bf16 v[124:127], v[218:221], v[28:31], v[64:67]
	v_mfma_f32_16x16x32_bf16 v[52:55], v[226:229], v[246:249], v[24:27]
	s_barrier
; template <class Epi, class Sched, bool ALIGN_EPI = false, bool SP2 = false, bool A_TILED = false>
; __device__ __forceinline__ void gemm_phase(PG8_LAS unsigned char* lds, const Gemm g, const Sched& S, const Epi& E, const int wave_s) {
;     ...
;         for (int t = PEEL ? 2 : 0; t < nt; t += 2) {
;             const bool last = (t == nt - 2);
;             const char* a1 = cA + (size_t)(t + 1) * kstepA;
;             const char* a2 = last ? nA : cA + (size_t)(t + 2) * kstepA; const char* b2 = last ? nB : cB + (size_t)(t + 2) * kstep;
;             const char* a3 = a2 + kstepA; const char* b3 = b2 + kstep;
;             if (last && has_next) S.a_ready(nxt);
	s_setprio 0
	s_add_i32 s67, s67, s36
	s_add_i32 s71, s67, 0x2000
	s_nop 1
	v_lshl_add_u64 v[24:25], v[250:251], 0, s[62:63]
	s_mov_b32 m0, s67
	s_add_u32 s78, s74, 0x20180
	ds_read_b128 v[32:35], v149 offset:49152
	ds_read_b128 v[36:39], v149 offset:50176
	ds_read_b128 v[150:153], v149 offset:51200
	ds_read_b128 v[154:157], v149 offset:52224
	ds_read_b128 v[230:233], v149 offset:53248
	ds_read_b128 v[234:237], v149 offset:54272
	ds_read_b128 v[238:241], v149 offset:55296
	ds_read_b128 v[242:245], v149 offset:56320
	global_load_lds_dwordx4 v[24:25], off
	v_lshl_add_u64 v[24:25], v[252:253], 0, s[62:63]
	s_mov_b32 m0, s71
	s_addc_u32 s79, s75, 0
	s_add_i32 s80, s80, s36
	global_load_lds_dwordx4 v[24:25], off
	v_lshl_add_u64 v[24:25], s[78:79], 0, v[128:129]
	s_mov_b32 m0, s80
	s_add_i32 s81, s80, 0x2000
	global_load_lds_dwordx4 v[24:25], off
	v_lshl_add_u64 v[24:25], s[78:79], 0, v[130:131]
	s_mov_b32 m0, s81
	s_nop 0
	global_load_lds_dwordx4 v[24:25], off
	v_lshl_add_u64 v[24:25], v[140:141], 0, s[62:63]
	s_mov_b32 m0, s42
	s_nop 0
	global_load_lds_dwordx4 v[24:25], off
	v_lshl_add_u64 v[24:25], v[142:143], 0, s[62:63]
	s_mov_b32 m0, s43
	s_nop 0
	global_load_lds_dwordx4 v[24:25], off
	s_waitcnt vmcnt(8) lgkmcnt(0)
	s_setprio 1
	s_barrier
	v_mfma_f32_16x16x32_bf16 v[24:27], v[8:11], v[32:35], v[158:161]
	v_mfma_f32_16x16x32_bf16 v[76:79], v[12:15], v[36:39], v[24:27]
	v_mfma_f32_16x16x32_bf16 v[24:27], v[16:19], v[32:35], v[162:165]
	v_mfma_f32_16x16x32_bf16 v[72:75], v[20:23], v[36:39], v[24:27]
	v_mfma_f32_16x16x32_bf16 v[24:27], v[8:11], v[150:153], v[166:169]
	v_mfma_f32_16x16x32_bf16 v[44:47], v[12:15], v[154:157], v[24:27]
	v_mfma_f32_16x16x32_bf16 v[24:27], v[16:19], v[150:153], v[170:173]
	v_mfma_f32_16x16x32_bf16 v[40:43], v[20:23], v[154:157], v[24:27]
	v_mfma_f32_16x16x32_bf16 v[24:27], v[8:11], v[230:233], v[174:177]
	v_mfma_f32_16x16x32_bf16 v[0:3], v[8:11], v[238:241], v[0:3]
	v_mfma_f32_16x16x32_bf16 v[28:31], v[12:15], v[234:237], v[24:27]
	v_mfma_f32_16x16x32_bf16 v[24:27], v[16:19], v[230:233], v[178:181]
	v_mfma_f32_16x16x32_bf16 v[12:15], v[12:15], v[242:245], v[0:3]
	v_mfma_f32_16x16x32_bf16 v[0:3], v[16:19], v[238:241], v[4:7]
	v_mfma_f32_16x16x32_bf16 v[24:27], v[20:23], v[234:237], v[24:27]
	v_mfma_f32_16x16x32_bf16 v[8:11], v[20:23], v[242:245], v[0:3]
	v_mfma_f32_16x16x32_bf16 v[0:3], v[214:217], v[32:35], v[182:185]
	v_mfma_f32_16x16x32_bf16 v[68:71], v[218:221], v[36:39], v[0:3]
	v_mfma_f32_16x16x32_bf16 v[0:3], v[222:225], v[32:35], v[186:189]
	v_mfma_f32_16x16x32_bf16 v[64:67], v[226:229], v[36:39], v[0:3]
	v_mfma_f32_16x16x32_bf16 v[0:3], v[214:217], v[150:153], v[190:193]
	v_mfma_f32_16x16x32_bf16 v[36:39], v[218:221], v[154:157], v[0:3]
	v_mfma_f32_16x16x32_bf16 v[0:3], v[222:225], v[150:153], v[194:197]
	v_mfma_f32_16x16x32_bf16 v[32:35], v[226:229], v[154:157], v[0:3]
	v_mfma_f32_16x16x32_bf16 v[0:3], v[214:217], v[230:233], v[198:201]
	v_mfma_f32_16x16x32_bf16 v[20:23], v[218:221], v[234:237], v[0:3]
	v_mfma_f32_16x16x32_bf16 v[0:3], v[222:225], v[230:233], v[202:205]
	v_mfma_f32_16x16x32_bf16 v[16:19], v[226:229], v[234:237], v[0:3]
	v_mfma_f32_16x16x32_bf16 v[0:3], v[214:217], v[238:241], v[206:209]
	v_mfma_f32_16x16x32_bf16 v[4:7], v[218:221], v[242:245], v[0:3]
	v_mfma_f32_16x16x32_bf16 v[0:3], v[222:225], v[238:241], v[210:213]
	v_mfma_f32_16x16x32_bf16 v[0:3], v[226:229], v[242:245], v[0:3]
	s_barrier
	s_setprio 0
	s_add_u32 s82, s74, 0x200
	s_addc_u32 s83, s75, 0
	s_add_u32 s74, s76, 0x20180
	s_addc_u32 s75, s77, 0
	s_mov_b32 s85, 0
.LBB0_2566:
	ds_read_b128 v[150:153], v147
	ds_read_b128 v[154:157], v147 offset:1024
	ds_read_b128 v[158:161], v147 offset:2048
	ds_read_b128 v[162:165], v147 offset:3072
	ds_read_b128 v[166:169], v148
	ds_read_b128 v[170:173], v148 offset:1024
	ds_read_b128 v[174:177], v148 offset:2048
	ds_read_b128 v[178:181], v148 offset:3072
	s_add_u32 s76, s74, 0xfffe0080
	s_addc_u32 s77, s75, -1
	s_cmp_eq_u32 s85, 4
	s_cselect_b32 s79, s51, s77
	s_cselect_b32 s78, s52, s76
	s_cselect_b32 s77, s53, s83
	s_cselect_b32 s76, s54, s82
	s_mov_b32 m0, s55
	v_lshl_add_u64 v[140:141], s[74:75], 0, v[138:139]
	ds_read_b128 v[182:185], v149
	ds_read_b128 v[186:189], v149 offset:1024
	ds_read_b128 v[190:193], v149 offset:2048
	ds_read_b128 v[194:197], v149 offset:3072
	ds_read_b128 v[198:201], v149 offset:4096
	ds_read_b128 v[202:205], v149 offset:5120
	ds_read_b128 v[206:209], v149 offset:6144
	ds_read_b128 v[210:213], v149 offset:7168
	global_load_lds_dwordx4 v[140:141], off
	v_lshl_add_u64 v[140:141], s[74:75], 0, v[136:137]
	s_mov_b32 m0, s56
	s_nop 0
	global_load_lds_dwordx4 v[140:141], off
	s_waitcnt vmcnt(8) lgkmcnt(0)
	s_setprio 1
	s_barrier
	v_mfma_f32_16x16x32_bf16 v[120:123], v[150:153], v[182:185], v[120:123]
	v_mfma_f32_16x16x32_bf16 v[112:115], v[158:161], v[182:185], v[112:115]
	v_mfma_f32_16x16x32_bf16 v[104:107], v[150:153], v[190:193], v[104:107]
	v_mfma_f32_16x16x32_bf16 v[96:99], v[158:161], v[190:193], v[96:99]
	v_mfma_f32_16x16x32_bf16 v[88:91], v[150:153], v[198:201], v[88:91]
	v_mfma_f32_16x16x32_bf16 v[80:83], v[158:161], v[198:201], v[80:83]
	v_mfma_f32_16x16x32_bf16 v[56:59], v[150:153], v[206:209], v[56:59]
	v_mfma_f32_16x16x32_bf16 v[48:51], v[158:161], v[206:209], v[48:51]
	v_mfma_f32_16x16x32_bf16 v[120:123], v[154:157], v[186:189], v[120:123]
	v_mfma_f32_16x16x32_bf16 v[112:115], v[162:165], v[186:189], v[112:115]
	v_mfma_f32_16x16x32_bf16 v[104:107], v[154:157], v[194:197], v[104:107]
	v_mfma_f32_16x16x32_bf16 v[96:99], v[162:165], v[194:197], v[96:99]
	v_mfma_f32_16x16x32_bf16 v[88:91], v[154:157], v[202:205], v[88:91]
	v_mfma_f32_16x16x32_bf16 v[80:83], v[162:165], v[202:205], v[80:83]
	v_mfma_f32_16x16x32_bf16 v[56:59], v[154:157], v[210:213], v[56:59]
	v_mfma_f32_16x16x32_bf16 v[48:51], v[162:165], v[210:213], v[48:51]
	v_mfma_f32_16x16x32_bf16 v[124:127], v[166:169], v[182:185], v[124:127]
	v_mfma_f32_16x16x32_bf16 v[116:119], v[174:177], v[182:185], v[116:119]
	v_mfma_f32_16x16x32_bf16 v[108:111], v[166:169], v[190:193], v[108:111]
	v_mfma_f32_16x16x32_bf16 v[100:103], v[174:177], v[190:193], v[100:103]
	v_mfma_f32_16x16x32_bf16 v[92:95], v[166:169], v[198:201], v[92:95]
	v_mfma_f32_16x16x32_bf16 v[84:87], v[174:177], v[198:201], v[84:87]
	v_mfma_f32_16x16x32_bf16 v[60:63], v[166:169], v[206:209], v[60:63]
	v_mfma_f32_16x16x32_bf16 v[52:55], v[174:177], v[206:209], v[52:55]
	v_mfma_f32_16x16x32_bf16 v[124:127], v[170:173], v[186:189], v[124:127]
	v_mfma_f32_16x16x32_bf16 v[116:119], v[178:181], v[186:189], v[116:119]
	v_mfma_f32_16x16x32_bf16 v[108:111], v[170:173], v[194:197], v[108:111]
	v_mfma_f32_16x16x32_bf16 v[100:103], v[178:181], v[194:197], v[100:103]
	v_mfma_f32_16x16x32_bf16 v[92:95], v[170:173], v[202:205], v[92:95]
	v_mfma_f32_16x16x32_bf16 v[84:87], v[178:181], v[202:205], v[84:87]
	v_mfma_f32_16x16x32_bf16 v[60:63], v[170:173], v[210:213], v[60:63]
	v_mfma_f32_16x16x32_bf16 v[52:55], v[178:181], v[210:213], v[52:55]
	s_barrier
	s_setprio 0
	s_mov_b32 m0, s57
	v_lshl_add_u64 v[140:141], s[76:77], 0, v[128:129]
	s_add_u32 s88, s76, 0x20000
	ds_read_b128 v[182:185], v149 offset:16384
	ds_read_b128 v[186:189], v149 offset:17408
	ds_read_b128 v[190:193], v149 offset:18432
	ds_read_b128 v[194:197], v149 offset:19456
	ds_read_b128 v[198:201], v149 offset:20480
	ds_read_b128 v[202:205], v149 offset:21504
	ds_read_b128 v[206:209], v149 offset:22528
	ds_read_b128 v[210:213], v149 offset:23552
	global_load_lds_dwordx4 v[140:141], off
	v_lshl_add_u64 v[142:143], s[76:77], 0, v[130:131]
	s_mov_b32 m0, s58
	s_addc_u32 s89, s77, 0
	global_load_lds_dwordx4 v[142:143], off
	v_lshl_add_u64 v[214:215], s[88:89], 0, v[128:129]
	s_mov_b32 m0, s59
	v_lshl_add_u64 v[216:217], s[78:79], 0, v[132:133]
	global_load_lds_dwordx4 v[214:215], off
	v_lshl_add_u64 v[214:215], s[88:89], 0, v[130:131]
	s_mov_b32 m0, s65
	s_nop 0
	global_load_lds_dwordx4 v[214:215], off
	v_lshl_add_u64 v[214:215], s[78:79], 0, v[134:135]
	s_mov_b32 m0, s0
	s_nop 0
	global_load_lds_dwordx4 v[214:215], off
	s_mov_b32 m0, s1
	s_nop 0
	global_load_lds_dwordx4 v[216:217], off
	s_waitcnt vmcnt(8) lgkmcnt(0)
	s_setprio 1
	s_barrier
	v_mfma_f32_16x16x32_bf16 v[76:79], v[150:153], v[182:185], v[76:79]
	v_mfma_f32_16x16x32_bf16 v[72:75], v[158:161], v[182:185], v[72:75]
	v_mfma_f32_16x16x32_bf16 v[44:47], v[150:153], v[190:193], v[44:47]
	v_mfma_f32_16x16x32_bf16 v[40:43], v[158:161], v[190:193], v[40:43]
	v_mfma_f32_16x16x32_bf16 v[28:31], v[150:153], v[198:201], v[28:31]
	v_mfma_f32_16x16x32_bf16 v[24:27], v[158:161], v[198:201], v[24:27]
	v_mfma_f32_16x16x32_bf16 v[12:15], v[150:153], v[206:209], v[12:15]
	v_mfma_f32_16x16x32_bf16 v[8:11], v[158:161], v[206:209], v[8:11]
	v_mfma_f32_16x16x32_bf16 v[76:79], v[154:157], v[186:189], v[76:79]
	v_mfma_f32_16x16x32_bf16 v[72:75], v[162:165], v[186:189], v[72:75]
	v_mfma_f32_16x16x32_bf16 v[44:47], v[154:157], v[194:197], v[44:47]
	v_mfma_f32_16x16x32_bf16 v[40:43], v[162:165], v[194:197], v[40:43]
	v_mfma_f32_16x16x32_bf16 v[28:31], v[154:157], v[202:205], v[28:31]
	v_mfma_f32_16x16x32_bf16 v[24:27], v[162:165], v[202:205], v[24:27]
	v_mfma_f32_16x16x32_bf16 v[12:15], v[154:157], v[210:213], v[12:15]
	v_mfma_f32_16x16x32_bf16 v[8:11], v[162:165], v[210:213], v[8:11]
	v_mfma_f32_16x16x32_bf16 v[68:71], v[166:169], v[182:185], v[68:71]
	v_mfma_f32_16x16x32_bf16 v[64:67], v[174:177], v[182:185], v[64:67]
	v_mfma_f32_16x16x32_bf16 v[36:39], v[166:169], v[190:193], v[36:39]
	v_mfma_f32_16x16x32_bf16 v[32:35], v[174:177], v[190:193], v[32:35]
	v_mfma_f32_16x16x32_bf16 v[20:23], v[166:169], v[198:201], v[20:23]
	v_mfma_f32_16x16x32_bf16 v[16:19], v[174:177], v[198:201], v[16:19]
	v_mfma_f32_16x16x32_bf16 v[4:7], v[166:169], v[206:209], v[4:7]
	v_mfma_f32_16x16x32_bf16 v[0:3], v[174:177], v[206:209], v[0:3]
	v_mfma_f32_16x16x32_bf16 v[68:71], v[170:173], v[186:189], v[68:71]
	v_mfma_f32_16x16x32_bf16 v[64:67], v[178:181], v[186:189], v[64:67]
	v_mfma_f32_16x16x32_bf16 v[36:39], v[170:173], v[194:197], v[36:39]
	v_mfma_f32_16x16x32_bf16 v[32:35], v[178:181], v[194:197], v[32:35]
	v_mfma_f32_16x16x32_bf16 v[20:23], v[170:173], v[202:205], v[20:23]
	v_mfma_f32_16x16x32_bf16 v[16:19], v[178:181], v[202:205], v[16:19]
	v_mfma_f32_16x16x32_bf16 v[4:7], v[170:173], v[210:213], v[4:7]
	v_mfma_f32_16x16x32_bf16 v[0:3], v[178:181], v[210:213], v[0:3]
	s_barrier
	s_setprio 0
	ds_read_b128 v[150:153], v144
	ds_read_b128 v[154:157], v144 offset:1024
	ds_read_b128 v[158:161], v144 offset:2048
	ds_read_b128 v[162:165], v144 offset:3072
	ds_read_b128 v[166:169], v145
	ds_read_b128 v[170:173], v145 offset:1024
	ds_read_b128 v[174:177], v145 offset:2048
	ds_read_b128 v[178:181], v145 offset:3072
	s_add_u32 s78, s78, 0x20000
	s_addc_u32 s79, s79, 0
	s_mov_b32 m0, s37
	v_lshl_add_u64 v[218:219], s[78:79], 0, v[134:135]
	ds_read_b128 v[182:185], v149 offset:32768
	ds_read_b128 v[186:189], v149 offset:33792
	ds_read_b128 v[190:193], v149 offset:34816
	ds_read_b128 v[194:197], v149 offset:35840
	ds_read_b128 v[198:201], v149 offset:36864
	ds_read_b128 v[202:205], v149 offset:37888
	ds_read_b128 v[206:209], v149 offset:38912
	ds_read_b128 v[210:213], v149 offset:39936
	global_load_lds_dwordx4 v[218:219], off
	v_lshl_add_u64 v[218:219], s[78:79], 0, v[132:133]
	s_mov_b32 m0, s38
	s_nop 0
	global_load_lds_dwordx4 v[218:219], off
	s_waitcnt vmcnt(8) lgkmcnt(0)
	s_setprio 1
	s_barrier
	v_mfma_f32_16x16x32_bf16 v[120:123], v[150:153], v[182:185], v[120:123]
	v_mfma_f32_16x16x32_bf16 v[112:115], v[158:161], v[182:185], v[112:115]
	v_mfma_f32_16x16x32_bf16 v[104:107], v[150:153], v[190:193], v[104:107]
	v_mfma_f32_16x16x32_bf16 v[96:99], v[158:161], v[190:193], v[96:99]
	v_mfma_f32_16x16x32_bf16 v[88:91], v[150:153], v[198:201], v[88:91]
	v_mfma_f32_16x16x32_bf16 v[80:83], v[158:161], v[198:201], v[80:83]
	v_mfma_f32_16x16x32_bf16 v[56:59], v[150:153], v[206:209], v[56:59]
	v_mfma_f32_16x16x32_bf16 v[48:51], v[158:161], v[206:209], v[48:51]
	v_mfma_f32_16x16x32_bf16 v[120:123], v[154:157], v[186:189], v[120:123]
	v_mfma_f32_16x16x32_bf16 v[112:115], v[162:165], v[186:189], v[112:115]
	v_mfma_f32_16x16x32_bf16 v[104:107], v[154:157], v[194:197], v[104:107]
	v_mfma_f32_16x16x32_bf16 v[96:99], v[162:165], v[194:197], v[96:99]
	v_mfma_f32_16x16x32_bf16 v[88:91], v[154:157], v[202:205], v[88:91]
	v_mfma_f32_16x16x32_bf16 v[80:83], v[162:165], v[202:205], v[80:83]
	v_mfma_f32_16x16x32_bf16 v[56:59], v[154:157], v[210:213], v[56:59]
	v_mfma_f32_16x16x32_bf16 v[48:51], v[162:165], v[210:213], v[48:51]
	v_mfma_f32_16x16x32_bf16 v[124:127], v[166:169], v[182:185], v[124:127]
	v_mfma_f32_16x16x32_bf16 v[116:119], v[174:177], v[182:185], v[116:119]
	v_mfma_f32_16x16x32_bf16 v[108:111], v[166:169], v[190:193], v[108:111]
	v_mfma_f32_16x16x32_bf16 v[100:103], v[174:177], v[190:193], v[100:103]
	v_mfma_f32_16x16x32_bf16 v[92:95], v[166:169], v[198:201], v[92:95]
	v_mfma_f32_16x16x32_bf16 v[84:87], v[174:177], v[198:201], v[84:87]
	v_mfma_f32_16x16x32_bf16 v[60:63], v[166:169], v[206:209], v[60:63]
	v_mfma_f32_16x16x32_bf16 v[52:55], v[174:177], v[206:209], v[52:55]
	v_mfma_f32_16x16x32_bf16 v[124:127], v[170:173], v[186:189], v[124:127]
	v_mfma_f32_16x16x32_bf16 v[116:119], v[178:181], v[186:189], v[116:119]
	v_mfma_f32_16x16x32_bf16 v[108:111], v[170:173], v[194:197], v[108:111]
	v_mfma_f32_16x16x32_bf16 v[100:103], v[178:181], v[194:197], v[100:103]
	v_mfma_f32_16x16x32_bf16 v[92:95], v[170:173], v[202:205], v[92:95]
	v_mfma_f32_16x16x32_bf16 v[84:87], v[178:181], v[202:205], v[84:87]
	v_mfma_f32_16x16x32_bf16 v[60:63], v[170:173], v[210:213], v[60:63]
	v_mfma_f32_16x16x32_bf16 v[52:55], v[178:181], v[210:213], v[52:55]
	s_barrier
	s_setprio 0
	s_mov_b32 m0, s67
	v_lshl_add_u64 v[140:141], v[140:141], 0, s[44:45]
	s_add_u32 s76, s76, 0x20080
	ds_read_b128 v[182:185], v149 offset:49152
	ds_read_b128 v[186:189], v149 offset:50176
	ds_read_b128 v[190:193], v149 offset:51200
	ds_read_b128 v[194:197], v149 offset:52224
	ds_read_b128 v[198:201], v149 offset:53248
	ds_read_b128 v[202:205], v149 offset:54272
	ds_read_b128 v[206:209], v149 offset:55296
	ds_read_b128 v[210:213], v149 offset:56320
	global_load_lds_dwordx4 v[140:141], off
	v_lshl_add_u64 v[140:141], v[142:143], 0, s[44:45]
	s_mov_b32 m0, s71
	s_addc_u32 s77, s77, 0
	global_load_lds_dwordx4 v[140:141], off
	v_lshl_add_u64 v[140:141], s[76:77], 0, v[128:129]
	s_mov_b32 m0, s80
	s_nop 0
	global_load_lds_dwordx4 v[140:141], off
	v_lshl_add_u64 v[140:141], s[76:77], 0, v[130:131]
	s_mov_b32 m0, s81
	s_nop 0
	global_load_lds_dwordx4 v[140:141], off
	v_lshl_add_u64 v[140:141], v[214:215], 0, s[44:45]
	s_mov_b32 m0, s42
	s_nop 0
	global_load_lds_dwordx4 v[140:141], off
	v_lshl_add_u64 v[140:141], v[216:217], 0, s[44:45]
	s_mov_b32 m0, s43
	s_nop 0
	global_load_lds_dwordx4 v[140:141], off
	s_waitcnt vmcnt(8) lgkmcnt(0)
	s_setprio 1
	s_barrier
	v_mfma_f32_16x16x32_bf16 v[76:79], v[150:153], v[182:185], v[76:79]
	v_mfma_f32_16x16x32_bf16 v[72:75], v[158:161], v[182:185], v[72:75]
	v_mfma_f32_16x16x32_bf16 v[44:47], v[150:153], v[190:193], v[44:47]
	v_mfma_f32_16x16x32_bf16 v[40:43], v[158:161], v[190:193], v[40:43]
	v_mfma_f32_16x16x32_bf16 v[28:31], v[150:153], v[198:201], v[28:31]
	v_mfma_f32_16x16x32_bf16 v[24:27], v[158:161], v[198:201], v[24:27]
	v_mfma_f32_16x16x32_bf16 v[12:15], v[150:153], v[206:209], v[12:15]
	v_mfma_f32_16x16x32_bf16 v[8:11], v[158:161], v[206:209], v[8:11]
	v_mfma_f32_16x16x32_bf16 v[76:79], v[154:157], v[186:189], v[76:79]
	v_mfma_f32_16x16x32_bf16 v[72:75], v[162:165], v[186:189], v[72:75]
	v_mfma_f32_16x16x32_bf16 v[44:47], v[154:157], v[194:197], v[44:47]
	v_mfma_f32_16x16x32_bf16 v[40:43], v[162:165], v[194:197], v[40:43]
	v_mfma_f32_16x16x32_bf16 v[28:31], v[154:157], v[202:205], v[28:31]
	v_mfma_f32_16x16x32_bf16 v[24:27], v[162:165], v[202:205], v[24:27]
	v_mfma_f32_16x16x32_bf16 v[12:15], v[154:157], v[210:213], v[12:15]
	v_mfma_f32_16x16x32_bf16 v[8:11], v[162:165], v[210:213], v[8:11]
	v_mfma_f32_16x16x32_bf16 v[68:71], v[166:169], v[182:185], v[68:71]
	v_mfma_f32_16x16x32_bf16 v[64:67], v[174:177], v[182:185], v[64:67]
	v_mfma_f32_16x16x32_bf16 v[36:39], v[166:169], v[190:193], v[36:39]
	v_mfma_f32_16x16x32_bf16 v[32:35], v[174:177], v[190:193], v[32:35]
	v_mfma_f32_16x16x32_bf16 v[20:23], v[166:169], v[198:201], v[20:23]
	v_mfma_f32_16x16x32_bf16 v[16:19], v[174:177], v[198:201], v[16:19]
	v_mfma_f32_16x16x32_bf16 v[4:7], v[166:169], v[206:209], v[4:7]
	v_mfma_f32_16x16x32_bf16 v[0:3], v[174:177], v[206:209], v[0:3]
	v_mfma_f32_16x16x32_bf16 v[68:71], v[170:173], v[186:189], v[68:71]
	v_mfma_f32_16x16x32_bf16 v[64:67], v[178:181], v[186:189], v[64:67]
	v_mfma_f32_16x16x32_bf16 v[36:39], v[170:173], v[194:197], v[36:39]
	v_mfma_f32_16x16x32_bf16 v[32:35], v[178:181], v[194:197], v[32:35]
	v_mfma_f32_16x16x32_bf16 v[20:23], v[170:173], v[202:205], v[20:23]
	v_mfma_f32_16x16x32_bf16 v[16:19], v[178:181], v[202:205], v[16:19]
	v_mfma_f32_16x16x32_bf16 v[4:7], v[170:173], v[210:213], v[4:7]
	v_mfma_f32_16x16x32_bf16 v[0:3], v[178:181], v[210:213], v[0:3]
	s_barrier
	s_setprio 0
	s_add_i32 s85, s85, 2
	s_add_u32 s82, s82, 0x100
	s_addc_u32 s83, s83, 0
	s_add_u32 s74, s74, 0x100
	s_addc_u32 s75, s75, 0
	s_cmp_gt_u32 s85, 5
	s_cbranch_scc0 .LBB0_2566
	s_and_b64 vcc, exec, s[46:47]
	s_cbranch_vccz .LBB0_2569
	s_barrier

; template <class Epi, class Sched, bool ALIGN_EPI = false, bool SP2 = false, bool A_TILED = false>
; __device__ __forceinline__ void gemm_phase(PG8_LAS unsigned char* lds, const Gemm g, const Sched& S, const Epi& E, const int wave_s) {
;     ...
;         for (int t = PEEL ? 2 : 0; t < nt; t += 2) {
;             const bool last = (t == nt - 2);
;             const char* a1 = cA + (size_t)(t + 1) * kstepA;
;             const char* a2 = last ? nA : cA + (size_t)(t + 2) * kstepA; const char* b2 = last ? nB : cB + (size_t)(t + 2) * kstep;
;             const char* a3 = a2 + kstepA; const char* b3 = b2 + kstep;
;             if (last && has_next) S.a_ready(nxt);
.LBB0_2729:
	ds_read_b128 v[146:149], v140
	ds_read_b128 v[150:153], v140 offset:1024
	ds_read_b128 v[154:157], v140 offset:2048
	ds_read_b128 v[158:161], v140 offset:3072
	ds_read_b128 v[162:165], v141
	ds_read_b128 v[166:169], v141 offset:1024
	ds_read_b128 v[170:173], v141 offset:2048
	ds_read_b128 v[174:177], v141 offset:3072
	s_add_u32 s55, s44, s39
	s_addc_u32 s56, s45, s40
	s_add_u32 s57, s44, s37
	s_addc_u32 s58, s45, s38
	s_cmp_eq_u32 s41, 28
	s_cselect_b32 s67, s7, s56
	s_cselect_b32 s66, s6, s55
	s_cselect_b32 s65, s3, s58
	s_cselect_b32 s64, s2, s57
	s_mov_b32 m0, s42
	v_lshl_add_u64 v[210:211], s[44:45], 0, v[138:139]
	ds_read_b128 v[178:181], v142
	ds_read_b128 v[182:185], v142 offset:1024
	ds_read_b128 v[186:189], v142 offset:2048
	ds_read_b128 v[190:193], v142 offset:3072
	ds_read_b128 v[194:197], v142 offset:4096
	ds_read_b128 v[198:201], v142 offset:5120
	ds_read_b128 v[202:205], v142 offset:6144
	ds_read_b128 v[206:209], v142 offset:7168
	global_load_lds_dwordx4 v[210:211], off
	v_lshl_add_u64 v[210:211], s[44:45], 0, v[136:137]
	s_mov_b32 m0, s43
	s_nop 0
	global_load_lds_dwordx4 v[210:211], off
	s_waitcnt vmcnt(8) lgkmcnt(0)
	s_setprio 1
	s_barrier
	v_mfma_f32_16x16x32_bf16 v[8:11], v[146:149], v[178:181], v[8:11]
	v_mfma_f32_16x16x32_bf16 v[12:15], v[154:157], v[178:181], v[12:15]
	v_mfma_f32_16x16x32_bf16 v[60:63], v[146:149], v[186:189], v[60:63]
	v_mfma_f32_16x16x32_bf16 v[20:23], v[154:157], v[186:189], v[20:23]
	v_mfma_f32_16x16x32_bf16 v[76:79], v[146:149], v[194:197], v[76:79]
	v_mfma_f32_16x16x32_bf16 v[52:55], v[154:157], v[194:197], v[52:55]
	v_mfma_f32_16x16x32_bf16 v[128:131], v[146:149], v[202:205], v[128:131]
	v_mfma_f32_16x16x32_bf16 v[68:71], v[154:157], v[202:205], v[68:71]
	v_mfma_f32_16x16x32_bf16 v[8:11], v[150:153], v[182:185], v[8:11]
	v_mfma_f32_16x16x32_bf16 v[12:15], v[158:161], v[182:185], v[12:15]
	v_mfma_f32_16x16x32_bf16 v[60:63], v[150:153], v[190:193], v[60:63]
	v_mfma_f32_16x16x32_bf16 v[20:23], v[158:161], v[190:193], v[20:23]
	v_mfma_f32_16x16x32_bf16 v[76:79], v[150:153], v[198:201], v[76:79]
	v_mfma_f32_16x16x32_bf16 v[52:55], v[158:161], v[198:201], v[52:55]
	v_mfma_f32_16x16x32_bf16 v[128:131], v[150:153], v[206:209], v[128:131]
	v_mfma_f32_16x16x32_bf16 v[68:71], v[158:161], v[206:209], v[68:71]
	v_mfma_f32_16x16x32_bf16 v[24:27], v[162:165], v[178:181], v[24:27]
	v_mfma_f32_16x16x32_bf16 v[16:19], v[170:173], v[178:181], v[16:19]
	v_mfma_f32_16x16x32_bf16 v[56:59], v[162:165], v[186:189], v[56:59]
	v_mfma_f32_16x16x32_bf16 v[48:51], v[170:173], v[186:189], v[48:51]
	v_mfma_f32_16x16x32_bf16 v[72:75], v[162:165], v[194:197], v[72:75]
	v_mfma_f32_16x16x32_bf16 v[64:67], v[170:173], v[194:197], v[64:67]
	v_mfma_f32_16x16x32_bf16 v[108:111], v[162:165], v[202:205], v[108:111]
	v_mfma_f32_16x16x32_bf16 v[96:99], v[170:173], v[202:205], v[96:99]
	v_mfma_f32_16x16x32_bf16 v[24:27], v[166:169], v[182:185], v[24:27]
	v_mfma_f32_16x16x32_bf16 v[16:19], v[174:177], v[182:185], v[16:19]
	v_mfma_f32_16x16x32_bf16 v[56:59], v[166:169], v[190:193], v[56:59]
	v_mfma_f32_16x16x32_bf16 v[48:51], v[174:177], v[190:193], v[48:51]
	v_mfma_f32_16x16x32_bf16 v[72:75], v[166:169], v[198:201], v[72:75]
	v_mfma_f32_16x16x32_bf16 v[64:67], v[174:177], v[198:201], v[64:67]
	v_mfma_f32_16x16x32_bf16 v[108:111], v[166:169], v[206:209], v[108:111]
	v_mfma_f32_16x16x32_bf16 v[96:99], v[174:177], v[206:209], v[96:99]
	s_barrier
	s_setprio 0
	s_mov_b32 m0, s47
	v_lshl_add_u64 v[210:211], s[64:65], 0, v[34:35]
	s_add_u32 s56, s64, 0x80000
	ds_read_b128 v[178:181], v142 offset:16384
	ds_read_b128 v[182:185], v142 offset:17408
	ds_read_b128 v[186:189], v142 offset:18432
	ds_read_b128 v[190:193], v142 offset:19456
	ds_read_b128 v[194:197], v142 offset:20480
	ds_read_b128 v[198:201], v142 offset:21504
	ds_read_b128 v[202:205], v142 offset:22528
	ds_read_b128 v[206:209], v142 offset:23552
	global_load_lds_dwordx4 v[210:211], off
	v_lshl_add_u64 v[212:213], s[64:65], 0, v[134:135]
	s_mov_b32 m0, s48
	s_addc_u32 s57, s65, 0
	global_load_lds_dwordx4 v[212:213], off
	v_lshl_add_u64 v[214:215], s[56:57], 0, v[34:35]
	s_mov_b32 m0, s49
	v_lshl_add_u64 v[216:217], s[66:67], 0, v[132:133]
	global_load_lds_dwordx4 v[214:215], off
	v_lshl_add_u64 v[214:215], s[56:57], 0, v[134:135]
	s_mov_b32 m0, s50
	s_nop 0
	global_load_lds_dwordx4 v[214:215], off
	v_lshl_add_u64 v[214:215], s[66:67], 0, v[32:33]
	s_mov_b32 m0, s14
	s_nop 0
	global_load_lds_dwordx4 v[214:215], off
	s_mov_b32 m0, s15
	s_nop 0
	global_load_lds_dwordx4 v[216:217], off
	s_waitcnt vmcnt(8) lgkmcnt(0)
	s_setprio 1
	s_barrier
	v_mfma_f32_16x16x32_bf16 v[100:103], v[146:149], v[178:181], v[100:103]
	v_mfma_f32_16x16x32_bf16 v[104:107], v[154:157], v[178:181], v[104:107]
	v_mfma_f32_16x16x32_bf16 v[116:119], v[146:149], v[186:189], v[116:119]
	v_mfma_f32_16x16x32_bf16 v[120:123], v[154:157], v[186:189], v[120:123]
	v_mfma_f32_16x16x32_bf16 v[84:87], v[146:149], v[194:197], v[84:87]
	v_mfma_f32_16x16x32_bf16 v[80:83], v[154:157], v[194:197], v[80:83]
	v_mfma_f32_16x16x32_bf16 v[36:39], v[146:149], v[202:205], v[36:39]
	v_mfma_f32_16x16x32_bf16 v[28:31], v[154:157], v[202:205], v[28:31]
	v_mfma_f32_16x16x32_bf16 v[100:103], v[150:153], v[182:185], v[100:103]
	v_mfma_f32_16x16x32_bf16 v[104:107], v[158:161], v[182:185], v[104:107]
	v_mfma_f32_16x16x32_bf16 v[116:119], v[150:153], v[190:193], v[116:119]
	v_mfma_f32_16x16x32_bf16 v[120:123], v[158:161], v[190:193], v[120:123]
	v_mfma_f32_16x16x32_bf16 v[84:87], v[150:153], v[198:201], v[84:87]
	v_mfma_f32_16x16x32_bf16 v[80:83], v[158:161], v[198:201], v[80:83]
	v_mfma_f32_16x16x32_bf16 v[36:39], v[150:153], v[206:209], v[36:39]
	v_mfma_f32_16x16x32_bf16 v[28:31], v[158:161], v[206:209], v[28:31]
	v_mfma_f32_16x16x32_bf16 v[124:127], v[162:165], v[178:181], v[124:127]
	v_mfma_f32_16x16x32_bf16 v[112:115], v[170:173], v[178:181], v[112:115]
	v_mfma_f32_16x16x32_bf16 v[92:95], v[162:165], v[186:189], v[92:95]
	v_mfma_f32_16x16x32_bf16 v[88:91], v[170:173], v[186:189], v[88:91]
	v_mfma_f32_16x16x32_bf16 v[44:47], v[162:165], v[194:197], v[44:47]
	v_mfma_f32_16x16x32_bf16 v[40:43], v[170:173], v[194:197], v[40:43]
	v_mfma_f32_16x16x32_bf16 v[4:7], v[162:165], v[202:205], v[4:7]
	v_mfma_f32_16x16x32_bf16 v[0:3], v[170:173], v[202:205], v[0:3]
	v_mfma_f32_16x16x32_bf16 v[124:127], v[166:169], v[182:185], v[124:127]
	v_mfma_f32_16x16x32_bf16 v[112:115], v[174:177], v[182:185], v[112:115]
	v_mfma_f32_16x16x32_bf16 v[92:95], v[166:169], v[190:193], v[92:95]
	v_mfma_f32_16x16x32_bf16 v[88:91], v[174:177], v[190:193], v[88:91]
	v_mfma_f32_16x16x32_bf16 v[44:47], v[166:169], v[198:201], v[44:47]
	v_mfma_f32_16x16x32_bf16 v[40:43], v[174:177], v[198:201], v[40:43]
	v_mfma_f32_16x16x32_bf16 v[4:7], v[166:169], v[206:209], v[4:7]
	v_mfma_f32_16x16x32_bf16 v[0:3], v[174:177], v[206:209], v[0:3]
	s_barrier
	s_setprio 0
	ds_read_b128 v[146:149], v143
	ds_read_b128 v[150:153], v143 offset:1024
	ds_read_b128 v[154:157], v143 offset:2048
	ds_read_b128 v[158:161], v143 offset:3072
	ds_read_b128 v[162:165], v144
	ds_read_b128 v[166:169], v144 offset:1024
	ds_read_b128 v[170:173], v144 offset:2048
	ds_read_b128 v[174:177], v144 offset:3072
	s_add_u32 s56, s66, 0x80000
	s_addc_u32 s57, s67, 0
	s_mov_b32 m0, s21
	v_lshl_add_u64 v[218:219], s[56:57], 0, v[32:33]
	ds_read_b128 v[178:181], v142 offset:32768
	ds_read_b128 v[182:185], v142 offset:33792
	ds_read_b128 v[186:189], v142 offset:34816
	ds_read_b128 v[190:193], v142 offset:35840
	ds_read_b128 v[194:197], v142 offset:36864
	ds_read_b128 v[198:201], v142 offset:37888
	ds_read_b128 v[202:205], v142 offset:38912
	ds_read_b128 v[206:209], v142 offset:39936
	global_load_lds_dwordx4 v[218:219], off
	v_lshl_add_u64 v[218:219], s[56:57], 0, v[132:133]
	s_mov_b32 m0, s22
	s_nop 0
	global_load_lds_dwordx4 v[218:219], off
	s_waitcnt vmcnt(8) lgkmcnt(0)
	s_setprio 1
	s_barrier
	v_mfma_f32_16x16x32_bf16 v[8:11], v[146:149], v[178:181], v[8:11]
	v_mfma_f32_16x16x32_bf16 v[12:15], v[154:157], v[178:181], v[12:15]
	v_mfma_f32_16x16x32_bf16 v[60:63], v[146:149], v[186:189], v[60:63]
	v_mfma_f32_16x16x32_bf16 v[20:23], v[154:157], v[186:189], v[20:23]
	v_mfma_f32_16x16x32_bf16 v[76:79], v[146:149], v[194:197], v[76:79]
	v_mfma_f32_16x16x32_bf16 v[52:55], v[154:157], v[194:197], v[52:55]
	v_mfma_f32_16x16x32_bf16 v[128:131], v[146:149], v[202:205], v[128:131]
	v_mfma_f32_16x16x32_bf16 v[68:71], v[154:157], v[202:205], v[68:71]
	v_mfma_f32_16x16x32_bf16 v[8:11], v[150:153], v[182:185], v[8:11]
	v_mfma_f32_16x16x32_bf16 v[12:15], v[158:161], v[182:185], v[12:15]
	v_mfma_f32_16x16x32_bf16 v[60:63], v[150:153], v[190:193], v[60:63]
	v_mfma_f32_16x16x32_bf16 v[20:23], v[158:161], v[190:193], v[20:23]
	v_mfma_f32_16x16x32_bf16 v[76:79], v[150:153], v[198:201], v[76:79]
	v_mfma_f32_16x16x32_bf16 v[52:55], v[158:161], v[198:201], v[52:55]
	v_mfma_f32_16x16x32_bf16 v[128:131], v[150:153], v[206:209], v[128:131]
	v_mfma_f32_16x16x32_bf16 v[68:71], v[158:161], v[206:209], v[68:71]
	v_mfma_f32_16x16x32_bf16 v[24:27], v[162:165], v[178:181], v[24:27]
	v_mfma_f32_16x16x32_bf16 v[16:19], v[170:173], v[178:181], v[16:19]
	v_mfma_f32_16x16x32_bf16 v[56:59], v[162:165], v[186:189], v[56:59]
	v_mfma_f32_16x16x32_bf16 v[48:51], v[170:173], v[186:189], v[48:51]
	v_mfma_f32_16x16x32_bf16 v[72:75], v[162:165], v[194:197], v[72:75]
	v_mfma_f32_16x16x32_bf16 v[64:67], v[170:173], v[194:197], v[64:67]
	v_mfma_f32_16x16x32_bf16 v[108:111], v[162:165], v[202:205], v[108:111]
	v_mfma_f32_16x16x32_bf16 v[96:99], v[170:173], v[202:205], v[96:99]
	v_mfma_f32_16x16x32_bf16 v[24:27], v[166:169], v[182:185], v[24:27]
	v_mfma_f32_16x16x32_bf16 v[16:19], v[174:177], v[182:185], v[16:19]
	v_mfma_f32_16x16x32_bf16 v[56:59], v[166:169], v[190:193], v[56:59]
	v_mfma_f32_16x16x32_bf16 v[48:51], v[174:177], v[190:193], v[48:51]
	v_mfma_f32_16x16x32_bf16 v[72:75], v[166:169], v[198:201], v[72:75]
	v_mfma_f32_16x16x32_bf16 v[64:67], v[174:177], v[198:201], v[64:67]
	v_mfma_f32_16x16x32_bf16 v[108:111], v[166:169], v[206:209], v[108:111]
	v_mfma_f32_16x16x32_bf16 v[96:99], v[174:177], v[206:209], v[96:99]
	s_barrier
	s_setprio 0
	s_mov_b32 m0, s51
	v_lshl_add_u64 v[210:211], v[210:211], 0, s[60:61]
	s_add_u32 s56, s64, 0x80080
	ds_read_b128 v[178:181], v142 offset:49152
	ds_read_b128 v[182:185], v142 offset:50176
	ds_read_b128 v[186:189], v142 offset:51200
	ds_read_b128 v[190:193], v142 offset:52224
	ds_read_b128 v[194:197], v142 offset:53248
	ds_read_b128 v[198:201], v142 offset:54272
	ds_read_b128 v[202:205], v142 offset:55296
	ds_read_b128 v[206:209], v142 offset:56320
	global_load_lds_dwordx4 v[210:211], off
	v_lshl_add_u64 v[210:211], v[212:213], 0, s[60:61]
	s_mov_b32 m0, s52
	s_addc_u32 s57, s65, 0
	global_load_lds_dwordx4 v[210:211], off
	v_lshl_add_u64 v[210:211], s[56:57], 0, v[34:35]
	s_mov_b32 m0, s53
	s_nop 0
	global_load_lds_dwordx4 v[210:211], off
	v_lshl_add_u64 v[210:211], s[56:57], 0, v[134:135]
	s_mov_b32 m0, s54
	s_nop 0
	global_load_lds_dwordx4 v[210:211], off
	v_lshl_add_u64 v[210:211], v[214:215], 0, s[60:61]
	s_mov_b32 m0, s23
	s_nop 0
	global_load_lds_dwordx4 v[210:211], off
	v_lshl_add_u64 v[210:211], v[216:217], 0, s[60:61]
	s_mov_b32 m0, s36
	s_nop 0
	global_load_lds_dwordx4 v[210:211], off
	s_waitcnt vmcnt(8) lgkmcnt(0)
	s_setprio 1
	s_barrier
	v_mfma_f32_16x16x32_bf16 v[100:103], v[146:149], v[178:181], v[100:103]
	v_mfma_f32_16x16x32_bf16 v[104:107], v[154:157], v[178:181], v[104:107]
	v_mfma_f32_16x16x32_bf16 v[116:119], v[146:149], v[186:189], v[116:119]
	v_mfma_f32_16x16x32_bf16 v[120:123], v[154:157], v[186:189], v[120:123]
	v_mfma_f32_16x16x32_bf16 v[84:87], v[146:149], v[194:197], v[84:87]
	v_mfma_f32_16x16x32_bf16 v[80:83], v[154:157], v[194:197], v[80:83]
	v_mfma_f32_16x16x32_bf16 v[36:39], v[146:149], v[202:205], v[36:39]
	v_mfma_f32_16x16x32_bf16 v[28:31], v[154:157], v[202:205], v[28:31]
	v_mfma_f32_16x16x32_bf16 v[100:103], v[150:153], v[182:185], v[100:103]
	v_mfma_f32_16x16x32_bf16 v[104:107], v[158:161], v[182:185], v[104:107]
	v_mfma_f32_16x16x32_bf16 v[116:119], v[150:153], v[190:193], v[116:119]
	v_mfma_f32_16x16x32_bf16 v[120:123], v[158:161], v[190:193], v[120:123]
	v_mfma_f32_16x16x32_bf16 v[84:87], v[150:153], v[198:201], v[84:87]
	v_mfma_f32_16x16x32_bf16 v[80:83], v[158:161], v[198:201], v[80:83]
	v_mfma_f32_16x16x32_bf16 v[36:39], v[150:153], v[206:209], v[36:39]
	v_mfma_f32_16x16x32_bf16 v[28:31], v[158:161], v[206:209], v[28:31]
	v_mfma_f32_16x16x32_bf16 v[124:127], v[162:165], v[178:181], v[124:127]
	v_mfma_f32_16x16x32_bf16 v[112:115], v[170:173], v[178:181], v[112:115]
	v_mfma_f32_16x16x32_bf16 v[92:95], v[162:165], v[186:189], v[92:95]
	v_mfma_f32_16x16x32_bf16 v[88:91], v[170:173], v[186:189], v[88:91]
	v_mfma_f32_16x16x32_bf16 v[44:47], v[162:165], v[194:197], v[44:47]
	v_mfma_f32_16x16x32_bf16 v[40:43], v[170:173], v[194:197], v[40:43]
	v_mfma_f32_16x16x32_bf16 v[4:7], v[162:165], v[202:205], v[4:7]
	v_mfma_f32_16x16x32_bf16 v[0:3], v[170:173], v[202:205], v[0:3]
	v_mfma_f32_16x16x32_bf16 v[124:127], v[166:169], v[182:185], v[124:127]
	v_mfma_f32_16x16x32_bf16 v[112:115], v[174:177], v[182:185], v[112:115]
	v_mfma_f32_16x16x32_bf16 v[92:95], v[166:169], v[190:193], v[92:95]
	v_mfma_f32_16x16x32_bf16 v[88:91], v[174:177], v[190:193], v[88:91]
	v_mfma_f32_16x16x32_bf16 v[44:47], v[166:169], v[198:201], v[44:47]
	v_mfma_f32_16x16x32_bf16 v[40:43], v[174:177], v[198:201], v[40:43]
	v_mfma_f32_16x16x32_bf16 v[4:7], v[166:169], v[206:209], v[4:7]
	v_mfma_f32_16x16x32_bf16 v[0:3], v[174:177], v[206:209], v[0:3]
	s_barrier
	s_setprio 0
	s_add_i32 s41, s41, 2
	s_add_u32 s37, s37, 0x100
	s_addc_u32 s38, s38, 0
	s_add_u32 s39, s39, 0x100
	s_addc_u32 s40, s40, 0
	v_lshl_add_u64 v[136:137], v[136:137], 0, s[62:63]
	s_cmp_gt_u32 s41, 29
	v_lshl_add_u64 v[138:139], v[138:139], 0, s[62:63]
	s_cbranch_scc0 .LBB0_2729
	s_waitcnt vmcnt(0)
	s_cmpk_lt_u32 s0, 0x100
	s_cbranch_scc0 .LBB0_2732
	s_barrier

; template <class Epi, class Sched, bool ALIGN_EPI = false, bool SP2 = false, bool A_TILED = false>
; __device__ __forceinline__ void gemm_phase(PG8_LAS unsigned char* lds, const Gemm g, const Sched& S, const Epi& E, const int wave_s) {
;     ...
;             const char* a1 = cA + kstepA; const char* a2 = cA + 2 * kstepA; const char* b2 = cB + 2 * kstep; const char* a3 = a2 + kstepA; const char* b3 = b2 + kstep;
;             PG8_ITER(PG8_MMAZ)
.LBB0_2840:
	s_ashr_i32 s65, s64, 31
	s_lshl_b64 s[54:55], s[64:65], 20
	s_add_u32 s66, s1, s54
	ds_read_b128 v[0:3], v145
	ds_read_b128 v[4:7], v145 offset:1024
	ds_read_b128 v[8:11], v145 offset:2048
	ds_read_b128 v[12:15], v145 offset:3072
	ds_read_b128 v[16:19], v146
	ds_read_b128 v[20:23], v146 offset:1024
	ds_read_b128 v[24:27], v146 offset:2048
	ds_read_b128 v[28:31], v146 offset:3072
	s_addc_u32 s67, s8, s55
	s_ashr_i32 s63, s62, 31
	s_lshl_b64 s[54:55], s[62:63], 20
	s_add_u32 s68, s9, s54
	s_addc_u32 s69, s14, s55
	s_and_b64 s[54:55], s[2:3], exec
	s_cselect_b32 s54, s67, s75
	s_cselect_b32 s55, s66, s74
	s_cselect_b32 s56, s69, s73
	s_cselect_b32 s57, s68, s72
	s_add_u32 s76, s74, 0x80080
	s_addc_u32 s77, s75, 0
	s_add_i32 s58, s22, 0xc000
	v_lshl_add_u64 v[64:65], s[76:77], 0, v[134:135]
	s_mov_b32 m0, s58
	s_add_i32 s59, s22, 0xe000
	ds_read_b128 v[32:35], v147
	ds_read_b128 v[36:39], v147 offset:1024
	ds_read_b128 v[40:43], v147 offset:2048
	ds_read_b128 v[44:47], v147 offset:3072
	ds_read_b128 v[48:51], v147 offset:4096
	ds_read_b128 v[52:55], v147 offset:5120
	ds_read_b128 v[56:59], v147 offset:6144
	ds_read_b128 v[60:63], v147 offset:7168
	global_load_lds_dwordx4 v[64:65], off
	v_lshl_add_u64 v[64:65], s[76:77], 0, v[132:133]
	s_mov_b32 m0, s59
	s_nop 0
	global_load_lds_dwordx4 v[64:65], off
	s_waitcnt vmcnt(8) lgkmcnt(0)
	s_setprio 1
	s_barrier
	v_mfma_f32_16x16x32_bf16 v[88:91], v[0:3], v[56:59], 0
	v_mfma_f32_16x16x32_bf16 v[64:67], v[0:3], v[32:35], 0
	v_mfma_f32_16x16x32_bf16 v[68:71], v[8:11], v[32:35], 0
	v_mfma_f32_16x16x32_bf16 v[72:75], v[0:3], v[40:43], 0
	v_mfma_f32_16x16x32_bf16 v[76:79], v[8:11], v[40:43], 0
	v_mfma_f32_16x16x32_bf16 v[80:83], v[0:3], v[48:51], 0
	v_mfma_f32_16x16x32_bf16 v[84:87], v[8:11], v[48:51], 0
	v_mfma_f32_16x16x32_bf16 v[96:99], v[4:7], v[60:63], v[88:91]
	v_mfma_f32_16x16x32_bf16 v[88:91], v[8:11], v[56:59], 0
	v_mfma_f32_16x16x32_bf16 v[64:67], v[4:7], v[36:39], v[64:67]
	v_mfma_f32_16x16x32_bf16 v[68:71], v[12:15], v[36:39], v[68:71]
	v_mfma_f32_16x16x32_bf16 v[72:75], v[4:7], v[44:47], v[72:75]
	v_mfma_f32_16x16x32_bf16 v[76:79], v[12:15], v[44:47], v[76:79]
	v_mfma_f32_16x16x32_bf16 v[80:83], v[4:7], v[52:55], v[80:83]
	v_mfma_f32_16x16x32_bf16 v[84:87], v[12:15], v[52:55], v[84:87]
	v_mfma_f32_16x16x32_bf16 v[100:103], v[12:15], v[60:63], v[88:91]
	v_mfma_f32_16x16x32_bf16 v[88:91], v[16:19], v[32:35], 0
	v_mfma_f32_16x16x32_bf16 v[32:35], v[24:27], v[32:35], 0
	v_mfma_f32_16x16x32_bf16 v[112:115], v[20:23], v[36:39], v[88:91]
	v_mfma_f32_16x16x32_bf16 v[32:35], v[28:31], v[36:39], v[32:35]
	v_mfma_f32_16x16x32_bf16 v[36:39], v[16:19], v[40:43], 0
	v_mfma_f32_16x16x32_bf16 v[40:43], v[24:27], v[40:43], 0
	v_mfma_f32_16x16x32_bf16 v[36:39], v[20:23], v[44:47], v[36:39]
	v_mfma_f32_16x16x32_bf16 v[40:43], v[28:31], v[44:47], v[40:43]
	v_mfma_f32_16x16x32_bf16 v[44:47], v[16:19], v[48:51], 0
	v_mfma_f32_16x16x32_bf16 v[48:51], v[24:27], v[48:51], 0
	v_mfma_f32_16x16x32_bf16 v[44:47], v[20:23], v[52:55], v[44:47]
	v_mfma_f32_16x16x32_bf16 v[48:51], v[28:31], v[52:55], v[48:51]
	v_mfma_f32_16x16x32_bf16 v[52:55], v[16:19], v[56:59], 0
	v_mfma_f32_16x16x32_bf16 v[56:59], v[24:27], v[56:59], 0
	v_mfma_f32_16x16x32_bf16 v[52:55], v[20:23], v[60:63], v[52:55]
	v_mfma_f32_16x16x32_bf16 v[56:59], v[28:31], v[60:63], v[56:59]
	s_barrier
	s_setprio 0
	s_add_i32 s63, s51, s15
	v_lshl_add_u64 v[242:243], s[72:73], 0, v[128:129]
	s_add_i32 s65, s63, 0x2000
	v_lshl_add_u64 v[148:149], v[242:243], 0, s[46:47]
	s_mov_b32 m0, s63
	v_lshl_add_u64 v[244:245], s[72:73], 0, v[130:131]
	s_add_u32 s76, s72, 0x80100
	ds_read_b128 v[60:63], v147 offset:16384
	ds_read_b128 v[88:91], v147 offset:17408
	ds_read_b128 v[92:95], v147 offset:18432
	ds_read_b128 v[104:107], v147 offset:19456
	ds_read_b128 v[108:111], v147 offset:20480
	ds_read_b128 v[116:119], v147 offset:21504
	ds_read_b128 v[120:123], v147 offset:22528
	ds_read_b128 v[124:127], v147 offset:23552
	global_load_lds_dwordx4 v[148:149], off
	v_lshl_add_u64 v[148:149], v[244:245], 0, s[46:47]
	s_mov_b32 m0, s65
	s_addc_u32 s77, s73, 0
	s_add_i32 s71, s52, s15
	global_load_lds_dwordx4 v[148:149], off
	v_lshl_add_u64 v[148:149], s[76:77], 0, v[128:129]
	s_mov_b32 m0, s71
	s_add_i32 s78, s71, 0x2000
	global_load_lds_dwordx4 v[148:149], off
	v_lshl_add_u64 v[148:149], s[76:77], 0, v[130:131]
	s_mov_b32 m0, s78
	v_lshl_add_u64 v[246:247], s[74:75], 0, v[134:135]
	global_load_lds_dwordx4 v[148:149], off
	v_lshl_add_u64 v[148:149], v[246:247], 0, s[46:47]
	s_mov_b32 m0, s22
	v_lshl_add_u64 v[248:249], s[74:75], 0, v[132:133]
	global_load_lds_dwordx4 v[148:149], off
	v_lshl_add_u64 v[148:149], v[248:249], 0, s[46:47]
	s_mov_b32 m0, s23
	s_nop 0
	global_load_lds_dwordx4 v[148:149], off
	s_waitcnt vmcnt(8) lgkmcnt(0)
	s_setprio 1
	s_barrier
	v_mfma_f32_16x16x32_bf16 v[148:151], v[0:3], v[60:63], 0
	v_mfma_f32_16x16x32_bf16 v[158:161], v[0:3], v[92:95], 0
	v_mfma_f32_16x16x32_bf16 v[166:169], v[0:3], v[108:111], 0
	v_mfma_f32_16x16x32_bf16 v[0:3], v[0:3], v[120:123], 0
	v_mfma_f32_16x16x32_bf16 v[150:153], v[4:7], v[88:91], v[148:151]
	v_mfma_f32_16x16x32_bf16 v[158:161], v[4:7], v[104:107], v[158:161]
	v_mfma_f32_16x16x32_bf16 v[166:169], v[4:7], v[116:119], v[166:169]
	v_mfma_f32_16x16x32_bf16 v[0:3], v[4:7], v[124:127], v[0:3]
	v_mfma_f32_16x16x32_bf16 v[4:7], v[8:11], v[120:123], 0
	v_mfma_f32_16x16x32_bf16 v[154:157], v[8:11], v[60:63], 0
	v_mfma_f32_16x16x32_bf16 v[162:165], v[8:11], v[92:95], 0
	v_mfma_f32_16x16x32_bf16 v[170:173], v[8:11], v[108:111], 0
	v_mfma_f32_16x16x32_bf16 v[4:7], v[12:15], v[124:127], v[4:7]
	v_mfma_f32_16x16x32_bf16 v[154:157], v[12:15], v[88:91], v[154:157]
	v_mfma_f32_16x16x32_bf16 v[162:165], v[12:15], v[104:107], v[162:165]
	v_mfma_f32_16x16x32_bf16 v[170:173], v[12:15], v[116:119], v[170:173]
	v_mfma_f32_16x16x32_bf16 v[8:11], v[16:19], v[60:63], 0
	v_mfma_f32_16x16x32_bf16 v[174:177], v[20:23], v[88:91], v[8:11]
	v_mfma_f32_16x16x32_bf16 v[8:11], v[24:27], v[60:63], 0
	v_mfma_f32_16x16x32_bf16 v[60:63], v[28:31], v[88:91], v[8:11]
	v_mfma_f32_16x16x32_bf16 v[8:11], v[16:19], v[92:95], 0
	v_mfma_f32_16x16x32_bf16 v[178:181], v[20:23], v[104:107], v[8:11]
	v_mfma_f32_16x16x32_bf16 v[8:11], v[24:27], v[92:95], 0
	v_mfma_f32_16x16x32_bf16 v[182:185], v[28:31], v[104:107], v[8:11]
	v_mfma_f32_16x16x32_bf16 v[8:11], v[16:19], v[108:111], 0
	v_mfma_f32_16x16x32_bf16 v[186:189], v[20:23], v[116:119], v[8:11]
	v_mfma_f32_16x16x32_bf16 v[8:11], v[24:27], v[108:111], 0
	v_mfma_f32_16x16x32_bf16 v[190:193], v[28:31], v[116:119], v[8:11]
	v_mfma_f32_16x16x32_bf16 v[8:11], v[16:19], v[120:123], 0
	v_mfma_f32_16x16x32_bf16 v[194:197], v[20:23], v[124:127], v[8:11]
	v_mfma_f32_16x16x32_bf16 v[8:11], v[24:27], v[120:123], 0
	v_mfma_f32_16x16x32_bf16 v[198:201], v[28:31], v[124:127], v[8:11]
	s_barrier
	s_setprio 0
	s_add_i32 s79, 0, 0x18000
	s_add_i32 s81, 0, 0x1c000
	v_add_u32_e32 v148, s79, v144
	v_add_u32_e32 v149, s81, v144
	s_nop 0
	ds_read_b128 v[8:11], v148
	ds_read_b128 v[12:15], v148 offset:1024
	ds_read_b128 v[16:19], v148 offset:2048
	ds_read_b128 v[20:23], v148 offset:3072
	ds_read_b128 v[202:205], v149
	ds_read_b128 v[206:209], v149 offset:1024
	ds_read_b128 v[210:213], v149 offset:2048
	ds_read_b128 v[214:217], v149 offset:3072
	s_add_u32 s76, s74, 0x80100
	s_addc_u32 s77, s75, 0
	s_mov_b32 m0, s36
	v_lshl_add_u64 v[88:89], s[76:77], 0, v[134:135]
	ds_read_b128 v[24:27], v147 offset:32768
	ds_read_b128 v[28:31], v147 offset:33792
	ds_read_b128 v[218:221], v147 offset:34816
	ds_read_b128 v[222:225], v147 offset:35840
	ds_read_b128 v[226:229], v147 offset:36864
	ds_read_b128 v[230:233], v147 offset:37888
	ds_read_b128 v[234:237], v147 offset:38912
	ds_read_b128 v[238:241], v147 offset:39936
	global_load_lds_dwordx4 v[88:89], off
	v_lshl_add_u64 v[88:89], s[76:77], 0, v[132:133]
	s_mov_b32 m0, s37
	s_nop 0
	global_load_lds_dwordx4 v[88:89], off
	s_waitcnt vmcnt(8) lgkmcnt(0)
	s_setprio 1
	s_barrier
	v_mfma_f32_16x16x32_bf16 v[64:67], v[8:11], v[24:27], v[64:67]
	v_mfma_f32_16x16x32_bf16 v[120:123], v[12:15], v[28:31], v[64:67]
	v_mfma_f32_16x16x32_bf16 v[64:67], v[16:19], v[24:27], v[68:71]
	v_mfma_f32_16x16x32_bf16 v[124:127], v[20:23], v[28:31], v[64:67]
	v_mfma_f32_16x16x32_bf16 v[64:67], v[8:11], v[218:221], v[72:75]
	v_mfma_f32_16x16x32_bf16 v[104:107], v[12:15], v[222:225], v[64:67]
	v_mfma_f32_16x16x32_bf16 v[64:67], v[16:19], v[218:221], v[76:79]
	v_mfma_f32_16x16x32_bf16 v[108:111], v[20:23], v[222:225], v[64:67]
	v_mfma_f32_16x16x32_bf16 v[64:67], v[8:11], v[226:229], v[80:83]
	v_mfma_f32_16x16x32_bf16 v[88:91], v[12:15], v[230:233], v[64:67]
	v_mfma_f32_16x16x32_bf16 v[64:67], v[16:19], v[226:229], v[84:87]
	v_mfma_f32_16x16x32_bf16 v[92:95], v[20:23], v[230:233], v[64:67]
	v_mfma_f32_16x16x32_bf16 v[64:67], v[8:11], v[234:237], v[96:99]
	v_mfma_f32_16x16x32_bf16 v[68:71], v[16:19], v[234:237], v[100:103]
	v_mfma_f32_16x16x32_bf16 v[64:67], v[12:15], v[238:241], v[64:67]
	v_mfma_f32_16x16x32_bf16 v[68:71], v[20:23], v[238:241], v[68:71]
	v_mfma_f32_16x16x32_bf16 v[72:75], v[202:205], v[24:27], v[112:115]
	v_mfma_f32_16x16x32_bf16 v[24:27], v[210:213], v[24:27], v[32:35]
	v_mfma_f32_16x16x32_bf16 v[116:119], v[214:217], v[28:31], v[24:27]
	v_mfma_f32_16x16x32_bf16 v[24:27], v[202:205], v[218:221], v[36:39]
	v_mfma_f32_16x16x32_bf16 v[96:99], v[206:209], v[222:225], v[24:27]
	v_mfma_f32_16x16x32_bf16 v[24:27], v[210:213], v[218:221], v[40:43]
	v_mfma_f32_16x16x32_bf16 v[100:103], v[214:217], v[222:225], v[24:27]
	v_mfma_f32_16x16x32_bf16 v[24:27], v[202:205], v[226:229], v[44:47]
	v_mfma_f32_16x16x32_bf16 v[80:83], v[206:209], v[230:233], v[24:27]
	v_mfma_f32_16x16x32_bf16 v[24:27], v[210:213], v[226:229], v[48:51]
	v_mfma_f32_16x16x32_bf16 v[84:87], v[214:217], v[230:233], v[24:27]
	v_mfma_f32_16x16x32_bf16 v[24:27], v[202:205], v[234:237], v[52:55]
	v_mfma_f32_16x16x32_bf16 v[48:51], v[206:209], v[238:241], v[24:27]
	v_mfma_f32_16x16x32_bf16 v[24:27], v[210:213], v[234:237], v[56:59]
	v_mfma_f32_16x16x32_bf16 v[112:115], v[206:209], v[28:31], v[72:75]
	v_mfma_f32_16x16x32_bf16 v[52:55], v[214:217], v[238:241], v[24:27]
	s_barrier
; template <class Epi, class Sched, bool ALIGN_EPI = false, bool SP2 = false, bool A_TILED = false>
; __device__ __forceinline__ void gemm_phase(PG8_LAS unsigned char* lds, const Gemm g, const Sched& S, const Epi& E, const int wave_s) {
;     ...
;         for (int t = PEEL ? 2 : 0; t < nt; t += 2) {
;             const bool last = (t == nt - 2);
;             const char* a1 = cA + (size_t)(t + 1) * kstepA;
;             const char* a2 = last ? nA : cA + (size_t)(t + 2) * kstepA; const char* b2 = last ? nB : cB + (size_t)(t + 2) * kstep;
;             const char* a3 = a2 + kstepA; const char* b3 = b2 + kstep;
;             if (last && has_next) S.a_ready(nxt);
	s_setprio 0
	s_add_i32 s79, s79, s15
	s_add_i32 s80, s79, 0x2000
	s_nop 1
	v_lshl_add_u64 v[24:25], v[242:243], 0, s[60:61]
	s_mov_b32 m0, s79
	s_add_u32 s76, s72, 0x80180
	ds_read_b128 v[32:35], v147 offset:49152
	ds_read_b128 v[36:39], v147 offset:50176
	ds_read_b128 v[218:221], v147 offset:51200
	ds_read_b128 v[222:225], v147 offset:52224
	ds_read_b128 v[226:229], v147 offset:53248
	ds_read_b128 v[230:233], v147 offset:54272
	ds_read_b128 v[234:237], v147 offset:55296
	ds_read_b128 v[238:241], v147 offset:56320
	global_load_lds_dwordx4 v[24:25], off
	v_lshl_add_u64 v[24:25], v[244:245], 0, s[60:61]
	s_mov_b32 m0, s80
	s_addc_u32 s77, s73, 0
	s_add_i32 s81, s81, s15
	global_load_lds_dwordx4 v[24:25], off
	v_lshl_add_u64 v[24:25], s[76:77], 0, v[128:129]
	s_mov_b32 m0, s81
	s_add_i32 s82, s81, 0x2000
	global_load_lds_dwordx4 v[24:25], off
	v_lshl_add_u64 v[24:25], s[76:77], 0, v[130:131]
	s_mov_b32 m0, s82
	s_nop 0
	global_load_lds_dwordx4 v[24:25], off
	v_lshl_add_u64 v[24:25], v[246:247], 0, s[60:61]
	s_mov_b32 m0, s43
	s_nop 0
	global_load_lds_dwordx4 v[24:25], off
	v_lshl_add_u64 v[24:25], v[248:249], 0, s[60:61]
	s_mov_b32 m0, s48
	s_nop 0
	global_load_lds_dwordx4 v[24:25], off
	s_waitcnt vmcnt(8) lgkmcnt(0)
	s_setprio 1
	s_barrier
	v_mfma_f32_16x16x32_bf16 v[24:27], v[8:11], v[32:35], v[150:153]
	v_mfma_f32_16x16x32_bf16 v[72:75], v[12:15], v[36:39], v[24:27]
	v_mfma_f32_16x16x32_bf16 v[24:27], v[16:19], v[32:35], v[154:157]
	v_mfma_f32_16x16x32_bf16 v[76:79], v[20:23], v[36:39], v[24:27]
	v_mfma_f32_16x16x32_bf16 v[24:27], v[8:11], v[218:221], v[158:161]
	v_mfma_f32_16x16x32_bf16 v[40:43], v[12:15], v[222:225], v[24:27]
	v_mfma_f32_16x16x32_bf16 v[24:27], v[16:19], v[218:221], v[162:165]
	v_mfma_f32_16x16x32_bf16 v[0:3], v[8:11], v[234:237], v[0:3]
	v_mfma_f32_16x16x32_bf16 v[44:47], v[20:23], v[222:225], v[24:27]
	v_mfma_f32_16x16x32_bf16 v[24:27], v[8:11], v[226:229], v[166:169]
	v_mfma_f32_16x16x32_bf16 v[28:31], v[16:19], v[226:229], v[170:173]
	v_mfma_f32_16x16x32_bf16 v[8:11], v[12:15], v[238:241], v[0:3]
	v_mfma_f32_16x16x32_bf16 v[0:3], v[16:19], v[234:237], v[4:7]
	v_mfma_f32_16x16x32_bf16 v[24:27], v[12:15], v[230:233], v[24:27]
	v_mfma_f32_16x16x32_bf16 v[28:31], v[20:23], v[230:233], v[28:31]
	v_mfma_f32_16x16x32_bf16 v[12:15], v[20:23], v[238:241], v[0:3]
	v_mfma_f32_16x16x32_bf16 v[0:3], v[202:205], v[32:35], v[174:177]
	v_mfma_f32_16x16x32_bf16 v[56:59], v[206:209], v[36:39], v[0:3]
	v_mfma_f32_16x16x32_bf16 v[0:3], v[210:213], v[32:35], v[60:63]
	v_mfma_f32_16x16x32_bf16 v[60:63], v[214:217], v[36:39], v[0:3]
	v_mfma_f32_16x16x32_bf16 v[0:3], v[202:205], v[218:221], v[178:181]
	v_mfma_f32_16x16x32_bf16 v[32:35], v[206:209], v[222:225], v[0:3]
	v_mfma_f32_16x16x32_bf16 v[0:3], v[210:213], v[218:221], v[182:185]
	v_mfma_f32_16x16x32_bf16 v[36:39], v[214:217], v[222:225], v[0:3]
	v_mfma_f32_16x16x32_bf16 v[0:3], v[202:205], v[226:229], v[186:189]
	v_mfma_f32_16x16x32_bf16 v[16:19], v[206:209], v[230:233], v[0:3]
	v_mfma_f32_16x16x32_bf16 v[0:3], v[210:213], v[226:229], v[190:193]
	v_mfma_f32_16x16x32_bf16 v[20:23], v[214:217], v[230:233], v[0:3]
	v_mfma_f32_16x16x32_bf16 v[0:3], v[202:205], v[234:237], v[194:197]
	v_mfma_f32_16x16x32_bf16 v[4:7], v[210:213], v[234:237], v[198:201]
	v_mfma_f32_16x16x32_bf16 v[0:3], v[206:209], v[238:241], v[0:3]
	v_mfma_f32_16x16x32_bf16 v[4:7], v[214:217], v[238:241], v[4:7]
	s_barrier
	s_setprio 0
	s_add_u32 s83, s72, 0x200
	s_addc_u32 s85, s73, 0
	s_add_u32 s72, s74, 0x80180
	s_addc_u32 s73, s75, 0
	s_mov_b32 s88, 0
.LBB0_2841:
	ds_read_b128 v[150:153], v145
	ds_read_b128 v[154:157], v145 offset:1024
	ds_read_b128 v[158:161], v145 offset:2048
	ds_read_b128 v[162:165], v145 offset:3072
	ds_read_b128 v[166:169], v146
	ds_read_b128 v[170:173], v146 offset:1024
	ds_read_b128 v[174:177], v146 offset:2048
	ds_read_b128 v[178:181], v146 offset:3072
	s_add_u32 s74, s72, 0xfff80080
	s_addc_u32 s75, s73, -1
	s_cmp_eq_u32 s88, 28
	s_cselect_b32 s77, s54, s75
	s_cselect_b32 s76, s55, s74
	s_cselect_b32 s75, s56, s85
	s_cselect_b32 s74, s57, s83
	s_mov_b32 m0, s58
	v_lshl_add_u64 v[214:215], s[72:73], 0, v[138:139]
	ds_read_b128 v[182:185], v147
	ds_read_b128 v[186:189], v147 offset:1024
	ds_read_b128 v[190:193], v147 offset:2048
	ds_read_b128 v[194:197], v147 offset:3072
	ds_read_b128 v[198:201], v147 offset:4096
	ds_read_b128 v[202:205], v147 offset:5120
	ds_read_b128 v[206:209], v147 offset:6144
	ds_read_b128 v[210:213], v147 offset:7168
	global_load_lds_dwordx4 v[214:215], off
	v_lshl_add_u64 v[214:215], s[72:73], 0, v[136:137]
	s_mov_b32 m0, s59
	s_nop 0
	global_load_lds_dwordx4 v[214:215], off
	s_waitcnt vmcnt(8) lgkmcnt(0)
	s_setprio 1
	s_barrier
	v_mfma_f32_16x16x32_bf16 v[120:123], v[150:153], v[182:185], v[120:123]
	v_mfma_f32_16x16x32_bf16 v[124:127], v[158:161], v[182:185], v[124:127]
	v_mfma_f32_16x16x32_bf16 v[104:107], v[150:153], v[190:193], v[104:107]
	v_mfma_f32_16x16x32_bf16 v[108:111], v[158:161], v[190:193], v[108:111]
	v_mfma_f32_16x16x32_bf16 v[88:91], v[150:153], v[198:201], v[88:91]
	v_mfma_f32_16x16x32_bf16 v[92:95], v[158:161], v[198:201], v[92:95]
	v_mfma_f32_16x16x32_bf16 v[64:67], v[150:153], v[206:209], v[64:67]
	v_mfma_f32_16x16x32_bf16 v[68:71], v[158:161], v[206:209], v[68:71]
	v_mfma_f32_16x16x32_bf16 v[120:123], v[154:157], v[186:189], v[120:123]
	v_mfma_f32_16x16x32_bf16 v[124:127], v[162:165], v[186:189], v[124:127]
	v_mfma_f32_16x16x32_bf16 v[104:107], v[154:157], v[194:197], v[104:107]
	v_mfma_f32_16x16x32_bf16 v[108:111], v[162:165], v[194:197], v[108:111]
	v_mfma_f32_16x16x32_bf16 v[88:91], v[154:157], v[202:205], v[88:91]
	v_mfma_f32_16x16x32_bf16 v[92:95], v[162:165], v[202:205], v[92:95]
	v_mfma_f32_16x16x32_bf16 v[64:67], v[154:157], v[210:213], v[64:67]
	v_mfma_f32_16x16x32_bf16 v[68:71], v[162:165], v[210:213], v[68:71]
	v_mfma_f32_16x16x32_bf16 v[112:115], v[166:169], v[182:185], v[112:115]
	v_mfma_f32_16x16x32_bf16 v[116:119], v[174:177], v[182:185], v[116:119]
	v_mfma_f32_16x16x32_bf16 v[96:99], v[166:169], v[190:193], v[96:99]
	v_mfma_f32_16x16x32_bf16 v[100:103], v[174:177], v[190:193], v[100:103]
	v_mfma_f32_16x16x32_bf16 v[80:83], v[166:169], v[198:201], v[80:83]
	v_mfma_f32_16x16x32_bf16 v[84:87], v[174:177], v[198:201], v[84:87]
	v_mfma_f32_16x16x32_bf16 v[48:51], v[166:169], v[206:209], v[48:51]
	v_mfma_f32_16x16x32_bf16 v[52:55], v[174:177], v[206:209], v[52:55]
	v_mfma_f32_16x16x32_bf16 v[112:115], v[170:173], v[186:189], v[112:115]
	v_mfma_f32_16x16x32_bf16 v[116:119], v[178:181], v[186:189], v[116:119]
	v_mfma_f32_16x16x32_bf16 v[96:99], v[170:173], v[194:197], v[96:99]
	v_mfma_f32_16x16x32_bf16 v[100:103], v[178:181], v[194:197], v[100:103]
	v_mfma_f32_16x16x32_bf16 v[80:83], v[170:173], v[202:205], v[80:83]
	v_mfma_f32_16x16x32_bf16 v[84:87], v[178:181], v[202:205], v[84:87]
	v_mfma_f32_16x16x32_bf16 v[48:51], v[170:173], v[210:213], v[48:51]
	v_mfma_f32_16x16x32_bf16 v[52:55], v[178:181], v[210:213], v[52:55]
	s_barrier
	s_setprio 0
	s_mov_b32 m0, s63
	v_lshl_add_u64 v[214:215], s[74:75], 0, v[128:129]
	s_add_u32 s90, s74, 0x80000
	ds_read_b128 v[182:185], v147 offset:16384
	ds_read_b128 v[186:189], v147 offset:17408
	ds_read_b128 v[190:193], v147 offset:18432
	ds_read_b128 v[194:197], v147 offset:19456
	ds_read_b128 v[198:201], v147 offset:20480
	ds_read_b128 v[202:205], v147 offset:21504
	ds_read_b128 v[206:209], v147 offset:22528
	ds_read_b128 v[210:213], v147 offset:23552
	global_load_lds_dwordx4 v[214:215], off
	v_lshl_add_u64 v[216:217], s[74:75], 0, v[130:131]
	s_mov_b32 m0, s65
	s_addc_u32 s91, s75, 0
	global_load_lds_dwordx4 v[216:217], off
	v_lshl_add_u64 v[218:219], s[90:91], 0, v[128:129]
	s_mov_b32 m0, s71
	v_lshl_add_u64 v[220:221], s[76:77], 0, v[132:133]
	global_load_lds_dwordx4 v[218:219], off
	v_lshl_add_u64 v[218:219], s[90:91], 0, v[130:131]
	s_mov_b32 m0, s78
	s_nop 0
	global_load_lds_dwordx4 v[218:219], off
	v_lshl_add_u64 v[218:219], s[76:77], 0, v[134:135]
	s_mov_b32 m0, s22
	s_nop 0
	global_load_lds_dwordx4 v[218:219], off
	s_mov_b32 m0, s23
	s_nop 0
	global_load_lds_dwordx4 v[220:221], off
	s_waitcnt vmcnt(8) lgkmcnt(0)
	s_setprio 1
	s_barrier
	v_mfma_f32_16x16x32_bf16 v[72:75], v[150:153], v[182:185], v[72:75]
	v_mfma_f32_16x16x32_bf16 v[76:79], v[158:161], v[182:185], v[76:79]
	v_mfma_f32_16x16x32_bf16 v[40:43], v[150:153], v[190:193], v[40:43]
	v_mfma_f32_16x16x32_bf16 v[44:47], v[158:161], v[190:193], v[44:47]
	v_mfma_f32_16x16x32_bf16 v[24:27], v[150:153], v[198:201], v[24:27]
	v_mfma_f32_16x16x32_bf16 v[28:31], v[158:161], v[198:201], v[28:31]
	v_mfma_f32_16x16x32_bf16 v[8:11], v[150:153], v[206:209], v[8:11]
	v_mfma_f32_16x16x32_bf16 v[12:15], v[158:161], v[206:209], v[12:15]
	v_mfma_f32_16x16x32_bf16 v[72:75], v[154:157], v[186:189], v[72:75]
	v_mfma_f32_16x16x32_bf16 v[76:79], v[162:165], v[186:189], v[76:79]
	v_mfma_f32_16x16x32_bf16 v[40:43], v[154:157], v[194:197], v[40:43]
	v_mfma_f32_16x16x32_bf16 v[44:47], v[162:165], v[194:197], v[44:47]
	v_mfma_f32_16x16x32_bf16 v[24:27], v[154:157], v[202:205], v[24:27]
	v_mfma_f32_16x16x32_bf16 v[28:31], v[162:165], v[202:205], v[28:31]
	v_mfma_f32_16x16x32_bf16 v[8:11], v[154:157], v[210:213], v[8:11]
	v_mfma_f32_16x16x32_bf16 v[12:15], v[162:165], v[210:213], v[12:15]
	v_mfma_f32_16x16x32_bf16 v[56:59], v[166:169], v[182:185], v[56:59]
	v_mfma_f32_16x16x32_bf16 v[60:63], v[174:177], v[182:185], v[60:63]
	v_mfma_f32_16x16x32_bf16 v[32:35], v[166:169], v[190:193], v[32:35]
	v_mfma_f32_16x16x32_bf16 v[36:39], v[174:177], v[190:193], v[36:39]
	v_mfma_f32_16x16x32_bf16 v[16:19], v[166:169], v[198:201], v[16:19]
	v_mfma_f32_16x16x32_bf16 v[20:23], v[174:177], v[198:201], v[20:23]
	v_mfma_f32_16x16x32_bf16 v[0:3], v[166:169], v[206:209], v[0:3]
	v_mfma_f32_16x16x32_bf16 v[4:7], v[174:177], v[206:209], v[4:7]
	v_mfma_f32_16x16x32_bf16 v[56:59], v[170:173], v[186:189], v[56:59]
	v_mfma_f32_16x16x32_bf16 v[60:63], v[178:181], v[186:189], v[60:63]
	v_mfma_f32_16x16x32_bf16 v[32:35], v[170:173], v[194:197], v[32:35]
	v_mfma_f32_16x16x32_bf16 v[36:39], v[178:181], v[194:197], v[36:39]
	v_mfma_f32_16x16x32_bf16 v[16:19], v[170:173], v[202:205], v[16:19]
	v_mfma_f32_16x16x32_bf16 v[20:23], v[178:181], v[202:205], v[20:23]
	v_mfma_f32_16x16x32_bf16 v[0:3], v[170:173], v[210:213], v[0:3]
	v_mfma_f32_16x16x32_bf16 v[4:7], v[178:181], v[210:213], v[4:7]
	s_barrier
	s_setprio 0
	ds_read_b128 v[150:153], v148
	ds_read_b128 v[154:157], v148 offset:1024
	ds_read_b128 v[158:161], v148 offset:2048
	ds_read_b128 v[162:165], v148 offset:3072
	ds_read_b128 v[166:169], v149
	ds_read_b128 v[170:173], v149 offset:1024
	ds_read_b128 v[174:177], v149 offset:2048
	ds_read_b128 v[178:181], v149 offset:3072
	s_add_u32 s76, s76, 0x80000
	s_addc_u32 s77, s77, 0
	s_mov_b32 m0, s36
	v_lshl_add_u64 v[222:223], s[76:77], 0, v[134:135]
	ds_read_b128 v[182:185], v147 offset:32768
	ds_read_b128 v[186:189], v147 offset:33792
	ds_read_b128 v[190:193], v147 offset:34816
	ds_read_b128 v[194:197], v147 offset:35840
	ds_read_b128 v[198:201], v147 offset:36864
	ds_read_b128 v[202:205], v147 offset:37888
	ds_read_b128 v[206:209], v147 offset:38912
	ds_read_b128 v[210:213], v147 offset:39936
	global_load_lds_dwordx4 v[222:223], off
	v_lshl_add_u64 v[222:223], s[76:77], 0, v[132:133]
	s_mov_b32 m0, s37
	s_nop 0
	global_load_lds_dwordx4 v[222:223], off
	s_waitcnt vmcnt(8) lgkmcnt(0)
	s_setprio 1
	s_barrier
	v_mfma_f32_16x16x32_bf16 v[120:123], v[150:153], v[182:185], v[120:123]
	v_mfma_f32_16x16x32_bf16 v[124:127], v[158:161], v[182:185], v[124:127]
	v_mfma_f32_16x16x32_bf16 v[104:107], v[150:153], v[190:193], v[104:107]
	v_mfma_f32_16x16x32_bf16 v[108:111], v[158:161], v[190:193], v[108:111]
	v_mfma_f32_16x16x32_bf16 v[88:91], v[150:153], v[198:201], v[88:91]
	v_mfma_f32_16x16x32_bf16 v[92:95], v[158:161], v[198:201], v[92:95]
	v_mfma_f32_16x16x32_bf16 v[64:67], v[150:153], v[206:209], v[64:67]
	v_mfma_f32_16x16x32_bf16 v[68:71], v[158:161], v[206:209], v[68:71]
	v_mfma_f32_16x16x32_bf16 v[120:123], v[154:157], v[186:189], v[120:123]
	v_mfma_f32_16x16x32_bf16 v[124:127], v[162:165], v[186:189], v[124:127]
	v_mfma_f32_16x16x32_bf16 v[104:107], v[154:157], v[194:197], v[104:107]
	v_mfma_f32_16x16x32_bf16 v[108:111], v[162:165], v[194:197], v[108:111]
	v_mfma_f32_16x16x32_bf16 v[88:91], v[154:157], v[202:205], v[88:91]
	v_mfma_f32_16x16x32_bf16 v[92:95], v[162:165], v[202:205], v[92:95]
	v_mfma_f32_16x16x32_bf16 v[64:67], v[154:157], v[210:213], v[64:67]
	v_mfma_f32_16x16x32_bf16 v[68:71], v[162:165], v[210:213], v[68:71]
	v_mfma_f32_16x16x32_bf16 v[112:115], v[166:169], v[182:185], v[112:115]
	v_mfma_f32_16x16x32_bf16 v[116:119], v[174:177], v[182:185], v[116:119]
	v_mfma_f32_16x16x32_bf16 v[96:99], v[166:169], v[190:193], v[96:99]
	v_mfma_f32_16x16x32_bf16 v[100:103], v[174:177], v[190:193], v[100:103]
	v_mfma_f32_16x16x32_bf16 v[80:83], v[166:169], v[198:201], v[80:83]
	v_mfma_f32_16x16x32_bf16 v[84:87], v[174:177], v[198:201], v[84:87]
	v_mfma_f32_16x16x32_bf16 v[48:51], v[166:169], v[206:209], v[48:51]
	v_mfma_f32_16x16x32_bf16 v[52:55], v[174:177], v[206:209], v[52:55]
	v_mfma_f32_16x16x32_bf16 v[112:115], v[170:173], v[186:189], v[112:115]
	v_mfma_f32_16x16x32_bf16 v[116:119], v[178:181], v[186:189], v[116:119]
	v_mfma_f32_16x16x32_bf16 v[96:99], v[170:173], v[194:197], v[96:99]
	v_mfma_f32_16x16x32_bf16 v[100:103], v[178:181], v[194:197], v[100:103]
	v_mfma_f32_16x16x32_bf16 v[80:83], v[170:173], v[202:205], v[80:83]
	v_mfma_f32_16x16x32_bf16 v[84:87], v[178:181], v[202:205], v[84:87]
	v_mfma_f32_16x16x32_bf16 v[48:51], v[170:173], v[210:213], v[48:51]
	v_mfma_f32_16x16x32_bf16 v[52:55], v[178:181], v[210:213], v[52:55]
	s_barrier
	s_setprio 0
	s_mov_b32 m0, s79
	v_lshl_add_u64 v[214:215], v[214:215], 0, s[12:13]
	s_add_u32 s74, s74, 0x80080
	ds_read_b128 v[182:185], v147 offset:49152
	ds_read_b128 v[186:189], v147 offset:50176
	ds_read_b128 v[190:193], v147 offset:51200
	ds_read_b128 v[194:197], v147 offset:52224
	ds_read_b128 v[198:201], v147 offset:53248
	ds_read_b128 v[202:205], v147 offset:54272
	ds_read_b128 v[206:209], v147 offset:55296
	ds_read_b128 v[210:213], v147 offset:56320
	global_load_lds_dwordx4 v[214:215], off
	v_lshl_add_u64 v[214:215], v[216:217], 0, s[12:13]
	s_mov_b32 m0, s80
	s_addc_u32 s75, s75, 0
	global_load_lds_dwordx4 v[214:215], off
	v_lshl_add_u64 v[214:215], s[74:75], 0, v[128:129]
	s_mov_b32 m0, s81
	s_nop 0
	global_load_lds_dwordx4 v[214:215], off
	v_lshl_add_u64 v[214:215], s[74:75], 0, v[130:131]
	s_mov_b32 m0, s82
	s_nop 0
	global_load_lds_dwordx4 v[214:215], off
	v_lshl_add_u64 v[214:215], v[218:219], 0, s[12:13]
	s_mov_b32 m0, s43
	s_nop 0
	global_load_lds_dwordx4 v[214:215], off
	v_lshl_add_u64 v[214:215], v[220:221], 0, s[12:13]
	s_mov_b32 m0, s48
	s_nop 0
	global_load_lds_dwordx4 v[214:215], off
	s_waitcnt vmcnt(8) lgkmcnt(0)
	s_setprio 1
	s_barrier
	v_mfma_f32_16x16x32_bf16 v[72:75], v[150:153], v[182:185], v[72:75]
	v_mfma_f32_16x16x32_bf16 v[76:79], v[158:161], v[182:185], v[76:79]
	v_mfma_f32_16x16x32_bf16 v[40:43], v[150:153], v[190:193], v[40:43]
	v_mfma_f32_16x16x32_bf16 v[44:47], v[158:161], v[190:193], v[44:47]
	v_mfma_f32_16x16x32_bf16 v[24:27], v[150:153], v[198:201], v[24:27]
	v_mfma_f32_16x16x32_bf16 v[28:31], v[158:161], v[198:201], v[28:31]
	v_mfma_f32_16x16x32_bf16 v[8:11], v[150:153], v[206:209], v[8:11]
	v_mfma_f32_16x16x32_bf16 v[12:15], v[158:161], v[206:209], v[12:15]
	v_mfma_f32_16x16x32_bf16 v[72:75], v[154:157], v[186:189], v[72:75]
	v_mfma_f32_16x16x32_bf16 v[76:79], v[162:165], v[186:189], v[76:79]
	v_mfma_f32_16x16x32_bf16 v[40:43], v[154:157], v[194:197], v[40:43]
	v_mfma_f32_16x16x32_bf16 v[44:47], v[162:165], v[194:197], v[44:47]
	v_mfma_f32_16x16x32_bf16 v[24:27], v[154:157], v[202:205], v[24:27]
	v_mfma_f32_16x16x32_bf16 v[28:31], v[162:165], v[202:205], v[28:31]
	v_mfma_f32_16x16x32_bf16 v[8:11], v[154:157], v[210:213], v[8:11]
	v_mfma_f32_16x16x32_bf16 v[12:15], v[162:165], v[210:213], v[12:15]
	v_mfma_f32_16x16x32_bf16 v[56:59], v[166:169], v[182:185], v[56:59]
	v_mfma_f32_16x16x32_bf16 v[60:63], v[174:177], v[182:185], v[60:63]
	v_mfma_f32_16x16x32_bf16 v[32:35], v[166:169], v[190:193], v[32:35]
	v_mfma_f32_16x16x32_bf16 v[36:39], v[174:177], v[190:193], v[36:39]
	v_mfma_f32_16x16x32_bf16 v[16:19], v[166:169], v[198:201], v[16:19]
	v_mfma_f32_16x16x32_bf16 v[20:23], v[174:177], v[198:201], v[20:23]
	v_mfma_f32_16x16x32_bf16 v[0:3], v[166:169], v[206:209], v[0:3]
	v_mfma_f32_16x16x32_bf16 v[4:7], v[174:177], v[206:209], v[4:7]
	v_mfma_f32_16x16x32_bf16 v[56:59], v[170:173], v[186:189], v[56:59]
	v_mfma_f32_16x16x32_bf16 v[60:63], v[178:181], v[186:189], v[60:63]
	v_mfma_f32_16x16x32_bf16 v[32:35], v[170:173], v[194:197], v[32:35]
	v_mfma_f32_16x16x32_bf16 v[36:39], v[178:181], v[194:197], v[36:39]
	v_mfma_f32_16x16x32_bf16 v[16:19], v[170:173], v[202:205], v[16:19]
	v_mfma_f32_16x16x32_bf16 v[20:23], v[178:181], v[202:205], v[20:23]
	v_mfma_f32_16x16x32_bf16 v[0:3], v[170:173], v[210:213], v[0:3]
	v_mfma_f32_16x16x32_bf16 v[4:7], v[178:181], v[210:213], v[4:7]
	s_barrier
	s_setprio 0
	s_add_i32 s88, s88, 2
	s_add_u32 s83, s83, 0x100
	s_addc_u32 s85, s85, 0
	s_add_u32 s72, s72, 0x100
	s_addc_u32 s73, s73, 0
	s_cmp_gt_u32 s88, 29
	s_cbranch_scc0 .LBB0_2841
	s_and_b64 vcc, exec, s[44:45]
	s_cbranch_vccz .LBB0_2844
	s_barrier

; template <class Epi, class Sched, bool ALIGN_EPI = false, bool SP2 = false, bool A_TILED = false>
; __device__ __forceinline__ void gemm_phase(PG8_LAS unsigned char* lds, const Gemm g, const Sched& S, const Epi& E, const int wave_s) {
;     ...
;         for (int t = PEEL ? 2 : 0; t < nt; t += 2) {
;             const bool last = (t == nt - 2);
;             const char* a1 = cA + (size_t)(t + 1) * kstepA;
;             const char* a2 = last ? nA : cA + (size_t)(t + 2) * kstepA; const char* b2 = last ? nB : cB + (size_t)(t + 2) * kstep;
;             const char* a3 = a2 + kstepA; const char* b3 = b2 + kstep;
;             if (last && has_next) S.a_ready(nxt);
.LBB0_2914:
	ds_read_b128 v[146:149], v140
	ds_read_b128 v[150:153], v140 offset:1024
	ds_read_b128 v[154:157], v140 offset:2048
	ds_read_b128 v[158:161], v140 offset:3072
	ds_read_b128 v[162:165], v141
	ds_read_b128 v[166:169], v141 offset:1024
	ds_read_b128 v[170:173], v141 offset:2048
	ds_read_b128 v[174:177], v141 offset:3072
	s_add_u32 s55, s44, s39
	s_addc_u32 s56, s45, s40
	s_add_u32 s57, s44, s37
	s_addc_u32 s58, s45, s38
	s_cmpk_eq_i32 s41, 0x7c
	s_cselect_b32 s68, s6, s55
	s_cselect_b32 s69, s7, s56
	s_cselect_b32 s66, s2, s57
	s_cselect_b32 s67, s3, s58
	s_add_u32 s64, s68, 0x8000
	s_addc_u32 s65, s69, 0
	s_mov_b32 m0, s42
	v_lshl_add_u64 v[210:211], s[44:45], 0, v[138:139]
	ds_read_b128 v[178:181], v142
	ds_read_b128 v[182:185], v142 offset:1024
	ds_read_b128 v[186:189], v142 offset:2048
	ds_read_b128 v[190:193], v142 offset:3072
	ds_read_b128 v[194:197], v142 offset:4096
	ds_read_b128 v[198:201], v142 offset:5120
	ds_read_b128 v[202:205], v142 offset:6144
	ds_read_b128 v[206:209], v142 offset:7168
	global_load_lds_dwordx4 v[210:211], off
	v_lshl_add_u64 v[210:211], s[44:45], 0, v[136:137]
	s_mov_b32 m0, s43
	s_nop 0
	global_load_lds_dwordx4 v[210:211], off
	s_waitcnt vmcnt(8) lgkmcnt(0)
	s_setprio 1
	s_barrier
	v_mfma_f32_16x16x32_bf16 v[8:11], v[146:149], v[178:181], v[8:11]
	v_mfma_f32_16x16x32_bf16 v[12:15], v[154:157], v[178:181], v[12:15]
	v_mfma_f32_16x16x32_bf16 v[60:63], v[146:149], v[186:189], v[60:63]
	v_mfma_f32_16x16x32_bf16 v[20:23], v[154:157], v[186:189], v[20:23]
	v_mfma_f32_16x16x32_bf16 v[76:79], v[146:149], v[194:197], v[76:79]
	v_mfma_f32_16x16x32_bf16 v[52:55], v[154:157], v[194:197], v[52:55]
	v_mfma_f32_16x16x32_bf16 v[128:131], v[146:149], v[202:205], v[128:131]
	v_mfma_f32_16x16x32_bf16 v[68:71], v[154:157], v[202:205], v[68:71]
	v_mfma_f32_16x16x32_bf16 v[8:11], v[150:153], v[182:185], v[8:11]
	v_mfma_f32_16x16x32_bf16 v[12:15], v[158:161], v[182:185], v[12:15]
	v_mfma_f32_16x16x32_bf16 v[60:63], v[150:153], v[190:193], v[60:63]
	v_mfma_f32_16x16x32_bf16 v[20:23], v[158:161], v[190:193], v[20:23]
	v_mfma_f32_16x16x32_bf16 v[76:79], v[150:153], v[198:201], v[76:79]
	v_mfma_f32_16x16x32_bf16 v[52:55], v[158:161], v[198:201], v[52:55]
	v_mfma_f32_16x16x32_bf16 v[128:131], v[150:153], v[206:209], v[128:131]
	v_mfma_f32_16x16x32_bf16 v[68:71], v[158:161], v[206:209], v[68:71]
	v_mfma_f32_16x16x32_bf16 v[28:31], v[162:165], v[178:181], v[28:31]
	v_mfma_f32_16x16x32_bf16 v[16:19], v[170:173], v[178:181], v[16:19]
	v_mfma_f32_16x16x32_bf16 v[56:59], v[162:165], v[186:189], v[56:59]
	v_mfma_f32_16x16x32_bf16 v[48:51], v[170:173], v[186:189], v[48:51]
	v_mfma_f32_16x16x32_bf16 v[72:75], v[162:165], v[194:197], v[72:75]
	v_mfma_f32_16x16x32_bf16 v[64:67], v[170:173], v[194:197], v[64:67]
	v_mfma_f32_16x16x32_bf16 v[108:111], v[162:165], v[202:205], v[108:111]
	v_mfma_f32_16x16x32_bf16 v[96:99], v[170:173], v[202:205], v[96:99]
	v_mfma_f32_16x16x32_bf16 v[28:31], v[166:169], v[182:185], v[28:31]
	v_mfma_f32_16x16x32_bf16 v[16:19], v[174:177], v[182:185], v[16:19]
	v_mfma_f32_16x16x32_bf16 v[56:59], v[166:169], v[190:193], v[56:59]
	v_mfma_f32_16x16x32_bf16 v[48:51], v[174:177], v[190:193], v[48:51]
	v_mfma_f32_16x16x32_bf16 v[72:75], v[166:169], v[198:201], v[72:75]
	v_mfma_f32_16x16x32_bf16 v[64:67], v[174:177], v[198:201], v[64:67]
	v_mfma_f32_16x16x32_bf16 v[108:111], v[166:169], v[206:209], v[108:111]
	v_mfma_f32_16x16x32_bf16 v[96:99], v[174:177], v[206:209], v[96:99]
	s_barrier
	s_setprio 0
	s_mov_b32 m0, s47
	v_lshl_add_u64 v[210:211], s[66:67], 0, v[34:35]
	s_add_u32 s56, s66, 0x200000
	ds_read_b128 v[178:181], v142 offset:16384
	ds_read_b128 v[182:185], v142 offset:17408
	ds_read_b128 v[186:189], v142 offset:18432
	ds_read_b128 v[190:193], v142 offset:19456
	ds_read_b128 v[194:197], v142 offset:20480
	ds_read_b128 v[198:201], v142 offset:21504
	ds_read_b128 v[202:205], v142 offset:22528
	ds_read_b128 v[206:209], v142 offset:23552
	global_load_lds_dwordx4 v[210:211], off
	v_lshl_add_u64 v[212:213], s[66:67], 0, v[134:135]
	s_mov_b32 m0, s48
	s_addc_u32 s57, s67, 0
	global_load_lds_dwordx4 v[212:213], off
	v_lshl_add_u64 v[214:215], s[56:57], 0, v[34:35]
	s_mov_b32 m0, s49
	s_nop 0
	global_load_lds_dwordx4 v[214:215], off
	v_lshl_add_u64 v[214:215], s[56:57], 0, v[134:135]
	s_mov_b32 m0, s50
	s_nop 0
	global_load_lds_dwordx4 v[214:215], off
	v_lshl_add_u64 v[214:215], s[68:69], 0, v[32:33]
	s_mov_b32 m0, s14
	s_nop 0
	global_load_lds_dwordx4 v[214:215], off
	v_lshl_add_u64 v[214:215], s[68:69], 0, v[132:133]
	s_mov_b32 m0, s15
	s_nop 0
	global_load_lds_dwordx4 v[214:215], off
	s_waitcnt vmcnt(8) lgkmcnt(0)
	s_setprio 1
	s_barrier
	v_mfma_f32_16x16x32_bf16 v[100:103], v[146:149], v[178:181], v[100:103]
	v_mfma_f32_16x16x32_bf16 v[104:107], v[154:157], v[178:181], v[104:107]
	v_mfma_f32_16x16x32_bf16 v[116:119], v[146:149], v[186:189], v[116:119]
	v_mfma_f32_16x16x32_bf16 v[120:123], v[154:157], v[186:189], v[120:123]
	v_mfma_f32_16x16x32_bf16 v[84:87], v[146:149], v[194:197], v[84:87]
	v_mfma_f32_16x16x32_bf16 v[80:83], v[154:157], v[194:197], v[80:83]
	v_mfma_f32_16x16x32_bf16 v[36:39], v[146:149], v[202:205], v[36:39]
	v_mfma_f32_16x16x32_bf16 v[24:27], v[154:157], v[202:205], v[24:27]
	v_mfma_f32_16x16x32_bf16 v[100:103], v[150:153], v[182:185], v[100:103]
	v_mfma_f32_16x16x32_bf16 v[104:107], v[158:161], v[182:185], v[104:107]
	v_mfma_f32_16x16x32_bf16 v[116:119], v[150:153], v[190:193], v[116:119]
	v_mfma_f32_16x16x32_bf16 v[120:123], v[158:161], v[190:193], v[120:123]
	v_mfma_f32_16x16x32_bf16 v[84:87], v[150:153], v[198:201], v[84:87]
	v_mfma_f32_16x16x32_bf16 v[80:83], v[158:161], v[198:201], v[80:83]
	v_mfma_f32_16x16x32_bf16 v[36:39], v[150:153], v[206:209], v[36:39]
	v_mfma_f32_16x16x32_bf16 v[24:27], v[158:161], v[206:209], v[24:27]
	v_mfma_f32_16x16x32_bf16 v[124:127], v[162:165], v[178:181], v[124:127]
	v_mfma_f32_16x16x32_bf16 v[112:115], v[170:173], v[178:181], v[112:115]
	v_mfma_f32_16x16x32_bf16 v[92:95], v[162:165], v[186:189], v[92:95]
	v_mfma_f32_16x16x32_bf16 v[88:91], v[170:173], v[186:189], v[88:91]
	v_mfma_f32_16x16x32_bf16 v[44:47], v[162:165], v[194:197], v[44:47]
	v_mfma_f32_16x16x32_bf16 v[40:43], v[170:173], v[194:197], v[40:43]
	v_mfma_f32_16x16x32_bf16 v[4:7], v[162:165], v[202:205], v[4:7]
	v_mfma_f32_16x16x32_bf16 v[0:3], v[170:173], v[202:205], v[0:3]
	v_mfma_f32_16x16x32_bf16 v[124:127], v[166:169], v[182:185], v[124:127]
	v_mfma_f32_16x16x32_bf16 v[112:115], v[174:177], v[182:185], v[112:115]
	v_mfma_f32_16x16x32_bf16 v[92:95], v[166:169], v[190:193], v[92:95]
	v_mfma_f32_16x16x32_bf16 v[88:91], v[174:177], v[190:193], v[88:91]
	v_mfma_f32_16x16x32_bf16 v[44:47], v[166:169], v[198:201], v[44:47]
	v_mfma_f32_16x16x32_bf16 v[40:43], v[174:177], v[198:201], v[40:43]
	v_mfma_f32_16x16x32_bf16 v[4:7], v[166:169], v[206:209], v[4:7]
	v_mfma_f32_16x16x32_bf16 v[0:3], v[174:177], v[206:209], v[0:3]
	s_barrier
	s_setprio 0
	ds_read_b128 v[146:149], v143
	ds_read_b128 v[150:153], v143 offset:1024
	ds_read_b128 v[154:157], v143 offset:2048
	ds_read_b128 v[158:161], v143 offset:3072
	ds_read_b128 v[162:165], v144
	ds_read_b128 v[166:169], v144 offset:1024
	ds_read_b128 v[170:173], v144 offset:2048
	ds_read_b128 v[174:177], v144 offset:3072
	s_add_u32 s56, s68, 0x4000
	s_addc_u32 s57, s69, 0
	s_mov_b32 m0, s21
	v_lshl_add_u64 v[214:215], s[56:57], 0, v[32:33]
	ds_read_b128 v[178:181], v142 offset:32768
	ds_read_b128 v[182:185], v142 offset:33792
	ds_read_b128 v[186:189], v142 offset:34816
	ds_read_b128 v[190:193], v142 offset:35840
	ds_read_b128 v[194:197], v142 offset:36864
	ds_read_b128 v[198:201], v142 offset:37888
	ds_read_b128 v[202:205], v142 offset:38912
	ds_read_b128 v[206:209], v142 offset:39936
	global_load_lds_dwordx4 v[214:215], off
	v_lshl_add_u64 v[214:215], s[56:57], 0, v[132:133]
	s_mov_b32 m0, s22
	s_nop 0
	global_load_lds_dwordx4 v[214:215], off
	s_waitcnt vmcnt(8) lgkmcnt(0)
	s_setprio 1
	s_barrier
	v_mfma_f32_16x16x32_bf16 v[8:11], v[146:149], v[178:181], v[8:11]
	v_mfma_f32_16x16x32_bf16 v[12:15], v[154:157], v[178:181], v[12:15]
	v_mfma_f32_16x16x32_bf16 v[60:63], v[146:149], v[186:189], v[60:63]
	v_mfma_f32_16x16x32_bf16 v[20:23], v[154:157], v[186:189], v[20:23]
	v_mfma_f32_16x16x32_bf16 v[76:79], v[146:149], v[194:197], v[76:79]
	v_mfma_f32_16x16x32_bf16 v[52:55], v[154:157], v[194:197], v[52:55]
	v_mfma_f32_16x16x32_bf16 v[128:131], v[146:149], v[202:205], v[128:131]
	v_mfma_f32_16x16x32_bf16 v[68:71], v[154:157], v[202:205], v[68:71]
	v_mfma_f32_16x16x32_bf16 v[8:11], v[150:153], v[182:185], v[8:11]
	v_mfma_f32_16x16x32_bf16 v[12:15], v[158:161], v[182:185], v[12:15]
	v_mfma_f32_16x16x32_bf16 v[60:63], v[150:153], v[190:193], v[60:63]
	v_mfma_f32_16x16x32_bf16 v[20:23], v[158:161], v[190:193], v[20:23]
	v_mfma_f32_16x16x32_bf16 v[76:79], v[150:153], v[198:201], v[76:79]
	v_mfma_f32_16x16x32_bf16 v[52:55], v[158:161], v[198:201], v[52:55]
	v_mfma_f32_16x16x32_bf16 v[128:131], v[150:153], v[206:209], v[128:131]
	v_mfma_f32_16x16x32_bf16 v[68:71], v[158:161], v[206:209], v[68:71]
	v_mfma_f32_16x16x32_bf16 v[28:31], v[162:165], v[178:181], v[28:31]
	v_mfma_f32_16x16x32_bf16 v[16:19], v[170:173], v[178:181], v[16:19]
	v_mfma_f32_16x16x32_bf16 v[56:59], v[162:165], v[186:189], v[56:59]
	v_mfma_f32_16x16x32_bf16 v[48:51], v[170:173], v[186:189], v[48:51]
	v_mfma_f32_16x16x32_bf16 v[72:75], v[162:165], v[194:197], v[72:75]
	v_mfma_f32_16x16x32_bf16 v[64:67], v[170:173], v[194:197], v[64:67]
	v_mfma_f32_16x16x32_bf16 v[108:111], v[162:165], v[202:205], v[108:111]
	v_mfma_f32_16x16x32_bf16 v[96:99], v[170:173], v[202:205], v[96:99]
	v_mfma_f32_16x16x32_bf16 v[28:31], v[166:169], v[182:185], v[28:31]
	v_mfma_f32_16x16x32_bf16 v[16:19], v[174:177], v[182:185], v[16:19]
	v_mfma_f32_16x16x32_bf16 v[56:59], v[166:169], v[190:193], v[56:59]
	v_mfma_f32_16x16x32_bf16 v[48:51], v[174:177], v[190:193], v[48:51]
	v_mfma_f32_16x16x32_bf16 v[72:75], v[166:169], v[198:201], v[72:75]
	v_mfma_f32_16x16x32_bf16 v[64:67], v[174:177], v[198:201], v[64:67]
	v_mfma_f32_16x16x32_bf16 v[108:111], v[166:169], v[206:209], v[108:111]
	v_mfma_f32_16x16x32_bf16 v[96:99], v[174:177], v[206:209], v[96:99]
	s_barrier
	s_setprio 0
	s_mov_b32 m0, s51
	v_lshl_add_u64 v[210:211], v[210:211], 0, s[60:61]
	s_add_u32 s56, s66, 0x200080
	ds_read_b128 v[178:181], v142 offset:49152
	ds_read_b128 v[182:185], v142 offset:50176
	ds_read_b128 v[186:189], v142 offset:51200
	ds_read_b128 v[190:193], v142 offset:52224
	ds_read_b128 v[194:197], v142 offset:53248
	ds_read_b128 v[198:201], v142 offset:54272
	ds_read_b128 v[202:205], v142 offset:55296
	ds_read_b128 v[206:209], v142 offset:56320
	global_load_lds_dwordx4 v[210:211], off
	v_lshl_add_u64 v[210:211], v[212:213], 0, s[60:61]
	s_mov_b32 m0, s52
	s_addc_u32 s57, s67, 0
	global_load_lds_dwordx4 v[210:211], off
	v_lshl_add_u64 v[210:211], s[56:57], 0, v[34:35]
	s_mov_b32 m0, s53
	s_nop 0
	global_load_lds_dwordx4 v[210:211], off
	v_lshl_add_u64 v[210:211], s[56:57], 0, v[134:135]
	s_mov_b32 m0, s54
	s_nop 0
	global_load_lds_dwordx4 v[210:211], off
	v_lshl_add_u64 v[210:211], s[64:65], 0, v[32:33]
	s_mov_b32 m0, s23
	s_nop 0
	global_load_lds_dwordx4 v[210:211], off
	v_lshl_add_u64 v[210:211], s[64:65], 0, v[132:133]
	s_mov_b32 m0, s36
	s_nop 0
	global_load_lds_dwordx4 v[210:211], off
	s_waitcnt vmcnt(8) lgkmcnt(0)
	s_setprio 1
	s_barrier
	v_mfma_f32_16x16x32_bf16 v[100:103], v[146:149], v[178:181], v[100:103]
	v_mfma_f32_16x16x32_bf16 v[104:107], v[154:157], v[178:181], v[104:107]
	v_mfma_f32_16x16x32_bf16 v[116:119], v[146:149], v[186:189], v[116:119]
	v_mfma_f32_16x16x32_bf16 v[120:123], v[154:157], v[186:189], v[120:123]
	v_mfma_f32_16x16x32_bf16 v[84:87], v[146:149], v[194:197], v[84:87]
	v_mfma_f32_16x16x32_bf16 v[80:83], v[154:157], v[194:197], v[80:83]
	v_mfma_f32_16x16x32_bf16 v[36:39], v[146:149], v[202:205], v[36:39]
	v_mfma_f32_16x16x32_bf16 v[24:27], v[154:157], v[202:205], v[24:27]
	v_mfma_f32_16x16x32_bf16 v[100:103], v[150:153], v[182:185], v[100:103]
	v_mfma_f32_16x16x32_bf16 v[104:107], v[158:161], v[182:185], v[104:107]
	v_mfma_f32_16x16x32_bf16 v[116:119], v[150:153], v[190:193], v[116:119]
	v_mfma_f32_16x16x32_bf16 v[120:123], v[158:161], v[190:193], v[120:123]
	v_mfma_f32_16x16x32_bf16 v[84:87], v[150:153], v[198:201], v[84:87]
	v_mfma_f32_16x16x32_bf16 v[80:83], v[158:161], v[198:201], v[80:83]
	v_mfma_f32_16x16x32_bf16 v[36:39], v[150:153], v[206:209], v[36:39]
	v_mfma_f32_16x16x32_bf16 v[24:27], v[158:161], v[206:209], v[24:27]
	v_mfma_f32_16x16x32_bf16 v[124:127], v[162:165], v[178:181], v[124:127]
	v_mfma_f32_16x16x32_bf16 v[112:115], v[170:173], v[178:181], v[112:115]
	v_mfma_f32_16x16x32_bf16 v[92:95], v[162:165], v[186:189], v[92:95]
	v_mfma_f32_16x16x32_bf16 v[88:91], v[170:173], v[186:189], v[88:91]
	v_mfma_f32_16x16x32_bf16 v[44:47], v[162:165], v[194:197], v[44:47]
	v_mfma_f32_16x16x32_bf16 v[40:43], v[170:173], v[194:197], v[40:43]
	v_mfma_f32_16x16x32_bf16 v[4:7], v[162:165], v[202:205], v[4:7]
	v_mfma_f32_16x16x32_bf16 v[0:3], v[170:173], v[202:205], v[0:3]
	v_mfma_f32_16x16x32_bf16 v[124:127], v[166:169], v[182:185], v[124:127]
	v_mfma_f32_16x16x32_bf16 v[112:115], v[174:177], v[182:185], v[112:115]
	v_mfma_f32_16x16x32_bf16 v[92:95], v[166:169], v[190:193], v[92:95]
	v_mfma_f32_16x16x32_bf16 v[88:91], v[174:177], v[190:193], v[88:91]
	v_mfma_f32_16x16x32_bf16 v[44:47], v[166:169], v[198:201], v[44:47]
	v_mfma_f32_16x16x32_bf16 v[40:43], v[174:177], v[198:201], v[40:43]
	v_mfma_f32_16x16x32_bf16 v[4:7], v[166:169], v[206:209], v[4:7]
	v_mfma_f32_16x16x32_bf16 v[0:3], v[174:177], v[206:209], v[0:3]
	s_barrier
	s_setprio 0
	s_add_i32 s41, s41, 2
	s_add_u32 s37, s37, 0x100
	s_addc_u32 s38, s38, 0
	s_add_u32 s39, s39, 0x10000
	s_addc_u32 s40, s40, 0
	v_lshl_add_u64 v[136:137], v[136:137], 0, s[62:63]
	s_cmpk_gt_u32 s41, 0x7d
	v_lshl_add_u64 v[138:139], v[138:139], 0, s[62:63]
	s_cbranch_scc0 .LBB0_2914
	s_waitcnt vmcnt(0)
	s_cmpk_lt_u32 s0, 0x100
	s_cbranch_scc0 .LBB0_2917
	s_barrier

; template <class Epi, class Sched, bool ALIGN_EPI = false, bool SP2 = false, bool A_TILED = false>
; __device__ __forceinline__ void gemm_phase(PG8_LAS unsigned char* lds, const Gemm g, const Sched& S, const Epi& E, const int wave_s) {
;     ...
;             const char* a1 = cA + kstepA; const char* a2 = cA + 2 * kstepA; const char* b2 = cB + 2 * kstep; const char* a3 = a2 + kstepA; const char* b3 = b2 + kstep;
;             PG8_ITER(PG8_MMAZ)
.LBB0_3341:
	s_ashr_i32 s25, s24, 31
	ds_read_b128 v[0:3], v149
	ds_read_b128 v[4:7], v149 offset:1024
	ds_read_b128 v[8:11], v149 offset:2048
	ds_read_b128 v[12:15], v149 offset:3072
	ds_read_b128 v[16:19], v150
	ds_read_b128 v[20:23], v150 offset:1024
	ds_read_b128 v[24:27], v150 offset:2048
	ds_read_b128 v[28:31], v150 offset:3072
	s_lshl_b64 s[26:27], s[24:25], 20
	s_add_u32 s26, s9, s26
	s_addc_u32 s27, s36, s27
	s_and_b64 s[38:39], s[0:1], exec
	s_cselect_b32 s25, s27, s45
	s_cselect_b32 s67, s26, s44
	s_ashr_i32 s23, s22, 31
	s_lshl_b64 s[38:39], s[22:23], 20
	s_add_u32 s38, s37, s38
	s_addc_u32 s39, s48, s39
	s_and_b64 s[46:47], s[0:1], exec
	s_cselect_b32 s23, s39, s43
	s_cselect_b32 s68, s38, s42
	s_add_u32 s46, s44, 0x80080
	s_addc_u32 s47, s45, 0
	s_mov_b32 m0, s64
	v_lshl_add_u64 v[64:65], s[46:47], 0, v[134:135]
	ds_read_b128 v[32:35], v151
	ds_read_b128 v[36:39], v151 offset:1024
	ds_read_b128 v[40:43], v151 offset:2048
	ds_read_b128 v[44:47], v151 offset:3072
	ds_read_b128 v[48:51], v151 offset:4096
	ds_read_b128 v[52:55], v151 offset:5120
	ds_read_b128 v[56:59], v151 offset:6144
	ds_read_b128 v[60:63], v151 offset:7168
	global_load_lds_dwordx4 v[64:65], off
	v_lshl_add_u64 v[64:65], s[46:47], 0, v[132:133]
	s_mov_b32 m0, s65
	s_nop 0
	global_load_lds_dwordx4 v[64:65], off
	s_waitcnt vmcnt(8) lgkmcnt(0)
	s_setprio 1
	s_barrier
	v_mfma_f32_16x16x32_bf16 v[88:91], v[0:3], v[56:59], 0
	v_mfma_f32_16x16x32_bf16 v[64:67], v[0:3], v[32:35], 0
	v_mfma_f32_16x16x32_bf16 v[68:71], v[8:11], v[32:35], 0
	v_mfma_f32_16x16x32_bf16 v[72:75], v[0:3], v[40:43], 0
	v_mfma_f32_16x16x32_bf16 v[76:79], v[8:11], v[40:43], 0
	v_mfma_f32_16x16x32_bf16 v[80:83], v[0:3], v[48:51], 0
	v_mfma_f32_16x16x32_bf16 v[84:87], v[8:11], v[48:51], 0
	v_mfma_f32_16x16x32_bf16 v[92:95], v[4:7], v[60:63], v[88:91]
	v_mfma_f32_16x16x32_bf16 v[88:91], v[8:11], v[56:59], 0
	v_mfma_f32_16x16x32_bf16 v[64:67], v[4:7], v[36:39], v[64:67]
	v_mfma_f32_16x16x32_bf16 v[68:71], v[12:15], v[36:39], v[68:71]
	v_mfma_f32_16x16x32_bf16 v[72:75], v[4:7], v[44:47], v[72:75]
	v_mfma_f32_16x16x32_bf16 v[76:79], v[12:15], v[44:47], v[76:79]
	v_mfma_f32_16x16x32_bf16 v[80:83], v[4:7], v[52:55], v[80:83]
	v_mfma_f32_16x16x32_bf16 v[84:87], v[12:15], v[52:55], v[84:87]
	v_mfma_f32_16x16x32_bf16 v[100:103], v[12:15], v[60:63], v[88:91]
	v_mfma_f32_16x16x32_bf16 v[88:91], v[16:19], v[32:35], 0
	v_mfma_f32_16x16x32_bf16 v[32:35], v[24:27], v[32:35], 0
	v_mfma_f32_16x16x32_bf16 v[108:111], v[20:23], v[36:39], v[88:91]
	v_mfma_f32_16x16x32_bf16 v[32:35], v[28:31], v[36:39], v[32:35]
	v_mfma_f32_16x16x32_bf16 v[36:39], v[16:19], v[40:43], 0
	v_mfma_f32_16x16x32_bf16 v[40:43], v[24:27], v[40:43], 0
	v_mfma_f32_16x16x32_bf16 v[36:39], v[20:23], v[44:47], v[36:39]
	v_mfma_f32_16x16x32_bf16 v[40:43], v[28:31], v[44:47], v[40:43]
	v_mfma_f32_16x16x32_bf16 v[44:47], v[16:19], v[48:51], 0
	v_mfma_f32_16x16x32_bf16 v[48:51], v[24:27], v[48:51], 0
	v_mfma_f32_16x16x32_bf16 v[44:47], v[20:23], v[52:55], v[44:47]
	v_mfma_f32_16x16x32_bf16 v[52:55], v[28:31], v[52:55], v[48:51]
	v_mfma_f32_16x16x32_bf16 v[48:51], v[16:19], v[56:59], 0
	v_mfma_f32_16x16x32_bf16 v[152:155], v[20:23], v[60:63], v[48:51]
	v_mfma_f32_16x16x32_bf16 v[48:51], v[24:27], v[56:59], 0
	v_mfma_f32_16x16x32_bf16 v[156:159], v[28:31], v[60:63], v[48:51]
	s_barrier
	s_setprio 0
	s_add_i32 s69, s61, s49
	v_lshl_add_u64 v[146:147], s[42:43], 0, v[128:129]
	s_add_i32 s70, s69, 0x2000
	v_lshl_add_u64 v[120:121], v[146:147], 0, s[20:21]
	s_mov_b32 m0, s69
	v_lshl_add_u64 v[252:253], s[42:43], 0, v[130:131]
	s_add_u32 s46, s42, 0x80100
	ds_read_b128 v[48:51], v151 offset:16384
	ds_read_b128 v[56:59], v151 offset:17408
	ds_read_b128 v[60:63], v151 offset:18432
	ds_read_b128 v[88:91], v151 offset:19456
	ds_read_b128 v[96:99], v151 offset:20480
	ds_read_b128 v[104:107], v151 offset:21504
	ds_read_b128 v[112:115], v151 offset:22528
	ds_read_b128 v[116:119], v151 offset:23552
	global_load_lds_dwordx4 v[120:121], off
	v_lshl_add_u64 v[120:121], v[252:253], 0, s[20:21]
	s_mov_b32 m0, s70
	s_addc_u32 s47, s43, 0
	s_add_i32 s71, s62, s49
	global_load_lds_dwordx4 v[120:121], off
	v_lshl_add_u64 v[120:121], s[46:47], 0, v[128:129]
	s_mov_b32 m0, s71
	s_add_i32 s72, s71, 0x2000
	global_load_lds_dwordx4 v[120:121], off
	v_lshl_add_u64 v[120:121], s[46:47], 0, v[130:131]
	s_mov_b32 m0, s72
	v_lshl_add_u64 v[140:141], s[44:45], 0, v[134:135]
	global_load_lds_dwordx4 v[120:121], off
	v_lshl_add_u64 v[120:121], v[140:141], 0, s[20:21]
	s_mov_b32 m0, s41
	v_lshl_add_u64 v[142:143], s[44:45], 0, v[132:133]
	global_load_lds_dwordx4 v[120:121], off
	v_lshl_add_u64 v[120:121], v[142:143], 0, s[20:21]
	s_mov_b32 m0, s52
	s_nop 0
	global_load_lds_dwordx4 v[120:121], off
	s_waitcnt vmcnt(8) lgkmcnt(0)
	s_setprio 1
	s_barrier
	v_mfma_f32_16x16x32_bf16 v[120:123], v[0:3], v[48:51], 0
	v_mfma_f32_16x16x32_bf16 v[160:163], v[4:7], v[56:59], v[120:123]
	v_mfma_f32_16x16x32_bf16 v[120:123], v[8:11], v[48:51], 0
	v_mfma_f32_16x16x32_bf16 v[164:167], v[12:15], v[56:59], v[120:123]
	v_mfma_f32_16x16x32_bf16 v[120:123], v[0:3], v[60:63], 0
	v_mfma_f32_16x16x32_bf16 v[168:171], v[4:7], v[88:91], v[120:123]
	v_mfma_f32_16x16x32_bf16 v[120:123], v[8:11], v[60:63], 0
	v_mfma_f32_16x16x32_bf16 v[172:175], v[12:15], v[88:91], v[120:123]
	v_mfma_f32_16x16x32_bf16 v[120:123], v[0:3], v[96:99], 0
	v_mfma_f32_16x16x32_bf16 v[0:3], v[0:3], v[112:115], 0
	v_mfma_f32_16x16x32_bf16 v[176:179], v[4:7], v[104:107], v[120:123]
	v_mfma_f32_16x16x32_bf16 v[0:3], v[4:7], v[116:119], v[0:3]
	v_mfma_f32_16x16x32_bf16 v[4:7], v[8:11], v[112:115], 0
	v_mfma_f32_16x16x32_bf16 v[120:123], v[8:11], v[96:99], 0
	v_mfma_f32_16x16x32_bf16 v[4:7], v[12:15], v[116:119], v[4:7]
	v_mfma_f32_16x16x32_bf16 v[180:183], v[12:15], v[104:107], v[120:123]
	v_mfma_f32_16x16x32_bf16 v[8:11], v[16:19], v[48:51], 0
	v_mfma_f32_16x16x32_bf16 v[12:15], v[20:23], v[56:59], v[8:11]
	v_mfma_f32_16x16x32_bf16 v[8:11], v[24:27], v[48:51], 0
	v_mfma_f32_16x16x32_bf16 v[184:187], v[28:31], v[56:59], v[8:11]
	v_mfma_f32_16x16x32_bf16 v[8:11], v[16:19], v[60:63], 0
	v_mfma_f32_16x16x32_bf16 v[188:191], v[20:23], v[88:91], v[8:11]
	v_mfma_f32_16x16x32_bf16 v[8:11], v[24:27], v[60:63], 0
	v_mfma_f32_16x16x32_bf16 v[192:195], v[28:31], v[88:91], v[8:11]
	v_mfma_f32_16x16x32_bf16 v[8:11], v[16:19], v[96:99], 0
	v_mfma_f32_16x16x32_bf16 v[196:199], v[20:23], v[104:107], v[8:11]
	v_mfma_f32_16x16x32_bf16 v[8:11], v[24:27], v[96:99], 0
	v_mfma_f32_16x16x32_bf16 v[200:203], v[28:31], v[104:107], v[8:11]
	v_mfma_f32_16x16x32_bf16 v[8:11], v[16:19], v[112:115], 0
	v_mfma_f32_16x16x32_bf16 v[204:207], v[20:23], v[116:119], v[8:11]
	v_mfma_f32_16x16x32_bf16 v[8:11], v[24:27], v[112:115], 0
	v_mfma_f32_16x16x32_bf16 v[208:211], v[28:31], v[116:119], v[8:11]
	s_barrier
	s_setprio 0
	s_add_i32 s73, 0, 0x18000
	s_add_i32 s75, 0, 0x1c000
	v_add_u32_e32 v144, s73, v148
	v_add_u32_e32 v145, s75, v148
	s_nop 0
	ds_read_b128 v[8:11], v144
	ds_read_b128 v[20:23], v144 offset:1024
	ds_read_b128 v[28:31], v144 offset:2048
	ds_read_b128 v[212:215], v144 offset:3072
	ds_read_b128 v[216:219], v145
	ds_read_b128 v[220:223], v145 offset:1024
	ds_read_b128 v[224:227], v145 offset:2048
	ds_read_b128 v[228:231], v145 offset:3072
	s_add_u32 s46, s44, 0x80100
	s_addc_u32 s47, s45, 0
	s_mov_b32 m0, s53
	v_lshl_add_u64 v[48:49], s[46:47], 0, v[134:135]
	ds_read_b128 v[16:19], v151 offset:32768
	ds_read_b128 v[24:27], v151 offset:33792
	ds_read_b128 v[60:63], v151 offset:34816
	ds_read_b128 v[232:235], v151 offset:35840
	ds_read_b128 v[236:239], v151 offset:36864
	ds_read_b128 v[240:243], v151 offset:37888
	ds_read_b128 v[244:247], v151 offset:38912
	ds_read_b128 v[248:251], v151 offset:39936
	global_load_lds_dwordx4 v[48:49], off
	v_lshl_add_u64 v[48:49], s[46:47], 0, v[132:133]
	s_mov_b32 m0, s54
	s_nop 0
	global_load_lds_dwordx4 v[48:49], off
	s_waitcnt vmcnt(8) lgkmcnt(0)
	s_setprio 1
	s_barrier
	v_mfma_f32_16x16x32_bf16 v[48:51], v[8:11], v[16:19], v[64:67]
	v_mfma_f32_16x16x32_bf16 v[120:123], v[20:23], v[24:27], v[48:51]
	v_mfma_f32_16x16x32_bf16 v[48:51], v[28:31], v[16:19], v[68:71]
	v_mfma_f32_16x16x32_bf16 v[112:115], v[212:215], v[24:27], v[48:51]
	v_mfma_f32_16x16x32_bf16 v[48:51], v[8:11], v[60:63], v[72:75]
	v_mfma_f32_16x16x32_bf16 v[104:107], v[20:23], v[232:235], v[48:51]
	v_mfma_f32_16x16x32_bf16 v[48:51], v[28:31], v[60:63], v[76:79]
	v_mfma_f32_16x16x32_bf16 v[96:99], v[212:215], v[232:235], v[48:51]
	v_mfma_f32_16x16x32_bf16 v[48:51], v[8:11], v[236:239], v[80:83]
	v_mfma_f32_16x16x32_bf16 v[88:91], v[20:23], v[240:243], v[48:51]
	v_mfma_f32_16x16x32_bf16 v[48:51], v[28:31], v[236:239], v[84:87]
	v_mfma_f32_16x16x32_bf16 v[80:83], v[212:215], v[240:243], v[48:51]
	v_mfma_f32_16x16x32_bf16 v[48:51], v[8:11], v[244:247], v[92:95]
	v_mfma_f32_16x16x32_bf16 v[56:59], v[20:23], v[248:251], v[48:51]
	v_mfma_f32_16x16x32_bf16 v[48:51], v[28:31], v[244:247], v[100:103]
	v_mfma_f32_16x16x32_bf16 v[48:51], v[212:215], v[248:251], v[48:51]
	v_mfma_f32_16x16x32_bf16 v[64:67], v[216:219], v[16:19], v[108:111]
	v_mfma_f32_16x16x32_bf16 v[16:19], v[224:227], v[16:19], v[32:35]
	v_mfma_f32_16x16x32_bf16 v[116:119], v[228:231], v[24:27], v[16:19]
	v_mfma_f32_16x16x32_bf16 v[16:19], v[216:219], v[60:63], v[36:39]
	v_mfma_f32_16x16x32_bf16 v[108:111], v[220:223], v[232:235], v[16:19]
	v_mfma_f32_16x16x32_bf16 v[16:19], v[224:227], v[60:63], v[40:43]
	v_mfma_f32_16x16x32_bf16 v[100:103], v[228:231], v[232:235], v[16:19]
	v_mfma_f32_16x16x32_bf16 v[16:19], v[216:219], v[236:239], v[44:47]
	v_mfma_f32_16x16x32_bf16 v[92:95], v[220:223], v[240:243], v[16:19]
	v_mfma_f32_16x16x32_bf16 v[16:19], v[224:227], v[236:239], v[52:55]
	v_mfma_f32_16x16x32_bf16 v[84:87], v[228:231], v[240:243], v[16:19]
	v_mfma_f32_16x16x32_bf16 v[16:19], v[216:219], v[244:247], v[152:155]
	v_mfma_f32_16x16x32_bf16 v[60:63], v[220:223], v[248:251], v[16:19]
	v_mfma_f32_16x16x32_bf16 v[16:19], v[224:227], v[244:247], v[156:159]
	v_mfma_f32_16x16x32_bf16 v[124:127], v[220:223], v[24:27], v[64:67]
	v_mfma_f32_16x16x32_bf16 v[52:55], v[228:231], v[248:251], v[16:19]
	s_barrier
; template <class Epi, class Sched, bool ALIGN_EPI = false, bool SP2 = false, bool A_TILED = false>
; __device__ __forceinline__ void gemm_phase(PG8_LAS unsigned char* lds, const Gemm g, const Sched& S, const Epi& E, const int wave_s) {
;     ...
;         for (int t = PEEL ? 2 : 0; t < nt; t += 2) {
;             const bool last = (t == nt - 2);
;             const char* a1 = cA + (size_t)(t + 1) * kstepA;
;             const char* a2 = last ? nA : cA + (size_t)(t + 2) * kstepA; const char* b2 = last ? nB : cB + (size_t)(t + 2) * kstep;
;             const char* a3 = a2 + kstepA; const char* b3 = b2 + kstep;
;             if (last && has_next) S.a_ready(nxt);
	s_setprio 0
	s_add_i32 s73, s73, s49
	s_add_i32 s74, s73, 0x2000
	s_nop 1
	v_lshl_add_u64 v[16:17], v[146:147], 0, s[16:17]
	s_mov_b32 m0, s73
	s_add_u32 s46, s42, 0x80180
	ds_read_b128 v[36:39], v151 offset:49152
	ds_read_b128 v[44:47], v151 offset:50176
	ds_read_b128 v[152:155], v151 offset:51200
	ds_read_b128 v[156:159], v151 offset:52224
	ds_read_b128 v[232:235], v151 offset:53248
	ds_read_b128 v[236:239], v151 offset:54272
	ds_read_b128 v[240:243], v151 offset:55296
	ds_read_b128 v[244:247], v151 offset:56320
	global_load_lds_dwordx4 v[16:17], off
	v_lshl_add_u64 v[16:17], v[252:253], 0, s[16:17]
	s_mov_b32 m0, s74
	s_addc_u32 s47, s43, 0
	s_add_i32 s75, s75, s49
	global_load_lds_dwordx4 v[16:17], off
	v_lshl_add_u64 v[16:17], s[46:47], 0, v[128:129]
	s_mov_b32 m0, s75
	s_add_i32 s76, s75, 0x2000
	global_load_lds_dwordx4 v[16:17], off
	v_lshl_add_u64 v[16:17], s[46:47], 0, v[130:131]
	s_mov_b32 m0, s76
	s_nop 0
	global_load_lds_dwordx4 v[16:17], off
	v_lshl_add_u64 v[16:17], v[140:141], 0, s[16:17]
	s_mov_b32 m0, s59
	s_nop 0
	global_load_lds_dwordx4 v[16:17], off
	v_lshl_add_u64 v[16:17], v[142:143], 0, s[16:17]
	s_mov_b32 m0, s60
	s_nop 0
	global_load_lds_dwordx4 v[16:17], off
	s_waitcnt vmcnt(8) lgkmcnt(0)
	s_setprio 1
	s_barrier
	v_mfma_f32_16x16x32_bf16 v[16:19], v[8:11], v[36:39], v[160:163]
	v_mfma_f32_16x16x32_bf16 v[72:75], v[20:23], v[44:47], v[16:19]
	v_mfma_f32_16x16x32_bf16 v[16:19], v[28:31], v[36:39], v[164:167]
	v_mfma_f32_16x16x32_bf16 v[64:67], v[212:215], v[44:47], v[16:19]
	v_mfma_f32_16x16x32_bf16 v[16:19], v[8:11], v[152:155], v[168:171]
	v_mfma_f32_16x16x32_bf16 v[40:43], v[20:23], v[156:159], v[16:19]
	v_mfma_f32_16x16x32_bf16 v[16:19], v[28:31], v[152:155], v[172:175]
	v_mfma_f32_16x16x32_bf16 v[32:35], v[212:215], v[156:159], v[16:19]
	v_mfma_f32_16x16x32_bf16 v[16:19], v[8:11], v[232:235], v[176:179]
	v_mfma_f32_16x16x32_bf16 v[0:3], v[8:11], v[240:243], v[0:3]
	v_mfma_f32_16x16x32_bf16 v[24:27], v[20:23], v[236:239], v[16:19]
	v_mfma_f32_16x16x32_bf16 v[16:19], v[28:31], v[232:235], v[180:183]
	v_mfma_f32_16x16x32_bf16 v[8:11], v[20:23], v[244:247], v[0:3]
	v_mfma_f32_16x16x32_bf16 v[0:3], v[28:31], v[240:243], v[4:7]
	v_mfma_f32_16x16x32_bf16 v[16:19], v[212:215], v[236:239], v[16:19]
	v_mfma_f32_16x16x32_bf16 v[0:3], v[212:215], v[244:247], v[0:3]
	v_mfma_f32_16x16x32_bf16 v[4:7], v[216:219], v[36:39], v[12:15]
	v_mfma_f32_16x16x32_bf16 v[76:79], v[220:223], v[44:47], v[4:7]
	v_mfma_f32_16x16x32_bf16 v[4:7], v[224:227], v[36:39], v[184:187]
	v_mfma_f32_16x16x32_bf16 v[68:71], v[228:231], v[44:47], v[4:7]
	v_mfma_f32_16x16x32_bf16 v[4:7], v[216:219], v[152:155], v[188:191]
	v_mfma_f32_16x16x32_bf16 v[44:47], v[220:223], v[156:159], v[4:7]
	v_mfma_f32_16x16x32_bf16 v[4:7], v[224:227], v[152:155], v[192:195]
	v_mfma_f32_16x16x32_bf16 v[36:39], v[228:231], v[156:159], v[4:7]
	v_mfma_f32_16x16x32_bf16 v[4:7], v[216:219], v[232:235], v[196:199]
	v_mfma_f32_16x16x32_bf16 v[28:31], v[220:223], v[236:239], v[4:7]
	v_mfma_f32_16x16x32_bf16 v[4:7], v[224:227], v[232:235], v[200:203]
	v_mfma_f32_16x16x32_bf16 v[20:23], v[228:231], v[236:239], v[4:7]
	v_mfma_f32_16x16x32_bf16 v[4:7], v[216:219], v[240:243], v[204:207]
	v_mfma_f32_16x16x32_bf16 v[12:15], v[220:223], v[244:247], v[4:7]
	v_mfma_f32_16x16x32_bf16 v[4:7], v[224:227], v[240:243], v[208:211]
	v_mfma_f32_16x16x32_bf16 v[4:7], v[228:231], v[244:247], v[4:7]
	s_barrier
	s_setprio 0
	s_add_u32 s77, s42, 0x200
	s_addc_u32 s78, s43, 0
	s_add_u32 s42, s44, 0x80180
	s_addc_u32 s43, s45, 0
	s_mov_b32 s79, 0
.LBB0_3342:
	ds_read_b128 v[152:155], v149
	ds_read_b128 v[156:159], v149 offset:1024
	ds_read_b128 v[160:163], v149 offset:2048
	ds_read_b128 v[164:167], v149 offset:3072
	ds_read_b128 v[168:171], v150
	ds_read_b128 v[172:175], v150 offset:1024
	ds_read_b128 v[176:179], v150 offset:2048
	ds_read_b128 v[180:183], v150 offset:3072
	s_add_u32 s44, s42, 0xfff80080
	s_addc_u32 s45, s43, -1
	s_cmp_eq_u32 s79, 28
	s_cselect_b32 s47, s25, s45
	s_cselect_b32 s46, s67, s44
	s_cselect_b32 s45, s23, s78
	s_cselect_b32 s44, s68, s77
	s_mov_b32 m0, s64
	v_lshl_add_u64 v[140:141], s[42:43], 0, v[138:139]
	ds_read_b128 v[184:187], v151
	ds_read_b128 v[188:191], v151 offset:1024
	ds_read_b128 v[192:195], v151 offset:2048
	ds_read_b128 v[196:199], v151 offset:3072
	ds_read_b128 v[200:203], v151 offset:4096
	ds_read_b128 v[204:207], v151 offset:5120
	ds_read_b128 v[208:211], v151 offset:6144
	ds_read_b128 v[212:215], v151 offset:7168
	global_load_lds_dwordx4 v[140:141], off
	v_lshl_add_u64 v[140:141], s[42:43], 0, v[136:137]
	s_mov_b32 m0, s65
	s_nop 0
	global_load_lds_dwordx4 v[140:141], off
	s_waitcnt vmcnt(8) lgkmcnt(0)
	s_setprio 1
	s_barrier
	v_mfma_f32_16x16x32_bf16 v[120:123], v[152:155], v[184:187], v[120:123]
	v_mfma_f32_16x16x32_bf16 v[112:115], v[160:163], v[184:187], v[112:115]
	v_mfma_f32_16x16x32_bf16 v[104:107], v[152:155], v[192:195], v[104:107]
	v_mfma_f32_16x16x32_bf16 v[96:99], v[160:163], v[192:195], v[96:99]
	v_mfma_f32_16x16x32_bf16 v[88:91], v[152:155], v[200:203], v[88:91]
	v_mfma_f32_16x16x32_bf16 v[80:83], v[160:163], v[200:203], v[80:83]
	v_mfma_f32_16x16x32_bf16 v[56:59], v[152:155], v[208:211], v[56:59]
	v_mfma_f32_16x16x32_bf16 v[48:51], v[160:163], v[208:211], v[48:51]
	v_mfma_f32_16x16x32_bf16 v[120:123], v[156:159], v[188:191], v[120:123]
	v_mfma_f32_16x16x32_bf16 v[112:115], v[164:167], v[188:191], v[112:115]
	v_mfma_f32_16x16x32_bf16 v[104:107], v[156:159], v[196:199], v[104:107]
	v_mfma_f32_16x16x32_bf16 v[96:99], v[164:167], v[196:199], v[96:99]
	v_mfma_f32_16x16x32_bf16 v[88:91], v[156:159], v[204:207], v[88:91]
	v_mfma_f32_16x16x32_bf16 v[80:83], v[164:167], v[204:207], v[80:83]
	v_mfma_f32_16x16x32_bf16 v[56:59], v[156:159], v[212:215], v[56:59]
	v_mfma_f32_16x16x32_bf16 v[48:51], v[164:167], v[212:215], v[48:51]
	v_mfma_f32_16x16x32_bf16 v[124:127], v[168:171], v[184:187], v[124:127]
	v_mfma_f32_16x16x32_bf16 v[116:119], v[176:179], v[184:187], v[116:119]
	v_mfma_f32_16x16x32_bf16 v[108:111], v[168:171], v[192:195], v[108:111]
	v_mfma_f32_16x16x32_bf16 v[100:103], v[176:179], v[192:195], v[100:103]
	v_mfma_f32_16x16x32_bf16 v[92:95], v[168:171], v[200:203], v[92:95]
	v_mfma_f32_16x16x32_bf16 v[84:87], v[176:179], v[200:203], v[84:87]
	v_mfma_f32_16x16x32_bf16 v[60:63], v[168:171], v[208:211], v[60:63]
	v_mfma_f32_16x16x32_bf16 v[52:55], v[176:179], v[208:211], v[52:55]
	v_mfma_f32_16x16x32_bf16 v[124:127], v[172:175], v[188:191], v[124:127]
	v_mfma_f32_16x16x32_bf16 v[116:119], v[180:183], v[188:191], v[116:119]
	v_mfma_f32_16x16x32_bf16 v[108:111], v[172:175], v[196:199], v[108:111]
	v_mfma_f32_16x16x32_bf16 v[100:103], v[180:183], v[196:199], v[100:103]
	v_mfma_f32_16x16x32_bf16 v[92:95], v[172:175], v[204:207], v[92:95]
	v_mfma_f32_16x16x32_bf16 v[84:87], v[180:183], v[204:207], v[84:87]
	v_mfma_f32_16x16x32_bf16 v[60:63], v[172:175], v[212:215], v[60:63]
	v_mfma_f32_16x16x32_bf16 v[52:55], v[180:183], v[212:215], v[52:55]
	s_barrier
	s_setprio 0
	s_mov_b32 m0, s69
	v_lshl_add_u64 v[140:141], s[44:45], 0, v[128:129]
	s_add_u32 s80, s44, 0x80000
	ds_read_b128 v[184:187], v151 offset:16384
	ds_read_b128 v[188:191], v151 offset:17408
	ds_read_b128 v[192:195], v151 offset:18432
	ds_read_b128 v[196:199], v151 offset:19456
	ds_read_b128 v[200:203], v151 offset:20480
	ds_read_b128 v[204:207], v151 offset:21504
	ds_read_b128 v[208:211], v151 offset:22528
	ds_read_b128 v[212:215], v151 offset:23552
	global_load_lds_dwordx4 v[140:141], off
	v_lshl_add_u64 v[142:143], s[44:45], 0, v[130:131]
	s_mov_b32 m0, s70
	s_addc_u32 s81, s45, 0
	global_load_lds_dwordx4 v[142:143], off
	v_lshl_add_u64 v[146:147], s[80:81], 0, v[128:129]
	s_mov_b32 m0, s71
	v_lshl_add_u64 v[216:217], s[46:47], 0, v[132:133]
	global_load_lds_dwordx4 v[146:147], off
	v_lshl_add_u64 v[146:147], s[80:81], 0, v[130:131]
	s_mov_b32 m0, s72
	s_nop 0
	global_load_lds_dwordx4 v[146:147], off
	v_lshl_add_u64 v[146:147], s[46:47], 0, v[134:135]
	s_mov_b32 m0, s41
	s_nop 0
	global_load_lds_dwordx4 v[146:147], off
	s_mov_b32 m0, s52
	s_nop 0
	global_load_lds_dwordx4 v[216:217], off
	s_waitcnt vmcnt(8) lgkmcnt(0)
	s_setprio 1
	s_barrier
	v_mfma_f32_16x16x32_bf16 v[72:75], v[152:155], v[184:187], v[72:75]
	v_mfma_f32_16x16x32_bf16 v[64:67], v[160:163], v[184:187], v[64:67]
	v_mfma_f32_16x16x32_bf16 v[40:43], v[152:155], v[192:195], v[40:43]
	v_mfma_f32_16x16x32_bf16 v[32:35], v[160:163], v[192:195], v[32:35]
	v_mfma_f32_16x16x32_bf16 v[24:27], v[152:155], v[200:203], v[24:27]
	v_mfma_f32_16x16x32_bf16 v[16:19], v[160:163], v[200:203], v[16:19]
	v_mfma_f32_16x16x32_bf16 v[8:11], v[152:155], v[208:211], v[8:11]
	v_mfma_f32_16x16x32_bf16 v[0:3], v[160:163], v[208:211], v[0:3]
	v_mfma_f32_16x16x32_bf16 v[72:75], v[156:159], v[188:191], v[72:75]
	v_mfma_f32_16x16x32_bf16 v[64:67], v[164:167], v[188:191], v[64:67]
	v_mfma_f32_16x16x32_bf16 v[40:43], v[156:159], v[196:199], v[40:43]
	v_mfma_f32_16x16x32_bf16 v[32:35], v[164:167], v[196:199], v[32:35]
	v_mfma_f32_16x16x32_bf16 v[24:27], v[156:159], v[204:207], v[24:27]
	v_mfma_f32_16x16x32_bf16 v[16:19], v[164:167], v[204:207], v[16:19]
	v_mfma_f32_16x16x32_bf16 v[8:11], v[156:159], v[212:215], v[8:11]
	v_mfma_f32_16x16x32_bf16 v[0:3], v[164:167], v[212:215], v[0:3]
	v_mfma_f32_16x16x32_bf16 v[76:79], v[168:171], v[184:187], v[76:79]
	v_mfma_f32_16x16x32_bf16 v[68:71], v[176:179], v[184:187], v[68:71]
	v_mfma_f32_16x16x32_bf16 v[44:47], v[168:171], v[192:195], v[44:47]
	v_mfma_f32_16x16x32_bf16 v[36:39], v[176:179], v[192:195], v[36:39]
	v_mfma_f32_16x16x32_bf16 v[28:31], v[168:171], v[200:203], v[28:31]
	v_mfma_f32_16x16x32_bf16 v[20:23], v[176:179], v[200:203], v[20:23]
	v_mfma_f32_16x16x32_bf16 v[12:15], v[168:171], v[208:211], v[12:15]
	v_mfma_f32_16x16x32_bf16 v[4:7], v[176:179], v[208:211], v[4:7]
	v_mfma_f32_16x16x32_bf16 v[76:79], v[172:175], v[188:191], v[76:79]
	v_mfma_f32_16x16x32_bf16 v[68:71], v[180:183], v[188:191], v[68:71]
	v_mfma_f32_16x16x32_bf16 v[44:47], v[172:175], v[196:199], v[44:47]
	v_mfma_f32_16x16x32_bf16 v[36:39], v[180:183], v[196:199], v[36:39]
	v_mfma_f32_16x16x32_bf16 v[28:31], v[172:175], v[204:207], v[28:31]
	v_mfma_f32_16x16x32_bf16 v[20:23], v[180:183], v[204:207], v[20:23]
	v_mfma_f32_16x16x32_bf16 v[12:15], v[172:175], v[212:215], v[12:15]
	v_mfma_f32_16x16x32_bf16 v[4:7], v[180:183], v[212:215], v[4:7]
	s_barrier
	s_setprio 0
	ds_read_b128 v[152:155], v144
	ds_read_b128 v[156:159], v144 offset:1024
	ds_read_b128 v[160:163], v144 offset:2048
	ds_read_b128 v[164:167], v144 offset:3072
	ds_read_b128 v[168:171], v145
	ds_read_b128 v[172:175], v145 offset:1024
	ds_read_b128 v[176:179], v145 offset:2048
	ds_read_b128 v[180:183], v145 offset:3072
	s_add_u32 s46, s46, 0x80000
	s_addc_u32 s47, s47, 0
	s_mov_b32 m0, s53
	v_lshl_add_u64 v[218:219], s[46:47], 0, v[134:135]
	ds_read_b128 v[184:187], v151 offset:32768
	ds_read_b128 v[188:191], v151 offset:33792
	ds_read_b128 v[192:195], v151 offset:34816
	ds_read_b128 v[196:199], v151 offset:35840
	ds_read_b128 v[200:203], v151 offset:36864
	ds_read_b128 v[204:207], v151 offset:37888
	ds_read_b128 v[208:211], v151 offset:38912
	ds_read_b128 v[212:215], v151 offset:39936
	global_load_lds_dwordx4 v[218:219], off
	v_lshl_add_u64 v[218:219], s[46:47], 0, v[132:133]
	s_mov_b32 m0, s54
	s_nop 0
	global_load_lds_dwordx4 v[218:219], off
	s_waitcnt vmcnt(8) lgkmcnt(0)
	s_setprio 1
	s_barrier
	v_mfma_f32_16x16x32_bf16 v[120:123], v[152:155], v[184:187], v[120:123]
	v_mfma_f32_16x16x32_bf16 v[112:115], v[160:163], v[184:187], v[112:115]
	v_mfma_f32_16x16x32_bf16 v[104:107], v[152:155], v[192:195], v[104:107]
	v_mfma_f32_16x16x32_bf16 v[96:99], v[160:163], v[192:195], v[96:99]
	v_mfma_f32_16x16x32_bf16 v[88:91], v[152:155], v[200:203], v[88:91]
	v_mfma_f32_16x16x32_bf16 v[80:83], v[160:163], v[200:203], v[80:83]
	v_mfma_f32_16x16x32_bf16 v[56:59], v[152:155], v[208:211], v[56:59]
	v_mfma_f32_16x16x32_bf16 v[48:51], v[160:163], v[208:211], v[48:51]
	v_mfma_f32_16x16x32_bf16 v[120:123], v[156:159], v[188:191], v[120:123]
	v_mfma_f32_16x16x32_bf16 v[112:115], v[164:167], v[188:191], v[112:115]
	v_mfma_f32_16x16x32_bf16 v[104:107], v[156:159], v[196:199], v[104:107]
	v_mfma_f32_16x16x32_bf16 v[96:99], v[164:167], v[196:199], v[96:99]
	v_mfma_f32_16x16x32_bf16 v[88:91], v[156:159], v[204:207], v[88:91]
	v_mfma_f32_16x16x32_bf16 v[80:83], v[164:167], v[204:207], v[80:83]
	v_mfma_f32_16x16x32_bf16 v[56:59], v[156:159], v[212:215], v[56:59]
	v_mfma_f32_16x16x32_bf16 v[48:51], v[164:167], v[212:215], v[48:51]
	v_mfma_f32_16x16x32_bf16 v[124:127], v[168:171], v[184:187], v[124:127]
	v_mfma_f32_16x16x32_bf16 v[116:119], v[176:179], v[184:187], v[116:119]
	v_mfma_f32_16x16x32_bf16 v[108:111], v[168:171], v[192:195], v[108:111]
	v_mfma_f32_16x16x32_bf16 v[100:103], v[176:179], v[192:195], v[100:103]
	v_mfma_f32_16x16x32_bf16 v[92:95], v[168:171], v[200:203], v[92:95]
	v_mfma_f32_16x16x32_bf16 v[84:87], v[176:179], v[200:203], v[84:87]
	v_mfma_f32_16x16x32_bf16 v[60:63], v[168:171], v[208:211], v[60:63]
	v_mfma_f32_16x16x32_bf16 v[52:55], v[176:179], v[208:211], v[52:55]
	v_mfma_f32_16x16x32_bf16 v[124:127], v[172:175], v[188:191], v[124:127]
	v_mfma_f32_16x16x32_bf16 v[116:119], v[180:183], v[188:191], v[116:119]
	v_mfma_f32_16x16x32_bf16 v[108:111], v[172:175], v[196:199], v[108:111]
	v_mfma_f32_16x16x32_bf16 v[100:103], v[180:183], v[196:199], v[100:103]
	v_mfma_f32_16x16x32_bf16 v[92:95], v[172:175], v[204:207], v[92:95]
	v_mfma_f32_16x16x32_bf16 v[84:87], v[180:183], v[204:207], v[84:87]
	v_mfma_f32_16x16x32_bf16 v[60:63], v[172:175], v[212:215], v[60:63]
	v_mfma_f32_16x16x32_bf16 v[52:55], v[180:183], v[212:215], v[52:55]
	s_barrier
	s_setprio 0
	s_mov_b32 m0, s73
	v_lshl_add_u64 v[140:141], v[140:141], 0, s[12:13]
	s_add_u32 s44, s44, 0x80080
	ds_read_b128 v[184:187], v151 offset:49152
	ds_read_b128 v[188:191], v151 offset:50176
	ds_read_b128 v[192:195], v151 offset:51200
	ds_read_b128 v[196:199], v151 offset:52224
	ds_read_b128 v[200:203], v151 offset:53248
	ds_read_b128 v[204:207], v151 offset:54272
	ds_read_b128 v[208:211], v151 offset:55296
	ds_read_b128 v[212:215], v151 offset:56320
	global_load_lds_dwordx4 v[140:141], off
	v_lshl_add_u64 v[140:141], v[142:143], 0, s[12:13]
	s_mov_b32 m0, s74
	s_addc_u32 s45, s45, 0
	global_load_lds_dwordx4 v[140:141], off
	v_lshl_add_u64 v[140:141], s[44:45], 0, v[128:129]
	s_mov_b32 m0, s75
	s_nop 0
	global_load_lds_dwordx4 v[140:141], off
	v_lshl_add_u64 v[140:141], s[44:45], 0, v[130:131]
	s_mov_b32 m0, s76
	s_nop 0
	global_load_lds_dwordx4 v[140:141], off
	v_lshl_add_u64 v[140:141], v[146:147], 0, s[12:13]
	s_mov_b32 m0, s59
	s_nop 0
	global_load_lds_dwordx4 v[140:141], off
	v_lshl_add_u64 v[140:141], v[216:217], 0, s[12:13]
	s_mov_b32 m0, s60
	s_nop 0
	global_load_lds_dwordx4 v[140:141], off
	s_waitcnt vmcnt(8) lgkmcnt(0)
	s_setprio 1
	s_barrier
	v_mfma_f32_16x16x32_bf16 v[72:75], v[152:155], v[184:187], v[72:75]
	v_mfma_f32_16x16x32_bf16 v[64:67], v[160:163], v[184:187], v[64:67]
	v_mfma_f32_16x16x32_bf16 v[40:43], v[152:155], v[192:195], v[40:43]
	v_mfma_f32_16x16x32_bf16 v[32:35], v[160:163], v[192:195], v[32:35]
	v_mfma_f32_16x16x32_bf16 v[24:27], v[152:155], v[200:203], v[24:27]
	v_mfma_f32_16x16x32_bf16 v[16:19], v[160:163], v[200:203], v[16:19]
	v_mfma_f32_16x16x32_bf16 v[8:11], v[152:155], v[208:211], v[8:11]
	v_mfma_f32_16x16x32_bf16 v[0:3], v[160:163], v[208:211], v[0:3]
	v_mfma_f32_16x16x32_bf16 v[72:75], v[156:159], v[188:191], v[72:75]
	v_mfma_f32_16x16x32_bf16 v[64:67], v[164:167], v[188:191], v[64:67]
	v_mfma_f32_16x16x32_bf16 v[40:43], v[156:159], v[196:199], v[40:43]
	v_mfma_f32_16x16x32_bf16 v[32:35], v[164:167], v[196:199], v[32:35]
	v_mfma_f32_16x16x32_bf16 v[24:27], v[156:159], v[204:207], v[24:27]
	v_mfma_f32_16x16x32_bf16 v[16:19], v[164:167], v[204:207], v[16:19]
	v_mfma_f32_16x16x32_bf16 v[8:11], v[156:159], v[212:215], v[8:11]
	v_mfma_f32_16x16x32_bf16 v[0:3], v[164:167], v[212:215], v[0:3]
	v_mfma_f32_16x16x32_bf16 v[76:79], v[168:171], v[184:187], v[76:79]
	v_mfma_f32_16x16x32_bf16 v[68:71], v[176:179], v[184:187], v[68:71]
	v_mfma_f32_16x16x32_bf16 v[44:47], v[168:171], v[192:195], v[44:47]
	v_mfma_f32_16x16x32_bf16 v[36:39], v[176:179], v[192:195], v[36:39]
	v_mfma_f32_16x16x32_bf16 v[28:31], v[168:171], v[200:203], v[28:31]
	v_mfma_f32_16x16x32_bf16 v[20:23], v[176:179], v[200:203], v[20:23]
	v_mfma_f32_16x16x32_bf16 v[12:15], v[168:171], v[208:211], v[12:15]
	v_mfma_f32_16x16x32_bf16 v[4:7], v[176:179], v[208:211], v[4:7]
	v_mfma_f32_16x16x32_bf16 v[76:79], v[172:175], v[188:191], v[76:79]
	v_mfma_f32_16x16x32_bf16 v[68:71], v[180:183], v[188:191], v[68:71]
	v_mfma_f32_16x16x32_bf16 v[44:47], v[172:175], v[196:199], v[44:47]
	v_mfma_f32_16x16x32_bf16 v[36:39], v[180:183], v[196:199], v[36:39]
	v_mfma_f32_16x16x32_bf16 v[28:31], v[172:175], v[204:207], v[28:31]
	v_mfma_f32_16x16x32_bf16 v[20:23], v[180:183], v[204:207], v[20:23]
	v_mfma_f32_16x16x32_bf16 v[12:15], v[172:175], v[212:215], v[12:15]
	v_mfma_f32_16x16x32_bf16 v[4:7], v[180:183], v[212:215], v[4:7]
	s_barrier
	s_setprio 0
	s_add_i32 s79, s79, 2
	s_add_u32 s77, s77, 0x100
	s_addc_u32 s78, s78, 0
	s_add_u32 s42, s42, 0x100
	s_addc_u32 s43, s43, 0
	s_cmp_gt_u32 s79, 29
	s_cbranch_scc0 .LBB0_3342
	s_and_b64 vcc, exec, s[14:15]
	s_cbranch_vccz .LBB0_3345
	s_barrier

.LBB0_3608:
	ds_read_b128 v[146:149], v140
	ds_read_b128 v[150:153], v140 offset:1024
	ds_read_b128 v[154:157], v140 offset:2048
	ds_read_b128 v[158:161], v140 offset:3072
	ds_read_b128 v[162:165], v141
	ds_read_b128 v[166:169], v141 offset:1024
	ds_read_b128 v[170:173], v141 offset:2048
	ds_read_b128 v[174:177], v141 offset:3072
	s_add_u32 s20, s8, s43
	s_addc_u32 s21, s9, s44
	s_add_u32 s56, s8, s41
	s_addc_u32 s57, s9, s42
	s_cmp_eq_u32 s45, 28
	s_cselect_b32 s23, s5, s21
	s_cselect_b32 s22, s4, s20
	s_cselect_b32 s21, s1, s57
	s_cselect_b32 s20, s0, s56
	s_mov_b32 m0, s46
	v_lshl_add_u64 v[210:211], s[8:9], 0, v[138:139]
	ds_read_b128 v[178:181], v142
	ds_read_b128 v[182:185], v142 offset:1024
	ds_read_b128 v[186:189], v142 offset:2048
	ds_read_b128 v[190:193], v142 offset:3072
	ds_read_b128 v[194:197], v142 offset:4096
	ds_read_b128 v[198:201], v142 offset:5120
	ds_read_b128 v[202:205], v142 offset:6144
	ds_read_b128 v[206:209], v142 offset:7168
	global_load_lds_dwordx4 v[210:211], off
	v_lshl_add_u64 v[210:211], s[8:9], 0, v[136:137]
	s_mov_b32 m0, s47
	s_nop 0
	global_load_lds_dwordx4 v[210:211], off
	s_waitcnt vmcnt(8) lgkmcnt(0)
	s_setprio 1
	s_barrier
	v_mfma_f32_16x16x32_bf16 v[8:11], v[146:149], v[178:181], v[8:11]
	v_mfma_f32_16x16x32_bf16 v[12:15], v[154:157], v[178:181], v[12:15]
	v_mfma_f32_16x16x32_bf16 v[60:63], v[146:149], v[186:189], v[60:63]
	v_mfma_f32_16x16x32_bf16 v[20:23], v[154:157], v[186:189], v[20:23]
	v_mfma_f32_16x16x32_bf16 v[76:79], v[146:149], v[194:197], v[76:79]
	v_mfma_f32_16x16x32_bf16 v[52:55], v[154:157], v[194:197], v[52:55]
	v_mfma_f32_16x16x32_bf16 v[128:131], v[146:149], v[202:205], v[128:131]
	v_mfma_f32_16x16x32_bf16 v[68:71], v[154:157], v[202:205], v[68:71]
	v_mfma_f32_16x16x32_bf16 v[8:11], v[150:153], v[182:185], v[8:11]
	v_mfma_f32_16x16x32_bf16 v[12:15], v[158:161], v[182:185], v[12:15]
	v_mfma_f32_16x16x32_bf16 v[60:63], v[150:153], v[190:193], v[60:63]
	v_mfma_f32_16x16x32_bf16 v[20:23], v[158:161], v[190:193], v[20:23]
	v_mfma_f32_16x16x32_bf16 v[76:79], v[150:153], v[198:201], v[76:79]
	v_mfma_f32_16x16x32_bf16 v[52:55], v[158:161], v[198:201], v[52:55]
	v_mfma_f32_16x16x32_bf16 v[128:131], v[150:153], v[206:209], v[128:131]
	v_mfma_f32_16x16x32_bf16 v[68:71], v[158:161], v[206:209], v[68:71]
	v_mfma_f32_16x16x32_bf16 v[24:27], v[162:165], v[178:181], v[24:27]
	v_mfma_f32_16x16x32_bf16 v[16:19], v[170:173], v[178:181], v[16:19]
	v_mfma_f32_16x16x32_bf16 v[56:59], v[162:165], v[186:189], v[56:59]
	v_mfma_f32_16x16x32_bf16 v[48:51], v[170:173], v[186:189], v[48:51]
	v_mfma_f32_16x16x32_bf16 v[72:75], v[162:165], v[194:197], v[72:75]
	v_mfma_f32_16x16x32_bf16 v[64:67], v[170:173], v[194:197], v[64:67]
	v_mfma_f32_16x16x32_bf16 v[108:111], v[162:165], v[202:205], v[108:111]
	v_mfma_f32_16x16x32_bf16 v[96:99], v[170:173], v[202:205], v[96:99]
	v_mfma_f32_16x16x32_bf16 v[24:27], v[166:169], v[182:185], v[24:27]
	v_mfma_f32_16x16x32_bf16 v[16:19], v[174:177], v[182:185], v[16:19]
	v_mfma_f32_16x16x32_bf16 v[56:59], v[166:169], v[190:193], v[56:59]
	v_mfma_f32_16x16x32_bf16 v[48:51], v[174:177], v[190:193], v[48:51]
	v_mfma_f32_16x16x32_bf16 v[72:75], v[166:169], v[198:201], v[72:75]
	v_mfma_f32_16x16x32_bf16 v[64:67], v[174:177], v[198:201], v[64:67]
	v_mfma_f32_16x16x32_bf16 v[108:111], v[166:169], v[206:209], v[108:111]
	v_mfma_f32_16x16x32_bf16 v[96:99], v[174:177], v[206:209], v[96:99]
	s_barrier
	s_setprio 0
	s_mov_b32 m0, s48
	v_lshl_add_u64 v[210:211], s[20:21], 0, v[34:35]
	s_add_u32 s56, s20, 0x80000
	ds_read_b128 v[178:181], v142 offset:16384
	ds_read_b128 v[182:185], v142 offset:17408
	ds_read_b128 v[186:189], v142 offset:18432
	ds_read_b128 v[190:193], v142 offset:19456
	ds_read_b128 v[194:197], v142 offset:20480
	ds_read_b128 v[198:201], v142 offset:21504
	ds_read_b128 v[202:205], v142 offset:22528
	ds_read_b128 v[206:209], v142 offset:23552
	global_load_lds_dwordx4 v[210:211], off
	v_lshl_add_u64 v[212:213], s[20:21], 0, v[134:135]
	s_mov_b32 m0, s49
	s_addc_u32 s57, s21, 0
	global_load_lds_dwordx4 v[212:213], off
	v_lshl_add_u64 v[214:215], s[56:57], 0, v[34:35]
	s_mov_b32 m0, s50
	v_lshl_add_u64 v[216:217], s[22:23], 0, v[132:133]
	global_load_lds_dwordx4 v[214:215], off
	v_lshl_add_u64 v[214:215], s[56:57], 0, v[134:135]
	s_mov_b32 m0, s51
	s_nop 0
	global_load_lds_dwordx4 v[214:215], off
	v_lshl_add_u64 v[214:215], s[22:23], 0, v[32:33]
	s_mov_b32 m0, s27
	s_nop 0
	global_load_lds_dwordx4 v[214:215], off
	s_mov_b32 m0, s36
	s_nop 0
	global_load_lds_dwordx4 v[216:217], off
	s_waitcnt vmcnt(8) lgkmcnt(0)
	s_setprio 1
	s_barrier
	v_mfma_f32_16x16x32_bf16 v[100:103], v[146:149], v[178:181], v[100:103]
	v_mfma_f32_16x16x32_bf16 v[104:107], v[154:157], v[178:181], v[104:107]
	v_mfma_f32_16x16x32_bf16 v[116:119], v[146:149], v[186:189], v[116:119]
	v_mfma_f32_16x16x32_bf16 v[120:123], v[154:157], v[186:189], v[120:123]
	v_mfma_f32_16x16x32_bf16 v[84:87], v[146:149], v[194:197], v[84:87]
	v_mfma_f32_16x16x32_bf16 v[80:83], v[154:157], v[194:197], v[80:83]
	v_mfma_f32_16x16x32_bf16 v[36:39], v[146:149], v[202:205], v[36:39]
	v_mfma_f32_16x16x32_bf16 v[28:31], v[154:157], v[202:205], v[28:31]
	v_mfma_f32_16x16x32_bf16 v[100:103], v[150:153], v[182:185], v[100:103]
	v_mfma_f32_16x16x32_bf16 v[104:107], v[158:161], v[182:185], v[104:107]
	v_mfma_f32_16x16x32_bf16 v[116:119], v[150:153], v[190:193], v[116:119]
	v_mfma_f32_16x16x32_bf16 v[120:123], v[158:161], v[190:193], v[120:123]
	v_mfma_f32_16x16x32_bf16 v[84:87], v[150:153], v[198:201], v[84:87]
	v_mfma_f32_16x16x32_bf16 v[80:83], v[158:161], v[198:201], v[80:83]
	v_mfma_f32_16x16x32_bf16 v[36:39], v[150:153], v[206:209], v[36:39]
	v_mfma_f32_16x16x32_bf16 v[28:31], v[158:161], v[206:209], v[28:31]
	v_mfma_f32_16x16x32_bf16 v[124:127], v[162:165], v[178:181], v[124:127]
	v_mfma_f32_16x16x32_bf16 v[112:115], v[170:173], v[178:181], v[112:115]
	v_mfma_f32_16x16x32_bf16 v[92:95], v[162:165], v[186:189], v[92:95]
	v_mfma_f32_16x16x32_bf16 v[88:91], v[170:173], v[186:189], v[88:91]
	v_mfma_f32_16x16x32_bf16 v[44:47], v[162:165], v[194:197], v[44:47]
	v_mfma_f32_16x16x32_bf16 v[40:43], v[170:173], v[194:197], v[40:43]
	v_mfma_f32_16x16x32_bf16 v[4:7], v[162:165], v[202:205], v[4:7]
	v_mfma_f32_16x16x32_bf16 v[0:3], v[170:173], v[202:205], v[0:3]
	v_mfma_f32_16x16x32_bf16 v[124:127], v[166:169], v[182:185], v[124:127]
	v_mfma_f32_16x16x32_bf16 v[112:115], v[174:177], v[182:185], v[112:115]
	v_mfma_f32_16x16x32_bf16 v[92:95], v[166:169], v[190:193], v[92:95]
	v_mfma_f32_16x16x32_bf16 v[88:91], v[174:177], v[190:193], v[88:91]
	v_mfma_f32_16x16x32_bf16 v[44:47], v[166:169], v[198:201], v[44:47]
	v_mfma_f32_16x16x32_bf16 v[40:43], v[174:177], v[198:201], v[40:43]
	v_mfma_f32_16x16x32_bf16 v[4:7], v[166:169], v[206:209], v[4:7]
	v_mfma_f32_16x16x32_bf16 v[0:3], v[174:177], v[206:209], v[0:3]
	s_barrier
	s_setprio 0
	ds_read_b128 v[146:149], v143
	ds_read_b128 v[150:153], v143 offset:1024
	ds_read_b128 v[154:157], v143 offset:2048
	ds_read_b128 v[158:161], v143 offset:3072
	ds_read_b128 v[162:165], v144
	ds_read_b128 v[166:169], v144 offset:1024
	ds_read_b128 v[170:173], v144 offset:2048
	ds_read_b128 v[174:177], v144 offset:3072
	s_add_u32 s22, s22, 0x80000
	s_addc_u32 s23, s23, 0
	s_mov_b32 m0, s37
	v_lshl_add_u64 v[218:219], s[22:23], 0, v[32:33]
	ds_read_b128 v[178:181], v142 offset:32768
	ds_read_b128 v[182:185], v142 offset:33792
	ds_read_b128 v[186:189], v142 offset:34816
	ds_read_b128 v[190:193], v142 offset:35840
	ds_read_b128 v[194:197], v142 offset:36864
	ds_read_b128 v[198:201], v142 offset:37888
	ds_read_b128 v[202:205], v142 offset:38912
	ds_read_b128 v[206:209], v142 offset:39936
	global_load_lds_dwordx4 v[218:219], off
	v_lshl_add_u64 v[218:219], s[22:23], 0, v[132:133]
	s_mov_b32 m0, s38
	s_nop 0
	global_load_lds_dwordx4 v[218:219], off
	s_waitcnt vmcnt(8) lgkmcnt(0)
	s_setprio 1
	s_barrier
	v_mfma_f32_16x16x32_bf16 v[8:11], v[146:149], v[178:181], v[8:11]
	v_mfma_f32_16x16x32_bf16 v[12:15], v[154:157], v[178:181], v[12:15]
	v_mfma_f32_16x16x32_bf16 v[60:63], v[146:149], v[186:189], v[60:63]
	v_mfma_f32_16x16x32_bf16 v[20:23], v[154:157], v[186:189], v[20:23]
	v_mfma_f32_16x16x32_bf16 v[76:79], v[146:149], v[194:197], v[76:79]
	v_mfma_f32_16x16x32_bf16 v[52:55], v[154:157], v[194:197], v[52:55]
	v_mfma_f32_16x16x32_bf16 v[128:131], v[146:149], v[202:205], v[128:131]
	v_mfma_f32_16x16x32_bf16 v[68:71], v[154:157], v[202:205], v[68:71]
	v_mfma_f32_16x16x32_bf16 v[8:11], v[150:153], v[182:185], v[8:11]
	v_mfma_f32_16x16x32_bf16 v[12:15], v[158:161], v[182:185], v[12:15]
	v_mfma_f32_16x16x32_bf16 v[60:63], v[150:153], v[190:193], v[60:63]
	v_mfma_f32_16x16x32_bf16 v[20:23], v[158:161], v[190:193], v[20:23]
	v_mfma_f32_16x16x32_bf16 v[76:79], v[150:153], v[198:201], v[76:79]
	v_mfma_f32_16x16x32_bf16 v[52:55], v[158:161], v[198:201], v[52:55]
	v_mfma_f32_16x16x32_bf16 v[128:131], v[150:153], v[206:209], v[128:131]
	v_mfma_f32_16x16x32_bf16 v[68:71], v[158:161], v[206:209], v[68:71]
	v_mfma_f32_16x16x32_bf16 v[24:27], v[162:165], v[178:181], v[24:27]
	v_mfma_f32_16x16x32_bf16 v[16:19], v[170:173], v[178:181], v[16:19]
	v_mfma_f32_16x16x32_bf16 v[56:59], v[162:165], v[186:189], v[56:59]
	v_mfma_f32_16x16x32_bf16 v[48:51], v[170:173], v[186:189], v[48:51]
	v_mfma_f32_16x16x32_bf16 v[72:75], v[162:165], v[194:197], v[72:75]
	v_mfma_f32_16x16x32_bf16 v[64:67], v[170:173], v[194:197], v[64:67]
	v_mfma_f32_16x16x32_bf16 v[108:111], v[162:165], v[202:205], v[108:111]
	v_mfma_f32_16x16x32_bf16 v[96:99], v[170:173], v[202:205], v[96:99]
	v_mfma_f32_16x16x32_bf16 v[24:27], v[166:169], v[182:185], v[24:27]
	v_mfma_f32_16x16x32_bf16 v[16:19], v[174:177], v[182:185], v[16:19]
	v_mfma_f32_16x16x32_bf16 v[56:59], v[166:169], v[190:193], v[56:59]
	v_mfma_f32_16x16x32_bf16 v[48:51], v[174:177], v[190:193], v[48:51]
	v_mfma_f32_16x16x32_bf16 v[72:75], v[166:169], v[198:201], v[72:75]
	v_mfma_f32_16x16x32_bf16 v[64:67], v[174:177], v[198:201], v[64:67]
	v_mfma_f32_16x16x32_bf16 v[108:111], v[166:169], v[206:209], v[108:111]
	v_mfma_f32_16x16x32_bf16 v[96:99], v[174:177], v[206:209], v[96:99]
	s_barrier
; #define PG8_WAIT_V(n) asm volatile("s_waitcnt vmcnt(" #n ")" ::: "memory")
; #define PG8_BAR __builtin_amdgcn_s_barrier()
; template <class Epi, class Sched, bool ALIGN_EPI = false, bool SP2 = false, bool A_TILED = false>
; __device__ __forceinline__ void gemm_phase(PG8_LAS unsigned char* lds, const Gemm g, const Sched& S, const Epi& E, const int wave_s) {
;     ...
;     PG8_WAIT_V(0);
;     if constexpr (!ALIGN_EPI) { if (wr == 0) PG8_BAR; }
	s_setprio 0
	s_mov_b32 m0, s52
	v_lshl_add_u64 v[210:211], v[210:211], 0, s[14:15]
	s_add_u32 s20, s20, 0x80080
	ds_read_b128 v[178:181], v142 offset:49152
	ds_read_b128 v[182:185], v142 offset:50176
	ds_read_b128 v[186:189], v142 offset:51200
	ds_read_b128 v[190:193], v142 offset:52224
	ds_read_b128 v[194:197], v142 offset:53248
	ds_read_b128 v[198:201], v142 offset:54272
	ds_read_b128 v[202:205], v142 offset:55296
	ds_read_b128 v[206:209], v142 offset:56320
	global_load_lds_dwordx4 v[210:211], off
	v_lshl_add_u64 v[210:211], v[212:213], 0, s[14:15]
	s_mov_b32 m0, s53
	s_addc_u32 s21, s21, 0
	global_load_lds_dwordx4 v[210:211], off
	v_lshl_add_u64 v[210:211], s[20:21], 0, v[34:35]
	s_mov_b32 m0, s54
	s_nop 0
	global_load_lds_dwordx4 v[210:211], off
	v_lshl_add_u64 v[210:211], s[20:21], 0, v[134:135]
	s_mov_b32 m0, s55
	s_nop 0
	global_load_lds_dwordx4 v[210:211], off
	v_lshl_add_u64 v[210:211], v[214:215], 0, s[14:15]
	s_mov_b32 m0, s39
	s_nop 0
	global_load_lds_dwordx4 v[210:211], off
	v_lshl_add_u64 v[210:211], v[216:217], 0, s[14:15]
	s_mov_b32 m0, s40
	s_nop 0
	global_load_lds_dwordx4 v[210:211], off
	s_waitcnt vmcnt(8) lgkmcnt(0)
	s_setprio 1
	s_barrier
	v_mfma_f32_16x16x32_bf16 v[100:103], v[146:149], v[178:181], v[100:103]
	v_mfma_f32_16x16x32_bf16 v[104:107], v[154:157], v[178:181], v[104:107]
	v_mfma_f32_16x16x32_bf16 v[116:119], v[146:149], v[186:189], v[116:119]
	v_mfma_f32_16x16x32_bf16 v[120:123], v[154:157], v[186:189], v[120:123]
	v_mfma_f32_16x16x32_bf16 v[84:87], v[146:149], v[194:197], v[84:87]
	v_mfma_f32_16x16x32_bf16 v[80:83], v[154:157], v[194:197], v[80:83]
	v_mfma_f32_16x16x32_bf16 v[36:39], v[146:149], v[202:205], v[36:39]
	v_mfma_f32_16x16x32_bf16 v[28:31], v[154:157], v[202:205], v[28:31]
	v_mfma_f32_16x16x32_bf16 v[100:103], v[150:153], v[182:185], v[100:103]
	v_mfma_f32_16x16x32_bf16 v[104:107], v[158:161], v[182:185], v[104:107]
	v_mfma_f32_16x16x32_bf16 v[116:119], v[150:153], v[190:193], v[116:119]
	v_mfma_f32_16x16x32_bf16 v[120:123], v[158:161], v[190:193], v[120:123]
	v_mfma_f32_16x16x32_bf16 v[84:87], v[150:153], v[198:201], v[84:87]
	v_mfma_f32_16x16x32_bf16 v[80:83], v[158:161], v[198:201], v[80:83]
	v_mfma_f32_16x16x32_bf16 v[36:39], v[150:153], v[206:209], v[36:39]
	v_mfma_f32_16x16x32_bf16 v[28:31], v[158:161], v[206:209], v[28:31]
	v_mfma_f32_16x16x32_bf16 v[124:127], v[162:165], v[178:181], v[124:127]
	v_mfma_f32_16x16x32_bf16 v[112:115], v[170:173], v[178:181], v[112:115]
	v_mfma_f32_16x16x32_bf16 v[92:95], v[162:165], v[186:189], v[92:95]
	v_mfma_f32_16x16x32_bf16 v[88:91], v[170:173], v[186:189], v[88:91]
	v_mfma_f32_16x16x32_bf16 v[44:47], v[162:165], v[194:197], v[44:47]
	v_mfma_f32_16x16x32_bf16 v[40:43], v[170:173], v[194:197], v[40:43]
	v_mfma_f32_16x16x32_bf16 v[4:7], v[162:165], v[202:205], v[4:7]
	v_mfma_f32_16x16x32_bf16 v[0:3], v[170:173], v[202:205], v[0:3]
	v_mfma_f32_16x16x32_bf16 v[124:127], v[166:169], v[182:185], v[124:127]
	v_mfma_f32_16x16x32_bf16 v[112:115], v[174:177], v[182:185], v[112:115]
	v_mfma_f32_16x16x32_bf16 v[92:95], v[166:169], v[190:193], v[92:95]
	v_mfma_f32_16x16x32_bf16 v[88:91], v[174:177], v[190:193], v[88:91]
	v_mfma_f32_16x16x32_bf16 v[44:47], v[166:169], v[198:201], v[44:47]
	v_mfma_f32_16x16x32_bf16 v[40:43], v[174:177], v[198:201], v[40:43]
	v_mfma_f32_16x16x32_bf16 v[4:7], v[166:169], v[206:209], v[4:7]
	v_mfma_f32_16x16x32_bf16 v[0:3], v[174:177], v[206:209], v[0:3]
	s_barrier
	s_setprio 0
	s_add_i32 s45, s45, 2
	s_add_u32 s41, s41, 0x100
	s_addc_u32 s42, s42, 0
	s_add_u32 s43, s43, 0x100
	s_addc_u32 s44, s44, 0
	v_lshl_add_u64 v[136:137], v[136:137], 0, s[16:17]
	s_cmp_gt_u32 s45, 29
	v_lshl_add_u64 v[138:139], v[138:139], 0, s[16:17]
	s_cbranch_scc0 .LBB0_3608
	s_waitcnt vmcnt(0)
	s_cmpk_lt_u32 s24, 0x100
	s_cbranch_scc0 .LBB0_3611
	s_barrier

; template <class Epi, class Sched, bool ALIGN_EPI = false, bool SP2 = false, bool A_TILED = false>
; __device__ __forceinline__ void gemm_phase(PG8_LAS unsigned char* lds, const Gemm g, const Sched& S, const Epi& E, const int wave_s) {
;     ...
;         const bool has_next = Epi::AFTER_DRAIN ? false : S.next(ui + 1, nxt);
;         const char* nA = has_next ? (const char*)g.A + (size_t)nxt.pm * tstepA : cA; const char* nB = has_next ? (const char*)g.Bt + (size_t)nxt.pn * tstep : cB;
;         constexpr bool PEEL = SP2 && !Epi::AFTER_DRAIN;
;         if constexpr (PEEL) {
;             const char* a1 = cA + kstepA; const char* a2 = cA + 2 * kstepA; const char* b2 = cB + 2 * kstep; const char* a3 = a2 + kstepA; const char* b3 = b2 + kstep;
;             PG8_ITER(PG8_MMAZ)
.LBB0_3719:
	s_ashr_i32 s19, s18, 31
	s_lshl_b64 s[20:21], s[18:19], 20
	s_add_u32 s20, s41, s20
	ds_read_b128 v[0:3], v145
	ds_read_b128 v[4:7], v145 offset:1024
	ds_read_b128 v[8:11], v145 offset:2048
	ds_read_b128 v[12:15], v145 offset:3072
	ds_read_b128 v[16:19], v146
	ds_read_b128 v[20:23], v146 offset:1024
	ds_read_b128 v[24:27], v146 offset:2048
	ds_read_b128 v[28:31], v146 offset:3072
	s_addc_u32 s21, s42, s21
	s_ashr_i32 s17, s16, 31
	s_lshl_b64 s[22:23], s[16:17], 20
	s_add_u32 s22, s43, s22
	s_addc_u32 s23, s44, s23
	s_and_b64 s[38:39], s[0:1], exec
	s_cselect_b32 s17, s21, s37
	s_cselect_b32 s19, s20, s36
	s_cselect_b32 s62, s23, s27
	s_cselect_b32 s63, s22, s26
	s_add_u32 s38, s36, 0x80080
	s_addc_u32 s39, s37, 0
	s_add_i32 s64, s47, 0xc000
	v_lshl_add_u64 v[64:65], s[38:39], 0, v[134:135]
	s_mov_b32 m0, s64
	s_add_i32 s65, s47, 0xe000
	ds_read_b128 v[32:35], v147
	ds_read_b128 v[36:39], v147 offset:1024
	ds_read_b128 v[40:43], v147 offset:2048
	ds_read_b128 v[44:47], v147 offset:3072
	ds_read_b128 v[48:51], v147 offset:4096
	ds_read_b128 v[52:55], v147 offset:5120
	ds_read_b128 v[56:59], v147 offset:6144
	ds_read_b128 v[60:63], v147 offset:7168
	global_load_lds_dwordx4 v[64:65], off
	v_lshl_add_u64 v[64:65], s[38:39], 0, v[132:133]
	s_mov_b32 m0, s65
	s_nop 0
	global_load_lds_dwordx4 v[64:65], off
	s_waitcnt vmcnt(8) lgkmcnt(0)
	s_setprio 1
	s_barrier
	v_mfma_f32_16x16x32_bf16 v[88:91], v[0:3], v[56:59], 0
	v_mfma_f32_16x16x32_bf16 v[64:67], v[0:3], v[32:35], 0
	v_mfma_f32_16x16x32_bf16 v[68:71], v[8:11], v[32:35], 0
	v_mfma_f32_16x16x32_bf16 v[72:75], v[0:3], v[40:43], 0
	v_mfma_f32_16x16x32_bf16 v[76:79], v[8:11], v[40:43], 0
	v_mfma_f32_16x16x32_bf16 v[80:83], v[0:3], v[48:51], 0
	v_mfma_f32_16x16x32_bf16 v[84:87], v[8:11], v[48:51], 0
	v_mfma_f32_16x16x32_bf16 v[96:99], v[4:7], v[60:63], v[88:91]
	v_mfma_f32_16x16x32_bf16 v[88:91], v[8:11], v[56:59], 0
	v_mfma_f32_16x16x32_bf16 v[64:67], v[4:7], v[36:39], v[64:67]
	v_mfma_f32_16x16x32_bf16 v[68:71], v[12:15], v[36:39], v[68:71]
	v_mfma_f32_16x16x32_bf16 v[72:75], v[4:7], v[44:47], v[72:75]
	v_mfma_f32_16x16x32_bf16 v[76:79], v[12:15], v[44:47], v[76:79]
	v_mfma_f32_16x16x32_bf16 v[80:83], v[4:7], v[52:55], v[80:83]
	v_mfma_f32_16x16x32_bf16 v[84:87], v[12:15], v[52:55], v[84:87]
	v_mfma_f32_16x16x32_bf16 v[100:103], v[12:15], v[60:63], v[88:91]
	v_mfma_f32_16x16x32_bf16 v[88:91], v[16:19], v[32:35], 0
	v_mfma_f32_16x16x32_bf16 v[32:35], v[24:27], v[32:35], 0
	v_mfma_f32_16x16x32_bf16 v[112:115], v[20:23], v[36:39], v[88:91]
	v_mfma_f32_16x16x32_bf16 v[32:35], v[28:31], v[36:39], v[32:35]
	v_mfma_f32_16x16x32_bf16 v[36:39], v[16:19], v[40:43], 0
	v_mfma_f32_16x16x32_bf16 v[40:43], v[24:27], v[40:43], 0
	v_mfma_f32_16x16x32_bf16 v[36:39], v[20:23], v[44:47], v[36:39]
	v_mfma_f32_16x16x32_bf16 v[40:43], v[28:31], v[44:47], v[40:43]
	v_mfma_f32_16x16x32_bf16 v[44:47], v[16:19], v[48:51], 0
	v_mfma_f32_16x16x32_bf16 v[48:51], v[24:27], v[48:51], 0
	v_mfma_f32_16x16x32_bf16 v[44:47], v[20:23], v[52:55], v[44:47]
	v_mfma_f32_16x16x32_bf16 v[48:51], v[28:31], v[52:55], v[48:51]
	v_mfma_f32_16x16x32_bf16 v[52:55], v[16:19], v[56:59], 0
	v_mfma_f32_16x16x32_bf16 v[56:59], v[24:27], v[56:59], 0
	v_mfma_f32_16x16x32_bf16 v[52:55], v[20:23], v[60:63], v[52:55]
	v_mfma_f32_16x16x32_bf16 v[56:59], v[28:31], v[60:63], v[56:59]
	s_barrier
	s_setprio 0
	s_add_i32 s66, s60, s45
	v_lshl_add_u64 v[242:243], s[26:27], 0, v[128:129]
	s_add_i32 s67, s66, 0x2000
	v_lshl_add_u64 v[148:149], v[242:243], 0, s[12:13]
	s_mov_b32 m0, s66
	v_lshl_add_u64 v[244:245], s[26:27], 0, v[130:131]
	s_add_u32 s38, s26, 0x80100
	ds_read_b128 v[60:63], v147 offset:16384
	ds_read_b128 v[88:91], v147 offset:17408
	ds_read_b128 v[92:95], v147 offset:18432
	ds_read_b128 v[104:107], v147 offset:19456
	ds_read_b128 v[108:111], v147 offset:20480
	ds_read_b128 v[116:119], v147 offset:21504
	ds_read_b128 v[120:123], v147 offset:22528
	ds_read_b128 v[124:127], v147 offset:23552
	global_load_lds_dwordx4 v[148:149], off
	v_lshl_add_u64 v[148:149], v[244:245], 0, s[12:13]
	s_mov_b32 m0, s67
	s_addc_u32 s39, s27, 0
	s_add_i32 s68, s61, s45
	global_load_lds_dwordx4 v[148:149], off
	v_lshl_add_u64 v[148:149], s[38:39], 0, v[128:129]
	s_mov_b32 m0, s68
	s_add_i32 s69, s68, 0x2000
	global_load_lds_dwordx4 v[148:149], off
	v_lshl_add_u64 v[148:149], s[38:39], 0, v[130:131]
	s_mov_b32 m0, s69
	v_lshl_add_u64 v[246:247], s[36:37], 0, v[134:135]
	global_load_lds_dwordx4 v[148:149], off
	v_lshl_add_u64 v[148:149], v[246:247], 0, s[12:13]
	s_mov_b32 m0, s47
	v_lshl_add_u64 v[248:249], s[36:37], 0, v[132:133]
	global_load_lds_dwordx4 v[148:149], off
	v_lshl_add_u64 v[148:149], v[248:249], 0, s[12:13]
	s_mov_b32 m0, s48
	s_nop 0
	global_load_lds_dwordx4 v[148:149], off
	s_waitcnt vmcnt(8) lgkmcnt(0)
	s_setprio 1
	s_barrier
; template <class Epi, class Sched, bool ALIGN_EPI = false, bool SP2 = false, bool A_TILED = false>
; __device__ __forceinline__ void gemm_phase(PG8_LAS unsigned char* lds, const Gemm g, const Sched& S, const Epi& E, const int wave_s) {
;     ...
;         const bool has_next = Epi::AFTER_DRAIN ? false : S.next(ui + 1, nxt);
;         const char* nA = has_next ? (const char*)g.A + (size_t)nxt.pm * tstepA : cA; const char* nB = has_next ? (const char*)g.Bt + (size_t)nxt.pn * tstep : cB;
;         constexpr bool PEEL = SP2 && !Epi::AFTER_DRAIN;
;         if constexpr (PEEL) {
;             const char* a1 = cA + kstepA; const char* a2 = cA + 2 * kstepA; const char* b2 = cB + 2 * kstep; const char* a3 = a2 + kstepA; const char* b3 = b2 + kstep;
;             PG8_ITER(PG8_MMAZ)
	v_mfma_f32_16x16x32_bf16 v[148:151], v[0:3], v[60:63], 0
	v_mfma_f32_16x16x32_bf16 v[158:161], v[0:3], v[92:95], 0
	v_mfma_f32_16x16x32_bf16 v[166:169], v[0:3], v[108:111], 0
	v_mfma_f32_16x16x32_bf16 v[0:3], v[0:3], v[120:123], 0
	v_mfma_f32_16x16x32_bf16 v[150:153], v[4:7], v[88:91], v[148:151]
	v_mfma_f32_16x16x32_bf16 v[158:161], v[4:7], v[104:107], v[158:161]
	v_mfma_f32_16x16x32_bf16 v[166:169], v[4:7], v[116:119], v[166:169]
	v_mfma_f32_16x16x32_bf16 v[0:3], v[4:7], v[124:127], v[0:3]
	v_mfma_f32_16x16x32_bf16 v[4:7], v[8:11], v[120:123], 0
	v_mfma_f32_16x16x32_bf16 v[154:157], v[8:11], v[60:63], 0
	v_mfma_f32_16x16x32_bf16 v[162:165], v[8:11], v[92:95], 0
	v_mfma_f32_16x16x32_bf16 v[170:173], v[8:11], v[108:111], 0
	v_mfma_f32_16x16x32_bf16 v[4:7], v[12:15], v[124:127], v[4:7]
	v_mfma_f32_16x16x32_bf16 v[154:157], v[12:15], v[88:91], v[154:157]
	v_mfma_f32_16x16x32_bf16 v[162:165], v[12:15], v[104:107], v[162:165]
	v_mfma_f32_16x16x32_bf16 v[170:173], v[12:15], v[116:119], v[170:173]
	v_mfma_f32_16x16x32_bf16 v[8:11], v[16:19], v[60:63], 0
	v_mfma_f32_16x16x32_bf16 v[174:177], v[20:23], v[88:91], v[8:11]
	v_mfma_f32_16x16x32_bf16 v[8:11], v[24:27], v[60:63], 0
	v_mfma_f32_16x16x32_bf16 v[60:63], v[28:31], v[88:91], v[8:11]
	v_mfma_f32_16x16x32_bf16 v[8:11], v[16:19], v[92:95], 0
	v_mfma_f32_16x16x32_bf16 v[178:181], v[20:23], v[104:107], v[8:11]
	v_mfma_f32_16x16x32_bf16 v[8:11], v[24:27], v[92:95], 0
	v_mfma_f32_16x16x32_bf16 v[182:185], v[28:31], v[104:107], v[8:11]
	v_mfma_f32_16x16x32_bf16 v[8:11], v[16:19], v[108:111], 0
	v_mfma_f32_16x16x32_bf16 v[186:189], v[20:23], v[116:119], v[8:11]
	v_mfma_f32_16x16x32_bf16 v[8:11], v[24:27], v[108:111], 0
	v_mfma_f32_16x16x32_bf16 v[190:193], v[28:31], v[116:119], v[8:11]
	v_mfma_f32_16x16x32_bf16 v[8:11], v[16:19], v[120:123], 0
	v_mfma_f32_16x16x32_bf16 v[194:197], v[20:23], v[124:127], v[8:11]
	v_mfma_f32_16x16x32_bf16 v[8:11], v[24:27], v[120:123], 0
	v_mfma_f32_16x16x32_bf16 v[198:201], v[28:31], v[124:127], v[8:11]
	s_barrier
	s_setprio 0
	s_add_i32 s70, 0, 0x18000
	s_add_i32 s72, 0, 0x1c000
	v_add_u32_e32 v148, s70, v144
	v_add_u32_e32 v149, s72, v144
	s_nop 0
	ds_read_b128 v[8:11], v148
	ds_read_b128 v[12:15], v148 offset:1024
	ds_read_b128 v[16:19], v148 offset:2048
	ds_read_b128 v[20:23], v148 offset:3072
	ds_read_b128 v[202:205], v149
	ds_read_b128 v[206:209], v149 offset:1024
	ds_read_b128 v[210:213], v149 offset:2048
	ds_read_b128 v[214:217], v149 offset:3072
	s_add_u32 s38, s36, 0x80100
	s_addc_u32 s39, s37, 0
	s_mov_b32 m0, s49
	v_lshl_add_u64 v[88:89], s[38:39], 0, v[134:135]
	ds_read_b128 v[24:27], v147 offset:32768
	ds_read_b128 v[28:31], v147 offset:33792
	ds_read_b128 v[218:221], v147 offset:34816
	ds_read_b128 v[222:225], v147 offset:35840
	ds_read_b128 v[226:229], v147 offset:36864
	ds_read_b128 v[230:233], v147 offset:37888
	ds_read_b128 v[234:237], v147 offset:38912
	ds_read_b128 v[238:241], v147 offset:39936
	global_load_lds_dwordx4 v[88:89], off
	v_lshl_add_u64 v[88:89], s[38:39], 0, v[132:133]
	s_mov_b32 m0, s50
	s_nop 0
	global_load_lds_dwordx4 v[88:89], off
	s_waitcnt vmcnt(8) lgkmcnt(0)
	s_setprio 1
	s_barrier
	v_mfma_f32_16x16x32_bf16 v[64:67], v[8:11], v[24:27], v[64:67]
	v_mfma_f32_16x16x32_bf16 v[120:123], v[12:15], v[28:31], v[64:67]
	v_mfma_f32_16x16x32_bf16 v[64:67], v[16:19], v[24:27], v[68:71]
	v_mfma_f32_16x16x32_bf16 v[124:127], v[20:23], v[28:31], v[64:67]
	v_mfma_f32_16x16x32_bf16 v[64:67], v[8:11], v[218:221], v[72:75]
	v_mfma_f32_16x16x32_bf16 v[104:107], v[12:15], v[222:225], v[64:67]
	v_mfma_f32_16x16x32_bf16 v[64:67], v[16:19], v[218:221], v[76:79]
	v_mfma_f32_16x16x32_bf16 v[108:111], v[20:23], v[222:225], v[64:67]
	v_mfma_f32_16x16x32_bf16 v[64:67], v[8:11], v[226:229], v[80:83]
	v_mfma_f32_16x16x32_bf16 v[88:91], v[12:15], v[230:233], v[64:67]
	v_mfma_f32_16x16x32_bf16 v[64:67], v[16:19], v[226:229], v[84:87]
	v_mfma_f32_16x16x32_bf16 v[92:95], v[20:23], v[230:233], v[64:67]
	v_mfma_f32_16x16x32_bf16 v[64:67], v[8:11], v[234:237], v[96:99]
	v_mfma_f32_16x16x32_bf16 v[68:71], v[16:19], v[234:237], v[100:103]
	v_mfma_f32_16x16x32_bf16 v[64:67], v[12:15], v[238:241], v[64:67]
	v_mfma_f32_16x16x32_bf16 v[68:71], v[20:23], v[238:241], v[68:71]
	v_mfma_f32_16x16x32_bf16 v[72:75], v[202:205], v[24:27], v[112:115]
	v_mfma_f32_16x16x32_bf16 v[24:27], v[210:213], v[24:27], v[32:35]
	v_mfma_f32_16x16x32_bf16 v[116:119], v[214:217], v[28:31], v[24:27]
	v_mfma_f32_16x16x32_bf16 v[24:27], v[202:205], v[218:221], v[36:39]
	v_mfma_f32_16x16x32_bf16 v[96:99], v[206:209], v[222:225], v[24:27]
	v_mfma_f32_16x16x32_bf16 v[24:27], v[210:213], v[218:221], v[40:43]
	v_mfma_f32_16x16x32_bf16 v[100:103], v[214:217], v[222:225], v[24:27]
	v_mfma_f32_16x16x32_bf16 v[24:27], v[202:205], v[226:229], v[44:47]
	v_mfma_f32_16x16x32_bf16 v[80:83], v[206:209], v[230:233], v[24:27]
	v_mfma_f32_16x16x32_bf16 v[24:27], v[210:213], v[226:229], v[48:51]
	v_mfma_f32_16x16x32_bf16 v[84:87], v[214:217], v[230:233], v[24:27]
	v_mfma_f32_16x16x32_bf16 v[24:27], v[202:205], v[234:237], v[52:55]
	v_mfma_f32_16x16x32_bf16 v[48:51], v[206:209], v[238:241], v[24:27]
	v_mfma_f32_16x16x32_bf16 v[24:27], v[210:213], v[234:237], v[56:59]
	v_mfma_f32_16x16x32_bf16 v[112:115], v[206:209], v[28:31], v[72:75]
	v_mfma_f32_16x16x32_bf16 v[52:55], v[214:217], v[238:241], v[24:27]
	s_barrier
	s_setprio 0
	s_add_i32 s70, s70, s45
	s_add_i32 s71, s70, 0x2000
	s_nop 1
	v_lshl_add_u64 v[24:25], v[242:243], 0, s[14:15]
	s_mov_b32 m0, s70
	s_add_u32 s38, s26, 0x80180
	ds_read_b128 v[32:35], v147 offset:49152
	ds_read_b128 v[36:39], v147 offset:50176
	ds_read_b128 v[218:221], v147 offset:51200
	ds_read_b128 v[222:225], v147 offset:52224
	ds_read_b128 v[226:229], v147 offset:53248
	ds_read_b128 v[230:233], v147 offset:54272
	ds_read_b128 v[234:237], v147 offset:55296
	ds_read_b128 v[238:241], v147 offset:56320
	global_load_lds_dwordx4 v[24:25], off
	v_lshl_add_u64 v[24:25], v[244:245], 0, s[14:15]
	s_mov_b32 m0, s71
	s_addc_u32 s39, s27, 0
	s_add_i32 s72, s72, s45
	global_load_lds_dwordx4 v[24:25], off
	v_lshl_add_u64 v[24:25], s[38:39], 0, v[128:129]
	s_mov_b32 m0, s72
	s_add_i32 s73, s72, 0x2000
	global_load_lds_dwordx4 v[24:25], off
	v_lshl_add_u64 v[24:25], s[38:39], 0, v[130:131]
	s_mov_b32 m0, s73
	s_nop 0
	global_load_lds_dwordx4 v[24:25], off
	v_lshl_add_u64 v[24:25], v[246:247], 0, s[14:15]
	s_mov_b32 m0, s56
	s_nop 0
	global_load_lds_dwordx4 v[24:25], off
	v_lshl_add_u64 v[24:25], v[248:249], 0, s[14:15]
	s_mov_b32 m0, s57
	s_nop 0
	global_load_lds_dwordx4 v[24:25], off
	s_waitcnt vmcnt(8) lgkmcnt(0)
	s_setprio 1
	s_barrier
	v_mfma_f32_16x16x32_bf16 v[24:27], v[8:11], v[32:35], v[150:153]
	v_mfma_f32_16x16x32_bf16 v[72:75], v[12:15], v[36:39], v[24:27]
	v_mfma_f32_16x16x32_bf16 v[24:27], v[16:19], v[32:35], v[154:157]
	v_mfma_f32_16x16x32_bf16 v[76:79], v[20:23], v[36:39], v[24:27]
	v_mfma_f32_16x16x32_bf16 v[24:27], v[8:11], v[218:221], v[158:161]
	v_mfma_f32_16x16x32_bf16 v[40:43], v[12:15], v[222:225], v[24:27]
	v_mfma_f32_16x16x32_bf16 v[24:27], v[16:19], v[218:221], v[162:165]
	v_mfma_f32_16x16x32_bf16 v[0:3], v[8:11], v[234:237], v[0:3]
	v_mfma_f32_16x16x32_bf16 v[44:47], v[20:23], v[222:225], v[24:27]
	v_mfma_f32_16x16x32_bf16 v[24:27], v[8:11], v[226:229], v[166:169]
	v_mfma_f32_16x16x32_bf16 v[28:31], v[16:19], v[226:229], v[170:173]
	v_mfma_f32_16x16x32_bf16 v[8:11], v[12:15], v[238:241], v[0:3]
	v_mfma_f32_16x16x32_bf16 v[0:3], v[16:19], v[234:237], v[4:7]
	v_mfma_f32_16x16x32_bf16 v[24:27], v[12:15], v[230:233], v[24:27]
	v_mfma_f32_16x16x32_bf16 v[28:31], v[20:23], v[230:233], v[28:31]
	v_mfma_f32_16x16x32_bf16 v[12:15], v[20:23], v[238:241], v[0:3]
	v_mfma_f32_16x16x32_bf16 v[0:3], v[202:205], v[32:35], v[174:177]
	v_mfma_f32_16x16x32_bf16 v[56:59], v[206:209], v[36:39], v[0:3]
	v_mfma_f32_16x16x32_bf16 v[0:3], v[210:213], v[32:35], v[60:63]
	v_mfma_f32_16x16x32_bf16 v[60:63], v[214:217], v[36:39], v[0:3]
	v_mfma_f32_16x16x32_bf16 v[0:3], v[202:205], v[218:221], v[178:181]
	v_mfma_f32_16x16x32_bf16 v[32:35], v[206:209], v[222:225], v[0:3]
	v_mfma_f32_16x16x32_bf16 v[0:3], v[210:213], v[218:221], v[182:185]
	v_mfma_f32_16x16x32_bf16 v[36:39], v[214:217], v[222:225], v[0:3]
	v_mfma_f32_16x16x32_bf16 v[0:3], v[202:205], v[226:229], v[186:189]
	v_mfma_f32_16x16x32_bf16 v[16:19], v[206:209], v[230:233], v[0:3]
	v_mfma_f32_16x16x32_bf16 v[0:3], v[210:213], v[226:229], v[190:193]
	v_mfma_f32_16x16x32_bf16 v[20:23], v[214:217], v[230:233], v[0:3]
	v_mfma_f32_16x16x32_bf16 v[0:3], v[202:205], v[234:237], v[194:197]
	v_mfma_f32_16x16x32_bf16 v[4:7], v[210:213], v[234:237], v[198:201]
	v_mfma_f32_16x16x32_bf16 v[0:3], v[206:209], v[238:241], v[0:3]
	v_mfma_f32_16x16x32_bf16 v[4:7], v[214:217], v[238:241], v[4:7]
	s_barrier
	s_setprio 0
	s_add_u32 s74, s26, 0x200
	s_addc_u32 s75, s27, 0
	s_add_u32 s26, s36, 0x80180
	s_addc_u32 s27, s37, 0
	s_mov_b32 s76, 0
.LBB0_3720:
	ds_read_b128 v[150:153], v145
	ds_read_b128 v[154:157], v145 offset:1024
	ds_read_b128 v[158:161], v145 offset:2048
	ds_read_b128 v[162:165], v145 offset:3072
	ds_read_b128 v[166:169], v146
	ds_read_b128 v[170:173], v146 offset:1024
	ds_read_b128 v[174:177], v146 offset:2048
	ds_read_b128 v[178:181], v146 offset:3072
	s_add_u32 s36, s26, 0xfff80080
	s_addc_u32 s37, s27, -1
	s_cmp_eq_u32 s76, 28
	s_cselect_b32 s39, s17, s37
	s_cselect_b32 s38, s19, s36
	s_cselect_b32 s37, s62, s75
	s_cselect_b32 s36, s63, s74
	s_mov_b32 m0, s64
	v_lshl_add_u64 v[214:215], s[26:27], 0, v[138:139]
	ds_read_b128 v[182:185], v147
	ds_read_b128 v[186:189], v147 offset:1024
	ds_read_b128 v[190:193], v147 offset:2048
	ds_read_b128 v[194:197], v147 offset:3072
	ds_read_b128 v[198:201], v147 offset:4096
	ds_read_b128 v[202:205], v147 offset:5120
	ds_read_b128 v[206:209], v147 offset:6144
	ds_read_b128 v[210:213], v147 offset:7168
	global_load_lds_dwordx4 v[214:215], off
	v_lshl_add_u64 v[214:215], s[26:27], 0, v[136:137]
	s_mov_b32 m0, s65
	s_nop 0
	global_load_lds_dwordx4 v[214:215], off
	s_waitcnt vmcnt(8) lgkmcnt(0)
	s_setprio 1
	s_barrier
	v_mfma_f32_16x16x32_bf16 v[120:123], v[150:153], v[182:185], v[120:123]
	v_mfma_f32_16x16x32_bf16 v[124:127], v[158:161], v[182:185], v[124:127]
	v_mfma_f32_16x16x32_bf16 v[104:107], v[150:153], v[190:193], v[104:107]
	v_mfma_f32_16x16x32_bf16 v[108:111], v[158:161], v[190:193], v[108:111]
	v_mfma_f32_16x16x32_bf16 v[88:91], v[150:153], v[198:201], v[88:91]
	v_mfma_f32_16x16x32_bf16 v[92:95], v[158:161], v[198:201], v[92:95]
	v_mfma_f32_16x16x32_bf16 v[64:67], v[150:153], v[206:209], v[64:67]
	v_mfma_f32_16x16x32_bf16 v[68:71], v[158:161], v[206:209], v[68:71]
	v_mfma_f32_16x16x32_bf16 v[120:123], v[154:157], v[186:189], v[120:123]
	v_mfma_f32_16x16x32_bf16 v[124:127], v[162:165], v[186:189], v[124:127]
	v_mfma_f32_16x16x32_bf16 v[104:107], v[154:157], v[194:197], v[104:107]
	v_mfma_f32_16x16x32_bf16 v[108:111], v[162:165], v[194:197], v[108:111]
	v_mfma_f32_16x16x32_bf16 v[88:91], v[154:157], v[202:205], v[88:91]
	v_mfma_f32_16x16x32_bf16 v[92:95], v[162:165], v[202:205], v[92:95]
	v_mfma_f32_16x16x32_bf16 v[64:67], v[154:157], v[210:213], v[64:67]
	v_mfma_f32_16x16x32_bf16 v[68:71], v[162:165], v[210:213], v[68:71]
	v_mfma_f32_16x16x32_bf16 v[112:115], v[166:169], v[182:185], v[112:115]
	v_mfma_f32_16x16x32_bf16 v[116:119], v[174:177], v[182:185], v[116:119]
	v_mfma_f32_16x16x32_bf16 v[96:99], v[166:169], v[190:193], v[96:99]
	v_mfma_f32_16x16x32_bf16 v[100:103], v[174:177], v[190:193], v[100:103]
	v_mfma_f32_16x16x32_bf16 v[80:83], v[166:169], v[198:201], v[80:83]
	v_mfma_f32_16x16x32_bf16 v[84:87], v[174:177], v[198:201], v[84:87]
	v_mfma_f32_16x16x32_bf16 v[48:51], v[166:169], v[206:209], v[48:51]
	v_mfma_f32_16x16x32_bf16 v[52:55], v[174:177], v[206:209], v[52:55]
	v_mfma_f32_16x16x32_bf16 v[112:115], v[170:173], v[186:189], v[112:115]
	v_mfma_f32_16x16x32_bf16 v[116:119], v[178:181], v[186:189], v[116:119]
	v_mfma_f32_16x16x32_bf16 v[96:99], v[170:173], v[194:197], v[96:99]
	v_mfma_f32_16x16x32_bf16 v[100:103], v[178:181], v[194:197], v[100:103]
	v_mfma_f32_16x16x32_bf16 v[80:83], v[170:173], v[202:205], v[80:83]
	v_mfma_f32_16x16x32_bf16 v[84:87], v[178:181], v[202:205], v[84:87]
	v_mfma_f32_16x16x32_bf16 v[48:51], v[170:173], v[210:213], v[48:51]
	v_mfma_f32_16x16x32_bf16 v[52:55], v[178:181], v[210:213], v[52:55]
	s_barrier
	s_setprio 0
	s_mov_b32 m0, s66
	v_lshl_add_u64 v[214:215], s[36:37], 0, v[128:129]
	s_add_u32 s78, s36, 0x80000
	ds_read_b128 v[182:185], v147 offset:16384
	ds_read_b128 v[186:189], v147 offset:17408
	ds_read_b128 v[190:193], v147 offset:18432
	ds_read_b128 v[194:197], v147 offset:19456
	ds_read_b128 v[198:201], v147 offset:20480
	ds_read_b128 v[202:205], v147 offset:21504
	ds_read_b128 v[206:209], v147 offset:22528
	ds_read_b128 v[210:213], v147 offset:23552
	global_load_lds_dwordx4 v[214:215], off
	v_lshl_add_u64 v[216:217], s[36:37], 0, v[130:131]
	s_mov_b32 m0, s67
	s_addc_u32 s79, s37, 0
	global_load_lds_dwordx4 v[216:217], off
	v_lshl_add_u64 v[218:219], s[78:79], 0, v[128:129]
	s_mov_b32 m0, s68
	v_lshl_add_u64 v[220:221], s[38:39], 0, v[132:133]
	global_load_lds_dwordx4 v[218:219], off
	v_lshl_add_u64 v[218:219], s[78:79], 0, v[130:131]
	s_mov_b32 m0, s69
	s_nop 0
	global_load_lds_dwordx4 v[218:219], off
	v_lshl_add_u64 v[218:219], s[38:39], 0, v[134:135]
	s_mov_b32 m0, s47
	s_nop 0
	global_load_lds_dwordx4 v[218:219], off
	s_mov_b32 m0, s48
	s_nop 0
	global_load_lds_dwordx4 v[220:221], off
	s_waitcnt vmcnt(8) lgkmcnt(0)
	s_setprio 1
	s_barrier
	v_mfma_f32_16x16x32_bf16 v[72:75], v[150:153], v[182:185], v[72:75]
	v_mfma_f32_16x16x32_bf16 v[76:79], v[158:161], v[182:185], v[76:79]
	v_mfma_f32_16x16x32_bf16 v[40:43], v[150:153], v[190:193], v[40:43]
	v_mfma_f32_16x16x32_bf16 v[44:47], v[158:161], v[190:193], v[44:47]
	v_mfma_f32_16x16x32_bf16 v[24:27], v[150:153], v[198:201], v[24:27]
	v_mfma_f32_16x16x32_bf16 v[28:31], v[158:161], v[198:201], v[28:31]
	v_mfma_f32_16x16x32_bf16 v[8:11], v[150:153], v[206:209], v[8:11]
	v_mfma_f32_16x16x32_bf16 v[12:15], v[158:161], v[206:209], v[12:15]
	v_mfma_f32_16x16x32_bf16 v[72:75], v[154:157], v[186:189], v[72:75]
	v_mfma_f32_16x16x32_bf16 v[76:79], v[162:165], v[186:189], v[76:79]
	v_mfma_f32_16x16x32_bf16 v[40:43], v[154:157], v[194:197], v[40:43]
	v_mfma_f32_16x16x32_bf16 v[44:47], v[162:165], v[194:197], v[44:47]
	v_mfma_f32_16x16x32_bf16 v[24:27], v[154:157], v[202:205], v[24:27]
	v_mfma_f32_16x16x32_bf16 v[28:31], v[162:165], v[202:205], v[28:31]
	v_mfma_f32_16x16x32_bf16 v[8:11], v[154:157], v[210:213], v[8:11]
	v_mfma_f32_16x16x32_bf16 v[12:15], v[162:165], v[210:213], v[12:15]
	v_mfma_f32_16x16x32_bf16 v[56:59], v[166:169], v[182:185], v[56:59]
	v_mfma_f32_16x16x32_bf16 v[60:63], v[174:177], v[182:185], v[60:63]
	v_mfma_f32_16x16x32_bf16 v[32:35], v[166:169], v[190:193], v[32:35]
	v_mfma_f32_16x16x32_bf16 v[36:39], v[174:177], v[190:193], v[36:39]
	v_mfma_f32_16x16x32_bf16 v[16:19], v[166:169], v[198:201], v[16:19]
	v_mfma_f32_16x16x32_bf16 v[20:23], v[174:177], v[198:201], v[20:23]
	v_mfma_f32_16x16x32_bf16 v[0:3], v[166:169], v[206:209], v[0:3]
	v_mfma_f32_16x16x32_bf16 v[4:7], v[174:177], v[206:209], v[4:7]
	v_mfma_f32_16x16x32_bf16 v[56:59], v[170:173], v[186:189], v[56:59]
	v_mfma_f32_16x16x32_bf16 v[60:63], v[178:181], v[186:189], v[60:63]
	v_mfma_f32_16x16x32_bf16 v[32:35], v[170:173], v[194:197], v[32:35]
	v_mfma_f32_16x16x32_bf16 v[36:39], v[178:181], v[194:197], v[36:39]
	v_mfma_f32_16x16x32_bf16 v[16:19], v[170:173], v[202:205], v[16:19]
	v_mfma_f32_16x16x32_bf16 v[20:23], v[178:181], v[202:205], v[20:23]
	v_mfma_f32_16x16x32_bf16 v[0:3], v[170:173], v[210:213], v[0:3]
	v_mfma_f32_16x16x32_bf16 v[4:7], v[178:181], v[210:213], v[4:7]
	s_barrier
; #define PG8_BAR __builtin_amdgcn_s_barrier()
; template <class Epi, class Sched, bool ALIGN_EPI = false, bool SP2 = false, bool A_TILED = false>
; __device__ __forceinline__ void gemm_phase(PG8_LAS unsigned char* lds, const Gemm g, const Sched& S, const Epi& E, const int wave_s) {
;     ...
;         if constexpr (ALIGN_EPI) { if (wr == 0) PG8_BAR; }
	s_setprio 0
	ds_read_b128 v[150:153], v148
	ds_read_b128 v[154:157], v148 offset:1024
	ds_read_b128 v[158:161], v148 offset:2048
	ds_read_b128 v[162:165], v148 offset:3072
	ds_read_b128 v[166:169], v149
	ds_read_b128 v[170:173], v149 offset:1024
	ds_read_b128 v[174:177], v149 offset:2048
	ds_read_b128 v[178:181], v149 offset:3072
	s_add_u32 s38, s38, 0x80000
	s_addc_u32 s39, s39, 0
	s_mov_b32 m0, s49
	v_lshl_add_u64 v[222:223], s[38:39], 0, v[134:135]
	ds_read_b128 v[182:185], v147 offset:32768
	ds_read_b128 v[186:189], v147 offset:33792
	ds_read_b128 v[190:193], v147 offset:34816
	ds_read_b128 v[194:197], v147 offset:35840
	ds_read_b128 v[198:201], v147 offset:36864
	ds_read_b128 v[202:205], v147 offset:37888
	ds_read_b128 v[206:209], v147 offset:38912
	ds_read_b128 v[210:213], v147 offset:39936
	global_load_lds_dwordx4 v[222:223], off
	v_lshl_add_u64 v[222:223], s[38:39], 0, v[132:133]
	s_mov_b32 m0, s50
	s_nop 0
	global_load_lds_dwordx4 v[222:223], off
	s_waitcnt vmcnt(8) lgkmcnt(0)
	s_setprio 1
	s_barrier
	v_mfma_f32_16x16x32_bf16 v[120:123], v[150:153], v[182:185], v[120:123]
	v_mfma_f32_16x16x32_bf16 v[124:127], v[158:161], v[182:185], v[124:127]
	v_mfma_f32_16x16x32_bf16 v[104:107], v[150:153], v[190:193], v[104:107]
	v_mfma_f32_16x16x32_bf16 v[108:111], v[158:161], v[190:193], v[108:111]
	v_mfma_f32_16x16x32_bf16 v[88:91], v[150:153], v[198:201], v[88:91]
	v_mfma_f32_16x16x32_bf16 v[92:95], v[158:161], v[198:201], v[92:95]
	v_mfma_f32_16x16x32_bf16 v[64:67], v[150:153], v[206:209], v[64:67]
	v_mfma_f32_16x16x32_bf16 v[68:71], v[158:161], v[206:209], v[68:71]
	v_mfma_f32_16x16x32_bf16 v[120:123], v[154:157], v[186:189], v[120:123]
	v_mfma_f32_16x16x32_bf16 v[124:127], v[162:165], v[186:189], v[124:127]
	v_mfma_f32_16x16x32_bf16 v[104:107], v[154:157], v[194:197], v[104:107]
	v_mfma_f32_16x16x32_bf16 v[108:111], v[162:165], v[194:197], v[108:111]
	v_mfma_f32_16x16x32_bf16 v[88:91], v[154:157], v[202:205], v[88:91]
	v_mfma_f32_16x16x32_bf16 v[92:95], v[162:165], v[202:205], v[92:95]
	v_mfma_f32_16x16x32_bf16 v[64:67], v[154:157], v[210:213], v[64:67]
	v_mfma_f32_16x16x32_bf16 v[68:71], v[162:165], v[210:213], v[68:71]
	v_mfma_f32_16x16x32_bf16 v[112:115], v[166:169], v[182:185], v[112:115]
	v_mfma_f32_16x16x32_bf16 v[116:119], v[174:177], v[182:185], v[116:119]
	v_mfma_f32_16x16x32_bf16 v[96:99], v[166:169], v[190:193], v[96:99]
	v_mfma_f32_16x16x32_bf16 v[100:103], v[174:177], v[190:193], v[100:103]
	v_mfma_f32_16x16x32_bf16 v[80:83], v[166:169], v[198:201], v[80:83]
	v_mfma_f32_16x16x32_bf16 v[84:87], v[174:177], v[198:201], v[84:87]
	v_mfma_f32_16x16x32_bf16 v[48:51], v[166:169], v[206:209], v[48:51]
	v_mfma_f32_16x16x32_bf16 v[52:55], v[174:177], v[206:209], v[52:55]
	v_mfma_f32_16x16x32_bf16 v[112:115], v[170:173], v[186:189], v[112:115]
	v_mfma_f32_16x16x32_bf16 v[116:119], v[178:181], v[186:189], v[116:119]
	v_mfma_f32_16x16x32_bf16 v[96:99], v[170:173], v[194:197], v[96:99]
	v_mfma_f32_16x16x32_bf16 v[100:103], v[178:181], v[194:197], v[100:103]
	v_mfma_f32_16x16x32_bf16 v[80:83], v[170:173], v[202:205], v[80:83]
	v_mfma_f32_16x16x32_bf16 v[84:87], v[178:181], v[202:205], v[84:87]
	v_mfma_f32_16x16x32_bf16 v[48:51], v[170:173], v[210:213], v[48:51]
	v_mfma_f32_16x16x32_bf16 v[52:55], v[178:181], v[210:213], v[52:55]
	s_barrier
	s_setprio 0
	s_mov_b32 m0, s70
	v_lshl_add_u64 v[214:215], v[214:215], 0, s[6:7]
	s_add_u32 s36, s36, 0x80080
	ds_read_b128 v[182:185], v147 offset:49152
	ds_read_b128 v[186:189], v147 offset:50176
	ds_read_b128 v[190:193], v147 offset:51200
	ds_read_b128 v[194:197], v147 offset:52224
	ds_read_b128 v[198:201], v147 offset:53248
	ds_read_b128 v[202:205], v147 offset:54272
	ds_read_b128 v[206:209], v147 offset:55296
	ds_read_b128 v[210:213], v147 offset:56320
	global_load_lds_dwordx4 v[214:215], off
	v_lshl_add_u64 v[214:215], v[216:217], 0, s[6:7]
	s_mov_b32 m0, s71
	s_addc_u32 s37, s37, 0
	global_load_lds_dwordx4 v[214:215], off
	v_lshl_add_u64 v[214:215], s[36:37], 0, v[128:129]
	s_mov_b32 m0, s72
	s_nop 0
	global_load_lds_dwordx4 v[214:215], off
	v_lshl_add_u64 v[214:215], s[36:37], 0, v[130:131]
	s_mov_b32 m0, s73
	s_nop 0
	global_load_lds_dwordx4 v[214:215], off
	v_lshl_add_u64 v[214:215], v[218:219], 0, s[6:7]
	s_mov_b32 m0, s56
	s_nop 0
	global_load_lds_dwordx4 v[214:215], off
	v_lshl_add_u64 v[214:215], v[220:221], 0, s[6:7]
	s_mov_b32 m0, s57
	s_nop 0
	global_load_lds_dwordx4 v[214:215], off
	s_waitcnt vmcnt(8) lgkmcnt(0)
	s_setprio 1
	s_barrier
	v_mfma_f32_16x16x32_bf16 v[72:75], v[150:153], v[182:185], v[72:75]
	v_mfma_f32_16x16x32_bf16 v[76:79], v[158:161], v[182:185], v[76:79]
	v_mfma_f32_16x16x32_bf16 v[40:43], v[150:153], v[190:193], v[40:43]
	v_mfma_f32_16x16x32_bf16 v[44:47], v[158:161], v[190:193], v[44:47]
	v_mfma_f32_16x16x32_bf16 v[24:27], v[150:153], v[198:201], v[24:27]
	v_mfma_f32_16x16x32_bf16 v[28:31], v[158:161], v[198:201], v[28:31]
	v_mfma_f32_16x16x32_bf16 v[8:11], v[150:153], v[206:209], v[8:11]
	v_mfma_f32_16x16x32_bf16 v[12:15], v[158:161], v[206:209], v[12:15]
	v_mfma_f32_16x16x32_bf16 v[72:75], v[154:157], v[186:189], v[72:75]
	v_mfma_f32_16x16x32_bf16 v[76:79], v[162:165], v[186:189], v[76:79]
	v_mfma_f32_16x16x32_bf16 v[40:43], v[154:157], v[194:197], v[40:43]
	v_mfma_f32_16x16x32_bf16 v[44:47], v[162:165], v[194:197], v[44:47]
	v_mfma_f32_16x16x32_bf16 v[24:27], v[154:157], v[202:205], v[24:27]
	v_mfma_f32_16x16x32_bf16 v[28:31], v[162:165], v[202:205], v[28:31]
	v_mfma_f32_16x16x32_bf16 v[8:11], v[154:157], v[210:213], v[8:11]
	v_mfma_f32_16x16x32_bf16 v[12:15], v[162:165], v[210:213], v[12:15]
	v_mfma_f32_16x16x32_bf16 v[56:59], v[166:169], v[182:185], v[56:59]
	v_mfma_f32_16x16x32_bf16 v[60:63], v[174:177], v[182:185], v[60:63]
	v_mfma_f32_16x16x32_bf16 v[32:35], v[166:169], v[190:193], v[32:35]
	v_mfma_f32_16x16x32_bf16 v[36:39], v[174:177], v[190:193], v[36:39]
	v_mfma_f32_16x16x32_bf16 v[16:19], v[166:169], v[198:201], v[16:19]
	v_mfma_f32_16x16x32_bf16 v[20:23], v[174:177], v[198:201], v[20:23]
	v_mfma_f32_16x16x32_bf16 v[0:3], v[166:169], v[206:209], v[0:3]
	v_mfma_f32_16x16x32_bf16 v[4:7], v[174:177], v[206:209], v[4:7]
	v_mfma_f32_16x16x32_bf16 v[56:59], v[170:173], v[186:189], v[56:59]
	v_mfma_f32_16x16x32_bf16 v[60:63], v[178:181], v[186:189], v[60:63]
	v_mfma_f32_16x16x32_bf16 v[32:35], v[170:173], v[194:197], v[32:35]
	v_mfma_f32_16x16x32_bf16 v[36:39], v[178:181], v[194:197], v[36:39]
	v_mfma_f32_16x16x32_bf16 v[16:19], v[170:173], v[202:205], v[16:19]
	v_mfma_f32_16x16x32_bf16 v[20:23], v[178:181], v[202:205], v[20:23]
	v_mfma_f32_16x16x32_bf16 v[0:3], v[170:173], v[210:213], v[0:3]
	v_mfma_f32_16x16x32_bf16 v[4:7], v[178:181], v[210:213], v[4:7]
	s_barrier
	s_setprio 0
	s_add_i32 s76, s76, 2
	s_add_u32 s74, s74, 0x100
	s_addc_u32 s75, s75, 0
	s_add_u32 s26, s26, 0x100
	s_addc_u32 s27, s27, 0
	s_cmp_gt_u32 s76, 29
	s_cbranch_scc0 .LBB0_3720
	s_and_b64 vcc, exec, s[8:9]
	s_cbranch_vccz .LBB0_3723
	s_barrier

.LBB0_3793:
	ds_read_b128 v[146:149], v140
	ds_read_b128 v[150:153], v140 offset:1024
	ds_read_b128 v[154:157], v140 offset:2048
	ds_read_b128 v[158:161], v140 offset:3072
	ds_read_b128 v[162:165], v141
	ds_read_b128 v[166:169], v141 offset:1024
	ds_read_b128 v[170:173], v141 offset:2048
	ds_read_b128 v[174:177], v141 offset:3072
	s_add_u32 s16, s58, s40
	s_addc_u32 s17, s59, s41
	s_add_u32 s18, s58, s38
	s_addc_u32 s19, s59, s39
	s_cmpk_eq_i32 s42, 0x7c
	s_cselect_b32 s20, s4, s16
	s_cselect_b32 s21, s5, s17
	s_cselect_b32 s18, s0, s18
	s_cselect_b32 s19, s1, s19
	s_add_u32 s16, s20, 0x8000
	s_addc_u32 s17, s21, 0
	s_mov_b32 m0, s43
	v_lshl_add_u64 v[210:211], s[58:59], 0, v[138:139]
	ds_read_b128 v[178:181], v142
	ds_read_b128 v[182:185], v142 offset:1024
	ds_read_b128 v[186:189], v142 offset:2048
	ds_read_b128 v[190:193], v142 offset:3072
	ds_read_b128 v[194:197], v142 offset:4096
	ds_read_b128 v[198:201], v142 offset:5120
	ds_read_b128 v[202:205], v142 offset:6144
	ds_read_b128 v[206:209], v142 offset:7168
	global_load_lds_dwordx4 v[210:211], off
	v_lshl_add_u64 v[210:211], s[58:59], 0, v[136:137]
	s_mov_b32 m0, s44
	s_nop 0
	global_load_lds_dwordx4 v[210:211], off
	s_waitcnt vmcnt(8) lgkmcnt(0)
	s_setprio 1
	s_barrier
	v_mfma_f32_16x16x32_bf16 v[32:35], v[146:149], v[178:181], v[32:35]
	v_mfma_f32_16x16x32_bf16 v[36:39], v[154:157], v[178:181], v[36:39]
	v_mfma_f32_16x16x32_bf16 v[76:79], v[146:149], v[186:189], v[76:79]
	v_mfma_f32_16x16x32_bf16 v[80:83], v[154:157], v[186:189], v[80:83]
	v_mfma_f32_16x16x32_bf16 v[92:95], v[146:149], v[194:197], v[92:95]
	v_mfma_f32_16x16x32_bf16 v[84:87], v[154:157], v[194:197], v[84:87]
	v_mfma_f32_16x16x32_bf16 v[108:111], v[146:149], v[202:205], v[108:111]
	v_mfma_f32_16x16x32_bf16 v[104:107], v[154:157], v[202:205], v[104:107]
	v_mfma_f32_16x16x32_bf16 v[32:35], v[150:153], v[182:185], v[32:35]
	v_mfma_f32_16x16x32_bf16 v[36:39], v[158:161], v[182:185], v[36:39]
	v_mfma_f32_16x16x32_bf16 v[76:79], v[150:153], v[190:193], v[76:79]
	v_mfma_f32_16x16x32_bf16 v[80:83], v[158:161], v[190:193], v[80:83]
	v_mfma_f32_16x16x32_bf16 v[92:95], v[150:153], v[198:201], v[92:95]
	v_mfma_f32_16x16x32_bf16 v[84:87], v[158:161], v[198:201], v[84:87]
	v_mfma_f32_16x16x32_bf16 v[108:111], v[150:153], v[206:209], v[108:111]
	v_mfma_f32_16x16x32_bf16 v[104:107], v[158:161], v[206:209], v[104:107]
	v_mfma_f32_16x16x32_bf16 v[40:43], v[162:165], v[178:181], v[40:43]
	v_mfma_f32_16x16x32_bf16 v[44:47], v[170:173], v[178:181], v[44:47]
	v_mfma_f32_16x16x32_bf16 v[68:71], v[162:165], v[186:189], v[68:71]
	v_mfma_f32_16x16x32_bf16 v[64:67], v[170:173], v[186:189], v[64:67]
	v_mfma_f32_16x16x32_bf16 v[60:63], v[162:165], v[194:197], v[60:63]
	v_mfma_f32_16x16x32_bf16 v[56:59], v[170:173], v[194:197], v[56:59]
	v_mfma_f32_16x16x32_bf16 v[100:103], v[162:165], v[202:205], v[100:103]
	v_mfma_f32_16x16x32_bf16 v[96:99], v[170:173], v[202:205], v[96:99]
	v_mfma_f32_16x16x32_bf16 v[40:43], v[166:169], v[182:185], v[40:43]
	v_mfma_f32_16x16x32_bf16 v[44:47], v[174:177], v[182:185], v[44:47]
	v_mfma_f32_16x16x32_bf16 v[68:71], v[166:169], v[190:193], v[68:71]
	v_mfma_f32_16x16x32_bf16 v[64:67], v[174:177], v[190:193], v[64:67]
	v_mfma_f32_16x16x32_bf16 v[60:63], v[166:169], v[198:201], v[60:63]
	v_mfma_f32_16x16x32_bf16 v[56:59], v[174:177], v[198:201], v[56:59]
	v_mfma_f32_16x16x32_bf16 v[100:103], v[166:169], v[206:209], v[100:103]
	v_mfma_f32_16x16x32_bf16 v[96:99], v[174:177], v[206:209], v[96:99]
	s_barrier
	s_setprio 0
	s_mov_b32 m0, s45
	v_lshl_add_u64 v[210:211], s[18:19], 0, v[130:131]
	s_add_u32 s54, s18, 0x200000
	ds_read_b128 v[178:181], v142 offset:16384
	ds_read_b128 v[182:185], v142 offset:17408
	ds_read_b128 v[186:189], v142 offset:18432
	ds_read_b128 v[190:193], v142 offset:19456
	ds_read_b128 v[194:197], v142 offset:20480
	ds_read_b128 v[198:201], v142 offset:21504
	ds_read_b128 v[202:205], v142 offset:22528
	ds_read_b128 v[206:209], v142 offset:23552
	global_load_lds_dwordx4 v[210:211], off
	v_lshl_add_u64 v[212:213], s[18:19], 0, v[134:135]
	s_mov_b32 m0, s46
	s_addc_u32 s55, s19, 0
	global_load_lds_dwordx4 v[212:213], off
	v_lshl_add_u64 v[214:215], s[54:55], 0, v[130:131]
	s_mov_b32 m0, s47
	s_nop 0
	global_load_lds_dwordx4 v[214:215], off
	v_lshl_add_u64 v[214:215], s[54:55], 0, v[134:135]
	s_mov_b32 m0, s48
	s_nop 0
	global_load_lds_dwordx4 v[214:215], off
	v_lshl_add_u64 v[214:215], s[20:21], 0, v[128:129]
	s_mov_b32 m0, s25
	s_nop 0
	global_load_lds_dwordx4 v[214:215], off
	v_lshl_add_u64 v[214:215], s[20:21], 0, v[132:133]
	s_mov_b32 m0, s26
	s_nop 0
	global_load_lds_dwordx4 v[214:215], off
	s_waitcnt vmcnt(8) lgkmcnt(0)
	s_setprio 1
	s_barrier
	v_mfma_f32_16x16x32_bf16 v[124:127], v[146:149], v[178:181], v[124:127]
	v_mfma_f32_16x16x32_bf16 v[120:123], v[154:157], v[178:181], v[120:123]
	v_mfma_f32_16x16x32_bf16 v[88:91], v[146:149], v[186:189], v[88:91]
	v_mfma_f32_16x16x32_bf16 v[72:75], v[154:157], v[186:189], v[72:75]
	v_mfma_f32_16x16x32_bf16 v[28:31], v[146:149], v[194:197], v[28:31]
	v_mfma_f32_16x16x32_bf16 v[24:27], v[154:157], v[194:197], v[24:27]
	v_mfma_f32_16x16x32_bf16 v[12:15], v[146:149], v[202:205], v[12:15]
	v_mfma_f32_16x16x32_bf16 v[8:11], v[154:157], v[202:205], v[8:11]
	v_mfma_f32_16x16x32_bf16 v[124:127], v[150:153], v[182:185], v[124:127]
	v_mfma_f32_16x16x32_bf16 v[120:123], v[158:161], v[182:185], v[120:123]
	v_mfma_f32_16x16x32_bf16 v[88:91], v[150:153], v[190:193], v[88:91]
	v_mfma_f32_16x16x32_bf16 v[72:75], v[158:161], v[190:193], v[72:75]
	v_mfma_f32_16x16x32_bf16 v[28:31], v[150:153], v[198:201], v[28:31]
	v_mfma_f32_16x16x32_bf16 v[24:27], v[158:161], v[198:201], v[24:27]
	v_mfma_f32_16x16x32_bf16 v[12:15], v[150:153], v[206:209], v[12:15]
	v_mfma_f32_16x16x32_bf16 v[8:11], v[158:161], v[206:209], v[8:11]
	v_mfma_f32_16x16x32_bf16 v[116:119], v[162:165], v[178:181], v[116:119]
	v_mfma_f32_16x16x32_bf16 v[112:115], v[170:173], v[178:181], v[112:115]
	v_mfma_f32_16x16x32_bf16 v[52:55], v[162:165], v[186:189], v[52:55]
	v_mfma_f32_16x16x32_bf16 v[48:51], v[170:173], v[186:189], v[48:51]
	v_mfma_f32_16x16x32_bf16 v[20:23], v[162:165], v[194:197], v[20:23]
	v_mfma_f32_16x16x32_bf16 v[16:19], v[170:173], v[194:197], v[16:19]
	v_mfma_f32_16x16x32_bf16 v[4:7], v[162:165], v[202:205], v[4:7]
	v_mfma_f32_16x16x32_bf16 v[0:3], v[170:173], v[202:205], v[0:3]
	v_mfma_f32_16x16x32_bf16 v[116:119], v[166:169], v[182:185], v[116:119]
	v_mfma_f32_16x16x32_bf16 v[112:115], v[174:177], v[182:185], v[112:115]
	v_mfma_f32_16x16x32_bf16 v[52:55], v[166:169], v[190:193], v[52:55]
	v_mfma_f32_16x16x32_bf16 v[48:51], v[174:177], v[190:193], v[48:51]
	v_mfma_f32_16x16x32_bf16 v[20:23], v[166:169], v[198:201], v[20:23]
	v_mfma_f32_16x16x32_bf16 v[16:19], v[174:177], v[198:201], v[16:19]
	v_mfma_f32_16x16x32_bf16 v[4:7], v[166:169], v[206:209], v[4:7]
	v_mfma_f32_16x16x32_bf16 v[0:3], v[174:177], v[206:209], v[0:3]
	s_barrier
	s_setprio 0
	ds_read_b128 v[146:149], v143
	ds_read_b128 v[150:153], v143 offset:1024
	ds_read_b128 v[154:157], v143 offset:2048
	ds_read_b128 v[158:161], v143 offset:3072
	ds_read_b128 v[162:165], v144
	ds_read_b128 v[166:169], v144 offset:1024
	ds_read_b128 v[170:173], v144 offset:2048
	ds_read_b128 v[174:177], v144 offset:3072
	s_add_u32 s20, s20, 0x4000
	s_addc_u32 s21, s21, 0
	s_mov_b32 m0, s27
	v_lshl_add_u64 v[214:215], s[20:21], 0, v[128:129]
	ds_read_b128 v[178:181], v142 offset:32768
	ds_read_b128 v[182:185], v142 offset:33792
	ds_read_b128 v[186:189], v142 offset:34816
	ds_read_b128 v[190:193], v142 offset:35840
	ds_read_b128 v[194:197], v142 offset:36864
	ds_read_b128 v[198:201], v142 offset:37888
	ds_read_b128 v[202:205], v142 offset:38912
	ds_read_b128 v[206:209], v142 offset:39936
	global_load_lds_dwordx4 v[214:215], off
	v_lshl_add_u64 v[214:215], s[20:21], 0, v[132:133]
	s_mov_b32 m0, s34
	s_nop 0
	global_load_lds_dwordx4 v[214:215], off
	s_waitcnt vmcnt(8) lgkmcnt(0)
	s_setprio 1
	s_barrier
	v_mfma_f32_16x16x32_bf16 v[32:35], v[146:149], v[178:181], v[32:35]
	v_mfma_f32_16x16x32_bf16 v[36:39], v[154:157], v[178:181], v[36:39]
	v_mfma_f32_16x16x32_bf16 v[76:79], v[146:149], v[186:189], v[76:79]
	v_mfma_f32_16x16x32_bf16 v[80:83], v[154:157], v[186:189], v[80:83]
	v_mfma_f32_16x16x32_bf16 v[92:95], v[146:149], v[194:197], v[92:95]
	v_mfma_f32_16x16x32_bf16 v[84:87], v[154:157], v[194:197], v[84:87]
	v_mfma_f32_16x16x32_bf16 v[108:111], v[146:149], v[202:205], v[108:111]
	v_mfma_f32_16x16x32_bf16 v[104:107], v[154:157], v[202:205], v[104:107]
	v_mfma_f32_16x16x32_bf16 v[32:35], v[150:153], v[182:185], v[32:35]
	v_mfma_f32_16x16x32_bf16 v[36:39], v[158:161], v[182:185], v[36:39]
	v_mfma_f32_16x16x32_bf16 v[76:79], v[150:153], v[190:193], v[76:79]
	v_mfma_f32_16x16x32_bf16 v[80:83], v[158:161], v[190:193], v[80:83]
	v_mfma_f32_16x16x32_bf16 v[92:95], v[150:153], v[198:201], v[92:95]
	v_mfma_f32_16x16x32_bf16 v[84:87], v[158:161], v[198:201], v[84:87]
	v_mfma_f32_16x16x32_bf16 v[108:111], v[150:153], v[206:209], v[108:111]
	v_mfma_f32_16x16x32_bf16 v[104:107], v[158:161], v[206:209], v[104:107]
	v_mfma_f32_16x16x32_bf16 v[40:43], v[162:165], v[178:181], v[40:43]
	v_mfma_f32_16x16x32_bf16 v[44:47], v[170:173], v[178:181], v[44:47]
	v_mfma_f32_16x16x32_bf16 v[68:71], v[162:165], v[186:189], v[68:71]
	v_mfma_f32_16x16x32_bf16 v[64:67], v[170:173], v[186:189], v[64:67]
	v_mfma_f32_16x16x32_bf16 v[60:63], v[162:165], v[194:197], v[60:63]
	v_mfma_f32_16x16x32_bf16 v[56:59], v[170:173], v[194:197], v[56:59]
	v_mfma_f32_16x16x32_bf16 v[100:103], v[162:165], v[202:205], v[100:103]
	v_mfma_f32_16x16x32_bf16 v[96:99], v[170:173], v[202:205], v[96:99]
	v_mfma_f32_16x16x32_bf16 v[40:43], v[166:169], v[182:185], v[40:43]
	v_mfma_f32_16x16x32_bf16 v[44:47], v[174:177], v[182:185], v[44:47]
	v_mfma_f32_16x16x32_bf16 v[68:71], v[166:169], v[190:193], v[68:71]
	v_mfma_f32_16x16x32_bf16 v[64:67], v[174:177], v[190:193], v[64:67]
	v_mfma_f32_16x16x32_bf16 v[60:63], v[166:169], v[198:201], v[60:63]
	v_mfma_f32_16x16x32_bf16 v[56:59], v[174:177], v[198:201], v[56:59]
	v_mfma_f32_16x16x32_bf16 v[100:103], v[166:169], v[206:209], v[100:103]
	v_mfma_f32_16x16x32_bf16 v[96:99], v[174:177], v[206:209], v[96:99]
	s_barrier
; #define PG8_WAIT_V(n) asm volatile("s_waitcnt vmcnt(" #n ")" ::: "memory")
; #define PG8_BAR __builtin_amdgcn_s_barrier()
; template <class Epi, class Sched, bool ALIGN_EPI = false, bool SP2 = false, bool A_TILED = false>
; __device__ __forceinline__ void gemm_phase(PG8_LAS unsigned char* lds, const Gemm g, const Sched& S, const Epi& E, const int wave_s) {
;     ...
;     PG8_WAIT_V(0);
;     if constexpr (!ALIGN_EPI) { if (wr == 0) PG8_BAR; }
	s_setprio 0
	s_mov_b32 m0, s49
	v_lshl_add_u64 v[210:211], v[210:211], 0, s[12:13]
	s_add_u32 s18, s18, 0x200080
	ds_read_b128 v[178:181], v142 offset:49152
	ds_read_b128 v[182:185], v142 offset:50176
	ds_read_b128 v[186:189], v142 offset:51200
	ds_read_b128 v[190:193], v142 offset:52224
	ds_read_b128 v[194:197], v142 offset:53248
	ds_read_b128 v[198:201], v142 offset:54272
	ds_read_b128 v[202:205], v142 offset:55296
	ds_read_b128 v[206:209], v142 offset:56320
	global_load_lds_dwordx4 v[210:211], off
	v_lshl_add_u64 v[210:211], v[212:213], 0, s[12:13]
	s_mov_b32 m0, s50
	s_addc_u32 s19, s19, 0
	global_load_lds_dwordx4 v[210:211], off
	v_lshl_add_u64 v[210:211], s[18:19], 0, v[130:131]
	s_mov_b32 m0, s51
	s_nop 0
	global_load_lds_dwordx4 v[210:211], off
	v_lshl_add_u64 v[210:211], s[18:19], 0, v[134:135]
	s_mov_b32 m0, s52
	s_nop 0
	global_load_lds_dwordx4 v[210:211], off
	v_lshl_add_u64 v[210:211], s[16:17], 0, v[128:129]
	s_mov_b32 m0, s36
	s_nop 0
	global_load_lds_dwordx4 v[210:211], off
	v_lshl_add_u64 v[210:211], s[16:17], 0, v[132:133]
	s_mov_b32 m0, s37
	s_nop 0
	global_load_lds_dwordx4 v[210:211], off
	s_waitcnt vmcnt(8) lgkmcnt(0)
	s_setprio 1
	s_barrier
	v_mfma_f32_16x16x32_bf16 v[124:127], v[146:149], v[178:181], v[124:127]
	v_mfma_f32_16x16x32_bf16 v[120:123], v[154:157], v[178:181], v[120:123]
	v_mfma_f32_16x16x32_bf16 v[88:91], v[146:149], v[186:189], v[88:91]
	v_mfma_f32_16x16x32_bf16 v[72:75], v[154:157], v[186:189], v[72:75]
	v_mfma_f32_16x16x32_bf16 v[28:31], v[146:149], v[194:197], v[28:31]
	v_mfma_f32_16x16x32_bf16 v[24:27], v[154:157], v[194:197], v[24:27]
	v_mfma_f32_16x16x32_bf16 v[12:15], v[146:149], v[202:205], v[12:15]
	v_mfma_f32_16x16x32_bf16 v[8:11], v[154:157], v[202:205], v[8:11]
	v_mfma_f32_16x16x32_bf16 v[124:127], v[150:153], v[182:185], v[124:127]
	v_mfma_f32_16x16x32_bf16 v[120:123], v[158:161], v[182:185], v[120:123]
	v_mfma_f32_16x16x32_bf16 v[88:91], v[150:153], v[190:193], v[88:91]
	v_mfma_f32_16x16x32_bf16 v[72:75], v[158:161], v[190:193], v[72:75]
	v_mfma_f32_16x16x32_bf16 v[28:31], v[150:153], v[198:201], v[28:31]
	v_mfma_f32_16x16x32_bf16 v[24:27], v[158:161], v[198:201], v[24:27]
	v_mfma_f32_16x16x32_bf16 v[12:15], v[150:153], v[206:209], v[12:15]
	v_mfma_f32_16x16x32_bf16 v[8:11], v[158:161], v[206:209], v[8:11]
	v_mfma_f32_16x16x32_bf16 v[116:119], v[162:165], v[178:181], v[116:119]
	v_mfma_f32_16x16x32_bf16 v[112:115], v[170:173], v[178:181], v[112:115]
	v_mfma_f32_16x16x32_bf16 v[52:55], v[162:165], v[186:189], v[52:55]
	v_mfma_f32_16x16x32_bf16 v[48:51], v[170:173], v[186:189], v[48:51]
	v_mfma_f32_16x16x32_bf16 v[20:23], v[162:165], v[194:197], v[20:23]
	v_mfma_f32_16x16x32_bf16 v[16:19], v[170:173], v[194:197], v[16:19]
	v_mfma_f32_16x16x32_bf16 v[4:7], v[162:165], v[202:205], v[4:7]
	v_mfma_f32_16x16x32_bf16 v[0:3], v[170:173], v[202:205], v[0:3]
	v_mfma_f32_16x16x32_bf16 v[116:119], v[166:169], v[182:185], v[116:119]
	v_mfma_f32_16x16x32_bf16 v[112:115], v[174:177], v[182:185], v[112:115]
	v_mfma_f32_16x16x32_bf16 v[52:55], v[166:169], v[190:193], v[52:55]
	v_mfma_f32_16x16x32_bf16 v[48:51], v[174:177], v[190:193], v[48:51]
	v_mfma_f32_16x16x32_bf16 v[20:23], v[166:169], v[198:201], v[20:23]
	v_mfma_f32_16x16x32_bf16 v[16:19], v[174:177], v[198:201], v[16:19]
	v_mfma_f32_16x16x32_bf16 v[4:7], v[166:169], v[206:209], v[4:7]
	v_mfma_f32_16x16x32_bf16 v[0:3], v[174:177], v[206:209], v[0:3]
	s_barrier
	s_setprio 0
	s_add_i32 s42, s42, 2
	s_add_u32 s38, s38, 0x100
	s_addc_u32 s39, s39, 0
	s_add_u32 s40, s40, 0x10000
	s_addc_u32 s41, s41, 0
	v_lshl_add_u64 v[136:137], v[136:137], 0, s[14:15]
	s_cmpk_gt_u32 s42, 0x7d
	v_lshl_add_u64 v[138:139], v[138:139], 0, s[14:15]
	s_cbranch_scc0 .LBB0_3793
	s_waitcnt vmcnt(0)
	s_cmpk_lt_u32 s22, 0x100
	s_cbranch_scc0 .LBB0_3796
	s_barrier

; __device__ __forceinline__ int tid_now(int wave_s) { unsigned z = 0u; asm volatile("" : "+v"(z)); return (wave_s << 6) | (int)__builtin_amdgcn_mbcnt_hi(~0u, __builtin_amdgcn_mbcnt_lo(~0u, z)); }
; __device__ __forceinline__ unsigned xb_add(unsigned* p, unsigned v) { return __hip_atomic_fetch_add(p, v, __ATOMIC_RELAXED, __HIP_MEMORY_SCOPE_AGENT); }
; __device__ __forceinline__ void xcd_barrier(const XcdBarrier& b) {
;     asm volatile("s_waitcnt vmcnt(0)" ::: "memory");
;     __syncthreads();
;     if (tid_now(b.w) == 0) {
;         unsigned* bar = b.bar;
;         __builtin_amdgcn_s_waitcnt(0);
;         unsigned nloc = b.st[0], nx = b.st[1];
;         if (nloc == 0u) { xcd_barrier_complete(bar, b.x, nloc, nx, b.np); b.st[0] = nloc; b.st[1] = nx; }
;         const unsigned old = xb_add(&bar[XB_XSUB(b.x)], 1u);
.LBB0_3837:
	s_cmp_gt_i32 s35, 25
	s_cselect_b64 s[0:1], -1, 0
	s_and_b64 s[0:1], s[6:7], s[0:1]
	s_andn2_b64 vcc, exec, s[0:1]
	s_branch .LBB0_3891
	s_waitcnt vmcnt(0)
	v_mov_b32_e32 v0, 0
	s_waitcnt vmcnt(0)
	s_waitcnt lgkmcnt(0)
	s_barrier
	s_nop 0
	v_mbcnt_lo_u32_b32 v0, -1, v0
	v_mbcnt_hi_u32_b32 v0, -1, v0
	v_or_b32_e32 v0, s33, v0
	v_cmp_eq_u32_e32 vcc, 0, v0
	s_and_saveexec_b64 s[0:1], vcc
	s_cbranch_execz .LBB0_3890
	s_add_i32 s2, 0, 0x27f68
	v_mov_b32_e32 v0, s2
	s_waitcnt vmcnt(0) expcnt(0) lgkmcnt(0)
	ds_read_b32 v2, v0
	s_add_i32 s2, 0, 0x27f6c
	v_mov_b32_e32 v0, s2
	ds_read_b32 v0, v0
	s_waitcnt lgkmcnt(1)
	v_cmp_ne_u32_e32 vcc, 0, v2
	s_cbranch_vccnz .LBB0_3854
	s_add_u32 s2, s10, 0x1000
	s_addc_u32 s3, s11, 0
	s_add_u32 s4, s10, 0x1100
	s_addc_u32 s5, s11, 0
	s_add_u32 s6, s10, 0x1200
	s_addc_u32 s7, s11, 0
	s_add_u32 s8, s10, 0x1300
	s_addc_u32 s9, s11, 0
	s_mov_b32 s18, 1
	v_mov_b32_e32 v16, 0
	s_branch .LBB0_3842
